# plus hyena: filter-accumulation loop software-pipelined (8 steps of loads in flight), gate words prefetched before the FFTs
# speedup vs baseline: 1.0280x; 1.0120x over previous
; #define LAS __attribute__((address_space(3)))
; __device__ __forceinline__ void hyena_phase(const Params& P, int l, LAS unsigned char* lds) {
;     ...
;             if (tid < 256) ((LAS float*)w3s)[tid] = w3[(size_t)(tid >> 2) * 4096 + ((tid >> 1) & 1) * 2048 + (tid & 1) * 1024 + c];
;             __syncthreads();
;             const float dl = hy_delta(c);
;             {
;                 f32x4 hacc[8];
; #pragma unroll
;                 for (int e = 0; e < 8; ++e) hacc[e] = (f32x4){0.f, 0.f, 0.f, 0.f};
; #pragma unroll 16
;                 for (int j = 0; j < 64; ++j) { const f32x4 w = w3s[j]; const f32x4 h0 = *(const f32x4*)(HID + (size_t)j * 4096 + 4 * tid), h1 = *(const f32x4*)(HID + (size_t)j * 4096 + 2048 + 4 * tid);
; #pragma unroll
;                     for (int e = 0; e < 4; ++e) { hacc[e] += h0[e] * w; hacc[4 + e] += h1[e] * w; } }
.LBB0_399:
	s_or_b64 exec, exec, s[4:5]
	v_lshlrev_b32_e32 v4, 2, v0
	v_ashrrev_i32_e32 v5, 31, v4
	s_waitcnt vmcnt(15)
	v_mov_b32_e32 v36, 0
	v_lshl_add_u64 v[6:7], v[4:5], 2, s[16:17]
	s_add_i32 s6, 0, 0x22000
	s_mov_b64 s[4:5], 0
	v_mov_b32_e32 v37, v36
	v_mov_b32_e32 v38, v36
	v_mov_b32_e32 v39, v36
	v_mov_b32_e32 v34, v36
	v_mov_b32_e32 v35, v36
	v_mov_b32_e32 v32, v36
	v_mov_b32_e32 v33, v36
	v_mov_b32_e32 v30, v36
	v_mov_b32_e32 v31, v36
	v_mov_b32_e32 v28, v36
	v_mov_b32_e32 v29, v36
	v_mov_b32_e32 v26, v36
	v_mov_b32_e32 v27, v36
	v_mov_b32_e32 v24, v36
	v_mov_b32_e32 v25, v36
	v_mov_b32_e32 v22, v36
	v_mov_b32_e32 v23, v36
	v_mov_b32_e32 v20, v36
	v_mov_b32_e32 v21, v36
	s_waitcnt vmcnt(1)
	v_mov_b32_e32 v18, v36
	v_mov_b32_e32 v19, v36
	v_mov_b32_e32 v16, v36
	v_mov_b32_e32 v17, v36
	s_waitcnt vmcnt(0)
	v_mov_b32_e32 v14, v36
	v_mov_b32_e32 v15, v36
	v_mov_b32_e32 v12, v36
	v_mov_b32_e32 v13, v36
	v_mov_b32_e32 v10, v36
	v_mov_b32_e32 v11, v36
	v_mov_b32_e32 v8, v36
	v_mov_b32_e32 v9, v36
	s_brev_b32 s22, 1
	s_waitcnt lgkmcnt(0)
	s_barrier
	v_lshlrev_b32_e32 v40, 2, v4
	v_add_u32_e32 v41, 0x2000, v40
	s_add_u32 s4, s16, 0x411a8000
	s_addc_u32 s5, s17, 0
	v_mov_b32_e32 v1, s6
	ds_read_b128 v[42:45], v1 offset:0
	ds_read_b128 v[46:49], v1 offset:16
	ds_read_b128 v[50:53], v1 offset:32
	ds_read_b128 v[54:57], v1 offset:48
	global_load_dwordx4 v[112:115], v40, s[4:5]
	global_load_dwordx4 v[116:119], v41, s[4:5]
	s_add_u32 s4, s4, 0x4000
	s_addc_u32 s5, s5, 0
	global_load_dwordx4 v[120:123], v40, s[4:5]
	global_load_dwordx4 v[124:127], v41, s[4:5]
	s_add_u32 s4, s4, 0x4000
	s_addc_u32 s5, s5, 0
	global_load_dwordx4 v[128:131], v40, s[4:5]
	global_load_dwordx4 v[132:135], v41, s[4:5]
	s_add_u32 s4, s4, 0x4000
	s_addc_u32 s5, s5, 0
	global_load_dwordx4 v[136:139], v40, s[4:5]
	global_load_dwordx4 v[140:143], v41, s[4:5]
	s_add_u32 s4, s4, 0x4000
	s_addc_u32 s5, s5, 0
	global_load_dwordx4 v[144:147], v40, s[4:5]
	global_load_dwordx4 v[148:151], v41, s[4:5]
	s_add_u32 s4, s4, 0x4000
	s_addc_u32 s5, s5, 0
	global_load_dwordx4 v[152:155], v40, s[4:5]
	global_load_dwordx4 v[156:159], v41, s[4:5]
	s_add_u32 s4, s4, 0x4000
	s_addc_u32 s5, s5, 0
	global_load_dwordx4 v[160:163], v40, s[4:5]
	global_load_dwordx4 v[164:167], v41, s[4:5]
	s_add_u32 s4, s4, 0x4000
	s_addc_u32 s5, s5, 0
	global_load_dwordx4 v[168:171], v40, s[4:5]
	global_load_dwordx4 v[172:175], v41, s[4:5]
	s_add_u32 s4, s4, 0x4000
	s_addc_u32 s5, s5, 0
	s_mov_b32 s7, 0
.Lhyf_loop:
	v_mov_b32_e32 v1, s6
	ds_read_b128 v[176:179], v1 offset:64
	ds_read_b128 v[180:183], v1 offset:80
	ds_read_b128 v[184:187], v1 offset:96
	ds_read_b128 v[188:191], v1 offset:112
	s_waitcnt lgkmcnt(4)
	s_waitcnt vmcnt(14)
	v_pk_fma_f32 v[36:37], v[42:43], v[112:113], v[36:37] op_sel_hi:[1,0,1]
	v_pk_fma_f32 v[38:39], v[44:45], v[112:113], v[38:39] op_sel_hi:[1,0,1]
	v_pk_fma_f32 v[34:35], v[42:43], v[112:113], v[34:35] op_sel:[0,1,0]
	v_pk_fma_f32 v[32:33], v[44:45], v[112:113], v[32:33] op_sel:[0,1,0]
	v_pk_fma_f32 v[30:31], v[42:43], v[114:115], v[30:31] op_sel_hi:[1,0,1]
	v_pk_fma_f32 v[28:29], v[44:45], v[114:115], v[28:29] op_sel_hi:[1,0,1]
	v_pk_fma_f32 v[26:27], v[42:43], v[114:115], v[26:27] op_sel:[0,1,0]
	v_pk_fma_f32 v[24:25], v[44:45], v[114:115], v[24:25] op_sel:[0,1,0]
	v_pk_fma_f32 v[22:23], v[42:43], v[116:117], v[22:23] op_sel_hi:[1,0,1]
	v_pk_fma_f32 v[20:21], v[44:45], v[116:117], v[20:21] op_sel_hi:[1,0,1]
	v_pk_fma_f32 v[18:19], v[42:43], v[116:117], v[18:19] op_sel:[0,1,0]
	v_pk_fma_f32 v[16:17], v[44:45], v[116:117], v[16:17] op_sel:[0,1,0]
	v_pk_fma_f32 v[14:15], v[42:43], v[118:119], v[14:15] op_sel_hi:[1,0,1]
	v_pk_fma_f32 v[12:13], v[44:45], v[118:119], v[12:13] op_sel_hi:[1,0,1]
	v_pk_fma_f32 v[10:11], v[42:43], v[118:119], v[10:11] op_sel:[0,1,0]
	v_pk_fma_f32 v[8:9], v[44:45], v[118:119], v[8:9] op_sel:[0,1,0]
	global_load_dwordx4 v[112:115], v40, s[4:5]
	global_load_dwordx4 v[116:119], v41, s[4:5]
	s_add_u32 s4, s4, 0x4000
	s_addc_u32 s5, s5, 0
	s_waitcnt vmcnt(14)
	v_pk_fma_f32 v[36:37], v[46:47], v[120:121], v[36:37] op_sel_hi:[1,0,1]
	v_pk_fma_f32 v[38:39], v[48:49], v[120:121], v[38:39] op_sel_hi:[1,0,1]
	v_pk_fma_f32 v[34:35], v[46:47], v[120:121], v[34:35] op_sel:[0,1,0]
	v_pk_fma_f32 v[32:33], v[48:49], v[120:121], v[32:33] op_sel:[0,1,0]
	v_pk_fma_f32 v[30:31], v[46:47], v[122:123], v[30:31] op_sel_hi:[1,0,1]
	v_pk_fma_f32 v[28:29], v[48:49], v[122:123], v[28:29] op_sel_hi:[1,0,1]
	v_pk_fma_f32 v[26:27], v[46:47], v[122:123], v[26:27] op_sel:[0,1,0]
	v_pk_fma_f32 v[24:25], v[48:49], v[122:123], v[24:25] op_sel:[0,1,0]
	v_pk_fma_f32 v[22:23], v[46:47], v[124:125], v[22:23] op_sel_hi:[1,0,1]
	v_pk_fma_f32 v[20:21], v[48:49], v[124:125], v[20:21] op_sel_hi:[1,0,1]
	v_pk_fma_f32 v[18:19], v[46:47], v[124:125], v[18:19] op_sel:[0,1,0]
	v_pk_fma_f32 v[16:17], v[48:49], v[124:125], v[16:17] op_sel:[0,1,0]
	v_pk_fma_f32 v[14:15], v[46:47], v[126:127], v[14:15] op_sel_hi:[1,0,1]
	v_pk_fma_f32 v[12:13], v[48:49], v[126:127], v[12:13] op_sel_hi:[1,0,1]
	v_pk_fma_f32 v[10:11], v[46:47], v[126:127], v[10:11] op_sel:[0,1,0]
	v_pk_fma_f32 v[8:9], v[48:49], v[126:127], v[8:9] op_sel:[0,1,0]
	global_load_dwordx4 v[120:123], v40, s[4:5]
	global_load_dwordx4 v[124:127], v41, s[4:5]
	s_add_u32 s4, s4, 0x4000
	s_addc_u32 s5, s5, 0
	s_waitcnt vmcnt(14)
; __device__ __forceinline__ void hyena_phase(const Params& P, int l, LAS unsigned char* lds) {
;     ...
; #pragma unroll 16
;                 for (int j = 0; j < 64; ++j) { const f32x4 w = w3s[j]; const f32x4 h0 = *(const f32x4*)(HID + (size_t)j * 4096 + 4 * tid), h1 = *(const f32x4*)(HID + (size_t)j * 4096 + 2048 + 4 * tid);
; #pragma unroll
;                     for (int e = 0; e < 4; ++e) { hacc[e] += h0[e] * w; hacc[4 + e] += h1[e] * w; } }
	v_pk_fma_f32 v[36:37], v[50:51], v[128:129], v[36:37] op_sel_hi:[1,0,1]
	v_pk_fma_f32 v[38:39], v[52:53], v[128:129], v[38:39] op_sel_hi:[1,0,1]
	v_pk_fma_f32 v[34:35], v[50:51], v[128:129], v[34:35] op_sel:[0,1,0]
	v_pk_fma_f32 v[32:33], v[52:53], v[128:129], v[32:33] op_sel:[0,1,0]
	v_pk_fma_f32 v[30:31], v[50:51], v[130:131], v[30:31] op_sel_hi:[1,0,1]
	v_pk_fma_f32 v[28:29], v[52:53], v[130:131], v[28:29] op_sel_hi:[1,0,1]
	v_pk_fma_f32 v[26:27], v[50:51], v[130:131], v[26:27] op_sel:[0,1,0]
	v_pk_fma_f32 v[24:25], v[52:53], v[130:131], v[24:25] op_sel:[0,1,0]
	v_pk_fma_f32 v[22:23], v[50:51], v[132:133], v[22:23] op_sel_hi:[1,0,1]
	v_pk_fma_f32 v[20:21], v[52:53], v[132:133], v[20:21] op_sel_hi:[1,0,1]
	v_pk_fma_f32 v[18:19], v[50:51], v[132:133], v[18:19] op_sel:[0,1,0]
	v_pk_fma_f32 v[16:17], v[52:53], v[132:133], v[16:17] op_sel:[0,1,0]
	v_pk_fma_f32 v[14:15], v[50:51], v[134:135], v[14:15] op_sel_hi:[1,0,1]
	v_pk_fma_f32 v[12:13], v[52:53], v[134:135], v[12:13] op_sel_hi:[1,0,1]
	v_pk_fma_f32 v[10:11], v[50:51], v[134:135], v[10:11] op_sel:[0,1,0]
	v_pk_fma_f32 v[8:9], v[52:53], v[134:135], v[8:9] op_sel:[0,1,0]
	global_load_dwordx4 v[128:131], v40, s[4:5]
	global_load_dwordx4 v[132:135], v41, s[4:5]
	s_add_u32 s4, s4, 0x4000
	s_addc_u32 s5, s5, 0
	s_waitcnt vmcnt(14)
	v_pk_fma_f32 v[36:37], v[54:55], v[136:137], v[36:37] op_sel_hi:[1,0,1]
	v_pk_fma_f32 v[38:39], v[56:57], v[136:137], v[38:39] op_sel_hi:[1,0,1]
	v_pk_fma_f32 v[34:35], v[54:55], v[136:137], v[34:35] op_sel:[0,1,0]
	v_pk_fma_f32 v[32:33], v[56:57], v[136:137], v[32:33] op_sel:[0,1,0]
	v_pk_fma_f32 v[30:31], v[54:55], v[138:139], v[30:31] op_sel_hi:[1,0,1]
	v_pk_fma_f32 v[28:29], v[56:57], v[138:139], v[28:29] op_sel_hi:[1,0,1]
	v_pk_fma_f32 v[26:27], v[54:55], v[138:139], v[26:27] op_sel:[0,1,0]
	v_pk_fma_f32 v[24:25], v[56:57], v[138:139], v[24:25] op_sel:[0,1,0]
	v_pk_fma_f32 v[22:23], v[54:55], v[140:141], v[22:23] op_sel_hi:[1,0,1]
	v_pk_fma_f32 v[20:21], v[56:57], v[140:141], v[20:21] op_sel_hi:[1,0,1]
	v_pk_fma_f32 v[18:19], v[54:55], v[140:141], v[18:19] op_sel:[0,1,0]
	v_pk_fma_f32 v[16:17], v[56:57], v[140:141], v[16:17] op_sel:[0,1,0]
	v_pk_fma_f32 v[14:15], v[54:55], v[142:143], v[14:15] op_sel_hi:[1,0,1]
	v_pk_fma_f32 v[12:13], v[56:57], v[142:143], v[12:13] op_sel_hi:[1,0,1]
	v_pk_fma_f32 v[10:11], v[54:55], v[142:143], v[10:11] op_sel:[0,1,0]
	v_pk_fma_f32 v[8:9], v[56:57], v[142:143], v[8:9] op_sel:[0,1,0]
	global_load_dwordx4 v[136:139], v40, s[4:5]
	global_load_dwordx4 v[140:143], v41, s[4:5]
	s_add_u32 s4, s4, 0x4000
	s_addc_u32 s5, s5, 0
	ds_read_b128 v[42:45], v1 offset:128
	ds_read_b128 v[46:49], v1 offset:144
	ds_read_b128 v[50:53], v1 offset:160
	ds_read_b128 v[54:57], v1 offset:176
	s_waitcnt lgkmcnt(4)
	s_waitcnt vmcnt(14)
	v_pk_fma_f32 v[36:37], v[176:177], v[144:145], v[36:37] op_sel_hi:[1,0,1]
	v_pk_fma_f32 v[38:39], v[178:179], v[144:145], v[38:39] op_sel_hi:[1,0,1]
	v_pk_fma_f32 v[34:35], v[176:177], v[144:145], v[34:35] op_sel:[0,1,0]
	v_pk_fma_f32 v[32:33], v[178:179], v[144:145], v[32:33] op_sel:[0,1,0]
	v_pk_fma_f32 v[30:31], v[176:177], v[146:147], v[30:31] op_sel_hi:[1,0,1]
	v_pk_fma_f32 v[28:29], v[178:179], v[146:147], v[28:29] op_sel_hi:[1,0,1]
	v_pk_fma_f32 v[26:27], v[176:177], v[146:147], v[26:27] op_sel:[0,1,0]
	v_pk_fma_f32 v[24:25], v[178:179], v[146:147], v[24:25] op_sel:[0,1,0]
	v_pk_fma_f32 v[22:23], v[176:177], v[148:149], v[22:23] op_sel_hi:[1,0,1]
	v_pk_fma_f32 v[20:21], v[178:179], v[148:149], v[20:21] op_sel_hi:[1,0,1]
	v_pk_fma_f32 v[18:19], v[176:177], v[148:149], v[18:19] op_sel:[0,1,0]
	v_pk_fma_f32 v[16:17], v[178:179], v[148:149], v[16:17] op_sel:[0,1,0]
	v_pk_fma_f32 v[14:15], v[176:177], v[150:151], v[14:15] op_sel_hi:[1,0,1]
	v_pk_fma_f32 v[12:13], v[178:179], v[150:151], v[12:13] op_sel_hi:[1,0,1]
	v_pk_fma_f32 v[10:11], v[176:177], v[150:151], v[10:11] op_sel:[0,1,0]
	v_pk_fma_f32 v[8:9], v[178:179], v[150:151], v[8:9] op_sel:[0,1,0]
	global_load_dwordx4 v[144:147], v40, s[4:5]
	global_load_dwordx4 v[148:151], v41, s[4:5]
	s_add_u32 s4, s4, 0x4000
	s_addc_u32 s5, s5, 0
	s_waitcnt vmcnt(14)
	v_pk_fma_f32 v[36:37], v[180:181], v[152:153], v[36:37] op_sel_hi:[1,0,1]
	v_pk_fma_f32 v[38:39], v[182:183], v[152:153], v[38:39] op_sel_hi:[1,0,1]
	v_pk_fma_f32 v[34:35], v[180:181], v[152:153], v[34:35] op_sel:[0,1,0]
	v_pk_fma_f32 v[32:33], v[182:183], v[152:153], v[32:33] op_sel:[0,1,0]
	v_pk_fma_f32 v[30:31], v[180:181], v[154:155], v[30:31] op_sel_hi:[1,0,1]
	v_pk_fma_f32 v[28:29], v[182:183], v[154:155], v[28:29] op_sel_hi:[1,0,1]
	v_pk_fma_f32 v[26:27], v[180:181], v[154:155], v[26:27] op_sel:[0,1,0]
	v_pk_fma_f32 v[24:25], v[182:183], v[154:155], v[24:25] op_sel:[0,1,0]
	v_pk_fma_f32 v[22:23], v[180:181], v[156:157], v[22:23] op_sel_hi:[1,0,1]
	v_pk_fma_f32 v[20:21], v[182:183], v[156:157], v[20:21] op_sel_hi:[1,0,1]
	v_pk_fma_f32 v[18:19], v[180:181], v[156:157], v[18:19] op_sel:[0,1,0]
	v_pk_fma_f32 v[16:17], v[182:183], v[156:157], v[16:17] op_sel:[0,1,0]
	v_pk_fma_f32 v[14:15], v[180:181], v[158:159], v[14:15] op_sel_hi:[1,0,1]
	v_pk_fma_f32 v[12:13], v[182:183], v[158:159], v[12:13] op_sel_hi:[1,0,1]
	v_pk_fma_f32 v[10:11], v[180:181], v[158:159], v[10:11] op_sel:[0,1,0]
	v_pk_fma_f32 v[8:9], v[182:183], v[158:159], v[8:9] op_sel:[0,1,0]
	global_load_dwordx4 v[152:155], v40, s[4:5]
	global_load_dwordx4 v[156:159], v41, s[4:5]
	s_add_u32 s4, s4, 0x4000
	s_addc_u32 s5, s5, 0
	s_waitcnt vmcnt(14)
; __device__ __forceinline__ void hyena_phase(const Params& P, int l, LAS unsigned char* lds) {
;     ...
; #pragma unroll 16
;                 for (int j = 0; j < 64; ++j) { const f32x4 w = w3s[j]; const f32x4 h0 = *(const f32x4*)(HID + (size_t)j * 4096 + 4 * tid), h1 = *(const f32x4*)(HID + (size_t)j * 4096 + 2048 + 4 * tid);
; #pragma unroll
;                     for (int e = 0; e < 4; ++e) { hacc[e] += h0[e] * w; hacc[4 + e] += h1[e] * w; } }
	v_pk_fma_f32 v[36:37], v[184:185], v[160:161], v[36:37] op_sel_hi:[1,0,1]
	v_pk_fma_f32 v[38:39], v[186:187], v[160:161], v[38:39] op_sel_hi:[1,0,1]
	v_pk_fma_f32 v[34:35], v[184:185], v[160:161], v[34:35] op_sel:[0,1,0]
	v_pk_fma_f32 v[32:33], v[186:187], v[160:161], v[32:33] op_sel:[0,1,0]
	v_pk_fma_f32 v[30:31], v[184:185], v[162:163], v[30:31] op_sel_hi:[1,0,1]
	v_pk_fma_f32 v[28:29], v[186:187], v[162:163], v[28:29] op_sel_hi:[1,0,1]
	v_pk_fma_f32 v[26:27], v[184:185], v[162:163], v[26:27] op_sel:[0,1,0]
	v_pk_fma_f32 v[24:25], v[186:187], v[162:163], v[24:25] op_sel:[0,1,0]
	v_pk_fma_f32 v[22:23], v[184:185], v[164:165], v[22:23] op_sel_hi:[1,0,1]
	v_pk_fma_f32 v[20:21], v[186:187], v[164:165], v[20:21] op_sel_hi:[1,0,1]
	v_pk_fma_f32 v[18:19], v[184:185], v[164:165], v[18:19] op_sel:[0,1,0]
	v_pk_fma_f32 v[16:17], v[186:187], v[164:165], v[16:17] op_sel:[0,1,0]
	v_pk_fma_f32 v[14:15], v[184:185], v[166:167], v[14:15] op_sel_hi:[1,0,1]
	v_pk_fma_f32 v[12:13], v[186:187], v[166:167], v[12:13] op_sel_hi:[1,0,1]
	v_pk_fma_f32 v[10:11], v[184:185], v[166:167], v[10:11] op_sel:[0,1,0]
	v_pk_fma_f32 v[8:9], v[186:187], v[166:167], v[8:9] op_sel:[0,1,0]
	global_load_dwordx4 v[160:163], v40, s[4:5]
	global_load_dwordx4 v[164:167], v41, s[4:5]
	s_add_u32 s4, s4, 0x4000
	s_addc_u32 s5, s5, 0
	s_waitcnt vmcnt(14)
	v_pk_fma_f32 v[36:37], v[188:189], v[168:169], v[36:37] op_sel_hi:[1,0,1]
	v_pk_fma_f32 v[38:39], v[190:191], v[168:169], v[38:39] op_sel_hi:[1,0,1]
	v_pk_fma_f32 v[34:35], v[188:189], v[168:169], v[34:35] op_sel:[0,1,0]
	v_pk_fma_f32 v[32:33], v[190:191], v[168:169], v[32:33] op_sel:[0,1,0]
	v_pk_fma_f32 v[30:31], v[188:189], v[170:171], v[30:31] op_sel_hi:[1,0,1]
	v_pk_fma_f32 v[28:29], v[190:191], v[170:171], v[28:29] op_sel_hi:[1,0,1]
	v_pk_fma_f32 v[26:27], v[188:189], v[170:171], v[26:27] op_sel:[0,1,0]
	v_pk_fma_f32 v[24:25], v[190:191], v[170:171], v[24:25] op_sel:[0,1,0]
	v_pk_fma_f32 v[22:23], v[188:189], v[172:173], v[22:23] op_sel_hi:[1,0,1]
	v_pk_fma_f32 v[20:21], v[190:191], v[172:173], v[20:21] op_sel_hi:[1,0,1]
	v_pk_fma_f32 v[18:19], v[188:189], v[172:173], v[18:19] op_sel:[0,1,0]
	v_pk_fma_f32 v[16:17], v[190:191], v[172:173], v[16:17] op_sel:[0,1,0]
	v_pk_fma_f32 v[14:15], v[188:189], v[174:175], v[14:15] op_sel_hi:[1,0,1]
	v_pk_fma_f32 v[12:13], v[190:191], v[174:175], v[12:13] op_sel_hi:[1,0,1]
	v_pk_fma_f32 v[10:11], v[188:189], v[174:175], v[10:11] op_sel:[0,1,0]
	v_pk_fma_f32 v[8:9], v[190:191], v[174:175], v[8:9] op_sel:[0,1,0]
	global_load_dwordx4 v[168:171], v40, s[4:5]
	global_load_dwordx4 v[172:175], v41, s[4:5]
	s_add_u32 s4, s4, 0x4000
	s_addc_u32 s5, s5, 0
	s_add_i32 s7, s7, 1
	s_addk_i32 s6, 0x80
	s_cmp_lg_u32 s7, 7
	s_cbranch_scc1 .Lhyf_loop
	v_mov_b32_e32 v1, s6
	ds_read_b128 v[176:179], v1 offset:64
	ds_read_b128 v[180:183], v1 offset:80
	ds_read_b128 v[184:187], v1 offset:96
	ds_read_b128 v[188:191], v1 offset:112
	s_waitcnt lgkmcnt(4)
	s_waitcnt vmcnt(14)
	v_pk_fma_f32 v[36:37], v[42:43], v[112:113], v[36:37] op_sel_hi:[1,0,1]
	v_pk_fma_f32 v[38:39], v[44:45], v[112:113], v[38:39] op_sel_hi:[1,0,1]
	v_pk_fma_f32 v[34:35], v[42:43], v[112:113], v[34:35] op_sel:[0,1,0]
	v_pk_fma_f32 v[32:33], v[44:45], v[112:113], v[32:33] op_sel:[0,1,0]
	v_pk_fma_f32 v[30:31], v[42:43], v[114:115], v[30:31] op_sel_hi:[1,0,1]
	v_pk_fma_f32 v[28:29], v[44:45], v[114:115], v[28:29] op_sel_hi:[1,0,1]
	v_pk_fma_f32 v[26:27], v[42:43], v[114:115], v[26:27] op_sel:[0,1,0]
	v_pk_fma_f32 v[24:25], v[44:45], v[114:115], v[24:25] op_sel:[0,1,0]
	v_pk_fma_f32 v[22:23], v[42:43], v[116:117], v[22:23] op_sel_hi:[1,0,1]
	v_pk_fma_f32 v[20:21], v[44:45], v[116:117], v[20:21] op_sel_hi:[1,0,1]
	v_pk_fma_f32 v[18:19], v[42:43], v[116:117], v[18:19] op_sel:[0,1,0]
	v_pk_fma_f32 v[16:17], v[44:45], v[116:117], v[16:17] op_sel:[0,1,0]
	v_pk_fma_f32 v[14:15], v[42:43], v[118:119], v[14:15] op_sel_hi:[1,0,1]
	v_pk_fma_f32 v[12:13], v[44:45], v[118:119], v[12:13] op_sel_hi:[1,0,1]
	v_pk_fma_f32 v[10:11], v[42:43], v[118:119], v[10:11] op_sel:[0,1,0]
	v_pk_fma_f32 v[8:9], v[44:45], v[118:119], v[8:9] op_sel:[0,1,0]
	s_waitcnt vmcnt(12)
	v_pk_fma_f32 v[36:37], v[46:47], v[120:121], v[36:37] op_sel_hi:[1,0,1]
	v_pk_fma_f32 v[38:39], v[48:49], v[120:121], v[38:39] op_sel_hi:[1,0,1]
	v_pk_fma_f32 v[34:35], v[46:47], v[120:121], v[34:35] op_sel:[0,1,0]
	v_pk_fma_f32 v[32:33], v[48:49], v[120:121], v[32:33] op_sel:[0,1,0]
	v_pk_fma_f32 v[30:31], v[46:47], v[122:123], v[30:31] op_sel_hi:[1,0,1]
	v_pk_fma_f32 v[28:29], v[48:49], v[122:123], v[28:29] op_sel_hi:[1,0,1]
	v_pk_fma_f32 v[26:27], v[46:47], v[122:123], v[26:27] op_sel:[0,1,0]
	v_pk_fma_f32 v[24:25], v[48:49], v[122:123], v[24:25] op_sel:[0,1,0]
	v_pk_fma_f32 v[22:23], v[46:47], v[124:125], v[22:23] op_sel_hi:[1,0,1]
	v_pk_fma_f32 v[20:21], v[48:49], v[124:125], v[20:21] op_sel_hi:[1,0,1]
	v_pk_fma_f32 v[18:19], v[46:47], v[124:125], v[18:19] op_sel:[0,1,0]
	v_pk_fma_f32 v[16:17], v[48:49], v[124:125], v[16:17] op_sel:[0,1,0]
	v_pk_fma_f32 v[14:15], v[46:47], v[126:127], v[14:15] op_sel_hi:[1,0,1]
	v_pk_fma_f32 v[12:13], v[48:49], v[126:127], v[12:13] op_sel_hi:[1,0,1]
	v_pk_fma_f32 v[10:11], v[46:47], v[126:127], v[10:11] op_sel:[0,1,0]
	v_pk_fma_f32 v[8:9], v[48:49], v[126:127], v[8:9] op_sel:[0,1,0]
	s_waitcnt vmcnt(10)
; __device__ __forceinline__ void hyena_phase(const Params& P, int l, LAS unsigned char* lds) {
;     ...
; #pragma unroll 16
;                 for (int j = 0; j < 64; ++j) { const f32x4 w = w3s[j]; const f32x4 h0 = *(const f32x4*)(HID + (size_t)j * 4096 + 4 * tid), h1 = *(const f32x4*)(HID + (size_t)j * 4096 + 2048 + 4 * tid);
; #pragma unroll
;                     for (int e = 0; e < 4; ++e) { hacc[e] += h0[e] * w; hacc[4 + e] += h1[e] * w; } }
	v_pk_fma_f32 v[36:37], v[50:51], v[128:129], v[36:37] op_sel_hi:[1,0,1]
	v_pk_fma_f32 v[38:39], v[52:53], v[128:129], v[38:39] op_sel_hi:[1,0,1]
	v_pk_fma_f32 v[34:35], v[50:51], v[128:129], v[34:35] op_sel:[0,1,0]
	v_pk_fma_f32 v[32:33], v[52:53], v[128:129], v[32:33] op_sel:[0,1,0]
	v_pk_fma_f32 v[30:31], v[50:51], v[130:131], v[30:31] op_sel_hi:[1,0,1]
	v_pk_fma_f32 v[28:29], v[52:53], v[130:131], v[28:29] op_sel_hi:[1,0,1]
	v_pk_fma_f32 v[26:27], v[50:51], v[130:131], v[26:27] op_sel:[0,1,0]
	v_pk_fma_f32 v[24:25], v[52:53], v[130:131], v[24:25] op_sel:[0,1,0]
	v_pk_fma_f32 v[22:23], v[50:51], v[132:133], v[22:23] op_sel_hi:[1,0,1]
	v_pk_fma_f32 v[20:21], v[52:53], v[132:133], v[20:21] op_sel_hi:[1,0,1]
	v_pk_fma_f32 v[18:19], v[50:51], v[132:133], v[18:19] op_sel:[0,1,0]
	v_pk_fma_f32 v[16:17], v[52:53], v[132:133], v[16:17] op_sel:[0,1,0]
	v_pk_fma_f32 v[14:15], v[50:51], v[134:135], v[14:15] op_sel_hi:[1,0,1]
	v_pk_fma_f32 v[12:13], v[52:53], v[134:135], v[12:13] op_sel_hi:[1,0,1]
	v_pk_fma_f32 v[10:11], v[50:51], v[134:135], v[10:11] op_sel:[0,1,0]
	v_pk_fma_f32 v[8:9], v[52:53], v[134:135], v[8:9] op_sel:[0,1,0]
	s_waitcnt vmcnt(8)
	v_pk_fma_f32 v[36:37], v[54:55], v[136:137], v[36:37] op_sel_hi:[1,0,1]
	v_pk_fma_f32 v[38:39], v[56:57], v[136:137], v[38:39] op_sel_hi:[1,0,1]
	v_pk_fma_f32 v[34:35], v[54:55], v[136:137], v[34:35] op_sel:[0,1,0]
	v_pk_fma_f32 v[32:33], v[56:57], v[136:137], v[32:33] op_sel:[0,1,0]
	v_pk_fma_f32 v[30:31], v[54:55], v[138:139], v[30:31] op_sel_hi:[1,0,1]
	v_pk_fma_f32 v[28:29], v[56:57], v[138:139], v[28:29] op_sel_hi:[1,0,1]
	v_pk_fma_f32 v[26:27], v[54:55], v[138:139], v[26:27] op_sel:[0,1,0]
	v_pk_fma_f32 v[24:25], v[56:57], v[138:139], v[24:25] op_sel:[0,1,0]
	v_pk_fma_f32 v[22:23], v[54:55], v[140:141], v[22:23] op_sel_hi:[1,0,1]
	v_pk_fma_f32 v[20:21], v[56:57], v[140:141], v[20:21] op_sel_hi:[1,0,1]
	v_pk_fma_f32 v[18:19], v[54:55], v[140:141], v[18:19] op_sel:[0,1,0]
	v_pk_fma_f32 v[16:17], v[56:57], v[140:141], v[16:17] op_sel:[0,1,0]
	v_pk_fma_f32 v[14:15], v[54:55], v[142:143], v[14:15] op_sel_hi:[1,0,1]
	v_pk_fma_f32 v[12:13], v[56:57], v[142:143], v[12:13] op_sel_hi:[1,0,1]
	v_pk_fma_f32 v[10:11], v[54:55], v[142:143], v[10:11] op_sel:[0,1,0]
	v_pk_fma_f32 v[8:9], v[56:57], v[142:143], v[8:9] op_sel:[0,1,0]
	s_waitcnt lgkmcnt(0)
	s_waitcnt vmcnt(6)
	v_pk_fma_f32 v[36:37], v[176:177], v[144:145], v[36:37] op_sel_hi:[1,0,1]
	v_pk_fma_f32 v[38:39], v[178:179], v[144:145], v[38:39] op_sel_hi:[1,0,1]
	v_pk_fma_f32 v[34:35], v[176:177], v[144:145], v[34:35] op_sel:[0,1,0]
	v_pk_fma_f32 v[32:33], v[178:179], v[144:145], v[32:33] op_sel:[0,1,0]
	v_pk_fma_f32 v[30:31], v[176:177], v[146:147], v[30:31] op_sel_hi:[1,0,1]
	v_pk_fma_f32 v[28:29], v[178:179], v[146:147], v[28:29] op_sel_hi:[1,0,1]
	v_pk_fma_f32 v[26:27], v[176:177], v[146:147], v[26:27] op_sel:[0,1,0]
	v_pk_fma_f32 v[24:25], v[178:179], v[146:147], v[24:25] op_sel:[0,1,0]
	v_pk_fma_f32 v[22:23], v[176:177], v[148:149], v[22:23] op_sel_hi:[1,0,1]
	v_pk_fma_f32 v[20:21], v[178:179], v[148:149], v[20:21] op_sel_hi:[1,0,1]
	v_pk_fma_f32 v[18:19], v[176:177], v[148:149], v[18:19] op_sel:[0,1,0]
	v_pk_fma_f32 v[16:17], v[178:179], v[148:149], v[16:17] op_sel:[0,1,0]
	v_pk_fma_f32 v[14:15], v[176:177], v[150:151], v[14:15] op_sel_hi:[1,0,1]
	v_pk_fma_f32 v[12:13], v[178:179], v[150:151], v[12:13] op_sel_hi:[1,0,1]
	v_pk_fma_f32 v[10:11], v[176:177], v[150:151], v[10:11] op_sel:[0,1,0]
	v_pk_fma_f32 v[8:9], v[178:179], v[150:151], v[8:9] op_sel:[0,1,0]
	s_waitcnt vmcnt(4)
; __device__ __forceinline__ void hyena_phase(const Params& P, int l, LAS unsigned char* lds) {
;     ...
; #pragma unroll 16
;                 for (int j = 0; j < 64; ++j) { const f32x4 w = w3s[j]; const f32x4 h0 = *(const f32x4*)(HID + (size_t)j * 4096 + 4 * tid), h1 = *(const f32x4*)(HID + (size_t)j * 4096 + 2048 + 4 * tid);
; #pragma unroll
;                     for (int e = 0; e < 4; ++e) { hacc[e] += h0[e] * w; hacc[4 + e] += h1[e] * w; } }
; #pragma unroll
;                 for (int e = 0; e < 8; ++e) { const int t = 4 * tid + (e & 3) + (e >> 2) * 2048; const float win = __expf(-((float)t * (1.f / 4095.f)) * dl);
;                     bufB[PADI(4 * tid) + (e & 3) + (e >> 2) * 2176] = (f32x2){win * hacc[e][0], win * hacc[e][2]};
;                     if (t >= 1) bufB[PADI(8192 - t)] = (f32x2){win * hacc[e][1], win * hacc[e][3]}; else bufB[PADI(4096)] = (f32x2){0.f, 0.f}; }
	v_pk_fma_f32 v[36:37], v[180:181], v[152:153], v[36:37] op_sel_hi:[1,0,1]
	v_pk_fma_f32 v[38:39], v[182:183], v[152:153], v[38:39] op_sel_hi:[1,0,1]
	v_pk_fma_f32 v[34:35], v[180:181], v[152:153], v[34:35] op_sel:[0,1,0]
	v_pk_fma_f32 v[32:33], v[182:183], v[152:153], v[32:33] op_sel:[0,1,0]
	v_pk_fma_f32 v[30:31], v[180:181], v[154:155], v[30:31] op_sel_hi:[1,0,1]
	v_pk_fma_f32 v[28:29], v[182:183], v[154:155], v[28:29] op_sel_hi:[1,0,1]
	v_pk_fma_f32 v[26:27], v[180:181], v[154:155], v[26:27] op_sel:[0,1,0]
	v_pk_fma_f32 v[24:25], v[182:183], v[154:155], v[24:25] op_sel:[0,1,0]
	v_pk_fma_f32 v[22:23], v[180:181], v[156:157], v[22:23] op_sel_hi:[1,0,1]
	v_pk_fma_f32 v[20:21], v[182:183], v[156:157], v[20:21] op_sel_hi:[1,0,1]
	v_pk_fma_f32 v[18:19], v[180:181], v[156:157], v[18:19] op_sel:[0,1,0]
	v_pk_fma_f32 v[16:17], v[182:183], v[156:157], v[16:17] op_sel:[0,1,0]
	v_pk_fma_f32 v[14:15], v[180:181], v[158:159], v[14:15] op_sel_hi:[1,0,1]
	v_pk_fma_f32 v[12:13], v[182:183], v[158:159], v[12:13] op_sel_hi:[1,0,1]
	v_pk_fma_f32 v[10:11], v[180:181], v[158:159], v[10:11] op_sel:[0,1,0]
	v_pk_fma_f32 v[8:9], v[182:183], v[158:159], v[8:9] op_sel:[0,1,0]
	s_waitcnt vmcnt(2)
	v_pk_fma_f32 v[36:37], v[184:185], v[160:161], v[36:37] op_sel_hi:[1,0,1]
	v_pk_fma_f32 v[38:39], v[186:187], v[160:161], v[38:39] op_sel_hi:[1,0,1]
	v_pk_fma_f32 v[34:35], v[184:185], v[160:161], v[34:35] op_sel:[0,1,0]
	v_pk_fma_f32 v[32:33], v[186:187], v[160:161], v[32:33] op_sel:[0,1,0]
	v_pk_fma_f32 v[30:31], v[184:185], v[162:163], v[30:31] op_sel_hi:[1,0,1]
	v_pk_fma_f32 v[28:29], v[186:187], v[162:163], v[28:29] op_sel_hi:[1,0,1]
	v_pk_fma_f32 v[26:27], v[184:185], v[162:163], v[26:27] op_sel:[0,1,0]
	v_pk_fma_f32 v[24:25], v[186:187], v[162:163], v[24:25] op_sel:[0,1,0]
	v_pk_fma_f32 v[22:23], v[184:185], v[164:165], v[22:23] op_sel_hi:[1,0,1]
	v_pk_fma_f32 v[20:21], v[186:187], v[164:165], v[20:21] op_sel_hi:[1,0,1]
	v_pk_fma_f32 v[18:19], v[184:185], v[164:165], v[18:19] op_sel:[0,1,0]
	v_pk_fma_f32 v[16:17], v[186:187], v[164:165], v[16:17] op_sel:[0,1,0]
	v_pk_fma_f32 v[14:15], v[184:185], v[166:167], v[14:15] op_sel_hi:[1,0,1]
	v_pk_fma_f32 v[12:13], v[186:187], v[166:167], v[12:13] op_sel_hi:[1,0,1]
	v_pk_fma_f32 v[10:11], v[184:185], v[166:167], v[10:11] op_sel:[0,1,0]
	v_pk_fma_f32 v[8:9], v[186:187], v[166:167], v[8:9] op_sel:[0,1,0]
	s_waitcnt vmcnt(0)
	v_pk_fma_f32 v[36:37], v[188:189], v[168:169], v[36:37] op_sel_hi:[1,0,1]
	v_pk_fma_f32 v[38:39], v[190:191], v[168:169], v[38:39] op_sel_hi:[1,0,1]
	v_pk_fma_f32 v[34:35], v[188:189], v[168:169], v[34:35] op_sel:[0,1,0]
	v_pk_fma_f32 v[32:33], v[190:191], v[168:169], v[32:33] op_sel:[0,1,0]
	v_pk_fma_f32 v[30:31], v[188:189], v[170:171], v[30:31] op_sel_hi:[1,0,1]
	v_pk_fma_f32 v[28:29], v[190:191], v[170:171], v[28:29] op_sel_hi:[1,0,1]
	v_pk_fma_f32 v[26:27], v[188:189], v[170:171], v[26:27] op_sel:[0,1,0]
	v_pk_fma_f32 v[24:25], v[190:191], v[170:171], v[24:25] op_sel:[0,1,0]
	v_pk_fma_f32 v[22:23], v[188:189], v[172:173], v[22:23] op_sel_hi:[1,0,1]
	v_pk_fma_f32 v[20:21], v[190:191], v[172:173], v[20:21] op_sel_hi:[1,0,1]
	v_pk_fma_f32 v[18:19], v[188:189], v[172:173], v[18:19] op_sel:[0,1,0]
	v_pk_fma_f32 v[16:17], v[190:191], v[172:173], v[16:17] op_sel:[0,1,0]
	v_pk_fma_f32 v[14:15], v[188:189], v[174:175], v[14:15] op_sel_hi:[1,0,1]
	v_pk_fma_f32 v[12:13], v[190:191], v[174:175], v[12:13] op_sel_hi:[1,0,1]
	v_pk_fma_f32 v[10:11], v[188:189], v[174:175], v[10:11] op_sel:[0,1,0]
	v_pk_fma_f32 v[8:9], v[190:191], v[174:175], v[8:9] op_sel:[0,1,0]
	v_cvt_f32_i32_e32 v1, s18
	v_cvt_f32_i32_e32 v6, v4
	v_lshlrev_b32_e32 v40, 1, v0
	v_lshlrev_b32_e32 v5, 3, v4
	v_fmamk_f32 v2, v1, 0xbc44ade8, v222
	v_mul_f32_e32 v6, 0xb9800801, v6
	v_mul_f32_e64 v6, |v2|, v6
	v_mul_f32_e32 v6, 0x3fb8aa3b, v6
	v_exp_f32_e32 v6, v6
	v_and_b32_e32 v1, -16, v40
	v_mov_b32_e32 v42, v36
	v_mov_b32_e32 v43, v38
	v_add3_u32 v1, s67, v5, v1
	v_pk_mul_f32 v[42:43], v[6:7], v[42:43] op_sel_hi:[0,1]
	v_cmp_gt_i32_e32 vcc, 1, v0
	ds_write_b64 v1, v[42:43]
	s_and_saveexec_b64 s[4:5], vcc
	s_xor_b64 s[4:5], exec, s[4:5]
	s_cbranch_execz .LBB0_403
	v_readlane_b32 s3, v250, 13
	s_nop 1
	v_mov_b32_e32 v5, s3
	ds_write_b64 v5, v[242:243]

; #define LAS __attribute__((address_space(3)))
; __device__ __forceinline__ f32x2 cmul(f32x2 a, f32x2 b) { return (f32x2){a.x * b.x - a.y * b.y, a.x * b.y + a.y * b.x}; }
; template <bool INV, int ST> __device__ __forceinline__ void fft_pass16(LAS f32x2* buf, int base, int bl) {
;     constexpr float C16[8] = {1.f, 0.92387953251f, 0.70710678119f, 0.38268343237f, 0.f, -0.38268343237f, -0.70710678119f, -0.92387953251f};
;     constexpr float S16[8] = {0.f, 0.38268343237f, 0.70710678119f, 0.92387953251f, 1.f, 0.92387953251f, 0.70710678119f, 0.38268343237f};
;     f32x2 x[16];
;     constexpr int STEP = (1 << ST) + ((1 << ST) >> 4);
;     LAS f32x2* pb = buf + PADI(base);
; #pragma unroll
;     for (int d = 0; d < 16; ++d) x[d] = pb[d * STEP];
;     const float th = (float)bl * (1.f / (float)(16 << ST));
;     const f32x2 W1 = {__builtin_amdgcn_cosf(th), -__builtin_amdgcn_sinf(th)};
;     const f32x2 W2 = cmul(W1, W1), W4 = cmul(W2, W2), W8 = cmul(W4, W4);
;     if (!INV) {
; #pragma unroll
;         for (int d = 0; d < 8; ++d) { const f32x2 w = cmul(W1, (f32x2){C16[d], -S16[d]}); const f32x2 a = x[d], b = x[d + 8]; x[d] = a + b; x[d + 8] = cmul(a - b, w); }
.LBB0_433:
	s_or_b64 exec, exec, s[4:5]
	v_mov_b32_e32 v1, v0
	s_waitcnt lgkmcnt(0)
	s_barrier
	s_mov_b32 s8, 0x3f3504f3
	v_ashrrev_i32_e32 v2, 4, v1
	v_lshlrev_b32_e32 v2, 3, v2
	v_lshlrev_b32_e32 v4, 3, v1
	v_and_b32_e32 v2, -16, v2
	v_add3_u32 v41, s67, v4, v2
	v_cvt_f32_i32_e32 v2, v1
	ds_read_b64 v[4:5], v41
	ds_read_b64 v[6:7], v41 offset:4352
	ds_read_b64 v[8:9], v41 offset:8704
	ds_read_b64 v[10:11], v41 offset:13056
	ds_read_b64 v[12:13], v41 offset:17408
	ds_read_b64 v[14:15], v41 offset:21760
	ds_read_b64 v[16:17], v41 offset:26112
	ds_read_b64 v[18:19], v41 offset:30464
	ds_read_b64 v[20:21], v41 offset:34816
	ds_read_b64 v[22:23], v41 offset:39168
	ds_read_b64 v[24:25], v41 offset:43520
	ds_read_b64 v[26:27], v41 offset:47872
	s_mov_b32 s9, 0xbf3504f3
	v_mul_f32_e32 v2, 0x39000000, v2
	v_sin_f32_e32 v30, v2
	v_cos_f32_e32 v28, v2
	s_waitcnt lgkmcnt(3)
	v_pk_add_f32 v[50:51], v[4:5], v[20:21]
	v_pk_add_f32 v[4:5], v[4:5], v[20:21] neg_lo:[0,1] neg_hi:[0,1]
	v_xor_b32_e32 v29, 0x80000000, v30
	v_mov_b32_e32 v31, v28
	v_mov_b32_e32 v42, v30
	v_mov_b32_e32 v43, v29
	v_pk_mul_f32 v[42:43], v[30:31], v[42:43]
	v_fmamk_f32 v2, v30, 0x80000000, v28
	v_pk_fma_f32 v[44:45], v[28:29], v[28:29], v[42:43] op_sel_hi:[0,1,1] neg_lo:[0,0,1] neg_hi:[0,0,1]
	v_pk_fma_f32 v[42:43], v[28:29], v[28:29], v[42:43] op_sel_hi:[0,1,1]
	v_mov_b32_e32 v45, v43
	v_pk_mul_f32 v[48:49], v[44:45], v[42:43] op_sel:[0,1] op_sel_hi:[1,0]
	v_fma_f32 v42, v28, s22, -v30
	v_pk_mul_f32 v[20:21], v[42:43], v[4:5] op_sel:[0,1] op_sel_hi:[0,0]
	v_pk_fma_f32 v[52:53], v[2:3], v[4:5], v[20:21] neg_lo:[0,0,1] neg_hi:[0,0,1]
	v_pk_fma_f32 v[4:5], v[2:3], v[4:5], v[20:21] op_sel_hi:[0,1,1]
	v_pk_mul_f32 v[20:21], v[30:31], s[8:9] op_sel_hi:[1,0]
	v_mov_b32_e32 v53, v5
	s_waitcnt lgkmcnt(2)
	v_pk_add_f32 v[4:5], v[6:7], v[22:23]
	v_pk_add_f32 v[6:7], v[6:7], v[22:23] neg_lo:[0,1] neg_hi:[0,1]
	v_fma_f32 v2, v30, s9, -v21
	s_waitcnt lgkmcnt(1)
	v_pk_add_f32 v[22:23], v[8:9], v[24:25]
	v_pk_add_f32 v[8:9], v[8:9], v[24:25] neg_lo:[0,1] neg_hi:[0,1]
	s_mov_b32 s10, 0x3f6c835e
	v_pk_mul_f32 v[24:25], v[2:3], v[8:9] op_sel:[0,1] op_sel_hi:[0,0]
	v_pk_add_f32 v[54:55], v[20:21], v[20:21] op_sel:[1,0] op_sel_hi:[1,0] neg_lo:[0,1] neg_hi:[0,1]
	s_mov_b32 s11, 0x3ec3ef15
	s_mov_b32 s97, s10
	v_pk_fma_f32 v[56:57], v[54:55], v[8:9], v[24:25] neg_lo:[0,0,1] neg_hi:[0,0,1]
	v_pk_fma_f32 v[8:9], v[54:55], v[8:9], v[24:25]
	v_pk_mul_f32 v[54:55], v[30:31], s[96:97]
	v_mov_b32_e32 v57, v9
	v_pk_mul_f32 v[8:9], v[30:31], s[10:11]
	s_waitcnt lgkmcnt(0)
	v_pk_add_f32 v[58:59], v[10:11], v[26:27]
	v_pk_add_f32 v[10:11], v[10:11], v[26:27] neg_lo:[0,1] neg_hi:[0,1]
	v_pk_add_f32 v[26:27], v[54:55], v[54:55] op_sel:[0,1] op_sel_hi:[0,1] neg_lo:[0,1] neg_hi:[0,1]
	ds_read_b64 v[32:33], v41 offset:52224
	ds_read_b64 v[34:35], v41 offset:56576
	ds_read_b64 v[36:37], v41 offset:60928
	ds_read_b64 v[38:39], v41 offset:65280
	v_pk_mul_f32 v[26:27], v[26:27], v[10:11] op_sel:[0,1] op_sel_hi:[1,0]
	v_pk_add_f32 v[60:61], v[8:9], v[8:9] op_sel:[1,0] op_sel_hi:[1,0] neg_lo:[0,1] neg_hi:[0,1]
	v_fma_f32 v2, v30, s2, -v9
	v_pk_fma_f32 v[62:63], v[60:61], v[10:11], v[26:27] neg_lo:[0,0,1] neg_hi:[0,0,1]
	v_pk_fma_f32 v[10:11], v[60:61], v[10:11], v[26:27]
	s_waitcnt lgkmcnt(3)
	v_pk_add_f32 v[26:27], v[12:13], v[32:33]
	v_fma_f32 v10, v30, s22, -v28
	v_pk_add_f32 v[12:13], v[12:13], v[32:33] neg_lo:[0,1] neg_hi:[0,1]
	v_pk_mul_f32 v[24:25], v[2:3], v[6:7] op_sel:[0,1] op_sel_hi:[0,0]
	v_mov_b32_e32 v63, v11
	v_fma_f32 v2, v28, 0, -v30
	v_pk_mul_f32 v[10:11], v[10:11], v[12:13] op_sel:[0,1] op_sel_hi:[0,0]
	v_pk_fma_f32 v[32:33], v[2:3], v[12:13], v[10:11] neg_lo:[0,0,1] neg_hi:[0,0,1]
	v_pk_fma_f32 v[10:11], v[2:3], v[12:13], v[10:11] op_sel_hi:[0,1,1]
	v_mov_b32_e32 v33, v11
	s_waitcnt lgkmcnt(2)
	v_pk_add_f32 v[10:11], v[14:15], v[34:35]
	v_pk_add_f32 v[12:13], v[14:15], v[34:35] neg_lo:[0,1] neg_hi:[0,1]
	v_fma_f32 v14, v28, s9, -v20
	s_waitcnt lgkmcnt(1)
	v_pk_add_f32 v[34:35], v[16:17], v[36:37]
	v_pk_add_f32 v[16:17], v[16:17], v[36:37] neg_lo:[0,1] neg_hi:[0,1]
	v_pk_add_f32 v[20:21], v[20:21], v[20:21] op_sel:[0,1] op_sel_hi:[0,1] neg_lo:[0,1] neg_hi:[0,1]
	v_pk_mul_f32 v[20:21], v[20:21], v[16:17] op_sel:[0,1] op_sel_hi:[1,0]
	v_mov_b32_e32 v29, v30
	v_pk_fma_f32 v[36:37], v[14:15], v[16:17], v[20:21] neg_lo:[0,0,1] neg_hi:[0,0,1]
	v_pk_fma_f32 v[14:15], v[14:15], v[16:17], v[20:21] op_sel_hi:[0,1,1]
	s_mov_b32 s3, s11
	v_mov_b32_e32 v37, v15
	v_pk_mul_f32 v[14:15], v[28:29], s[2:3]
	v_fma_f32 v2, v28, s96, -v8
	v_sub_f32_e32 v16, v55, v15
	v_pk_fma_f32 v[20:21], v[16:17], v[6:7], v[24:25] op_sel_hi:[0,1,1] neg_lo:[0,0,1] neg_hi:[0,0,1]
	v_pk_fma_f32 v[6:7], v[16:17], v[6:7], v[24:25] op_sel_hi:[0,1,1]
	v_sub_f32_e32 v6, v15, v55
	v_mov_b32_e32 v21, v7
	v_pk_mul_f32 v[6:7], v[6:7], v[12:13] op_sel:[0,1] op_sel_hi:[0,0]
	v_pk_fma_f32 v[16:17], v[2:3], v[12:13], v[6:7] neg_lo:[0,0,1] neg_hi:[0,0,1]
	v_pk_fma_f32 v[6:7], v[2:3], v[12:13], v[6:7] op_sel_hi:[0,1,1]
	s_waitcnt lgkmcnt(0)
; __device__ __forceinline__ f32x2 cmul(f32x2 a, f32x2 b) { return (f32x2){a.x * b.x - a.y * b.y, a.x * b.y + a.y * b.x}; }
; template <bool INV, int ST> __device__ __forceinline__ void fft_pass16(LAS f32x2* buf, int base, int bl) {
;     ...
;         for (int d = 0; d < 8; ++d) { const f32x2 w = cmul(W1, (f32x2){C16[d], -S16[d]}); const f32x2 a = x[d], b = x[d + 8]; x[d] = a + b; x[d + 8] = cmul(a - b, w); }
; #pragma unroll
;         for (int g = 0; g < 16; g += 8)
; #pragma unroll
;             for (int dd = 0; dd < 4; ++dd) { const int d = g + dd; const f32x2 w = cmul(W2, (f32x2){C16[2 * dd], -S16[2 * dd]}); const f32x2 a = x[d], b = x[d + 4]; x[d] = a + b; x[d + 4] = cmul(a - b, w); }
; #pragma unroll
;         for (int g = 0; g < 16; g += 4)
; #pragma unroll
;             for (int dd = 0; dd < 2; ++dd) { const int d = g + dd; const f32x2 w = dd ? (f32x2){W4.y, -W4.x} : W4; const f32x2 a = x[d], b = x[d + 2]; x[d] = a + b; x[d + 2] = cmul(a - b, w); }
; #pragma unroll
;         for (int g = 0; g < 16; g += 2) { const f32x2 a = x[g], b = x[g + 1]; x[g] = a + b; x[g + 1] = cmul(a - b, W8); }
	v_pk_add_f32 v[12:13], v[18:19], v[38:39] neg_lo:[0,1] neg_hi:[0,1]
	v_pk_add_f32 v[8:9], v[8:9], v[8:9] op_sel:[0,1] op_sel_hi:[0,1] neg_lo:[0,1] neg_hi:[0,1]
	v_pk_mul_f32 v[8:9], v[8:9], v[12:13] op_sel:[0,1] op_sel_hi:[1,0]
	v_pk_add_f32 v[14:15], v[14:15], v[14:15] op_sel:[0,1] op_sel_hi:[0,1] neg_lo:[0,1] neg_hi:[0,1]
	v_fmamk_f32 v24, v44, 0x80000000, v43
	v_pk_add_f32 v[28:29], v[50:51], v[26:27]
	v_pk_add_f32 v[26:27], v[50:51], v[26:27] neg_lo:[0,1] neg_hi:[0,1]
	v_pk_mul_f32 v[46:47], v[44:45], v[44:45]
	v_mov_b32_e32 v17, v7
	v_pk_add_f32 v[6:7], v[18:19], v[38:39]
	v_pk_fma_f32 v[18:19], v[14:15], v[12:13], v[8:9] neg_lo:[0,0,1] neg_hi:[0,0,1]
	v_pk_fma_f32 v[8:9], v[14:15], v[12:13], v[8:9]
	v_fma_f32 v2, 0, v43, v44
	v_pk_mul_f32 v[30:31], v[24:25], v[26:27] op_sel_hi:[0,1]
	v_mov_b32_e32 v8, v46
	v_pk_mov_b32 v[12:13], v[46:47], v[48:49] op_sel:[1,0]
	v_pk_fma_f32 v[38:39], v[2:3], v[26:27], v[30:31] op_sel:[0,0,1] op_sel_hi:[1,1,0] neg_lo:[0,0,1] neg_hi:[0,0,1]
	v_pk_fma_f32 v[26:27], v[2:3], v[26:27], v[30:31] op_sel:[0,0,1] op_sel_hi:[0,1,0]
	v_fma_f32 v30, v43, 0, -v44
	v_pk_add_f32 v[46:47], v[22:23], v[34:35]
	v_pk_add_f32 v[22:23], v[22:23], v[34:35] neg_lo:[0,1] neg_hi:[0,1]
	v_mov_b32_e32 v39, v27
	v_pk_add_f32 v[26:27], v[4:5], v[10:11]
	v_pk_add_f32 v[4:5], v[4:5], v[10:11] neg_lo:[0,1] neg_hi:[0,1]
	v_fma_f32 v10, 0, v44, v43
	v_pk_mul_f32 v[34:35], v[30:31], v[22:23] op_sel_hi:[0,1]
	v_mov_b32_e32 v19, v9
	v_mov_b32_e32 v9, v48
	v_pk_fma_f32 v[48:49], v[10:11], v[22:23], v[34:35] op_sel:[0,0,1] op_sel_hi:[1,1,0] neg_lo:[0,0,1] neg_hi:[0,0,1]
	v_pk_fma_f32 v[22:23], v[10:11], v[22:23], v[34:35] op_sel:[0,0,1] op_sel_hi:[0,1,0]
	v_mov_b32_e32 v49, v23
	v_pk_mul_f32 v[22:23], v[44:45], s[8:9]
	v_pk_add_f32 v[14:15], v[8:9], v[12:13] neg_lo:[0,1] neg_hi:[0,1]
	v_fma_f32 v42, v43, s8, -v22
	v_fmamk_f32 v34, v43, 0x3f3504f3, v22
	v_pk_mul_f32 v[44:45], v[42:43], v[4:5] op_sel_hi:[0,1]
	v_pk_fma_f32 v[50:51], v[34:35], v[4:5], v[44:45] op_sel:[0,0,1] op_sel_hi:[1,1,0] neg_lo:[0,0,1] neg_hi:[0,0,1]
	v_pk_fma_f32 v[4:5], v[34:35], v[4:5], v[44:45] op_sel:[0,0,1] op_sel_hi:[0,1,0]
	v_mov_b32_e32 v51, v5
	v_pk_add_f32 v[4:5], v[58:59], v[6:7]
	v_pk_add_f32 v[6:7], v[58:59], v[6:7] neg_lo:[0,1] neg_hi:[0,1]
	v_pk_add_f32 v[22:23], v[22:23], v[22:23] op_sel:[1,0] op_sel_hi:[1,0] neg_lo:[0,1] neg_hi:[0,1]
	v_pk_add_f32 v[8:9], v[8:9], v[12:13]
	v_pk_mul_f32 v[44:45], v[22:23], v[6:7]
	v_mov_b32_e32 v12, v14
	v_pk_fma_f32 v[54:55], v[42:43], v[6:7], v[44:45] op_sel:[0,0,1] op_sel_hi:[1,1,0] neg_lo:[0,0,1] neg_hi:[0,0,1]
	v_pk_fma_f32 v[6:7], v[42:43], v[6:7], v[44:45] op_sel:[0,0,1] op_sel_hi:[0,1,0]
	v_mov_b32_e32 v55, v7
	v_pk_add_f32 v[6:7], v[52:53], v[32:33]
	v_pk_add_f32 v[32:33], v[52:53], v[32:33] neg_lo:[0,1] neg_hi:[0,1]
	v_mov_b32_e32 v13, v9
	v_pk_mul_f32 v[24:25], v[24:25], v[32:33] op_sel_hi:[0,1]
	v_pk_fma_f32 v[44:45], v[2:3], v[32:33], v[24:25] op_sel:[0,0,1] op_sel_hi:[1,1,0] neg_lo:[0,0,1] neg_hi:[0,0,1]
	v_pk_fma_f32 v[24:25], v[2:3], v[32:33], v[24:25] op_sel:[0,0,1] op_sel_hi:[0,1,0]
	v_mov_b32_e32 v45, v25
	v_pk_add_f32 v[24:25], v[20:21], v[16:17]
	v_pk_add_f32 v[16:17], v[20:21], v[16:17] neg_lo:[0,1] neg_hi:[0,1]
	v_mul_f32_e32 v2, v14, v9
	v_pk_mul_f32 v[20:21], v[42:43], v[16:17] op_sel_hi:[0,1]
	v_pk_fma_f32 v[32:33], v[34:35], v[16:17], v[20:21] op_sel:[0,0,1] op_sel_hi:[1,1,0] neg_lo:[0,0,1] neg_hi:[0,0,1]
	v_pk_fma_f32 v[16:17], v[34:35], v[16:17], v[20:21] op_sel:[0,0,1] op_sel_hi:[0,1,0]
	v_pk_add_f32 v[20:21], v[56:57], v[36:37] neg_lo:[0,1] neg_hi:[0,1]
	v_mov_b32_e32 v33, v17
	v_pk_mul_f32 v[30:31], v[30:31], v[20:21] op_sel_hi:[0,1]
	v_pk_fma_f32 v[34:35], v[10:11], v[20:21], v[30:31] op_sel:[0,0,1] op_sel_hi:[1,1,0] neg_lo:[0,0,1] neg_hi:[0,0,1]
	v_pk_fma_f32 v[10:11], v[10:11], v[20:21], v[30:31] op_sel:[0,0,1] op_sel_hi:[0,1,0]
	v_mov_b32_e32 v35, v11
	v_pk_add_f32 v[10:11], v[62:63], v[18:19]
	v_pk_add_f32 v[18:19], v[62:63], v[18:19] neg_lo:[0,1] neg_hi:[0,1]
	v_pk_add_f32 v[16:17], v[56:57], v[36:37]
	v_pk_mul_f32 v[20:21], v[22:23], v[18:19]
	v_pk_mul_f32 v[12:13], v[12:13], v[12:13]
	v_pk_fma_f32 v[22:23], v[42:43], v[18:19], v[20:21] op_sel:[0,0,1] op_sel_hi:[1,1,0] neg_lo:[0,0,1] neg_hi:[0,0,1]
	v_pk_fma_f32 v[18:19], v[42:43], v[18:19], v[20:21] op_sel:[0,0,1] op_sel_hi:[0,1,0]
	v_pk_add_f32 v[20:21], v[28:29], v[46:47] neg_lo:[0,1] neg_hi:[0,1]
	v_mov_b32_e32 v23, v19
	v_pk_add_f32 v[18:19], v[28:29], v[46:47]
	v_pk_mul_f32 v[28:29], v[8:9], v[20:21] op_sel:[1,0]
	v_add_f32_e32 v2, v2, v2
	v_pk_fma_f32 v[30:31], v[14:15], v[20:21], v[28:29] op_sel:[0,0,1] op_sel_hi:[1,1,0] neg_lo:[0,0,1] neg_hi:[0,0,1]
	v_pk_fma_f32 v[20:21], v[14:15], v[20:21], v[28:29] op_sel:[0,0,1] op_sel_hi:[0,1,0]
	v_mov_b32_e32 v31, v21
	v_pk_add_f32 v[20:21], v[26:27], v[4:5]
	v_pk_add_f32 v[4:5], v[26:27], v[4:5] neg_lo:[0,1] neg_hi:[0,1]
	v_pk_add_f32 v[12:13], v[12:13], v[12:13] op_sel:[0,1] op_sel_hi:[0,1] neg_lo:[0,1] neg_hi:[0,1]
	v_pk_mul_f32 v[26:27], v[14:15], v[4:5] op_sel_hi:[0,1]
	v_pk_fma_f32 v[28:29], v[8:9], v[4:5], v[26:27] op_sel:[1,0,1] op_sel_hi:[1,1,0]
	v_pk_fma_f32 v[4:5], v[8:9], v[4:5], v[26:27] op_sel:[1,0,1] op_sel_hi:[1,1,0] neg_lo:[0,0,1] neg_hi:[0,0,1]
	v_pk_add_f32 v[26:27], v[38:39], v[48:49] neg_lo:[0,1] neg_hi:[0,1]
	v_mov_b32_e32 v29, v5
	v_pk_mul_f32 v[36:37], v[8:9], v[26:27] op_sel:[1,0]
	v_pk_add_f32 v[4:5], v[38:39], v[48:49]
	v_pk_fma_f32 v[38:39], v[14:15], v[26:27], v[36:37] op_sel:[0,0,1] op_sel_hi:[1,1,0] neg_lo:[0,0,1] neg_hi:[0,0,1]
	v_pk_fma_f32 v[26:27], v[14:15], v[26:27], v[36:37] op_sel:[0,0,1] op_sel_hi:[0,1,0]
	v_pk_add_f32 v[36:37], v[50:51], v[54:55] neg_lo:[0,1] neg_hi:[0,1]
; #define LAS __attribute__((address_space(3)))
; template <bool INV, int ST> __device__ __forceinline__ void fft_pass16(LAS f32x2* buf, int base, int bl) {
;     ...
;         for (int d = 0; d < 8; ++d) { const f32x2 w = cmul(W1, (f32x2){C16[d], -S16[d]}); const f32x2 a = x[d], b = x[d + 8]; x[d] = a + b; x[d + 8] = cmul(a - b, w); }
; #pragma unroll
;         for (int g = 0; g < 16; g += 8)
; #pragma unroll
;             for (int dd = 0; dd < 4; ++dd) { const int d = g + dd; const f32x2 w = cmul(W2, (f32x2){C16[2 * dd], -S16[2 * dd]}); const f32x2 a = x[d], b = x[d + 4]; x[d] = a + b; x[d + 4] = cmul(a - b, w); }
; #pragma unroll
;         for (int g = 0; g < 16; g += 4)
; #pragma unroll
;             for (int dd = 0; dd < 2; ++dd) { const int d = g + dd; const f32x2 w = dd ? (f32x2){W4.y, -W4.x} : W4; const f32x2 a = x[d], b = x[d + 2]; x[d] = a + b; x[d + 2] = cmul(a - b, w); }
; #pragma unroll
;         for (int g = 0; g < 16; g += 2) { const f32x2 a = x[g], b = x[g + 1]; x[g] = a + b; x[g + 1] = cmul(a - b, W8); }
;     } else {
; #pragma unroll
;         for (int g = 0; g < 16; g += 2) { const f32x2 a = x[g], b = cmulc(x[g + 1], W8); x[g] = a + b; x[g + 1] = a - b; }
; #pragma unroll
;         for (int g = 0; g < 16; g += 4)
; #pragma unroll
;             for (int dd = 0; dd < 2; ++dd) { const int d = g + dd; const f32x2 w = dd ? (f32x2){W4.y, -W4.x} : W4; const f32x2 a = x[d], b = cmulc(x[d + 2], w); x[d] = a + b; x[d + 2] = a - b; }
; #pragma unroll
;         for (int g = 0; g < 16; g += 8)
; #pragma unroll
;             for (int dd = 0; dd < 4; ++dd) { const int d = g + dd; const f32x2 w = cmul(W2, (f32x2){C16[2 * dd], -S16[2 * dd]}); const f32x2 a = x[d], b = cmulc(x[d + 4], w); x[d] = a + b; x[d + 4] = a - b; }
; #pragma unroll
;         for (int d = 0; d < 8; ++d) { const f32x2 w = cmul(W1, (f32x2){C16[d], -S16[d]}); const f32x2 a = x[d], b = cmulc(x[d + 8], w); x[d] = a + b; x[d + 8] = a - b; }
;     }
; #pragma unroll
;     for (int d = 0; d < 16; ++d) pb[d * STEP] = x[d];
; }
; __device__ __forceinline__ void fft_fwd_abc(LAS f32x2* buf, int tid) {
;     asm volatile("" : "+v"(tid));
;     fft_pass16<false, 9>(buf, tid, tid); __syncthreads();
;     fft_pass16<false, 5>(buf, ((tid >> 5) << 9) + (tid & 31), tid & 31); __syncthreads();
	v_mov_b32_e32 v39, v27
	v_pk_mul_f32 v[42:43], v[14:15], v[36:37] op_sel_hi:[0,1]
	v_pk_fma_f32 v[46:47], v[8:9], v[36:37], v[42:43] op_sel:[1,0,1] op_sel_hi:[1,1,0]
	v_pk_fma_f32 v[36:37], v[8:9], v[36:37], v[42:43] op_sel:[1,0,1] op_sel_hi:[1,1,0] neg_lo:[0,0,1] neg_hi:[0,0,1]
	v_pk_add_f32 v[26:27], v[50:51], v[54:55]
	v_mov_b32_e32 v47, v37
	v_pk_add_f32 v[36:37], v[6:7], v[16:17]
	v_pk_add_f32 v[6:7], v[6:7], v[16:17] neg_lo:[0,1] neg_hi:[0,1]
	s_ashr_i32 s19, s18, 31
	v_pk_mul_f32 v[16:17], v[8:9], v[6:7] op_sel:[1,0]
	s_lshl_b64 s[4:5], s[18:19], 14
	v_pk_fma_f32 v[42:43], v[14:15], v[6:7], v[16:17] op_sel:[0,0,1] op_sel_hi:[1,1,0] neg_lo:[0,0,1] neg_hi:[0,0,1]
	v_pk_fma_f32 v[6:7], v[14:15], v[6:7], v[16:17] op_sel:[0,0,1] op_sel_hi:[0,1,0]
	v_mov_b32_e32 v43, v7
	v_pk_add_f32 v[6:7], v[24:25], v[10:11]
	v_pk_add_f32 v[10:11], v[24:25], v[10:11] neg_lo:[0,1] neg_hi:[0,1]
	s_add_u32 s6, s28, s4
	v_pk_mul_f32 v[16:17], v[14:15], v[10:11] op_sel_hi:[0,1]
	v_pk_fma_f32 v[24:25], v[8:9], v[10:11], v[16:17] op_sel:[1,0,1] op_sel_hi:[1,1,0]
	v_pk_fma_f32 v[10:11], v[8:9], v[10:11], v[16:17] op_sel:[1,0,1] op_sel_hi:[1,1,0] neg_lo:[0,0,1] neg_hi:[0,0,1]
	v_pk_add_f32 v[16:17], v[44:45], v[34:35] neg_lo:[0,1] neg_hi:[0,1]
	v_mov_b32_e32 v25, v11
	v_pk_add_f32 v[10:11], v[44:45], v[34:35]
	v_pk_mul_f32 v[34:35], v[8:9], v[16:17] op_sel:[1,0]
	s_addc_u32 s7, s29, s5
	v_pk_fma_f32 v[44:45], v[14:15], v[16:17], v[34:35] op_sel:[0,0,1] op_sel_hi:[1,1,0] neg_lo:[0,0,1] neg_hi:[0,0,1]
	v_pk_fma_f32 v[16:17], v[14:15], v[16:17], v[34:35] op_sel:[0,0,1] op_sel_hi:[0,1,0]
	v_mov_b32_e32 v45, v17
	v_pk_add_f32 v[16:17], v[32:33], v[22:23]
	v_pk_add_f32 v[22:23], v[32:33], v[22:23] neg_lo:[0,1] neg_hi:[0,1]
	s_nop 0
	v_pk_mul_f32 v[32:33], v[14:15], v[22:23] op_sel_hi:[0,1]
	v_pk_fma_f32 v[34:35], v[8:9], v[22:23], v[32:33] op_sel:[1,0,1] op_sel_hi:[1,1,0]
	v_pk_fma_f32 v[22:23], v[8:9], v[22:23], v[32:33] op_sel:[1,0,1] op_sel_hi:[1,1,0] neg_lo:[0,0,1] neg_hi:[0,0,1]
	s_nop 0
	v_mov_b32_e32 v35, v23
	v_pk_add_f32 v[22:23], v[18:19], v[20:21]
	v_pk_add_f32 v[18:19], v[18:19], v[20:21] neg_lo:[0,1] neg_hi:[0,1]
	s_nop 0
	v_pk_mul_f32 v[8:9], v[2:3], v[18:19] op_sel_hi:[0,1]
	v_pk_fma_f32 v[14:15], v[12:13], v[18:19], v[8:9] op_sel:[0,0,1] op_sel_hi:[1,1,0] neg_lo:[0,0,1] neg_hi:[0,0,1]
	v_pk_fma_f32 v[8:9], v[12:13], v[18:19], v[8:9] op_sel:[0,0,1] op_sel_hi:[1,1,0]
	v_pk_add_f32 v[18:19], v[30:31], v[28:29] neg_lo:[0,1] neg_hi:[0,1]
	v_mov_b32_e32 v15, v9
	v_pk_mul_f32 v[20:21], v[2:3], v[18:19] op_sel_hi:[0,1]
	v_pk_add_f32 v[8:9], v[30:31], v[28:29]
	v_pk_fma_f32 v[28:29], v[12:13], v[18:19], v[20:21] op_sel:[0,0,1] op_sel_hi:[1,1,0] neg_lo:[0,0,1] neg_hi:[0,0,1]
	v_pk_fma_f32 v[18:19], v[12:13], v[18:19], v[20:21] op_sel:[0,0,1] op_sel_hi:[1,1,0]
	s_nop 0
	v_mov_b32_e32 v29, v19
	v_pk_add_f32 v[18:19], v[4:5], v[26:27]
	v_pk_add_f32 v[4:5], v[4:5], v[26:27] neg_lo:[0,1] neg_hi:[0,1]
	s_nop 0
	v_pk_mul_f32 v[20:21], v[2:3], v[4:5] op_sel_hi:[0,1]
	v_pk_fma_f32 v[26:27], v[12:13], v[4:5], v[20:21] op_sel:[0,0,1] op_sel_hi:[1,1,0] neg_lo:[0,0,1] neg_hi:[0,0,1]
	v_pk_fma_f32 v[4:5], v[12:13], v[4:5], v[20:21] op_sel:[0,0,1] op_sel_hi:[1,1,0]
	v_pk_add_f32 v[20:21], v[38:39], v[46:47] neg_lo:[0,1] neg_hi:[0,1]
	v_mov_b32_e32 v27, v5
	v_pk_mul_f32 v[30:31], v[2:3], v[20:21] op_sel_hi:[0,1]
	v_pk_fma_f32 v[32:33], v[12:13], v[20:21], v[30:31] op_sel:[0,0,1] op_sel_hi:[1,1,0] neg_lo:[0,0,1] neg_hi:[0,0,1]
	v_pk_fma_f32 v[20:21], v[12:13], v[20:21], v[30:31] op_sel:[0,0,1] op_sel_hi:[1,1,0]
	v_pk_add_f32 v[4:5], v[38:39], v[46:47]
	v_mov_b32_e32 v33, v21
	v_pk_add_f32 v[20:21], v[36:37], v[6:7]
	v_pk_add_f32 v[6:7], v[36:37], v[6:7] neg_lo:[0,1] neg_hi:[0,1]
	s_nop 0
	v_pk_mul_f32 v[30:31], v[2:3], v[6:7] op_sel_hi:[0,1]
	v_pk_fma_f32 v[36:37], v[12:13], v[6:7], v[30:31] op_sel:[0,0,1] op_sel_hi:[1,1,0] neg_lo:[0,0,1] neg_hi:[0,0,1]
	v_pk_fma_f32 v[6:7], v[12:13], v[6:7], v[30:31] op_sel:[0,0,1] op_sel_hi:[1,1,0]
	s_nop 0
	v_mov_b32_e32 v37, v7
	v_pk_add_f32 v[6:7], v[42:43], v[24:25]
	v_pk_add_f32 v[24:25], v[42:43], v[24:25] neg_lo:[0,1] neg_hi:[0,1]
	s_nop 0
	v_pk_mul_f32 v[30:31], v[2:3], v[24:25] op_sel_hi:[0,1]
	v_pk_fma_f32 v[38:39], v[12:13], v[24:25], v[30:31] op_sel:[0,0,1] op_sel_hi:[1,1,0] neg_lo:[0,0,1] neg_hi:[0,0,1]
	v_pk_fma_f32 v[24:25], v[12:13], v[24:25], v[30:31] op_sel:[0,0,1] op_sel_hi:[1,1,0]
	s_nop 0
	v_mov_b32_e32 v39, v25
	v_pk_add_f32 v[24:25], v[10:11], v[16:17]
	v_pk_add_f32 v[10:11], v[10:11], v[16:17] neg_lo:[0,1] neg_hi:[0,1]
	s_nop 0
	v_pk_mul_f32 v[16:17], v[2:3], v[10:11] op_sel_hi:[0,1]
	v_pk_fma_f32 v[30:31], v[12:13], v[10:11], v[16:17] op_sel:[0,0,1] op_sel_hi:[1,1,0] neg_lo:[0,0,1] neg_hi:[0,0,1]
	v_pk_fma_f32 v[10:11], v[12:13], v[10:11], v[16:17] op_sel:[0,0,1] op_sel_hi:[1,1,0]
	v_pk_add_f32 v[16:17], v[44:45], v[34:35] neg_lo:[0,1] neg_hi:[0,1]
	v_mov_b32_e32 v31, v11
	v_pk_add_f32 v[10:11], v[44:45], v[34:35]
	v_pk_mul_f32 v[34:35], v[2:3], v[16:17] op_sel_hi:[0,1]
	v_pk_fma_f32 v[42:43], v[12:13], v[16:17], v[34:35] op_sel:[0,0,1] op_sel_hi:[1,1,0] neg_lo:[0,0,1] neg_hi:[0,0,1]
	v_pk_fma_f32 v[12:13], v[12:13], v[16:17], v[34:35] op_sel:[0,0,1] op_sel_hi:[1,1,0]
	v_lshlrev_b32_e32 v2, 4, v1
	v_mov_b32_e32 v43, v13
	ds_write_b64 v41, v[22:23]
	ds_write_b64 v41, v[14:15] offset:4352
	ds_write_b64 v41, v[8:9] offset:8704
	ds_write_b64 v41, v[28:29] offset:13056
	ds_write_b64 v41, v[18:19] offset:17408
	ds_write_b64 v41, v[26:27] offset:21760
	ds_write_b64 v41, v[4:5] offset:26112
	ds_write_b64 v41, v[32:33] offset:30464
	ds_write_b64 v41, v[20:21] offset:34816
	ds_write_b64 v41, v[36:37] offset:39168
	ds_write_b64 v41, v[6:7] offset:43520
	ds_write_b64 v41, v[38:39] offset:47872
	ds_write_b64 v41, v[24:25] offset:52224
	ds_write_b64 v41, v[30:31] offset:56576
	ds_write_b64 v41, v[10:11] offset:60928
	ds_write_b64 v41, v[42:43] offset:65280
	v_and_b32_e32 v2, 0xfffffe00, v2
	v_and_b32_e32 v28, 31, v1
	v_lshl_add_u32 v4, v2, 3, s67
	v_lshlrev_b32_e32 v5, 3, v28
	v_ashrrev_i32_e32 v2, 1, v2
	v_add3_u32 v41, v4, v5, v2
	v_cvt_f32_ubyte0_e32 v2, v28
	v_mul_f32_e32 v2, 0x3b000000, v2
	v_sin_f32_e32 v36, v2
	v_cos_f32_e32 v38, v2
	v_add_u32_e32 v64, 0x800, v41
	s_waitcnt lgkmcnt(0)
	v_xor_b32_e32 v39, 0x80000000, v36
	s_barrier
; #define LAS __attribute__((address_space(3)))
; __device__ __forceinline__ f32x2 cmul(f32x2 a, f32x2 b) { return (f32x2){a.x * b.x - a.y * b.y, a.x * b.y + a.y * b.x}; }
; template <bool INV, int ST> __device__ __forceinline__ void fft_pass16(LAS f32x2* buf, int base, int bl) {
;     constexpr float C16[8] = {1.f, 0.92387953251f, 0.70710678119f, 0.38268343237f, 0.f, -0.38268343237f, -0.70710678119f, -0.92387953251f};
;     constexpr float S16[8] = {0.f, 0.38268343237f, 0.70710678119f, 0.92387953251f, 1.f, 0.92387953251f, 0.70710678119f, 0.38268343237f};
;     f32x2 x[16];
;     constexpr int STEP = (1 << ST) + ((1 << ST) >> 4);
;     LAS f32x2* pb = buf + PADI(base);
; #pragma unroll
;     for (int d = 0; d < 16; ++d) x[d] = pb[d * STEP];
;     const float th = (float)bl * (1.f / (float)(16 << ST));
;     const f32x2 W1 = {__builtin_amdgcn_cosf(th), -__builtin_amdgcn_sinf(th)};
;     const f32x2 W2 = cmul(W1, W1), W4 = cmul(W2, W2), W8 = cmul(W4, W4);
;     if (!INV) {
; #pragma unroll
;         for (int d = 0; d < 8; ++d) { const f32x2 w = cmul(W1, (f32x2){C16[d], -S16[d]}); const f32x2 a = x[d], b = x[d + 8]; x[d] = a + b; x[d + 8] = cmul(a - b, w); }
; #pragma unroll
;         for (int g = 0; g < 16; g += 8)
; #pragma unroll
;             for (int dd = 0; dd < 4; ++dd) { const int d = g + dd; const f32x2 w = cmul(W2, (f32x2){C16[2 * dd], -S16[2 * dd]}); const f32x2 a = x[d], b = x[d + 4]; x[d] = a + b; x[d + 4] = cmul(a - b, w); }
; #pragma unroll
;         for (int g = 0; g < 16; g += 4)
; #pragma unroll
;             for (int dd = 0; dd < 2; ++dd) { const int d = g + dd; const f32x2 w = dd ? (f32x2){W4.y, -W4.x} : W4; const f32x2 a = x[d], b = x[d + 2]; x[d] = a + b; x[d + 2] = cmul(a - b, w); }
; #pragma unroll
;         for (int g = 0; g < 16; g += 2) { const f32x2 a = x[g], b = x[g + 1]; x[g] = a + b; x[g + 1] = cmul(a - b, W8); }
	ds_read2_b64 v[4:7], v41 offset1:34
	ds_read2_b64 v[8:11], v41 offset0:68 offset1:102
	ds_read2_b64 v[12:15], v41 offset0:136 offset1:170
	ds_read2_b64 v[16:19], v41 offset0:204 offset1:238
	ds_read2_b64 v[20:23], v64 offset0:16 offset1:50
	ds_read2_b64 v[24:27], v64 offset0:84 offset1:118
	v_mov_b32_e32 v37, v38
	v_mov_b32_e32 v42, v36
	v_mov_b32_e32 v43, v39
	v_pk_mul_f32 v[42:43], v[36:37], v[42:43]
	s_waitcnt lgkmcnt(1)
	v_pk_add_f32 v[50:51], v[4:5], v[20:21]
	v_pk_fma_f32 v[44:45], v[38:39], v[38:39], v[42:43] op_sel_hi:[0,1,1] neg_lo:[0,0,1] neg_hi:[0,0,1]
	v_pk_fma_f32 v[42:43], v[38:39], v[38:39], v[42:43] op_sel_hi:[0,1,1]
	v_mov_b32_e32 v45, v43
	v_pk_mul_f32 v[48:49], v[44:45], v[42:43] op_sel:[0,1] op_sel_hi:[1,0]
	v_fma_f32 v42, v38, s22, -v36
	v_pk_add_f32 v[4:5], v[4:5], v[20:21] neg_lo:[0,1] neg_hi:[0,1]
	v_fmamk_f32 v2, v36, 0x80000000, v38
	v_pk_mul_f32 v[20:21], v[42:43], v[4:5] op_sel:[0,1] op_sel_hi:[0,0]
	v_pk_fma_f32 v[52:53], v[2:3], v[4:5], v[20:21] neg_lo:[0,0,1] neg_hi:[0,0,1]
	v_pk_fma_f32 v[4:5], v[2:3], v[4:5], v[20:21] op_sel_hi:[0,1,1]
	v_pk_mul_f32 v[20:21], v[36:37], s[8:9] op_sel_hi:[1,0]
	v_mov_b32_e32 v53, v5
	v_pk_add_f32 v[4:5], v[6:7], v[22:23]
	v_pk_add_f32 v[6:7], v[6:7], v[22:23] neg_lo:[0,1] neg_hi:[0,1]
	v_fma_f32 v2, v36, s9, -v21
	s_waitcnt lgkmcnt(0)
	v_pk_add_f32 v[22:23], v[8:9], v[24:25]
	v_pk_add_f32 v[8:9], v[8:9], v[24:25] neg_lo:[0,1] neg_hi:[0,1]
	v_pk_add_f32 v[54:55], v[20:21], v[20:21] op_sel:[1,0] op_sel_hi:[1,0] neg_lo:[0,1] neg_hi:[0,1]
	v_pk_mul_f32 v[24:25], v[2:3], v[8:9] op_sel:[0,1] op_sel_hi:[0,0]
	ds_read2_b64 v[28:31], v64 offset0:152 offset1:186
	ds_read2_b64 v[32:35], v64 offset0:220 offset1:254
	v_pk_fma_f32 v[56:57], v[54:55], v[8:9], v[24:25] neg_lo:[0,0,1] neg_hi:[0,0,1]
	v_pk_fma_f32 v[8:9], v[54:55], v[8:9], v[24:25]
	v_pk_mul_f32 v[54:55], v[36:37], s[96:97]
	v_mov_b32_e32 v57, v9
	v_pk_mul_f32 v[8:9], v[36:37], s[10:11]
	v_pk_add_f32 v[58:59], v[10:11], v[26:27]
	v_pk_add_f32 v[10:11], v[10:11], v[26:27] neg_lo:[0,1] neg_hi:[0,1]
	v_pk_add_f32 v[26:27], v[54:55], v[54:55] op_sel:[0,1] op_sel_hi:[0,1] neg_lo:[0,1] neg_hi:[0,1]
	v_pk_mul_f32 v[26:27], v[26:27], v[10:11] op_sel:[0,1] op_sel_hi:[1,0]
	v_pk_add_f32 v[60:61], v[8:9], v[8:9] op_sel:[1,0] op_sel_hi:[1,0] neg_lo:[0,1] neg_hi:[0,1]
	v_fma_f32 v2, v36, s2, -v9
	v_pk_fma_f32 v[62:63], v[60:61], v[10:11], v[26:27] neg_lo:[0,0,1] neg_hi:[0,0,1]
	v_pk_fma_f32 v[10:11], v[60:61], v[10:11], v[26:27]
	s_waitcnt lgkmcnt(1)
	v_pk_add_f32 v[26:27], v[12:13], v[28:29]
	v_fma_f32 v10, v36, s22, -v38
	v_pk_add_f32 v[12:13], v[12:13], v[28:29] neg_lo:[0,1] neg_hi:[0,1]
	v_pk_mul_f32 v[24:25], v[2:3], v[6:7] op_sel:[0,1] op_sel_hi:[0,0]
	v_mov_b32_e32 v63, v11
	v_fma_f32 v2, v38, 0, -v36
	v_pk_mul_f32 v[10:11], v[10:11], v[12:13] op_sel:[0,1] op_sel_hi:[0,0]
	v_pk_fma_f32 v[28:29], v[2:3], v[12:13], v[10:11] neg_lo:[0,0,1] neg_hi:[0,0,1]
	v_pk_fma_f32 v[10:11], v[2:3], v[12:13], v[10:11] op_sel_hi:[0,1,1]
	v_mov_b32_e32 v29, v11
	v_pk_add_f32 v[10:11], v[14:15], v[30:31]
	v_pk_add_f32 v[12:13], v[14:15], v[30:31] neg_lo:[0,1] neg_hi:[0,1]
	v_fma_f32 v14, v38, s9, -v20
	s_waitcnt lgkmcnt(0)
	v_pk_add_f32 v[30:31], v[16:17], v[32:33]
	v_pk_add_f32 v[16:17], v[16:17], v[32:33] neg_lo:[0,1] neg_hi:[0,1]
	v_pk_add_f32 v[20:21], v[20:21], v[20:21] op_sel:[0,1] op_sel_hi:[0,1] neg_lo:[0,1] neg_hi:[0,1]
	v_pk_mul_f32 v[20:21], v[20:21], v[16:17] op_sel:[0,1] op_sel_hi:[1,0]
	v_mov_b32_e32 v39, v36
	v_pk_fma_f32 v[32:33], v[14:15], v[16:17], v[20:21] neg_lo:[0,0,1] neg_hi:[0,0,1]
	v_pk_fma_f32 v[14:15], v[14:15], v[16:17], v[20:21] op_sel_hi:[0,1,1]
	v_mov_b32_e32 v33, v15
	v_pk_mul_f32 v[14:15], v[38:39], s[2:3]
	v_fma_f32 v2, v38, s96, -v8
	v_sub_f32_e32 v16, v55, v15
	v_pk_fma_f32 v[20:21], v[16:17], v[6:7], v[24:25] op_sel_hi:[0,1,1] neg_lo:[0,0,1] neg_hi:[0,0,1]
	v_pk_fma_f32 v[6:7], v[16:17], v[6:7], v[24:25] op_sel_hi:[0,1,1]
	v_sub_f32_e32 v6, v15, v55
	v_mov_b32_e32 v21, v7
	v_pk_mul_f32 v[6:7], v[6:7], v[12:13] op_sel:[0,1] op_sel_hi:[0,0]
	v_pk_fma_f32 v[16:17], v[2:3], v[12:13], v[6:7] neg_lo:[0,0,1] neg_hi:[0,0,1]
	v_pk_fma_f32 v[6:7], v[2:3], v[12:13], v[6:7] op_sel_hi:[0,1,1]
	v_pk_add_f32 v[12:13], v[18:19], v[34:35] neg_lo:[0,1] neg_hi:[0,1]
	v_pk_add_f32 v[8:9], v[8:9], v[8:9] op_sel:[0,1] op_sel_hi:[0,1] neg_lo:[0,1] neg_hi:[0,1]
	v_mov_b32_e32 v17, v7
	v_pk_add_f32 v[6:7], v[18:19], v[34:35]
	v_pk_mul_f32 v[8:9], v[8:9], v[12:13] op_sel:[0,1] op_sel_hi:[1,0]
	v_pk_add_f32 v[14:15], v[14:15], v[14:15] op_sel:[0,1] op_sel_hi:[0,1] neg_lo:[0,1] neg_hi:[0,1]
	v_fmamk_f32 v24, v44, 0x80000000, v43
	v_pk_add_f32 v[34:35], v[50:51], v[26:27]
	v_pk_add_f32 v[26:27], v[50:51], v[26:27] neg_lo:[0,1] neg_hi:[0,1]
	v_pk_mul_f32 v[46:47], v[44:45], v[44:45]
	v_pk_fma_f32 v[18:19], v[14:15], v[12:13], v[8:9] neg_lo:[0,0,1] neg_hi:[0,0,1]
	v_pk_fma_f32 v[8:9], v[14:15], v[12:13], v[8:9]
	v_fma_f32 v2, 0, v43, v44
	v_pk_mul_f32 v[36:37], v[24:25], v[26:27] op_sel_hi:[0,1]
	v_mov_b32_e32 v8, v46
	v_pk_mov_b32 v[12:13], v[46:47], v[48:49] op_sel:[1,0]
	v_pk_fma_f32 v[38:39], v[2:3], v[26:27], v[36:37] op_sel:[0,0,1] op_sel_hi:[1,1,0] neg_lo:[0,0,1] neg_hi:[0,0,1]
	v_pk_fma_f32 v[26:27], v[2:3], v[26:27], v[36:37] op_sel:[0,0,1] op_sel_hi:[0,1,0]
	v_fma_f32 v36, v43, 0, -v44
	v_pk_add_f32 v[46:47], v[22:23], v[30:31]
	v_pk_add_f32 v[22:23], v[22:23], v[30:31] neg_lo:[0,1] neg_hi:[0,1]
	v_mov_b32_e32 v39, v27
	v_pk_add_f32 v[26:27], v[4:5], v[10:11]
	v_pk_add_f32 v[4:5], v[4:5], v[10:11] neg_lo:[0,1] neg_hi:[0,1]
	v_fma_f32 v10, 0, v44, v43
	v_pk_mul_f32 v[30:31], v[36:37], v[22:23] op_sel_hi:[0,1]
	v_mov_b32_e32 v19, v9
; __device__ __forceinline__ f32x2 cmul(f32x2 a, f32x2 b) { return (f32x2){a.x * b.x - a.y * b.y, a.x * b.y + a.y * b.x}; }
; template <bool INV, int ST> __device__ __forceinline__ void fft_pass16(LAS f32x2* buf, int base, int bl) {
;     ...
;         for (int d = 0; d < 8; ++d) { const f32x2 w = cmul(W1, (f32x2){C16[d], -S16[d]}); const f32x2 a = x[d], b = x[d + 8]; x[d] = a + b; x[d + 8] = cmul(a - b, w); }
; #pragma unroll
;         for (int g = 0; g < 16; g += 8)
; #pragma unroll
;             for (int dd = 0; dd < 4; ++dd) { const int d = g + dd; const f32x2 w = cmul(W2, (f32x2){C16[2 * dd], -S16[2 * dd]}); const f32x2 a = x[d], b = x[d + 4]; x[d] = a + b; x[d + 4] = cmul(a - b, w); }
; #pragma unroll
;         for (int g = 0; g < 16; g += 4)
; #pragma unroll
;             for (int dd = 0; dd < 2; ++dd) { const int d = g + dd; const f32x2 w = dd ? (f32x2){W4.y, -W4.x} : W4; const f32x2 a = x[d], b = x[d + 2]; x[d] = a + b; x[d + 2] = cmul(a - b, w); }
; #pragma unroll
;         for (int g = 0; g < 16; g += 2) { const f32x2 a = x[g], b = x[g + 1]; x[g] = a + b; x[g + 1] = cmul(a - b, W8); }
	v_mov_b32_e32 v9, v48
	v_pk_fma_f32 v[48:49], v[10:11], v[22:23], v[30:31] op_sel:[0,0,1] op_sel_hi:[1,1,0] neg_lo:[0,0,1] neg_hi:[0,0,1]
	v_pk_fma_f32 v[22:23], v[10:11], v[22:23], v[30:31] op_sel:[0,0,1] op_sel_hi:[0,1,0]
	v_mov_b32_e32 v49, v23
	v_pk_mul_f32 v[22:23], v[44:45], s[8:9]
	v_pk_add_f32 v[14:15], v[8:9], v[12:13] neg_lo:[0,1] neg_hi:[0,1]
	v_fma_f32 v42, v43, s8, -v22
	v_fmamk_f32 v30, v43, 0x3f3504f3, v22
	v_pk_mul_f32 v[44:45], v[42:43], v[4:5] op_sel_hi:[0,1]
	v_pk_fma_f32 v[50:51], v[30:31], v[4:5], v[44:45] op_sel:[0,0,1] op_sel_hi:[1,1,0] neg_lo:[0,0,1] neg_hi:[0,0,1]
	v_pk_fma_f32 v[4:5], v[30:31], v[4:5], v[44:45] op_sel:[0,0,1] op_sel_hi:[0,1,0]
	v_mov_b32_e32 v51, v5
	v_pk_add_f32 v[4:5], v[58:59], v[6:7]
	v_pk_add_f32 v[6:7], v[58:59], v[6:7] neg_lo:[0,1] neg_hi:[0,1]
	v_pk_add_f32 v[22:23], v[22:23], v[22:23] op_sel:[1,0] op_sel_hi:[1,0] neg_lo:[0,1] neg_hi:[0,1]
	v_pk_add_f32 v[8:9], v[8:9], v[12:13]
	v_pk_mul_f32 v[44:45], v[22:23], v[6:7]
	v_mov_b32_e32 v12, v14
	v_pk_fma_f32 v[54:55], v[42:43], v[6:7], v[44:45] op_sel:[0,0,1] op_sel_hi:[1,1,0] neg_lo:[0,0,1] neg_hi:[0,0,1]
	v_pk_fma_f32 v[6:7], v[42:43], v[6:7], v[44:45] op_sel:[0,0,1] op_sel_hi:[0,1,0]
	v_mov_b32_e32 v55, v7
	v_pk_add_f32 v[6:7], v[52:53], v[28:29]
	v_pk_add_f32 v[28:29], v[52:53], v[28:29] neg_lo:[0,1] neg_hi:[0,1]
	v_mov_b32_e32 v13, v9
	v_pk_mul_f32 v[24:25], v[24:25], v[28:29] op_sel_hi:[0,1]
	v_pk_fma_f32 v[44:45], v[2:3], v[28:29], v[24:25] op_sel:[0,0,1] op_sel_hi:[1,1,0] neg_lo:[0,0,1] neg_hi:[0,0,1]
	v_pk_fma_f32 v[24:25], v[2:3], v[28:29], v[24:25] op_sel:[0,0,1] op_sel_hi:[0,1,0]
	v_mov_b32_e32 v45, v25
	v_pk_add_f32 v[24:25], v[20:21], v[16:17]
	v_pk_add_f32 v[16:17], v[20:21], v[16:17] neg_lo:[0,1] neg_hi:[0,1]
	v_mul_f32_e32 v2, v14, v9
	v_pk_mul_f32 v[20:21], v[42:43], v[16:17] op_sel_hi:[0,1]
	v_pk_fma_f32 v[28:29], v[30:31], v[16:17], v[20:21] op_sel:[0,0,1] op_sel_hi:[1,1,0] neg_lo:[0,0,1] neg_hi:[0,0,1]
	v_pk_fma_f32 v[16:17], v[30:31], v[16:17], v[20:21] op_sel:[0,0,1] op_sel_hi:[0,1,0]
	v_pk_add_f32 v[20:21], v[56:57], v[32:33] neg_lo:[0,1] neg_hi:[0,1]
	v_mov_b32_e32 v29, v17
	v_pk_mul_f32 v[30:31], v[36:37], v[20:21] op_sel_hi:[0,1]
	v_pk_add_f32 v[16:17], v[56:57], v[32:33]
	v_pk_fma_f32 v[32:33], v[10:11], v[20:21], v[30:31] op_sel:[0,0,1] op_sel_hi:[1,1,0] neg_lo:[0,0,1] neg_hi:[0,0,1]
	v_pk_fma_f32 v[10:11], v[10:11], v[20:21], v[30:31] op_sel:[0,0,1] op_sel_hi:[0,1,0]
	v_mov_b32_e32 v33, v11
	v_pk_add_f32 v[10:11], v[62:63], v[18:19]
	v_pk_add_f32 v[18:19], v[62:63], v[18:19] neg_lo:[0,1] neg_hi:[0,1]
	v_pk_mul_f32 v[12:13], v[12:13], v[12:13]
	v_pk_mul_f32 v[20:21], v[22:23], v[18:19]
	v_add_f32_e32 v2, v2, v2
	v_pk_fma_f32 v[22:23], v[42:43], v[18:19], v[20:21] op_sel:[0,0,1] op_sel_hi:[1,1,0] neg_lo:[0,0,1] neg_hi:[0,0,1]
	v_pk_fma_f32 v[18:19], v[42:43], v[18:19], v[20:21] op_sel:[0,0,1] op_sel_hi:[0,1,0]
	v_pk_add_f32 v[20:21], v[34:35], v[46:47] neg_lo:[0,1] neg_hi:[0,1]
	v_mov_b32_e32 v23, v19
	v_pk_mul_f32 v[30:31], v[8:9], v[20:21] op_sel:[1,0]
	v_pk_add_f32 v[18:19], v[34:35], v[46:47]
	v_pk_fma_f32 v[34:35], v[14:15], v[20:21], v[30:31] op_sel:[0,0,1] op_sel_hi:[1,1,0] neg_lo:[0,0,1] neg_hi:[0,0,1]
	v_pk_fma_f32 v[20:21], v[14:15], v[20:21], v[30:31] op_sel:[0,0,1] op_sel_hi:[0,1,0]
	v_mov_b32_e32 v35, v21
	v_pk_add_f32 v[20:21], v[26:27], v[4:5]
	v_pk_add_f32 v[4:5], v[26:27], v[4:5] neg_lo:[0,1] neg_hi:[0,1]
	v_pk_add_f32 v[12:13], v[12:13], v[12:13] op_sel:[0,1] op_sel_hi:[0,1] neg_lo:[0,1] neg_hi:[0,1]
	v_pk_mul_f32 v[26:27], v[14:15], v[4:5] op_sel_hi:[0,1]
	v_pk_fma_f32 v[30:31], v[8:9], v[4:5], v[26:27] op_sel:[1,0,1] op_sel_hi:[1,1,0]
	v_pk_fma_f32 v[4:5], v[8:9], v[4:5], v[26:27] op_sel:[1,0,1] op_sel_hi:[1,1,0] neg_lo:[0,0,1] neg_hi:[0,0,1]
	v_pk_add_f32 v[26:27], v[38:39], v[48:49] neg_lo:[0,1] neg_hi:[0,1]
	v_mov_b32_e32 v31, v5
	v_pk_mul_f32 v[36:37], v[8:9], v[26:27] op_sel:[1,0]
	v_pk_add_f32 v[4:5], v[38:39], v[48:49]
	v_pk_fma_f32 v[38:39], v[14:15], v[26:27], v[36:37] op_sel:[0,0,1] op_sel_hi:[1,1,0] neg_lo:[0,0,1] neg_hi:[0,0,1]
	v_pk_fma_f32 v[26:27], v[14:15], v[26:27], v[36:37] op_sel:[0,0,1] op_sel_hi:[0,1,0]
	v_pk_add_f32 v[36:37], v[50:51], v[54:55] neg_lo:[0,1] neg_hi:[0,1]
	v_mov_b32_e32 v39, v27
	v_pk_mul_f32 v[42:43], v[14:15], v[36:37] op_sel_hi:[0,1]
	v_pk_fma_f32 v[46:47], v[8:9], v[36:37], v[42:43] op_sel:[1,0,1] op_sel_hi:[1,1,0]
	v_pk_fma_f32 v[36:37], v[8:9], v[36:37], v[42:43] op_sel:[1,0,1] op_sel_hi:[1,1,0] neg_lo:[0,0,1] neg_hi:[0,0,1]
	v_pk_add_f32 v[26:27], v[50:51], v[54:55]
	v_mov_b32_e32 v47, v37
	v_pk_add_f32 v[36:37], v[6:7], v[16:17]
	v_pk_add_f32 v[6:7], v[6:7], v[16:17] neg_lo:[0,1] neg_hi:[0,1]
	s_nop 0
	v_pk_mul_f32 v[16:17], v[8:9], v[6:7] op_sel:[1,0]
	s_nop 0
	v_pk_fma_f32 v[42:43], v[14:15], v[6:7], v[16:17] op_sel:[0,0,1] op_sel_hi:[1,1,0] neg_lo:[0,0,1] neg_hi:[0,0,1]
	v_pk_fma_f32 v[6:7], v[14:15], v[6:7], v[16:17] op_sel:[0,0,1] op_sel_hi:[0,1,0]
	v_mov_b32_e32 v43, v7
	v_pk_add_f32 v[6:7], v[24:25], v[10:11]
	v_pk_add_f32 v[10:11], v[24:25], v[10:11] neg_lo:[0,1] neg_hi:[0,1]
	s_nop 0
	v_pk_mul_f32 v[16:17], v[14:15], v[10:11] op_sel_hi:[0,1]
	v_pk_fma_f32 v[24:25], v[8:9], v[10:11], v[16:17] op_sel:[1,0,1] op_sel_hi:[1,1,0]
	v_pk_fma_f32 v[10:11], v[8:9], v[10:11], v[16:17] op_sel:[1,0,1] op_sel_hi:[1,1,0] neg_lo:[0,0,1] neg_hi:[0,0,1]
	v_pk_add_f32 v[16:17], v[44:45], v[32:33] neg_lo:[0,1] neg_hi:[0,1]
	v_mov_b32_e32 v25, v11
	v_pk_add_f32 v[10:11], v[44:45], v[32:33]
	v_pk_mul_f32 v[32:33], v[8:9], v[16:17] op_sel:[1,0]
	s_nop 0
	v_pk_fma_f32 v[44:45], v[14:15], v[16:17], v[32:33] op_sel:[0,0,1] op_sel_hi:[1,1,0] neg_lo:[0,0,1] neg_hi:[0,0,1]
; #define LAS __attribute__((address_space(3)))
; __device__ __forceinline__ f32x2 cmul(f32x2 a, f32x2 b) { return (f32x2){a.x * b.x - a.y * b.y, a.x * b.y + a.y * b.x}; }
; __device__ __forceinline__ f32x2 cmulc(f32x2 a, f32x2 b) { return (f32x2){a.x * b.x + a.y * b.y, a.y * b.x - a.x * b.y}; }
; template <bool INV, int ST> __device__ __forceinline__ void fft_pass16(LAS f32x2* buf, int base, int bl) {
;     ...
;             for (int dd = 0; dd < 2; ++dd) { const int d = g + dd; const f32x2 w = dd ? (f32x2){W4.y, -W4.x} : W4; const f32x2 a = x[d], b = x[d + 2]; x[d] = a + b; x[d + 2] = cmul(a - b, w); }
; #pragma unroll
;         for (int g = 0; g < 16; g += 2) { const f32x2 a = x[g], b = x[g + 1]; x[g] = a + b; x[g + 1] = cmul(a - b, W8); }
;     } else {
; #pragma unroll
;         for (int g = 0; g < 16; g += 2) { const f32x2 a = x[g], b = cmulc(x[g + 1], W8); x[g] = a + b; x[g + 1] = a - b; }
; #pragma unroll
;         for (int g = 0; g < 16; g += 4)
; #pragma unroll
;             for (int dd = 0; dd < 2; ++dd) { const int d = g + dd; const f32x2 w = dd ? (f32x2){W4.y, -W4.x} : W4; const f32x2 a = x[d], b = cmulc(x[d + 2], w); x[d] = a + b; x[d + 2] = a - b; }
; #pragma unroll
;         for (int g = 0; g < 16; g += 8)
; #pragma unroll
;             for (int dd = 0; dd < 4; ++dd) { const int d = g + dd; const f32x2 w = cmul(W2, (f32x2){C16[2 * dd], -S16[2 * dd]}); const f32x2 a = x[d], b = cmulc(x[d + 4], w); x[d] = a + b; x[d + 4] = a - b; }
; #pragma unroll
;         for (int d = 0; d < 8; ++d) { const f32x2 w = cmul(W1, (f32x2){C16[d], -S16[d]}); const f32x2 a = x[d], b = cmulc(x[d + 8], w); x[d] = a + b; x[d + 8] = a - b; }
;     }
; #pragma unroll
;     for (int d = 0; d < 16; ++d) pb[d * STEP] = x[d];
; }
; __device__ __forceinline__ void fft_fwd_abc(LAS f32x2* buf, int tid) {
;     asm volatile("" : "+v"(tid));
;     fft_pass16<false, 9>(buf, tid, tid); __syncthreads();
;     fft_pass16<false, 5>(buf, ((tid >> 5) << 9) + (tid & 31), tid & 31); __syncthreads();
;     fft_pass16<false, 1>(buf, ((tid >> 1) << 5) + (tid & 1), tid & 1); __syncthreads();
	v_pk_fma_f32 v[16:17], v[14:15], v[16:17], v[32:33] op_sel:[0,0,1] op_sel_hi:[0,1,0]
	v_mov_b32_e32 v45, v17
	v_pk_add_f32 v[16:17], v[28:29], v[22:23]
	v_pk_add_f32 v[22:23], v[28:29], v[22:23] neg_lo:[0,1] neg_hi:[0,1]
	s_nop 0
	v_pk_mul_f32 v[28:29], v[14:15], v[22:23] op_sel_hi:[0,1]
	v_pk_fma_f32 v[32:33], v[8:9], v[22:23], v[28:29] op_sel:[1,0,1] op_sel_hi:[1,1,0]
	v_pk_fma_f32 v[22:23], v[8:9], v[22:23], v[28:29] op_sel:[1,0,1] op_sel_hi:[1,1,0] neg_lo:[0,0,1] neg_hi:[0,0,1]
	s_nop 0
	v_mov_b32_e32 v33, v23
	v_pk_add_f32 v[22:23], v[18:19], v[20:21]
	v_pk_add_f32 v[18:19], v[18:19], v[20:21] neg_lo:[0,1] neg_hi:[0,1]
	s_nop 0
	v_pk_mul_f32 v[8:9], v[2:3], v[18:19] op_sel_hi:[0,1]
	v_pk_fma_f32 v[14:15], v[12:13], v[18:19], v[8:9] op_sel:[0,0,1] op_sel_hi:[1,1,0] neg_lo:[0,0,1] neg_hi:[0,0,1]
	v_pk_fma_f32 v[8:9], v[12:13], v[18:19], v[8:9] op_sel:[0,0,1] op_sel_hi:[1,1,0]
	v_pk_add_f32 v[18:19], v[34:35], v[30:31] neg_lo:[0,1] neg_hi:[0,1]
	v_mov_b32_e32 v15, v9
	v_pk_mul_f32 v[20:21], v[2:3], v[18:19] op_sel_hi:[0,1]
	v_pk_fma_f32 v[28:29], v[12:13], v[18:19], v[20:21] op_sel:[0,0,1] op_sel_hi:[1,1,0] neg_lo:[0,0,1] neg_hi:[0,0,1]
	v_pk_fma_f32 v[18:19], v[12:13], v[18:19], v[20:21] op_sel:[0,0,1] op_sel_hi:[1,1,0]
	v_pk_add_f32 v[8:9], v[34:35], v[30:31]
	v_mov_b32_e32 v29, v19
	v_pk_add_f32 v[18:19], v[4:5], v[26:27]
	v_pk_add_f32 v[4:5], v[4:5], v[26:27] neg_lo:[0,1] neg_hi:[0,1]
	s_nop 0
	v_pk_mul_f32 v[20:21], v[2:3], v[4:5] op_sel_hi:[0,1]
	v_pk_fma_f32 v[26:27], v[12:13], v[4:5], v[20:21] op_sel:[0,0,1] op_sel_hi:[1,1,0] neg_lo:[0,0,1] neg_hi:[0,0,1]
	v_pk_fma_f32 v[4:5], v[12:13], v[4:5], v[20:21] op_sel:[0,0,1] op_sel_hi:[1,1,0]
	v_pk_add_f32 v[20:21], v[38:39], v[46:47] neg_lo:[0,1] neg_hi:[0,1]
	v_mov_b32_e32 v27, v5
	v_pk_mul_f32 v[30:31], v[2:3], v[20:21] op_sel_hi:[0,1]
	v_pk_fma_f32 v[34:35], v[12:13], v[20:21], v[30:31] op_sel:[0,0,1] op_sel_hi:[1,1,0] neg_lo:[0,0,1] neg_hi:[0,0,1]
	v_pk_fma_f32 v[20:21], v[12:13], v[20:21], v[30:31] op_sel:[0,0,1] op_sel_hi:[1,1,0]
	v_pk_add_f32 v[4:5], v[38:39], v[46:47]
	v_mov_b32_e32 v35, v21
	v_pk_add_f32 v[20:21], v[36:37], v[6:7]
	v_pk_add_f32 v[6:7], v[36:37], v[6:7] neg_lo:[0,1] neg_hi:[0,1]
	s_nop 0
	v_pk_mul_f32 v[30:31], v[2:3], v[6:7] op_sel_hi:[0,1]
	v_pk_fma_f32 v[36:37], v[12:13], v[6:7], v[30:31] op_sel:[0,0,1] op_sel_hi:[1,1,0] neg_lo:[0,0,1] neg_hi:[0,0,1]
	v_pk_fma_f32 v[6:7], v[12:13], v[6:7], v[30:31] op_sel:[0,0,1] op_sel_hi:[1,1,0]
	s_nop 0
	v_mov_b32_e32 v37, v7
	v_pk_add_f32 v[6:7], v[42:43], v[24:25]
	v_pk_add_f32 v[24:25], v[42:43], v[24:25] neg_lo:[0,1] neg_hi:[0,1]
	s_nop 0
	v_pk_mul_f32 v[30:31], v[2:3], v[24:25] op_sel_hi:[0,1]
	v_pk_fma_f32 v[38:39], v[12:13], v[24:25], v[30:31] op_sel:[0,0,1] op_sel_hi:[1,1,0] neg_lo:[0,0,1] neg_hi:[0,0,1]
	v_pk_fma_f32 v[24:25], v[12:13], v[24:25], v[30:31] op_sel:[0,0,1] op_sel_hi:[1,1,0]
	s_nop 0
	v_mov_b32_e32 v39, v25
	v_pk_add_f32 v[24:25], v[10:11], v[16:17]
	v_pk_add_f32 v[10:11], v[10:11], v[16:17] neg_lo:[0,1] neg_hi:[0,1]
	s_nop 0
	v_pk_mul_f32 v[16:17], v[2:3], v[10:11] op_sel_hi:[0,1]
	v_pk_fma_f32 v[30:31], v[12:13], v[10:11], v[16:17] op_sel:[0,0,1] op_sel_hi:[1,1,0] neg_lo:[0,0,1] neg_hi:[0,0,1]
	v_pk_fma_f32 v[10:11], v[12:13], v[10:11], v[16:17] op_sel:[0,0,1] op_sel_hi:[1,1,0]
	v_pk_add_f32 v[16:17], v[44:45], v[32:33] neg_lo:[0,1] neg_hi:[0,1]
	v_mov_b32_e32 v31, v11
	v_pk_add_f32 v[10:11], v[44:45], v[32:33]
	v_pk_mul_f32 v[32:33], v[2:3], v[16:17] op_sel_hi:[0,1]
	v_pk_fma_f32 v[42:43], v[12:13], v[16:17], v[32:33] op_sel:[0,0,1] op_sel_hi:[1,1,0] neg_lo:[0,0,1] neg_hi:[0,0,1]
	v_pk_fma_f32 v[12:13], v[12:13], v[16:17], v[32:33] op_sel:[0,0,1] op_sel_hi:[1,1,0]
	v_and_b32_e32 v2, 1, v1
	v_mov_b32_e32 v43, v13
	ds_write2_b64 v41, v[22:23], v[14:15] offset1:34
	ds_write2_b64 v41, v[8:9], v[28:29] offset0:68 offset1:102
	ds_write2_b64 v41, v[18:19], v[26:27] offset0:136 offset1:170
	ds_write2_b64 v41, v[4:5], v[34:35] offset0:204 offset1:238
	ds_write2_b64 v64, v[20:21], v[36:37] offset0:16 offset1:50
	ds_write2_b64 v64, v[6:7], v[38:39] offset0:84 offset1:118
	ds_write2_b64 v64, v[24:25], v[30:31] offset0:152 offset1:186
	ds_write2_b64 v64, v[10:11], v[42:43] offset0:220 offset1:254
	v_lshlrev_b32_e32 v5, 3, v2
	v_cvt_f32_ubyte0_e32 v2, v2
	v_mul_f32_e32 v2, 0x3d000000, v2
	v_sin_f32_e32 v36, v2
	v_bfe_i32 v4, v1, 0, 28
	v_lshlrev_b32_e32 v1, 7, v1
	v_cos_f32_e32 v38, v2
	v_and_b32_e32 v1, 0xffffff00, v1
	v_lshlrev_b32_e32 v4, 3, v4
	v_add_u32_e32 v1, s67, v1
	v_and_b32_e32 v4, -16, v4
	v_add3_u32 v1, v1, v5, v4
	v_xor_b32_e32 v39, 0x80000000, v36
	s_waitcnt lgkmcnt(0)
	s_barrier
; #define LAS __attribute__((address_space(3)))
; __device__ __forceinline__ f32x2 cmul(f32x2 a, f32x2 b) { return (f32x2){a.x * b.x - a.y * b.y, a.x * b.y + a.y * b.x}; }
; template <bool INV, int ST> __device__ __forceinline__ void fft_pass16(LAS f32x2* buf, int base, int bl) {
;     constexpr float C16[8] = {1.f, 0.92387953251f, 0.70710678119f, 0.38268343237f, 0.f, -0.38268343237f, -0.70710678119f, -0.92387953251f};
;     constexpr float S16[8] = {0.f, 0.38268343237f, 0.70710678119f, 0.92387953251f, 1.f, 0.92387953251f, 0.70710678119f, 0.38268343237f};
;     f32x2 x[16];
;     constexpr int STEP = (1 << ST) + ((1 << ST) >> 4);
;     LAS f32x2* pb = buf + PADI(base);
; #pragma unroll
;     for (int d = 0; d < 16; ++d) x[d] = pb[d * STEP];
;     const float th = (float)bl * (1.f / (float)(16 << ST));
;     const f32x2 W1 = {__builtin_amdgcn_cosf(th), -__builtin_amdgcn_sinf(th)};
;     const f32x2 W2 = cmul(W1, W1), W4 = cmul(W2, W2), W8 = cmul(W4, W4);
;     if (!INV) {
; #pragma unroll
;         for (int d = 0; d < 8; ++d) { const f32x2 w = cmul(W1, (f32x2){C16[d], -S16[d]}); const f32x2 a = x[d], b = x[d + 8]; x[d] = a + b; x[d + 8] = cmul(a - b, w); }
; #pragma unroll
;         for (int g = 0; g < 16; g += 8)
; #pragma unroll
;             for (int dd = 0; dd < 4; ++dd) { const int d = g + dd; const f32x2 w = cmul(W2, (f32x2){C16[2 * dd], -S16[2 * dd]}); const f32x2 a = x[d], b = x[d + 4]; x[d] = a + b; x[d + 4] = cmul(a - b, w); }
; #pragma unroll
;         for (int g = 0; g < 16; g += 4)
; #pragma unroll
;             for (int dd = 0; dd < 2; ++dd) { const int d = g + dd; const f32x2 w = dd ? (f32x2){W4.y, -W4.x} : W4; const f32x2 a = x[d], b = x[d + 2]; x[d] = a + b; x[d + 2] = cmul(a - b, w); }
; #pragma unroll
;         for (int g = 0; g < 16; g += 2) { const f32x2 a = x[g], b = x[g + 1]; x[g] = a + b; x[g + 1] = cmul(a - b, W8); }
	ds_read2_b64 v[4:7], v1 offset1:2
	ds_read2_b64 v[8:11], v1 offset0:4 offset1:6
	ds_read2_b64 v[12:15], v1 offset0:8 offset1:10
	ds_read2_b64 v[16:19], v1 offset0:12 offset1:14
	ds_read2_b64 v[20:23], v1 offset0:16 offset1:18
	ds_read2_b64 v[24:27], v1 offset0:20 offset1:22
	v_mov_b32_e32 v37, v38
	v_mov_b32_e32 v42, v36
	v_mov_b32_e32 v43, v39
	v_pk_mul_f32 v[42:43], v[36:37], v[42:43]
	s_waitcnt lgkmcnt(1)
	v_pk_add_f32 v[50:51], v[4:5], v[20:21]
	v_pk_fma_f32 v[44:45], v[38:39], v[38:39], v[42:43] op_sel_hi:[0,1,1] neg_lo:[0,0,1] neg_hi:[0,0,1]
	v_pk_fma_f32 v[42:43], v[38:39], v[38:39], v[42:43] op_sel_hi:[0,1,1]
	v_mov_b32_e32 v45, v43
	v_pk_mul_f32 v[48:49], v[44:45], v[42:43] op_sel:[0,1] op_sel_hi:[1,0]
	v_fma_f32 v42, v38, s22, -v36
	v_pk_add_f32 v[4:5], v[4:5], v[20:21] neg_lo:[0,1] neg_hi:[0,1]
	v_fmamk_f32 v2, v36, 0x80000000, v38
	v_pk_mul_f32 v[20:21], v[42:43], v[4:5] op_sel:[0,1] op_sel_hi:[0,0]
	v_pk_fma_f32 v[52:53], v[2:3], v[4:5], v[20:21] neg_lo:[0,0,1] neg_hi:[0,0,1]
	v_pk_fma_f32 v[4:5], v[2:3], v[4:5], v[20:21] op_sel_hi:[0,1,1]
	v_pk_mul_f32 v[20:21], v[36:37], s[8:9] op_sel_hi:[1,0]
	v_mov_b32_e32 v53, v5
	v_pk_add_f32 v[4:5], v[6:7], v[22:23]
	v_pk_add_f32 v[6:7], v[6:7], v[22:23] neg_lo:[0,1] neg_hi:[0,1]
	v_fma_f32 v2, v36, s9, -v21
	s_waitcnt lgkmcnt(0)
	v_pk_add_f32 v[22:23], v[8:9], v[24:25]
	v_pk_add_f32 v[8:9], v[8:9], v[24:25] neg_lo:[0,1] neg_hi:[0,1]
	v_pk_add_f32 v[54:55], v[20:21], v[20:21] op_sel:[1,0] op_sel_hi:[1,0] neg_lo:[0,1] neg_hi:[0,1]
	v_pk_mul_f32 v[24:25], v[2:3], v[8:9] op_sel:[0,1] op_sel_hi:[0,0]
	ds_read2_b64 v[28:31], v1 offset0:24 offset1:26
	ds_read2_b64 v[32:35], v1 offset0:28 offset1:30
	v_pk_fma_f32 v[56:57], v[54:55], v[8:9], v[24:25] neg_lo:[0,0,1] neg_hi:[0,0,1]
	v_pk_fma_f32 v[8:9], v[54:55], v[8:9], v[24:25]
	v_pk_mul_f32 v[54:55], v[36:37], s[96:97]
	v_mov_b32_e32 v57, v9
	v_pk_mul_f32 v[8:9], v[36:37], s[10:11]
	v_pk_add_f32 v[58:59], v[10:11], v[26:27]
	v_pk_add_f32 v[10:11], v[10:11], v[26:27] neg_lo:[0,1] neg_hi:[0,1]
	v_pk_add_f32 v[26:27], v[54:55], v[54:55] op_sel:[0,1] op_sel_hi:[0,1] neg_lo:[0,1] neg_hi:[0,1]
	v_pk_mul_f32 v[26:27], v[26:27], v[10:11] op_sel:[0,1] op_sel_hi:[1,0]
	v_pk_add_f32 v[60:61], v[8:9], v[8:9] op_sel:[1,0] op_sel_hi:[1,0] neg_lo:[0,1] neg_hi:[0,1]
	v_fma_f32 v2, v36, s2, -v9
	v_pk_fma_f32 v[62:63], v[60:61], v[10:11], v[26:27] neg_lo:[0,0,1] neg_hi:[0,0,1]
	v_pk_fma_f32 v[10:11], v[60:61], v[10:11], v[26:27]
	s_waitcnt lgkmcnt(1)
	v_pk_add_f32 v[26:27], v[12:13], v[28:29]
	v_fma_f32 v10, v36, s22, -v38
	v_pk_add_f32 v[12:13], v[12:13], v[28:29] neg_lo:[0,1] neg_hi:[0,1]
	v_pk_mul_f32 v[24:25], v[2:3], v[6:7] op_sel:[0,1] op_sel_hi:[0,0]
	v_mov_b32_e32 v63, v11
	v_fma_f32 v2, v38, 0, -v36
	v_pk_mul_f32 v[10:11], v[10:11], v[12:13] op_sel:[0,1] op_sel_hi:[0,0]
	v_pk_fma_f32 v[28:29], v[2:3], v[12:13], v[10:11] neg_lo:[0,0,1] neg_hi:[0,0,1]
	v_pk_fma_f32 v[10:11], v[2:3], v[12:13], v[10:11] op_sel_hi:[0,1,1]
	v_mov_b32_e32 v29, v11
	v_pk_add_f32 v[10:11], v[14:15], v[30:31]
	v_pk_add_f32 v[12:13], v[14:15], v[30:31] neg_lo:[0,1] neg_hi:[0,1]
	v_fma_f32 v14, v38, s9, -v20
	s_waitcnt lgkmcnt(0)
	v_pk_add_f32 v[30:31], v[16:17], v[32:33]
	v_pk_add_f32 v[16:17], v[16:17], v[32:33] neg_lo:[0,1] neg_hi:[0,1]
	v_pk_add_f32 v[20:21], v[20:21], v[20:21] op_sel:[0,1] op_sel_hi:[0,1] neg_lo:[0,1] neg_hi:[0,1]
	v_pk_mul_f32 v[20:21], v[20:21], v[16:17] op_sel:[0,1] op_sel_hi:[1,0]
	v_mov_b32_e32 v39, v36
	v_pk_fma_f32 v[32:33], v[14:15], v[16:17], v[20:21] neg_lo:[0,0,1] neg_hi:[0,0,1]
	v_pk_fma_f32 v[14:15], v[14:15], v[16:17], v[20:21] op_sel_hi:[0,1,1]
	v_mov_b32_e32 v33, v15
	v_pk_mul_f32 v[14:15], v[38:39], s[2:3]
	v_fma_f32 v2, v38, s96, -v8
	v_sub_f32_e32 v16, v55, v15
	v_pk_fma_f32 v[20:21], v[16:17], v[6:7], v[24:25] op_sel_hi:[0,1,1] neg_lo:[0,0,1] neg_hi:[0,0,1]
	v_pk_fma_f32 v[6:7], v[16:17], v[6:7], v[24:25] op_sel_hi:[0,1,1]
	v_sub_f32_e32 v6, v15, v55
	v_mov_b32_e32 v21, v7
	v_pk_mul_f32 v[6:7], v[6:7], v[12:13] op_sel:[0,1] op_sel_hi:[0,0]
	v_pk_fma_f32 v[16:17], v[2:3], v[12:13], v[6:7] neg_lo:[0,0,1] neg_hi:[0,0,1]
	v_pk_fma_f32 v[6:7], v[2:3], v[12:13], v[6:7] op_sel_hi:[0,1,1]
	v_pk_add_f32 v[12:13], v[18:19], v[34:35] neg_lo:[0,1] neg_hi:[0,1]
	v_pk_add_f32 v[8:9], v[8:9], v[8:9] op_sel:[0,1] op_sel_hi:[0,1] neg_lo:[0,1] neg_hi:[0,1]
	v_mov_b32_e32 v17, v7
	v_pk_add_f32 v[6:7], v[18:19], v[34:35]
	v_pk_mul_f32 v[8:9], v[8:9], v[12:13] op_sel:[0,1] op_sel_hi:[1,0]
	v_pk_add_f32 v[14:15], v[14:15], v[14:15] op_sel:[0,1] op_sel_hi:[0,1] neg_lo:[0,1] neg_hi:[0,1]
	v_fmamk_f32 v24, v44, 0x80000000, v43
	v_pk_add_f32 v[34:35], v[50:51], v[26:27]
	v_pk_add_f32 v[26:27], v[50:51], v[26:27] neg_lo:[0,1] neg_hi:[0,1]
	v_pk_mul_f32 v[46:47], v[44:45], v[44:45]
	v_pk_fma_f32 v[18:19], v[14:15], v[12:13], v[8:9] neg_lo:[0,0,1] neg_hi:[0,0,1]
	v_pk_fma_f32 v[8:9], v[14:15], v[12:13], v[8:9]
	v_fma_f32 v2, 0, v43, v44
	v_pk_mul_f32 v[36:37], v[24:25], v[26:27] op_sel_hi:[0,1]
	v_mov_b32_e32 v8, v46
	v_pk_mov_b32 v[12:13], v[46:47], v[48:49] op_sel:[1,0]
	v_pk_fma_f32 v[38:39], v[2:3], v[26:27], v[36:37] op_sel:[0,0,1] op_sel_hi:[1,1,0] neg_lo:[0,0,1] neg_hi:[0,0,1]
	v_pk_fma_f32 v[26:27], v[2:3], v[26:27], v[36:37] op_sel:[0,0,1] op_sel_hi:[0,1,0]
	v_fma_f32 v36, v43, 0, -v44
	v_pk_add_f32 v[46:47], v[22:23], v[30:31]
	v_pk_add_f32 v[22:23], v[22:23], v[30:31] neg_lo:[0,1] neg_hi:[0,1]
	v_mov_b32_e32 v39, v27
	v_pk_add_f32 v[26:27], v[4:5], v[10:11]
	v_pk_add_f32 v[4:5], v[4:5], v[10:11] neg_lo:[0,1] neg_hi:[0,1]
	v_fma_f32 v10, 0, v44, v43
	v_pk_mul_f32 v[30:31], v[36:37], v[22:23] op_sel_hi:[0,1]
	v_mov_b32_e32 v19, v9
	v_mov_b32_e32 v9, v48
; __device__ __forceinline__ f32x2 cmul(f32x2 a, f32x2 b) { return (f32x2){a.x * b.x - a.y * b.y, a.x * b.y + a.y * b.x}; }
; template <bool INV, int ST> __device__ __forceinline__ void fft_pass16(LAS f32x2* buf, int base, int bl) {
;     ...
;         for (int d = 0; d < 8; ++d) { const f32x2 w = cmul(W1, (f32x2){C16[d], -S16[d]}); const f32x2 a = x[d], b = x[d + 8]; x[d] = a + b; x[d + 8] = cmul(a - b, w); }
; #pragma unroll
;         for (int g = 0; g < 16; g += 8)
; #pragma unroll
;             for (int dd = 0; dd < 4; ++dd) { const int d = g + dd; const f32x2 w = cmul(W2, (f32x2){C16[2 * dd], -S16[2 * dd]}); const f32x2 a = x[d], b = x[d + 4]; x[d] = a + b; x[d + 4] = cmul(a - b, w); }
; #pragma unroll
;         for (int g = 0; g < 16; g += 4)
; #pragma unroll
;             for (int dd = 0; dd < 2; ++dd) { const int d = g + dd; const f32x2 w = dd ? (f32x2){W4.y, -W4.x} : W4; const f32x2 a = x[d], b = x[d + 2]; x[d] = a + b; x[d + 2] = cmul(a - b, w); }
; #pragma unroll
;         for (int g = 0; g < 16; g += 2) { const f32x2 a = x[g], b = x[g + 1]; x[g] = a + b; x[g + 1] = cmul(a - b, W8); }
	v_pk_fma_f32 v[48:49], v[10:11], v[22:23], v[30:31] op_sel:[0,0,1] op_sel_hi:[1,1,0] neg_lo:[0,0,1] neg_hi:[0,0,1]
	v_pk_fma_f32 v[22:23], v[10:11], v[22:23], v[30:31] op_sel:[0,0,1] op_sel_hi:[0,1,0]
	v_mov_b32_e32 v49, v23
	v_pk_mul_f32 v[22:23], v[44:45], s[8:9]
	v_pk_add_f32 v[14:15], v[8:9], v[12:13] neg_lo:[0,1] neg_hi:[0,1]
	v_fma_f32 v42, v43, s8, -v22
	v_fmamk_f32 v30, v43, 0x3f3504f3, v22
	v_pk_mul_f32 v[44:45], v[42:43], v[4:5] op_sel_hi:[0,1]
	v_pk_fma_f32 v[50:51], v[30:31], v[4:5], v[44:45] op_sel:[0,0,1] op_sel_hi:[1,1,0] neg_lo:[0,0,1] neg_hi:[0,0,1]
	v_pk_fma_f32 v[4:5], v[30:31], v[4:5], v[44:45] op_sel:[0,0,1] op_sel_hi:[0,1,0]
	v_mov_b32_e32 v51, v5
	v_pk_add_f32 v[4:5], v[58:59], v[6:7]
	v_pk_add_f32 v[6:7], v[58:59], v[6:7] neg_lo:[0,1] neg_hi:[0,1]
	v_pk_add_f32 v[22:23], v[22:23], v[22:23] op_sel:[1,0] op_sel_hi:[1,0] neg_lo:[0,1] neg_hi:[0,1]
	v_pk_add_f32 v[8:9], v[8:9], v[12:13]
	v_pk_mul_f32 v[44:45], v[22:23], v[6:7]
	v_mov_b32_e32 v12, v14
	v_pk_fma_f32 v[54:55], v[42:43], v[6:7], v[44:45] op_sel:[0,0,1] op_sel_hi:[1,1,0] neg_lo:[0,0,1] neg_hi:[0,0,1]
	v_pk_fma_f32 v[6:7], v[42:43], v[6:7], v[44:45] op_sel:[0,0,1] op_sel_hi:[0,1,0]
	v_mov_b32_e32 v55, v7
	v_pk_add_f32 v[6:7], v[52:53], v[28:29]
	v_pk_add_f32 v[28:29], v[52:53], v[28:29] neg_lo:[0,1] neg_hi:[0,1]
	v_mov_b32_e32 v13, v9
	v_pk_mul_f32 v[24:25], v[24:25], v[28:29] op_sel_hi:[0,1]
	v_pk_fma_f32 v[44:45], v[2:3], v[28:29], v[24:25] op_sel:[0,0,1] op_sel_hi:[1,1,0] neg_lo:[0,0,1] neg_hi:[0,0,1]
	v_pk_fma_f32 v[24:25], v[2:3], v[28:29], v[24:25] op_sel:[0,0,1] op_sel_hi:[0,1,0]
	v_mov_b32_e32 v45, v25
	v_pk_add_f32 v[24:25], v[20:21], v[16:17]
	v_pk_add_f32 v[16:17], v[20:21], v[16:17] neg_lo:[0,1] neg_hi:[0,1]
	v_mul_f32_e32 v2, v14, v9
	v_pk_mul_f32 v[20:21], v[42:43], v[16:17] op_sel_hi:[0,1]
	v_pk_fma_f32 v[28:29], v[30:31], v[16:17], v[20:21] op_sel:[0,0,1] op_sel_hi:[1,1,0] neg_lo:[0,0,1] neg_hi:[0,0,1]
	v_pk_fma_f32 v[16:17], v[30:31], v[16:17], v[20:21] op_sel:[0,0,1] op_sel_hi:[0,1,0]
	v_pk_add_f32 v[20:21], v[56:57], v[32:33] neg_lo:[0,1] neg_hi:[0,1]
	v_mov_b32_e32 v29, v17
	v_pk_mul_f32 v[30:31], v[36:37], v[20:21] op_sel_hi:[0,1]
	v_pk_add_f32 v[16:17], v[56:57], v[32:33]
	v_pk_fma_f32 v[32:33], v[10:11], v[20:21], v[30:31] op_sel:[0,0,1] op_sel_hi:[1,1,0] neg_lo:[0,0,1] neg_hi:[0,0,1]
	v_pk_fma_f32 v[10:11], v[10:11], v[20:21], v[30:31] op_sel:[0,0,1] op_sel_hi:[0,1,0]
	v_mov_b32_e32 v33, v11
	v_pk_add_f32 v[10:11], v[62:63], v[18:19]
	v_pk_add_f32 v[18:19], v[62:63], v[18:19] neg_lo:[0,1] neg_hi:[0,1]
	v_pk_mul_f32 v[12:13], v[12:13], v[12:13]
	v_pk_mul_f32 v[20:21], v[22:23], v[18:19]
	v_add_f32_e32 v2, v2, v2
	v_pk_fma_f32 v[22:23], v[42:43], v[18:19], v[20:21] op_sel:[0,0,1] op_sel_hi:[1,1,0] neg_lo:[0,0,1] neg_hi:[0,0,1]
	v_pk_fma_f32 v[18:19], v[42:43], v[18:19], v[20:21] op_sel:[0,0,1] op_sel_hi:[0,1,0]
	v_pk_add_f32 v[20:21], v[34:35], v[46:47] neg_lo:[0,1] neg_hi:[0,1]
	v_mov_b32_e32 v23, v19
	v_pk_mul_f32 v[30:31], v[8:9], v[20:21] op_sel:[1,0]
	v_pk_add_f32 v[18:19], v[34:35], v[46:47]
	v_pk_fma_f32 v[34:35], v[14:15], v[20:21], v[30:31] op_sel:[0,0,1] op_sel_hi:[1,1,0] neg_lo:[0,0,1] neg_hi:[0,0,1]
	v_pk_fma_f32 v[20:21], v[14:15], v[20:21], v[30:31] op_sel:[0,0,1] op_sel_hi:[0,1,0]
	v_mov_b32_e32 v35, v21
	v_pk_add_f32 v[20:21], v[26:27], v[4:5]
	v_pk_add_f32 v[4:5], v[26:27], v[4:5] neg_lo:[0,1] neg_hi:[0,1]
	v_pk_add_f32 v[12:13], v[12:13], v[12:13] op_sel:[0,1] op_sel_hi:[0,1] neg_lo:[0,1] neg_hi:[0,1]
	v_pk_mul_f32 v[26:27], v[14:15], v[4:5] op_sel_hi:[0,1]
	v_pk_fma_f32 v[30:31], v[8:9], v[4:5], v[26:27] op_sel:[1,0,1] op_sel_hi:[1,1,0]
	v_pk_fma_f32 v[4:5], v[8:9], v[4:5], v[26:27] op_sel:[1,0,1] op_sel_hi:[1,1,0] neg_lo:[0,0,1] neg_hi:[0,0,1]
	v_pk_add_f32 v[26:27], v[38:39], v[48:49] neg_lo:[0,1] neg_hi:[0,1]
	v_mov_b32_e32 v31, v5
	v_pk_mul_f32 v[36:37], v[8:9], v[26:27] op_sel:[1,0]
	v_pk_add_f32 v[4:5], v[38:39], v[48:49]
	v_pk_fma_f32 v[38:39], v[14:15], v[26:27], v[36:37] op_sel:[0,0,1] op_sel_hi:[1,1,0] neg_lo:[0,0,1] neg_hi:[0,0,1]
	v_pk_fma_f32 v[26:27], v[14:15], v[26:27], v[36:37] op_sel:[0,0,1] op_sel_hi:[0,1,0]
	v_pk_add_f32 v[36:37], v[50:51], v[54:55] neg_lo:[0,1] neg_hi:[0,1]
	v_mov_b32_e32 v39, v27
	v_pk_mul_f32 v[42:43], v[14:15], v[36:37] op_sel_hi:[0,1]
	v_pk_fma_f32 v[46:47], v[8:9], v[36:37], v[42:43] op_sel:[1,0,1] op_sel_hi:[1,1,0]
	v_pk_fma_f32 v[36:37], v[8:9], v[36:37], v[42:43] op_sel:[1,0,1] op_sel_hi:[1,1,0] neg_lo:[0,0,1] neg_hi:[0,0,1]
	v_pk_add_f32 v[26:27], v[50:51], v[54:55]
	v_mov_b32_e32 v47, v37
	v_pk_add_f32 v[36:37], v[6:7], v[16:17]
	v_pk_add_f32 v[6:7], v[6:7], v[16:17] neg_lo:[0,1] neg_hi:[0,1]
	s_nop 0
	v_pk_mul_f32 v[16:17], v[8:9], v[6:7] op_sel:[1,0]
	s_nop 0
	v_pk_fma_f32 v[42:43], v[14:15], v[6:7], v[16:17] op_sel:[0,0,1] op_sel_hi:[1,1,0] neg_lo:[0,0,1] neg_hi:[0,0,1]
	v_pk_fma_f32 v[6:7], v[14:15], v[6:7], v[16:17] op_sel:[0,0,1] op_sel_hi:[0,1,0]
	v_mov_b32_e32 v43, v7
	v_pk_add_f32 v[6:7], v[24:25], v[10:11]
	v_pk_add_f32 v[10:11], v[24:25], v[10:11] neg_lo:[0,1] neg_hi:[0,1]
	s_nop 0
	v_pk_mul_f32 v[16:17], v[14:15], v[10:11] op_sel_hi:[0,1]
	v_pk_fma_f32 v[24:25], v[8:9], v[10:11], v[16:17] op_sel:[1,0,1] op_sel_hi:[1,1,0]
	v_pk_fma_f32 v[10:11], v[8:9], v[10:11], v[16:17] op_sel:[1,0,1] op_sel_hi:[1,1,0] neg_lo:[0,0,1] neg_hi:[0,0,1]
	v_pk_add_f32 v[16:17], v[44:45], v[32:33] neg_lo:[0,1] neg_hi:[0,1]
	v_mov_b32_e32 v25, v11
	v_pk_add_f32 v[10:11], v[44:45], v[32:33]
	v_pk_mul_f32 v[32:33], v[8:9], v[16:17] op_sel:[1,0]
	s_nop 0
	v_pk_fma_f32 v[44:45], v[14:15], v[16:17], v[32:33] op_sel:[0,0,1] op_sel_hi:[1,1,0] neg_lo:[0,0,1] neg_hi:[0,0,1]
; #define LAS __attribute__((address_space(3)))
; __device__ __forceinline__ float bflo(unsigned u) { return __uint_as_float(u << 16); }
; __device__ __forceinline__ float bfhi(unsigned u) { return __uint_as_float(u & 0xffff0000u); }
; template <bool INV, int ST> __device__ __forceinline__ void fft_pass16(LAS f32x2* buf, int base, int bl) {
;     ...
;             for (int dd = 0; dd < 2; ++dd) { const int d = g + dd; const f32x2 w = dd ? (f32x2){W4.y, -W4.x} : W4; const f32x2 a = x[d], b = x[d + 2]; x[d] = a + b; x[d + 2] = cmul(a - b, w); }
; #pragma unroll
;         for (int g = 0; g < 16; g += 2) { const f32x2 a = x[g], b = x[g + 1]; x[g] = a + b; x[g + 1] = cmul(a - b, W8); }
;     } else {
; #pragma unroll
;         for (int g = 0; g < 16; g += 2) { const f32x2 a = x[g], b = cmulc(x[g + 1], W8); x[g] = a + b; x[g + 1] = a - b; }
; #pragma unroll
;         for (int g = 0; g < 16; g += 4)
; #pragma unroll
;             for (int dd = 0; dd < 2; ++dd) { const int d = g + dd; const f32x2 w = dd ? (f32x2){W4.y, -W4.x} : W4; const f32x2 a = x[d], b = cmulc(x[d + 2], w); x[d] = a + b; x[d + 2] = a - b; }
; #pragma unroll
;         for (int g = 0; g < 16; g += 8)
; #pragma unroll
;             for (int dd = 0; dd < 4; ++dd) { const int d = g + dd; const f32x2 w = cmul(W2, (f32x2){C16[2 * dd], -S16[2 * dd]}); const f32x2 a = x[d], b = cmulc(x[d + 4], w); x[d] = a + b; x[d + 4] = a - b; }
; #pragma unroll
;         for (int d = 0; d < 8; ++d) { const f32x2 w = cmul(W1, (f32x2){C16[d], -S16[d]}); const f32x2 a = x[d], b = cmulc(x[d + 8], w); x[d] = a + b; x[d + 8] = a - b; }
;     }
; #pragma unroll
;     for (int d = 0; d < 16; ++d) pb[d * STEP] = x[d];
; }
; __device__ __forceinline__ void fft_fwd_abc(LAS f32x2* buf, int tid) {
;     asm volatile("" : "+v"(tid));
;     fft_pass16<false, 9>(buf, tid, tid); __syncthreads();
;     fft_pass16<false, 5>(buf, ((tid >> 5) << 9) + (tid & 31), tid & 31); __syncthreads();
;     fft_pass16<false, 1>(buf, ((tid >> 1) << 5) + (tid & 1), tid & 1); __syncthreads();
; }
; __device__ __forceinline__ void hyena_phase(const Params& P, int l, LAS unsigned char* lds) {
;     ...
; #pragma unroll
;             for (int u = 0; u < 8; ++u) { const int t = tid + 512 * u; { const unsigned w_ = ZT[(size_t)c * 4096 + t]; vv[u] = (f32x2){bflo(w_), bfhi(w_)}; } bufA[PADI(tid) + 544 * u] = vv[u]; bufA[PADI(tid) + 544 * u + 4352] = (f32x2){0.f, 0.f}; }
	v_pk_fma_f32 v[16:17], v[14:15], v[16:17], v[32:33] op_sel:[0,0,1] op_sel_hi:[0,1,0]
	v_mov_b32_e32 v45, v17
	v_pk_add_f32 v[16:17], v[28:29], v[22:23]
	v_pk_add_f32 v[22:23], v[28:29], v[22:23] neg_lo:[0,1] neg_hi:[0,1]
	s_nop 0
	v_pk_mul_f32 v[28:29], v[14:15], v[22:23] op_sel_hi:[0,1]
	v_pk_fma_f32 v[32:33], v[8:9], v[22:23], v[28:29] op_sel:[1,0,1] op_sel_hi:[1,1,0]
	v_pk_fma_f32 v[22:23], v[8:9], v[22:23], v[28:29] op_sel:[1,0,1] op_sel_hi:[1,1,0] neg_lo:[0,0,1] neg_hi:[0,0,1]
	s_nop 0
	v_mov_b32_e32 v33, v23
	v_pk_add_f32 v[22:23], v[18:19], v[20:21]
	v_pk_add_f32 v[18:19], v[18:19], v[20:21] neg_lo:[0,1] neg_hi:[0,1]
	s_nop 0
	v_pk_mul_f32 v[8:9], v[2:3], v[18:19] op_sel_hi:[0,1]
	v_pk_fma_f32 v[14:15], v[12:13], v[18:19], v[8:9] op_sel:[0,0,1] op_sel_hi:[1,1,0] neg_lo:[0,0,1] neg_hi:[0,0,1]
	v_pk_fma_f32 v[8:9], v[12:13], v[18:19], v[8:9] op_sel:[0,0,1] op_sel_hi:[1,1,0]
	v_pk_add_f32 v[18:19], v[34:35], v[30:31] neg_lo:[0,1] neg_hi:[0,1]
	v_mov_b32_e32 v15, v9
	v_pk_mul_f32 v[20:21], v[2:3], v[18:19] op_sel_hi:[0,1]
	v_pk_fma_f32 v[28:29], v[12:13], v[18:19], v[20:21] op_sel:[0,0,1] op_sel_hi:[1,1,0] neg_lo:[0,0,1] neg_hi:[0,0,1]
	v_pk_fma_f32 v[18:19], v[12:13], v[18:19], v[20:21] op_sel:[0,0,1] op_sel_hi:[1,1,0]
	v_pk_add_f32 v[8:9], v[34:35], v[30:31]
	v_mov_b32_e32 v29, v19
	v_pk_add_f32 v[18:19], v[4:5], v[26:27]
	v_pk_add_f32 v[4:5], v[4:5], v[26:27] neg_lo:[0,1] neg_hi:[0,1]
	s_nop 0
	v_pk_mul_f32 v[20:21], v[2:3], v[4:5] op_sel_hi:[0,1]
	v_pk_fma_f32 v[26:27], v[12:13], v[4:5], v[20:21] op_sel:[0,0,1] op_sel_hi:[1,1,0] neg_lo:[0,0,1] neg_hi:[0,0,1]
	v_pk_fma_f32 v[4:5], v[12:13], v[4:5], v[20:21] op_sel:[0,0,1] op_sel_hi:[1,1,0]
	v_pk_add_f32 v[20:21], v[38:39], v[46:47] neg_lo:[0,1] neg_hi:[0,1]
	v_mov_b32_e32 v27, v5
	v_pk_mul_f32 v[30:31], v[2:3], v[20:21] op_sel_hi:[0,1]
	v_pk_fma_f32 v[34:35], v[12:13], v[20:21], v[30:31] op_sel:[0,0,1] op_sel_hi:[1,1,0] neg_lo:[0,0,1] neg_hi:[0,0,1]
	v_pk_fma_f32 v[20:21], v[12:13], v[20:21], v[30:31] op_sel:[0,0,1] op_sel_hi:[1,1,0]
	v_pk_add_f32 v[4:5], v[38:39], v[46:47]
	v_mov_b32_e32 v35, v21
	v_pk_add_f32 v[20:21], v[36:37], v[6:7]
	v_pk_add_f32 v[6:7], v[36:37], v[6:7] neg_lo:[0,1] neg_hi:[0,1]
	s_nop 0
	v_pk_mul_f32 v[30:31], v[2:3], v[6:7] op_sel_hi:[0,1]
	v_pk_fma_f32 v[36:37], v[12:13], v[6:7], v[30:31] op_sel:[0,0,1] op_sel_hi:[1,1,0] neg_lo:[0,0,1] neg_hi:[0,0,1]
	v_pk_fma_f32 v[6:7], v[12:13], v[6:7], v[30:31] op_sel:[0,0,1] op_sel_hi:[1,1,0]
	s_nop 0
	v_mov_b32_e32 v37, v7
	v_pk_add_f32 v[6:7], v[42:43], v[24:25]
	v_pk_add_f32 v[24:25], v[42:43], v[24:25] neg_lo:[0,1] neg_hi:[0,1]
	s_nop 0
	v_pk_mul_f32 v[30:31], v[2:3], v[24:25] op_sel_hi:[0,1]
	v_pk_fma_f32 v[38:39], v[12:13], v[24:25], v[30:31] op_sel:[0,0,1] op_sel_hi:[1,1,0] neg_lo:[0,0,1] neg_hi:[0,0,1]
	v_pk_fma_f32 v[24:25], v[12:13], v[24:25], v[30:31] op_sel:[0,0,1] op_sel_hi:[1,1,0]
	s_nop 0
	v_mov_b32_e32 v39, v25
	v_pk_add_f32 v[24:25], v[10:11], v[16:17]
	v_pk_add_f32 v[10:11], v[10:11], v[16:17] neg_lo:[0,1] neg_hi:[0,1]
	s_nop 0
	v_pk_mul_f32 v[16:17], v[2:3], v[10:11] op_sel_hi:[0,1]
	v_pk_fma_f32 v[30:31], v[12:13], v[10:11], v[16:17] op_sel:[0,0,1] op_sel_hi:[1,1,0] neg_lo:[0,0,1] neg_hi:[0,0,1]
	v_pk_fma_f32 v[10:11], v[12:13], v[10:11], v[16:17] op_sel:[0,0,1] op_sel_hi:[1,1,0]
	v_pk_add_f32 v[16:17], v[44:45], v[32:33] neg_lo:[0,1] neg_hi:[0,1]
	v_mov_b32_e32 v31, v11
	v_pk_add_f32 v[10:11], v[44:45], v[32:33]
	v_pk_mul_f32 v[32:33], v[2:3], v[16:17] op_sel_hi:[0,1]
	v_pk_fma_f32 v[42:43], v[12:13], v[16:17], v[32:33] op_sel:[0,0,1] op_sel_hi:[1,1,0] neg_lo:[0,0,1] neg_hi:[0,0,1]
	v_pk_fma_f32 v[12:13], v[12:13], v[16:17], v[32:33] op_sel:[0,0,1] op_sel_hi:[1,1,0]
	s_nop 0
	v_mov_b32_e32 v43, v13
	ds_write2_b64 v1, v[22:23], v[14:15] offset1:2
	ds_write2_b64 v1, v[8:9], v[28:29] offset0:4 offset1:6
	ds_write2_b64 v1, v[18:19], v[26:27] offset0:8 offset1:10
	ds_write2_b64 v1, v[4:5], v[34:35] offset0:12 offset1:14
	ds_write2_b64 v1, v[20:21], v[36:37] offset0:16 offset1:18
	ds_write2_b64 v1, v[6:7], v[38:39] offset0:20 offset1:22
	ds_write2_b64 v1, v[24:25], v[30:31] offset0:24 offset1:26
	ds_write2_b64 v1, v[10:11], v[42:43] offset0:28 offset1:30
	v_ashrrev_i32_e32 v1, 31, v0
	v_lshl_add_u64 v[4:5], v[0:1], 2, s[6:7]
	s_mov_b64 s[6:7], 0x1000000
	v_lshl_add_u64 v[206:207], v[4:5], 0, s[6:7]
	v_lshl_add_u64 v[212:213], v[206:207], 0, s[6:7]
	s_mov_b64 s[6:7], 0x2000
	v_lshl_add_u64 v[208:209], v[206:207], 0, s[6:7]
	v_lshl_add_u64 v[210:211], v[208:209], 0, s[6:7]
	v_lshl_add_u64 v[214:215], v[212:213], 0, s[6:7]
	v_lshl_add_u64 v[216:217], v[214:215], 0, s[6:7]
	global_load_dword v192, v[206:207], off
	global_load_dword v193, v[206:207], off offset:2048
	global_load_dword v194, v[208:209], off offset:-4096
	global_load_dword v195, v[208:209], off offset:-2048
	global_load_dword v202, v[208:209], off
	global_load_dword v203, v[208:209], off offset:2048
	global_load_dword v204, v[210:211], off offset:-4096
	global_load_dword v205, v[210:211], off offset:-2048
	s_movk_i32 s6, 0x2000
	v_add_co_u32_e32 v6, vcc, s6, v4
	s_waitcnt lgkmcnt(0)
	s_nop 0
	v_addc_co_u32_e32 v7, vcc, 0, v5, vcc
	v_add_co_u32_e32 v8, vcc, s59, v4
	s_barrier
; #define LAS __attribute__((address_space(3)))
; __device__ __forceinline__ float bflo(unsigned u) { return __uint_as_float(u << 16); }
; __device__ __forceinline__ float bfhi(unsigned u) { return __uint_as_float(u & 0xffff0000u); }
; __device__ __forceinline__ f32x2 cmul(f32x2 a, f32x2 b) { return (f32x2){a.x * b.x - a.y * b.y, a.x * b.y + a.y * b.x}; }
; template <bool INV, int ST> __device__ __forceinline__ void fft_pass16(LAS f32x2* buf, int base, int bl) {
;     constexpr float C16[8] = {1.f, 0.92387953251f, 0.70710678119f, 0.38268343237f, 0.f, -0.38268343237f, -0.70710678119f, -0.92387953251f};
;     constexpr float S16[8] = {0.f, 0.38268343237f, 0.70710678119f, 0.92387953251f, 1.f, 0.92387953251f, 0.70710678119f, 0.38268343237f};
;     f32x2 x[16];
;     constexpr int STEP = (1 << ST) + ((1 << ST) >> 4);
;     LAS f32x2* pb = buf + PADI(base);
; #pragma unroll
;     for (int d = 0; d < 16; ++d) x[d] = pb[d * STEP];
;     const float th = (float)bl * (1.f / (float)(16 << ST));
;     const f32x2 W1 = {__builtin_amdgcn_cosf(th), -__builtin_amdgcn_sinf(th)};
;     const f32x2 W2 = cmul(W1, W1), W4 = cmul(W2, W2), W8 = cmul(W4, W4);
;     if (!INV) {
; #pragma unroll
;         for (int d = 0; d < 8; ++d) { const f32x2 w = cmul(W1, (f32x2){C16[d], -S16[d]}); const f32x2 a = x[d], b = x[d + 8]; x[d] = a + b; x[d + 8] = cmul(a - b, w); }
; __device__ __forceinline__ void hyena_phase(const Params& P, int l, LAS unsigned char* lds) {
;     ...
;             fft_fwd_abc(bufB, tid);
; #pragma unroll
;             for (int u = 0; u < 8; ++u) { LAS f32x4* pp = (LAS f32x4*)(bufB + PADI(2 * tid) + 1088 * u); const f32x4 v = *pp;
;                 *pp = (f32x4){v[0] + v[2], v[1] + v[3], v[0] - v[2], v[1] - v[3]}; }
;             f32x2 vv[8], y1[8];
; #pragma unroll
;             for (int u = 0; u < 8; ++u) { const int t = tid + 512 * u; { const unsigned w_ = ZT[(size_t)c * 4096 + t]; vv[u] = (f32x2){bflo(w_), bfhi(w_)}; } bufA[PADI(tid) + 544 * u] = vv[u]; bufA[PADI(tid) + 544 * u + 4352] = (f32x2){0.f, 0.f}; }
;             __syncthreads();
; #pragma unroll
;             for (int ord = 0; ord < 2; ++ord) {
;                 fft_fwd_abc(bufA, tid);
	s_nop 0
	v_addc_co_u32_e32 v9, vcc, 0, v5, vcc
	global_load_dword v2, v[4:5], off
	global_load_dword v16, v[4:5], off offset:2048
	v_add_co_u32_e32 v4, vcc, s20, v4
	global_load_dword v17, v[6:7], off offset:-4096
	s_nop 0
	v_addc_co_u32_e32 v5, vcc, 0, v5, vcc
	global_load_dword v20, v[8:9], off offset:2048
	global_load_dword v21, v[6:7], off
	global_load_dword v23, v[6:7], off offset:2048
	global_load_dword v24, v[4:5], off
	global_load_dword v25, v[4:5], off offset:2048
	v_ashrrev_i32_e32 v4, 3, v0
	v_and_b32_e32 v26, -2, v4
	v_lshlrev_b32_e32 v4, 4, v0
	v_lshlrev_b32_e32 v5, 3, v26
	v_add3_u32 v18, s67, v4, v5
	ds_read_b128 v[4:7], v18
	ds_read_b128 v[8:11], v18 offset:8704
	s_mov_b32 s6, 0
	s_mov_b32 s7, s6
	v_mov_b64_e32 v[28:29], s[6:7]
	s_waitcnt lgkmcnt(1)
	v_pk_add_f32 v[12:13], v[4:5], v[6:7]
	v_pk_add_f32 v[14:15], v[4:5], v[6:7] neg_lo:[0,1] neg_hi:[0,1]
	ds_read_b128 v[4:7], v18 offset:17408
	ds_write_b128 v18, v[12:15]
	s_waitcnt lgkmcnt(2)
	v_pk_add_f32 v[12:13], v[8:9], v[10:11]
	v_pk_add_f32 v[14:15], v[8:9], v[10:11] neg_lo:[0,1] neg_hi:[0,1]
	ds_read_b128 v[8:11], v18 offset:26112
	ds_write_b128 v18, v[12:15] offset:8704
	s_waitcnt lgkmcnt(3)
	v_pk_add_f32 v[12:13], v[4:5], v[6:7]
	v_pk_add_f32 v[14:15], v[4:5], v[6:7] neg_lo:[0,1] neg_hi:[0,1]
	ds_read_b128 v[4:7], v18 offset:34816
	ds_write_b128 v18, v[12:15] offset:17408
	s_waitcnt lgkmcnt(3)
	v_pk_add_f32 v[12:13], v[8:9], v[10:11]
	v_pk_add_f32 v[14:15], v[8:9], v[10:11] neg_lo:[0,1] neg_hi:[0,1]
	ds_read_b128 v[8:11], v18 offset:43520
	ds_write_b128 v18, v[12:15] offset:26112
	s_waitcnt lgkmcnt(3)
	v_pk_add_f32 v[12:13], v[4:5], v[6:7]
	v_pk_add_f32 v[14:15], v[4:5], v[6:7] neg_lo:[0,1] neg_hi:[0,1]
	ds_write_b128 v18, v[12:15] offset:34816
	ds_read_b128 v[4:7], v18 offset:52224
	s_waitcnt lgkmcnt(3)
	v_pk_add_f32 v[12:13], v[8:9], v[10:11]
	v_pk_add_f32 v[14:15], v[8:9], v[10:11] neg_lo:[0,1] neg_hi:[0,1]
	ds_read_b128 v[8:11], v18 offset:60928
	ds_write_b128 v18, v[12:15] offset:43520
	s_waitcnt lgkmcnt(2)
	v_pk_add_f32 v[12:13], v[4:5], v[6:7]
	v_pk_add_f32 v[14:15], v[4:5], v[6:7] neg_lo:[0,1] neg_hi:[0,1]
	ds_write_b128 v18, v[12:15] offset:52224
	s_waitcnt lgkmcnt(2)
	v_pk_add_f32 v[4:5], v[8:9], v[10:11]
	v_pk_add_f32 v[6:7], v[8:9], v[10:11] neg_lo:[0,1] neg_hi:[0,1]
	ds_write_b128 v18, v[4:7] offset:60928
	v_ashrrev_i32_e32 v4, 4, v0
	v_lshlrev_b32_e32 v4, 3, v4
	v_lshlrev_b32_e32 v5, 3, v0
	v_and_b32_e32 v4, -16, v4
	v_add3_u32 v22, 0, v5, v4
	ds_write_b64 v22, v[28:29] offset:34816
	s_waitcnt vmcnt(7)
	v_lshlrev_b32_e32 v14, 16, v2
	v_and_b32_e32 v15, 0xffff0000, v2
	v_add_u32_e32 v2, v26, v40
	s_waitcnt vmcnt(6)
	v_lshlrev_b32_e32 v18, 16, v16
	v_and_b32_e32 v19, 0xffff0000, v16
	s_waitcnt vmcnt(5)
	v_lshlrev_b32_e32 v16, 16, v17
	v_and_b32_e32 v17, 0xffff0000, v17
	s_waitcnt vmcnt(4)
	v_lshlrev_b32_e32 v12, 16, v20
	v_and_b32_e32 v13, 0xffff0000, v20
	s_waitcnt vmcnt(3)
	v_lshlrev_b32_e32 v10, 16, v21
	v_and_b32_e32 v11, 0xffff0000, v21
	s_waitcnt vmcnt(2)
	v_lshlrev_b32_e32 v8, 16, v23
	v_and_b32_e32 v9, 0xffff0000, v23
	s_waitcnt vmcnt(1)
	v_lshlrev_b32_e32 v6, 16, v24
	v_and_b32_e32 v7, 0xffff0000, v24
	s_waitcnt vmcnt(0)
	v_lshlrev_b32_e32 v4, 16, v25
	v_and_b32_e32 v5, 0xffff0000, v25
	v_lshl_add_u32 v23, v2, 3, 0
	v_mov_b32_e32 v2, v0
	ds_write_b64 v22, v[14:15]
	ds_write_b64 v22, v[18:19] offset:4352
	ds_write_b64 v22, v[28:29] offset:39168
	ds_write_b64 v22, v[16:17] offset:8704
	ds_write_b64 v22, v[28:29] offset:43520
	ds_write_b64 v22, v[12:13] offset:13056
	ds_write_b64 v22, v[28:29] offset:47872
	ds_write_b64 v22, v[10:11] offset:17408
	ds_write_b64 v22, v[28:29] offset:52224
	ds_write_b64 v22, v[8:9] offset:21760
	ds_write_b64 v22, v[28:29] offset:56576
	ds_write_b64 v22, v[6:7] offset:26112
	ds_write_b64 v22, v[28:29] offset:60928
	ds_write_b64 v22, v[4:5] offset:30464
	ds_write_b64 v22, v[28:29] offset:65280
	s_waitcnt lgkmcnt(0)
	s_barrier
	s_nop 0
	v_cvt_f32_i32_e32 v48, v2
	v_ashrrev_i32_e32 v20, 4, v2
	v_lshlrev_b32_e32 v20, 3, v20
	v_lshlrev_b32_e32 v21, 3, v2
	v_mul_f32_e32 v49, 0x39000000, v48
	v_sin_f32_e32 v50, v49
	v_cos_f32_e32 v48, v49
	v_and_b32_e32 v20, -16, v20
	v_add3_u32 v41, 0, v21, v20
	v_xor_b32_e32 v49, 0x80000000, v50
	v_mov_b32_e32 v51, v48
	v_mov_b32_e32 v60, v50
	v_mov_b32_e32 v61, v49
	ds_read_b64 v[20:21], v41
	ds_read_b64 v[24:25], v41 offset:4352
	ds_read_b64 v[26:27], v41 offset:8704
	ds_read_b64 v[28:29], v41 offset:13056
	ds_read_b64 v[30:31], v41 offset:17408
	ds_read_b64 v[32:33], v41 offset:21760
	ds_read_b64 v[34:35], v41 offset:26112
	ds_read_b64 v[36:37], v41 offset:30464
	ds_read_b64 v[38:39], v41 offset:34816
	ds_read_b64 v[42:43], v41 offset:39168
	ds_read_b64 v[44:45], v41 offset:43520
	ds_read_b64 v[46:47], v41 offset:47872
	v_pk_mul_f32 v[60:61], v[50:51], v[60:61]
	v_fma_f32 v68, v48, s22, -v50
	v_pk_fma_f32 v[62:63], v[48:49], v[48:49], v[60:61] op_sel_hi:[0,1,1] neg_lo:[0,0,1] neg_hi:[0,0,1]
	v_pk_fma_f32 v[60:61], v[48:49], v[48:49], v[60:61] op_sel_hi:[0,1,1]
	v_mov_b32_e32 v63, v61
	s_waitcnt lgkmcnt(3)
	v_pk_add_f32 v[70:71], v[20:21], v[38:39]
	v_pk_add_f32 v[20:21], v[20:21], v[38:39] neg_lo:[0,1] neg_hi:[0,1]
	v_pk_mul_f32 v[66:67], v[62:63], v[60:61] op_sel:[0,1] op_sel_hi:[1,0]
	v_fmamk_f32 v60, v50, 0x80000000, v48
	v_pk_mul_f32 v[38:39], v[68:69], v[20:21] op_sel:[0,1] op_sel_hi:[0,0]
	v_pk_fma_f32 v[68:69], v[60:61], v[20:21], v[38:39] neg_lo:[0,0,1] neg_hi:[0,0,1]
	v_pk_fma_f32 v[20:21], v[60:61], v[20:21], v[38:39] op_sel_hi:[0,1,1]
	v_pk_mul_f32 v[38:39], v[50:51], s[8:9] op_sel_hi:[1,0]
	v_mov_b32_e32 v69, v21
	s_waitcnt lgkmcnt(2)
; #define LAS __attribute__((address_space(3)))
; __device__ __forceinline__ f32x2 cmul(f32x2 a, f32x2 b) { return (f32x2){a.x * b.x - a.y * b.y, a.x * b.y + a.y * b.x}; }
; template <bool INV, int ST> __device__ __forceinline__ void fft_pass16(LAS f32x2* buf, int base, int bl) {
;     constexpr float C16[8] = {1.f, 0.92387953251f, 0.70710678119f, 0.38268343237f, 0.f, -0.38268343237f, -0.70710678119f, -0.92387953251f};
;     constexpr float S16[8] = {0.f, 0.38268343237f, 0.70710678119f, 0.92387953251f, 1.f, 0.92387953251f, 0.70710678119f, 0.38268343237f};
;     f32x2 x[16];
;     constexpr int STEP = (1 << ST) + ((1 << ST) >> 4);
;     LAS f32x2* pb = buf + PADI(base);
; #pragma unroll
;     for (int d = 0; d < 16; ++d) x[d] = pb[d * STEP];
;     const float th = (float)bl * (1.f / (float)(16 << ST));
;     const f32x2 W1 = {__builtin_amdgcn_cosf(th), -__builtin_amdgcn_sinf(th)};
;     const f32x2 W2 = cmul(W1, W1), W4 = cmul(W2, W2), W8 = cmul(W4, W4);
;     if (!INV) {
; #pragma unroll
;         for (int d = 0; d < 8; ++d) { const f32x2 w = cmul(W1, (f32x2){C16[d], -S16[d]}); const f32x2 a = x[d], b = x[d + 8]; x[d] = a + b; x[d + 8] = cmul(a - b, w); }
; #pragma unroll
;         for (int g = 0; g < 16; g += 8)
; #pragma unroll
;             for (int dd = 0; dd < 4; ++dd) { const int d = g + dd; const f32x2 w = cmul(W2, (f32x2){C16[2 * dd], -S16[2 * dd]}); const f32x2 a = x[d], b = x[d + 4]; x[d] = a + b; x[d + 4] = cmul(a - b, w); }
; #pragma unroll
;         for (int g = 0; g < 16; g += 4)
; #pragma unroll
;             for (int dd = 0; dd < 2; ++dd) { const int d = g + dd; const f32x2 w = dd ? (f32x2){W4.y, -W4.x} : W4; const f32x2 a = x[d], b = x[d + 2]; x[d] = a + b; x[d + 2] = cmul(a - b, w); }
; #pragma unroll
;         for (int g = 0; g < 16; g += 2) { const f32x2 a = x[g], b = x[g + 1]; x[g] = a + b; x[g + 1] = cmul(a - b, W8); }
	v_pk_add_f32 v[20:21], v[24:25], v[42:43]
	v_pk_add_f32 v[24:25], v[24:25], v[42:43] neg_lo:[0,1] neg_hi:[0,1]
	v_fma_f32 v42, v50, s9, -v39
	s_waitcnt lgkmcnt(1)
	v_pk_add_f32 v[72:73], v[26:27], v[44:45]
	v_pk_add_f32 v[26:27], v[26:27], v[44:45] neg_lo:[0,1] neg_hi:[0,1]
	v_pk_add_f32 v[44:45], v[38:39], v[38:39] op_sel:[1,0] op_sel_hi:[1,0] neg_lo:[0,1] neg_hi:[0,1]
	v_pk_mul_f32 v[42:43], v[42:43], v[26:27] op_sel:[0,1] op_sel_hi:[0,0]
	v_pk_fma_f32 v[74:75], v[44:45], v[26:27], v[42:43] neg_lo:[0,0,1] neg_hi:[0,0,1]
	v_pk_fma_f32 v[26:27], v[44:45], v[26:27], v[42:43]
	v_pk_mul_f32 v[44:45], v[50:51], s[96:97]
	ds_read_b64 v[52:53], v41 offset:52224
	ds_read_b64 v[54:55], v41 offset:56576
	ds_read_b64 v[56:57], v41 offset:60928
	ds_read_b64 v[58:59], v41 offset:65280
	v_mov_b32_e32 v75, v27
	v_pk_mul_f32 v[26:27], v[50:51], s[10:11]
	s_waitcnt lgkmcnt(4)
	v_pk_add_f32 v[76:77], v[28:29], v[46:47]
	v_pk_add_f32 v[28:29], v[28:29], v[46:47] neg_lo:[0,1] neg_hi:[0,1]
	v_pk_add_f32 v[46:47], v[44:45], v[44:45] op_sel:[0,1] op_sel_hi:[0,1] neg_lo:[0,1] neg_hi:[0,1]
	v_pk_mul_f32 v[46:47], v[46:47], v[28:29] op_sel:[0,1] op_sel_hi:[1,0]
	v_pk_add_f32 v[78:79], v[26:27], v[26:27] op_sel:[1,0] op_sel_hi:[1,0] neg_lo:[0,1] neg_hi:[0,1]
	v_fma_f32 v44, v50, s22, -v48
	v_pk_fma_f32 v[80:81], v[78:79], v[28:29], v[46:47] neg_lo:[0,0,1] neg_hi:[0,0,1]
	v_pk_fma_f32 v[28:29], v[78:79], v[28:29], v[46:47]
	s_waitcnt lgkmcnt(3)
	v_pk_add_f32 v[46:47], v[30:31], v[52:53]
	v_pk_add_f32 v[30:31], v[30:31], v[52:53] neg_lo:[0,1] neg_hi:[0,1]
	v_fma_f32 v28, v48, 0, -v50
	v_pk_mul_f32 v[52:53], v[44:45], v[30:31] op_sel:[0,1] op_sel_hi:[0,0]
	v_mov_b32_e32 v81, v29
	v_pk_fma_f32 v[78:79], v[28:29], v[30:31], v[52:53] neg_lo:[0,0,1] neg_hi:[0,0,1]
	v_pk_fma_f32 v[28:29], v[28:29], v[30:31], v[52:53] op_sel_hi:[0,1,1]
	v_fma_f32 v44, v48, s9, -v38
	s_waitcnt lgkmcnt(1)
	v_pk_add_f32 v[52:53], v[34:35], v[56:57]
	v_pk_add_f32 v[34:35], v[34:35], v[56:57] neg_lo:[0,1] neg_hi:[0,1]
	v_pk_add_f32 v[38:39], v[38:39], v[38:39] op_sel:[0,1] op_sel_hi:[0,1] neg_lo:[0,1] neg_hi:[0,1]
	v_pk_mul_f32 v[38:39], v[38:39], v[34:35] op_sel:[0,1] op_sel_hi:[1,0]
	v_pk_add_f32 v[30:31], v[32:33], v[54:55]
	v_pk_add_f32 v[32:33], v[32:33], v[54:55] neg_lo:[0,1] neg_hi:[0,1]
	v_pk_fma_f32 v[54:55], v[44:45], v[34:35], v[38:39] neg_lo:[0,0,1] neg_hi:[0,0,1]
	v_pk_fma_f32 v[34:35], v[44:45], v[34:35], v[38:39] op_sel_hi:[0,1,1]
	v_mov_b32_e32 v49, v50
	v_fma_f32 v42, v50, s2, -v27
	v_mov_b32_e32 v55, v35
	v_pk_mul_f32 v[34:35], v[48:49], s[2:3]
	v_pk_mul_f32 v[42:43], v[42:43], v[24:25] op_sel:[0,1] op_sel_hi:[0,0]
	v_sub_f32_e32 v38, v45, v35
	v_fma_f32 v28, v48, s96, -v26
	v_pk_fma_f32 v[48:49], v[38:39], v[24:25], v[42:43] op_sel_hi:[0,1,1] neg_lo:[0,0,1] neg_hi:[0,0,1]
	v_pk_fma_f32 v[24:25], v[38:39], v[24:25], v[42:43] op_sel_hi:[0,1,1]
	v_sub_f32_e32 v24, v35, v45
	v_mov_b32_e32 v49, v25
	v_pk_mul_f32 v[24:25], v[24:25], v[32:33] op_sel:[0,1] op_sel_hi:[0,0]
	v_mov_b32_e32 v79, v29
	v_pk_fma_f32 v[38:39], v[28:29], v[32:33], v[24:25] neg_lo:[0,0,1] neg_hi:[0,0,1]
	v_pk_fma_f32 v[24:25], v[28:29], v[32:33], v[24:25] op_sel_hi:[0,1,1]
	s_waitcnt lgkmcnt(0)
	v_pk_add_f32 v[28:29], v[36:37], v[58:59] neg_lo:[0,1] neg_hi:[0,1]
	v_pk_add_f32 v[26:27], v[26:27], v[26:27] op_sel:[0,1] op_sel_hi:[0,1] neg_lo:[0,1] neg_hi:[0,1]
	v_fmamk_f32 v42, v62, 0x80000000, v61
	v_pk_add_f32 v[44:45], v[70:71], v[46:47]
	v_pk_add_f32 v[46:47], v[70:71], v[46:47] neg_lo:[0,1] neg_hi:[0,1]
	v_mov_b32_e32 v39, v25
	v_pk_add_f32 v[24:25], v[36:37], v[58:59]
	v_pk_mul_f32 v[26:27], v[26:27], v[28:29] op_sel:[0,1] op_sel_hi:[1,0]
	v_pk_add_f32 v[32:33], v[34:35], v[34:35] op_sel:[0,1] op_sel_hi:[0,1] neg_lo:[0,1] neg_hi:[0,1]
	v_fma_f32 v36, 0, v61, v62
	v_pk_mul_f32 v[50:51], v[42:43], v[46:47] op_sel_hi:[0,1]
	v_pk_mul_f32 v[64:65], v[62:63], v[62:63]
	v_pk_fma_f32 v[34:35], v[32:33], v[28:29], v[26:27] neg_lo:[0,0,1] neg_hi:[0,0,1]
	v_pk_fma_f32 v[26:27], v[32:33], v[28:29], v[26:27]
	v_pk_fma_f32 v[56:57], v[36:37], v[46:47], v[50:51] op_sel:[0,0,1] op_sel_hi:[1,1,0] neg_lo:[0,0,1] neg_hi:[0,0,1]
	v_pk_fma_f32 v[46:47], v[36:37], v[46:47], v[50:51] op_sel:[0,0,1] op_sel_hi:[0,1,0]
	v_fma_f32 v50, v61, 0, -v62
	v_pk_add_f32 v[58:59], v[72:73], v[52:53]
	v_pk_add_f32 v[52:53], v[72:73], v[52:53] neg_lo:[0,1] neg_hi:[0,1]
	v_mov_b32_e32 v26, v64
	v_pk_mov_b32 v[28:29], v[64:65], v[66:67] op_sel:[1,0]
	v_mov_b32_e32 v57, v47
	v_pk_add_f32 v[46:47], v[20:21], v[30:31]
	v_pk_add_f32 v[20:21], v[20:21], v[30:31] neg_lo:[0,1] neg_hi:[0,1]
	v_fma_f32 v30, 0, v62, v61
	v_pk_mul_f32 v[64:65], v[50:51], v[52:53] op_sel_hi:[0,1]
	v_mov_b32_e32 v35, v27
	v_mov_b32_e32 v27, v66
	v_pk_fma_f32 v[66:67], v[30:31], v[52:53], v[64:65] op_sel:[0,0,1] op_sel_hi:[1,1,0] neg_lo:[0,0,1] neg_hi:[0,0,1]
	v_pk_fma_f32 v[52:53], v[30:31], v[52:53], v[64:65] op_sel:[0,0,1] op_sel_hi:[0,1,0]
	v_mov_b32_e32 v67, v53
	v_pk_mul_f32 v[52:53], v[62:63], s[8:9]
	v_pk_add_f32 v[32:33], v[26:27], v[28:29] neg_lo:[0,1] neg_hi:[0,1]
	v_fma_f32 v62, v61, s8, -v52
	v_fmamk_f32 v60, v61, 0x3f3504f3, v52
	v_pk_mul_f32 v[64:65], v[62:63], v[20:21] op_sel_hi:[0,1]
	v_pk_fma_f32 v[70:71], v[60:61], v[20:21], v[64:65] op_sel:[0,0,1] op_sel_hi:[1,1,0] neg_lo:[0,0,1] neg_hi:[0,0,1]
	v_pk_fma_f32 v[20:21], v[60:61], v[20:21], v[64:65] op_sel:[0,0,1] op_sel_hi:[0,1,0]
	v_mov_b32_e32 v71, v21
	v_pk_add_f32 v[20:21], v[76:77], v[24:25]
	v_pk_add_f32 v[24:25], v[76:77], v[24:25] neg_lo:[0,1] neg_hi:[0,1]
	v_pk_add_f32 v[52:53], v[52:53], v[52:53] op_sel:[1,0] op_sel_hi:[1,0] neg_lo:[0,1] neg_hi:[0,1]
	v_pk_add_f32 v[26:27], v[26:27], v[28:29]
; __device__ __forceinline__ f32x2 cmul(f32x2 a, f32x2 b) { return (f32x2){a.x * b.x - a.y * b.y, a.x * b.y + a.y * b.x}; }
; template <bool INV, int ST> __device__ __forceinline__ void fft_pass16(LAS f32x2* buf, int base, int bl) {
;     ...
;         for (int d = 0; d < 8; ++d) { const f32x2 w = cmul(W1, (f32x2){C16[d], -S16[d]}); const f32x2 a = x[d], b = x[d + 8]; x[d] = a + b; x[d + 8] = cmul(a - b, w); }
; #pragma unroll
;         for (int g = 0; g < 16; g += 8)
; #pragma unroll
;             for (int dd = 0; dd < 4; ++dd) { const int d = g + dd; const f32x2 w = cmul(W2, (f32x2){C16[2 * dd], -S16[2 * dd]}); const f32x2 a = x[d], b = x[d + 4]; x[d] = a + b; x[d + 4] = cmul(a - b, w); }
; #pragma unroll
;         for (int g = 0; g < 16; g += 4)
; #pragma unroll
;             for (int dd = 0; dd < 2; ++dd) { const int d = g + dd; const f32x2 w = dd ? (f32x2){W4.y, -W4.x} : W4; const f32x2 a = x[d], b = x[d + 2]; x[d] = a + b; x[d + 2] = cmul(a - b, w); }
; #pragma unroll
;         for (int g = 0; g < 16; g += 2) { const f32x2 a = x[g], b = x[g + 1]; x[g] = a + b; x[g + 1] = cmul(a - b, W8); }
	v_pk_mul_f32 v[64:65], v[52:53], v[24:25]
	v_mov_b32_e32 v28, v32
	v_pk_fma_f32 v[72:73], v[62:63], v[24:25], v[64:65] op_sel:[0,0,1] op_sel_hi:[1,1,0] neg_lo:[0,0,1] neg_hi:[0,0,1]
	v_pk_fma_f32 v[24:25], v[62:63], v[24:25], v[64:65] op_sel:[0,0,1] op_sel_hi:[0,1,0]
	v_pk_add_f32 v[64:65], v[68:69], v[78:79] neg_lo:[0,1] neg_hi:[0,1]
	v_mov_b32_e32 v73, v25
	v_pk_mul_f32 v[42:43], v[42:43], v[64:65] op_sel_hi:[0,1]
	v_pk_add_f32 v[24:25], v[68:69], v[78:79]
	v_pk_fma_f32 v[68:69], v[36:37], v[64:65], v[42:43] op_sel:[0,0,1] op_sel_hi:[1,1,0] neg_lo:[0,0,1] neg_hi:[0,0,1]
	v_pk_fma_f32 v[36:37], v[36:37], v[64:65], v[42:43] op_sel:[0,0,1] op_sel_hi:[0,1,0]
	v_mov_b32_e32 v69, v37
	v_pk_add_f32 v[36:37], v[48:49], v[38:39]
	v_pk_add_f32 v[38:39], v[48:49], v[38:39] neg_lo:[0,1] neg_hi:[0,1]
	v_mov_b32_e32 v29, v27
	v_pk_mul_f32 v[42:43], v[62:63], v[38:39] op_sel_hi:[0,1]
	v_pk_fma_f32 v[48:49], v[60:61], v[38:39], v[42:43] op_sel:[0,0,1] op_sel_hi:[1,1,0] neg_lo:[0,0,1] neg_hi:[0,0,1]
	v_pk_fma_f32 v[38:39], v[60:61], v[38:39], v[42:43] op_sel:[0,0,1] op_sel_hi:[0,1,0]
	v_pk_add_f32 v[42:43], v[74:75], v[54:55] neg_lo:[0,1] neg_hi:[0,1]
	v_mov_b32_e32 v49, v39
	v_pk_mul_f32 v[50:51], v[50:51], v[42:43] op_sel_hi:[0,1]
	v_pk_add_f32 v[38:39], v[74:75], v[54:55]
	v_pk_fma_f32 v[54:55], v[30:31], v[42:43], v[50:51] op_sel:[0,0,1] op_sel_hi:[1,1,0] neg_lo:[0,0,1] neg_hi:[0,0,1]
	v_pk_fma_f32 v[30:31], v[30:31], v[42:43], v[50:51] op_sel:[0,0,1] op_sel_hi:[0,1,0]
	v_mov_b32_e32 v55, v31
	v_pk_add_f32 v[30:31], v[80:81], v[34:35]
	v_pk_add_f32 v[34:35], v[80:81], v[34:35] neg_lo:[0,1] neg_hi:[0,1]
	v_pk_mul_f32 v[28:29], v[28:29], v[28:29]
	v_pk_mul_f32 v[42:43], v[52:53], v[34:35]
	v_pk_add_f32 v[28:29], v[28:29], v[28:29] op_sel:[0,1] op_sel_hi:[0,1] neg_lo:[0,1] neg_hi:[0,1]
	v_pk_fma_f32 v[50:51], v[62:63], v[34:35], v[42:43] op_sel:[0,0,1] op_sel_hi:[1,1,0] neg_lo:[0,0,1] neg_hi:[0,0,1]
	v_pk_fma_f32 v[34:35], v[62:63], v[34:35], v[42:43] op_sel:[0,0,1] op_sel_hi:[0,1,0]
	v_pk_add_f32 v[42:43], v[44:45], v[58:59] neg_lo:[0,1] neg_hi:[0,1]
	v_mov_b32_e32 v51, v35
	v_pk_add_f32 v[34:35], v[44:45], v[58:59]
	v_pk_mul_f32 v[44:45], v[26:27], v[42:43] op_sel:[1,0]
	s_nop 0
	v_pk_fma_f32 v[52:53], v[32:33], v[42:43], v[44:45] op_sel:[0,0,1] op_sel_hi:[1,1,0] neg_lo:[0,0,1] neg_hi:[0,0,1]
	v_pk_fma_f32 v[42:43], v[32:33], v[42:43], v[44:45] op_sel:[0,0,1] op_sel_hi:[0,1,0]
	v_mov_b32_e32 v53, v43
	v_pk_add_f32 v[42:43], v[46:47], v[20:21]
	v_pk_add_f32 v[20:21], v[46:47], v[20:21] neg_lo:[0,1] neg_hi:[0,1]
	s_nop 0
	v_pk_mul_f32 v[44:45], v[32:33], v[20:21] op_sel_hi:[0,1]
	v_pk_fma_f32 v[46:47], v[26:27], v[20:21], v[44:45] op_sel:[1,0,1] op_sel_hi:[1,1,0]
	v_pk_fma_f32 v[20:21], v[26:27], v[20:21], v[44:45] op_sel:[1,0,1] op_sel_hi:[1,1,0] neg_lo:[0,0,1] neg_hi:[0,0,1]
	v_pk_add_f32 v[44:45], v[56:57], v[66:67] neg_lo:[0,1] neg_hi:[0,1]
	v_mov_b32_e32 v47, v21
	v_pk_add_f32 v[20:21], v[56:57], v[66:67]
	v_pk_mul_f32 v[56:57], v[26:27], v[44:45] op_sel:[1,0]
	s_nop 0
	v_pk_fma_f32 v[58:59], v[32:33], v[44:45], v[56:57] op_sel:[0,0,1] op_sel_hi:[1,1,0] neg_lo:[0,0,1] neg_hi:[0,0,1]
	v_pk_fma_f32 v[44:45], v[32:33], v[44:45], v[56:57] op_sel:[0,0,1] op_sel_hi:[0,1,0]
	v_pk_add_f32 v[56:57], v[70:71], v[72:73] neg_lo:[0,1] neg_hi:[0,1]
	v_mov_b32_e32 v59, v45
	v_pk_mul_f32 v[60:61], v[32:33], v[56:57] op_sel_hi:[0,1]
	v_pk_fma_f32 v[62:63], v[26:27], v[56:57], v[60:61] op_sel:[1,0,1] op_sel_hi:[1,1,0]
	v_pk_fma_f32 v[56:57], v[26:27], v[56:57], v[60:61] op_sel:[1,0,1] op_sel_hi:[1,1,0] neg_lo:[0,0,1] neg_hi:[0,0,1]
	v_pk_add_f32 v[44:45], v[70:71], v[72:73]
	v_mov_b32_e32 v63, v57
	v_pk_add_f32 v[56:57], v[24:25], v[38:39]
	v_pk_add_f32 v[24:25], v[24:25], v[38:39] neg_lo:[0,1] neg_hi:[0,1]
	s_nop 0
	v_pk_mul_f32 v[38:39], v[26:27], v[24:25] op_sel:[1,0]
	s_nop 0
	v_pk_fma_f32 v[60:61], v[32:33], v[24:25], v[38:39] op_sel:[0,0,1] op_sel_hi:[1,1,0] neg_lo:[0,0,1] neg_hi:[0,0,1]
	v_pk_fma_f32 v[24:25], v[32:33], v[24:25], v[38:39] op_sel:[0,0,1] op_sel_hi:[0,1,0]
	v_mov_b32_e32 v61, v25
	v_pk_add_f32 v[24:25], v[36:37], v[30:31]
	v_pk_add_f32 v[30:31], v[36:37], v[30:31] neg_lo:[0,1] neg_hi:[0,1]
	s_nop 0
	v_pk_mul_f32 v[36:37], v[32:33], v[30:31] op_sel_hi:[0,1]
	v_pk_fma_f32 v[38:39], v[26:27], v[30:31], v[36:37] op_sel:[1,0,1] op_sel_hi:[1,1,0]
	v_pk_fma_f32 v[30:31], v[26:27], v[30:31], v[36:37] op_sel:[1,0,1] op_sel_hi:[1,1,0] neg_lo:[0,0,1] neg_hi:[0,0,1]
	v_pk_add_f32 v[36:37], v[68:69], v[54:55] neg_lo:[0,1] neg_hi:[0,1]
	v_mov_b32_e32 v39, v31
	v_pk_add_f32 v[30:31], v[68:69], v[54:55]
	v_pk_mul_f32 v[54:55], v[26:27], v[36:37] op_sel:[1,0]
	s_nop 0
	v_pk_fma_f32 v[64:65], v[32:33], v[36:37], v[54:55] op_sel:[0,0,1] op_sel_hi:[1,1,0] neg_lo:[0,0,1] neg_hi:[0,0,1]
	v_pk_fma_f32 v[36:37], v[32:33], v[36:37], v[54:55] op_sel:[0,0,1] op_sel_hi:[0,1,0]
	v_mov_b32_e32 v65, v37
	v_pk_add_f32 v[36:37], v[48:49], v[50:51]
	v_pk_add_f32 v[48:49], v[48:49], v[50:51] neg_lo:[0,1] neg_hi:[0,1]
	s_nop 0
	v_pk_mul_f32 v[50:51], v[32:33], v[48:49] op_sel_hi:[0,1]
	v_pk_fma_f32 v[54:55], v[26:27], v[48:49], v[50:51] op_sel:[1,0,1] op_sel_hi:[1,1,0]
	v_pk_fma_f32 v[48:49], v[26:27], v[48:49], v[50:51] op_sel:[1,0,1] op_sel_hi:[1,1,0] neg_lo:[0,0,1] neg_hi:[0,0,1]
	v_mul_f32_e32 v26, v32, v27
	v_mov_b32_e32 v55, v49
	v_pk_add_f32 v[48:49], v[34:35], v[42:43]
	v_pk_add_f32 v[34:35], v[34:35], v[42:43] neg_lo:[0,1] neg_hi:[0,1]
	v_add_f32_e32 v26, v26, v26
	v_pk_mul_f32 v[32:33], v[26:27], v[34:35] op_sel_hi:[0,1]
	v_pk_fma_f32 v[42:43], v[28:29], v[34:35], v[32:33] op_sel:[0,0,1] op_sel_hi:[1,1,0] neg_lo:[0,0,1] neg_hi:[0,0,1]
; #define LAS __attribute__((address_space(3)))
; __device__ __forceinline__ f32x2 cmul(f32x2 a, f32x2 b) { return (f32x2){a.x * b.x - a.y * b.y, a.x * b.y + a.y * b.x}; }
; template <bool INV, int ST> __device__ __forceinline__ void fft_pass16(LAS f32x2* buf, int base, int bl) {
;     constexpr float C16[8] = {1.f, 0.92387953251f, 0.70710678119f, 0.38268343237f, 0.f, -0.38268343237f, -0.70710678119f, -0.92387953251f};
;     constexpr float S16[8] = {0.f, 0.38268343237f, 0.70710678119f, 0.92387953251f, 1.f, 0.92387953251f, 0.70710678119f, 0.38268343237f};
;     f32x2 x[16];
;     constexpr int STEP = (1 << ST) + ((1 << ST) >> 4);
;     LAS f32x2* pb = buf + PADI(base);
; #pragma unroll
;     for (int d = 0; d < 16; ++d) x[d] = pb[d * STEP];
;     const float th = (float)bl * (1.f / (float)(16 << ST));
;     const f32x2 W1 = {__builtin_amdgcn_cosf(th), -__builtin_amdgcn_sinf(th)};
;     const f32x2 W2 = cmul(W1, W1), W4 = cmul(W2, W2), W8 = cmul(W4, W4);
;     if (!INV) {
; #pragma unroll
;         for (int d = 0; d < 8; ++d) { const f32x2 w = cmul(W1, (f32x2){C16[d], -S16[d]}); const f32x2 a = x[d], b = x[d + 8]; x[d] = a + b; x[d + 8] = cmul(a - b, w); }
;     ...
;             for (int dd = 0; dd < 2; ++dd) { const int d = g + dd; const f32x2 w = dd ? (f32x2){W4.y, -W4.x} : W4; const f32x2 a = x[d], b = x[d + 2]; x[d] = a + b; x[d + 2] = cmul(a - b, w); }
; #pragma unroll
;         for (int g = 0; g < 16; g += 2) { const f32x2 a = x[g], b = x[g + 1]; x[g] = a + b; x[g + 1] = cmul(a - b, W8); }
;     ...
;     for (int d = 0; d < 16; ++d) pb[d * STEP] = x[d];
; __device__ __forceinline__ void fft_fwd_abc(LAS f32x2* buf, int tid) {
;     ...
;     fft_pass16<false, 9>(buf, tid, tid); __syncthreads();
;     fft_pass16<false, 5>(buf, ((tid >> 5) << 9) + (tid & 31), tid & 31); __syncthreads();
	v_pk_fma_f32 v[32:33], v[28:29], v[34:35], v[32:33] op_sel:[0,0,1] op_sel_hi:[1,1,0]
	v_pk_add_f32 v[34:35], v[52:53], v[46:47] neg_lo:[0,1] neg_hi:[0,1]
	v_mov_b32_e32 v43, v33
	v_pk_add_f32 v[32:33], v[52:53], v[46:47]
	v_pk_mul_f32 v[46:47], v[26:27], v[34:35] op_sel_hi:[0,1]
	v_pk_fma_f32 v[50:51], v[28:29], v[34:35], v[46:47] op_sel:[0,0,1] op_sel_hi:[1,1,0] neg_lo:[0,0,1] neg_hi:[0,0,1]
	v_pk_fma_f32 v[34:35], v[28:29], v[34:35], v[46:47] op_sel:[0,0,1] op_sel_hi:[1,1,0]
	s_nop 0
	v_mov_b32_e32 v51, v35
	v_pk_add_f32 v[34:35], v[20:21], v[44:45]
	v_pk_add_f32 v[20:21], v[20:21], v[44:45] neg_lo:[0,1] neg_hi:[0,1]
	s_nop 0
	v_pk_mul_f32 v[44:45], v[26:27], v[20:21] op_sel_hi:[0,1]
	v_pk_fma_f32 v[46:47], v[28:29], v[20:21], v[44:45] op_sel:[0,0,1] op_sel_hi:[1,1,0] neg_lo:[0,0,1] neg_hi:[0,0,1]
	v_pk_fma_f32 v[20:21], v[28:29], v[20:21], v[44:45] op_sel:[0,0,1] op_sel_hi:[1,1,0]
	v_pk_add_f32 v[44:45], v[58:59], v[62:63] neg_lo:[0,1] neg_hi:[0,1]
	v_mov_b32_e32 v47, v21
	v_pk_mul_f32 v[52:53], v[26:27], v[44:45] op_sel_hi:[0,1]
	v_pk_add_f32 v[20:21], v[58:59], v[62:63]
	v_pk_fma_f32 v[58:59], v[28:29], v[44:45], v[52:53] op_sel:[0,0,1] op_sel_hi:[1,1,0] neg_lo:[0,0,1] neg_hi:[0,0,1]
	v_pk_fma_f32 v[44:45], v[28:29], v[44:45], v[52:53] op_sel:[0,0,1] op_sel_hi:[1,1,0]
	s_nop 0
	v_mov_b32_e32 v59, v45
	v_pk_add_f32 v[44:45], v[56:57], v[24:25]
	v_pk_add_f32 v[24:25], v[56:57], v[24:25] neg_lo:[0,1] neg_hi:[0,1]
	s_nop 0
	v_pk_mul_f32 v[52:53], v[26:27], v[24:25] op_sel_hi:[0,1]
	v_pk_fma_f32 v[56:57], v[28:29], v[24:25], v[52:53] op_sel:[0,0,1] op_sel_hi:[1,1,0] neg_lo:[0,0,1] neg_hi:[0,0,1]
	v_pk_fma_f32 v[24:25], v[28:29], v[24:25], v[52:53] op_sel:[0,0,1] op_sel_hi:[1,1,0]
	s_nop 0
	v_mov_b32_e32 v57, v25
	v_pk_add_f32 v[24:25], v[60:61], v[38:39]
	v_pk_add_f32 v[38:39], v[60:61], v[38:39] neg_lo:[0,1] neg_hi:[0,1]
	s_nop 0
	v_pk_mul_f32 v[52:53], v[26:27], v[38:39] op_sel_hi:[0,1]
	v_pk_fma_f32 v[60:61], v[28:29], v[38:39], v[52:53] op_sel:[0,0,1] op_sel_hi:[1,1,0] neg_lo:[0,0,1] neg_hi:[0,0,1]
	v_pk_fma_f32 v[38:39], v[28:29], v[38:39], v[52:53] op_sel:[0,0,1] op_sel_hi:[1,1,0]
	s_nop 0
	v_mov_b32_e32 v61, v39
	v_pk_add_f32 v[38:39], v[30:31], v[36:37]
	v_pk_add_f32 v[30:31], v[30:31], v[36:37] neg_lo:[0,1] neg_hi:[0,1]
	s_nop 0
	v_pk_mul_f32 v[36:37], v[26:27], v[30:31] op_sel_hi:[0,1]
	v_pk_fma_f32 v[52:53], v[28:29], v[30:31], v[36:37] op_sel:[0,0,1] op_sel_hi:[1,1,0] neg_lo:[0,0,1] neg_hi:[0,0,1]
	v_pk_fma_f32 v[30:31], v[28:29], v[30:31], v[36:37] op_sel:[0,0,1] op_sel_hi:[1,1,0]
	v_pk_add_f32 v[36:37], v[64:65], v[54:55] neg_lo:[0,1] neg_hi:[0,1]
	v_mov_b32_e32 v53, v31
	v_pk_mul_f32 v[26:27], v[26:27], v[36:37] op_sel_hi:[0,1]
	v_pk_add_f32 v[30:31], v[64:65], v[54:55]
	v_pk_fma_f32 v[54:55], v[28:29], v[36:37], v[26:27] op_sel:[0,0,1] op_sel_hi:[1,1,0] neg_lo:[0,0,1] neg_hi:[0,0,1]
	v_pk_fma_f32 v[26:27], v[28:29], v[36:37], v[26:27] op_sel:[0,0,1] op_sel_hi:[1,1,0]
	s_nop 0
	v_mov_b32_e32 v55, v27
	ds_write_b64 v41, v[48:49]
	ds_write_b64 v41, v[42:43] offset:4352
	ds_write_b64 v41, v[32:33] offset:8704
	ds_write_b64 v41, v[50:51] offset:13056
	ds_write_b64 v41, v[34:35] offset:17408
	ds_write_b64 v41, v[46:47] offset:21760
	ds_write_b64 v41, v[20:21] offset:26112
	ds_write_b64 v41, v[58:59] offset:30464
	ds_write_b64 v41, v[44:45] offset:34816
	ds_write_b64 v41, v[56:57] offset:39168
	ds_write_b64 v41, v[24:25] offset:43520
	ds_write_b64 v41, v[60:61] offset:47872
	ds_write_b64 v41, v[38:39] offset:52224
	ds_write_b64 v41, v[52:53] offset:56576
	ds_write_b64 v41, v[30:31] offset:60928
	ds_write_b64 v41, v[54:55] offset:65280
	v_lshlrev_b32_e32 v20, 4, v2
	v_and_b32_e32 v20, 0xfffffe00, v20
	v_and_b32_e32 v21, 31, v2
	v_lshl_add_u32 v24, v20, 3, 0
	v_lshlrev_b32_e32 v25, 3, v21
	v_ashrrev_i32_e32 v20, 1, v20
	v_add3_u32 v41, v24, v25, v20
	v_cvt_f32_ubyte0_e32 v20, v21
	v_mul_f32_e32 v21, 0x3b000000, v20
	v_sin_f32_e32 v20, v21
	v_cos_f32_e32 v58, v21
	v_add_u32_e32 v82, 0x800, v41
	s_waitcnt lgkmcnt(0)
	s_barrier
	ds_read2_b64 v[24:27], v41 offset1:34
	ds_read2_b64 v[28:31], v41 offset0:68 offset1:102
	ds_read2_b64 v[32:35], v41 offset0:136 offset1:170
	ds_read2_b64 v[36:39], v41 offset0:204 offset1:238
	ds_read2_b64 v[42:45], v82 offset0:16 offset1:50
	ds_read2_b64 v[46:49], v82 offset0:84 offset1:118
	v_xor_b32_e32 v59, 0x80000000, v20
	v_mov_b32_e32 v21, v58
	v_mov_b32_e32 v60, v20
	v_mov_b32_e32 v61, v59
	v_pk_mul_f32 v[60:61], v[20:21], v[60:61]
	v_fma_f32 v68, v58, s22, -v20
	v_pk_fma_f32 v[62:63], v[58:59], v[58:59], v[60:61] op_sel_hi:[0,1,1] neg_lo:[0,0,1] neg_hi:[0,0,1]
	v_pk_fma_f32 v[60:61], v[58:59], v[58:59], v[60:61] op_sel_hi:[0,1,1]
	v_mov_b32_e32 v63, v61
	s_waitcnt lgkmcnt(1)
	v_pk_add_f32 v[70:71], v[24:25], v[42:43]
	v_pk_add_f32 v[24:25], v[24:25], v[42:43] neg_lo:[0,1] neg_hi:[0,1]
	v_pk_mul_f32 v[66:67], v[62:63], v[60:61] op_sel:[0,1] op_sel_hi:[1,0]
	v_fmamk_f32 v60, v20, 0x80000000, v58
	v_pk_mul_f32 v[42:43], v[68:69], v[24:25] op_sel:[0,1] op_sel_hi:[0,0]
	v_pk_fma_f32 v[68:69], v[60:61], v[24:25], v[42:43] neg_lo:[0,0,1] neg_hi:[0,0,1]
	v_pk_fma_f32 v[24:25], v[60:61], v[24:25], v[42:43] op_sel_hi:[0,1,1]
	v_pk_mul_f32 v[42:43], v[20:21], s[8:9] op_sel_hi:[1,0]
	v_mov_b32_e32 v69, v25
	v_pk_add_f32 v[24:25], v[26:27], v[44:45]
	v_pk_add_f32 v[26:27], v[26:27], v[44:45] neg_lo:[0,1] neg_hi:[0,1]
	v_fma_f32 v44, v20, s9, -v43
	s_waitcnt lgkmcnt(0)
; __device__ __forceinline__ f32x2 cmul(f32x2 a, f32x2 b) { return (f32x2){a.x * b.x - a.y * b.y, a.x * b.y + a.y * b.x}; }
; template <bool INV, int ST> __device__ __forceinline__ void fft_pass16(LAS f32x2* buf, int base, int bl) {
;     ...
;         for (int d = 0; d < 8; ++d) { const f32x2 w = cmul(W1, (f32x2){C16[d], -S16[d]}); const f32x2 a = x[d], b = x[d + 8]; x[d] = a + b; x[d + 8] = cmul(a - b, w); }
; #pragma unroll
;         for (int g = 0; g < 16; g += 8)
; #pragma unroll
;             for (int dd = 0; dd < 4; ++dd) { const int d = g + dd; const f32x2 w = cmul(W2, (f32x2){C16[2 * dd], -S16[2 * dd]}); const f32x2 a = x[d], b = x[d + 4]; x[d] = a + b; x[d + 4] = cmul(a - b, w); }
; #pragma unroll
;         for (int g = 0; g < 16; g += 4)
; #pragma unroll
;             for (int dd = 0; dd < 2; ++dd) { const int d = g + dd; const f32x2 w = dd ? (f32x2){W4.y, -W4.x} : W4; const f32x2 a = x[d], b = x[d + 2]; x[d] = a + b; x[d + 2] = cmul(a - b, w); }
; #pragma unroll
;         for (int g = 0; g < 16; g += 2) { const f32x2 a = x[g], b = x[g + 1]; x[g] = a + b; x[g + 1] = cmul(a - b, W8); }
	v_pk_add_f32 v[72:73], v[28:29], v[46:47]
	v_pk_add_f32 v[28:29], v[28:29], v[46:47] neg_lo:[0,1] neg_hi:[0,1]
	ds_read2_b64 v[50:53], v82 offset0:152 offset1:186
	ds_read2_b64 v[54:57], v82 offset0:220 offset1:254
	v_pk_mul_f32 v[44:45], v[44:45], v[28:29] op_sel:[0,1] op_sel_hi:[0,0]
	v_pk_add_f32 v[46:47], v[42:43], v[42:43] op_sel:[1,0] op_sel_hi:[1,0] neg_lo:[0,1] neg_hi:[0,1]
	v_pk_add_f32 v[76:77], v[30:31], v[48:49]
	v_pk_fma_f32 v[74:75], v[46:47], v[28:29], v[44:45] neg_lo:[0,0,1] neg_hi:[0,0,1]
	v_pk_fma_f32 v[28:29], v[46:47], v[28:29], v[44:45]
	v_pk_mul_f32 v[46:47], v[20:21], s[96:97]
	v_mov_b32_e32 v75, v29
	v_pk_mul_f32 v[28:29], v[20:21], s[10:11]
	v_pk_add_f32 v[30:31], v[30:31], v[48:49] neg_lo:[0,1] neg_hi:[0,1]
	v_pk_add_f32 v[48:49], v[46:47], v[46:47] op_sel:[0,1] op_sel_hi:[0,1] neg_lo:[0,1] neg_hi:[0,1]
	v_pk_mul_f32 v[48:49], v[48:49], v[30:31] op_sel:[0,1] op_sel_hi:[1,0]
	v_pk_add_f32 v[78:79], v[28:29], v[28:29] op_sel:[1,0] op_sel_hi:[1,0] neg_lo:[0,1] neg_hi:[0,1]
	v_fma_f32 v46, v20, s22, -v58
	v_pk_fma_f32 v[80:81], v[78:79], v[30:31], v[48:49] neg_lo:[0,0,1] neg_hi:[0,0,1]
	v_pk_fma_f32 v[30:31], v[78:79], v[30:31], v[48:49]
	s_waitcnt lgkmcnt(1)
	v_pk_add_f32 v[48:49], v[32:33], v[50:51]
	v_pk_add_f32 v[32:33], v[32:33], v[50:51] neg_lo:[0,1] neg_hi:[0,1]
	v_fma_f32 v30, v58, 0, -v20
	v_pk_mul_f32 v[50:51], v[46:47], v[32:33] op_sel:[0,1] op_sel_hi:[0,0]
	v_mov_b32_e32 v81, v31
	v_pk_fma_f32 v[78:79], v[30:31], v[32:33], v[50:51] neg_lo:[0,0,1] neg_hi:[0,0,1]
	v_pk_fma_f32 v[30:31], v[30:31], v[32:33], v[50:51] op_sel_hi:[0,1,1]
	v_fma_f32 v46, v58, s9, -v42
	s_waitcnt lgkmcnt(0)
	v_pk_add_f32 v[50:51], v[36:37], v[54:55]
	v_pk_add_f32 v[36:37], v[36:37], v[54:55] neg_lo:[0,1] neg_hi:[0,1]
	v_pk_add_f32 v[42:43], v[42:43], v[42:43] op_sel:[0,1] op_sel_hi:[0,1] neg_lo:[0,1] neg_hi:[0,1]
	v_pk_mul_f32 v[42:43], v[42:43], v[36:37] op_sel:[0,1] op_sel_hi:[1,0]
	v_mov_b32_e32 v59, v20
	v_fma_f32 v44, v20, s2, -v29
	v_pk_add_f32 v[32:33], v[34:35], v[52:53]
	v_pk_add_f32 v[34:35], v[34:35], v[52:53] neg_lo:[0,1] neg_hi:[0,1]
	v_pk_fma_f32 v[52:53], v[46:47], v[36:37], v[42:43] neg_lo:[0,0,1] neg_hi:[0,0,1]
	v_pk_fma_f32 v[36:37], v[46:47], v[36:37], v[42:43] op_sel_hi:[0,1,1]
	v_pk_mul_f32 v[20:21], v[58:59], s[2:3]
	v_pk_mul_f32 v[44:45], v[44:45], v[26:27] op_sel:[0,1] op_sel_hi:[0,0]
	v_sub_f32_e32 v36, v47, v21
	v_pk_fma_f32 v[42:43], v[36:37], v[26:27], v[44:45] op_sel_hi:[0,1,1] neg_lo:[0,0,1] neg_hi:[0,0,1]
	v_pk_fma_f32 v[26:27], v[36:37], v[26:27], v[44:45] op_sel_hi:[0,1,1]
	v_sub_f32_e32 v26, v21, v47
	v_fma_f32 v30, v58, s96, -v28
	v_mov_b32_e32 v43, v27
	v_pk_mul_f32 v[26:27], v[26:27], v[34:35] op_sel:[0,1] op_sel_hi:[0,0]
	v_mov_b32_e32 v79, v31
	v_mov_b32_e32 v53, v37
	v_pk_fma_f32 v[36:37], v[30:31], v[34:35], v[26:27] neg_lo:[0,0,1] neg_hi:[0,0,1]
	v_pk_fma_f32 v[26:27], v[30:31], v[34:35], v[26:27] op_sel_hi:[0,1,1]
	v_pk_add_f32 v[30:31], v[38:39], v[56:57] neg_lo:[0,1] neg_hi:[0,1]
	v_pk_add_f32 v[28:29], v[28:29], v[28:29] op_sel:[0,1] op_sel_hi:[0,1] neg_lo:[0,1] neg_hi:[0,1]
	v_fmamk_f32 v44, v62, 0x80000000, v61
	v_pk_add_f32 v[46:47], v[70:71], v[48:49]
	v_pk_add_f32 v[48:49], v[70:71], v[48:49] neg_lo:[0,1] neg_hi:[0,1]
	v_mov_b32_e32 v37, v27
	v_pk_add_f32 v[26:27], v[38:39], v[56:57]
	v_pk_mul_f32 v[28:29], v[28:29], v[30:31] op_sel:[0,1] op_sel_hi:[1,0]
	v_pk_add_f32 v[20:21], v[20:21], v[20:21] op_sel:[0,1] op_sel_hi:[0,1] neg_lo:[0,1] neg_hi:[0,1]
	v_fma_f32 v38, 0, v61, v62
	v_pk_mul_f32 v[54:55], v[44:45], v[48:49] op_sel_hi:[0,1]
	v_pk_mul_f32 v[64:65], v[62:63], v[62:63]
	v_pk_fma_f32 v[34:35], v[20:21], v[30:31], v[28:29] neg_lo:[0,0,1] neg_hi:[0,0,1]
	v_pk_fma_f32 v[20:21], v[20:21], v[30:31], v[28:29]
	v_pk_fma_f32 v[56:57], v[38:39], v[48:49], v[54:55] op_sel:[0,0,1] op_sel_hi:[1,1,0] neg_lo:[0,0,1] neg_hi:[0,0,1]
	v_pk_fma_f32 v[48:49], v[38:39], v[48:49], v[54:55] op_sel:[0,0,1] op_sel_hi:[0,1,0]
	v_fma_f32 v54, v61, 0, -v62
	v_pk_add_f32 v[58:59], v[72:73], v[50:51]
	v_pk_add_f32 v[50:51], v[72:73], v[50:51] neg_lo:[0,1] neg_hi:[0,1]
	v_mov_b32_e32 v20, v64
	v_pk_mov_b32 v[28:29], v[64:65], v[66:67] op_sel:[1,0]
	v_mov_b32_e32 v57, v49
	v_pk_add_f32 v[48:49], v[24:25], v[32:33]
	v_pk_add_f32 v[24:25], v[24:25], v[32:33] neg_lo:[0,1] neg_hi:[0,1]
	v_fma_f32 v32, 0, v62, v61
	v_pk_mul_f32 v[64:65], v[54:55], v[50:51] op_sel_hi:[0,1]
	v_mov_b32_e32 v35, v21
	v_mov_b32_e32 v21, v66
	v_pk_fma_f32 v[66:67], v[32:33], v[50:51], v[64:65] op_sel:[0,0,1] op_sel_hi:[1,1,0] neg_lo:[0,0,1] neg_hi:[0,0,1]
	v_pk_fma_f32 v[50:51], v[32:33], v[50:51], v[64:65] op_sel:[0,0,1] op_sel_hi:[0,1,0]
	v_mov_b32_e32 v67, v51
	v_pk_mul_f32 v[50:51], v[62:63], s[8:9]
	v_pk_add_f32 v[30:31], v[20:21], v[28:29] neg_lo:[0,1] neg_hi:[0,1]
	v_fma_f32 v62, v61, s8, -v50
	v_fmamk_f32 v60, v61, 0x3f3504f3, v50
	v_pk_mul_f32 v[64:65], v[62:63], v[24:25] op_sel_hi:[0,1]
	v_pk_fma_f32 v[70:71], v[60:61], v[24:25], v[64:65] op_sel:[0,0,1] op_sel_hi:[1,1,0] neg_lo:[0,0,1] neg_hi:[0,0,1]
	v_pk_fma_f32 v[24:25], v[60:61], v[24:25], v[64:65] op_sel:[0,0,1] op_sel_hi:[0,1,0]
	v_mov_b32_e32 v71, v25
	v_pk_add_f32 v[24:25], v[76:77], v[26:27]
	v_pk_add_f32 v[26:27], v[76:77], v[26:27] neg_lo:[0,1] neg_hi:[0,1]
	v_pk_add_f32 v[50:51], v[50:51], v[50:51] op_sel:[1,0] op_sel_hi:[1,0] neg_lo:[0,1] neg_hi:[0,1]
	v_pk_add_f32 v[20:21], v[20:21], v[28:29]
	v_pk_mul_f32 v[64:65], v[50:51], v[26:27]
	v_mov_b32_e32 v28, v30
	v_pk_fma_f32 v[72:73], v[62:63], v[26:27], v[64:65] op_sel:[0,0,1] op_sel_hi:[1,1,0] neg_lo:[0,0,1] neg_hi:[0,0,1]
	v_pk_fma_f32 v[26:27], v[62:63], v[26:27], v[64:65] op_sel:[0,0,1] op_sel_hi:[0,1,0]
; __device__ __forceinline__ f32x2 cmul(f32x2 a, f32x2 b) { return (f32x2){a.x * b.x - a.y * b.y, a.x * b.y + a.y * b.x}; }
; template <bool INV, int ST> __device__ __forceinline__ void fft_pass16(LAS f32x2* buf, int base, int bl) {
;     ...
;             for (int dd = 0; dd < 4; ++dd) { const int d = g + dd; const f32x2 w = cmul(W2, (f32x2){C16[2 * dd], -S16[2 * dd]}); const f32x2 a = x[d], b = x[d + 4]; x[d] = a + b; x[d + 4] = cmul(a - b, w); }
; #pragma unroll
;         for (int g = 0; g < 16; g += 4)
; #pragma unroll
;             for (int dd = 0; dd < 2; ++dd) { const int d = g + dd; const f32x2 w = dd ? (f32x2){W4.y, -W4.x} : W4; const f32x2 a = x[d], b = x[d + 2]; x[d] = a + b; x[d + 2] = cmul(a - b, w); }
; #pragma unroll
;         for (int g = 0; g < 16; g += 2) { const f32x2 a = x[g], b = x[g + 1]; x[g] = a + b; x[g + 1] = cmul(a - b, W8); }
	v_pk_add_f32 v[64:65], v[68:69], v[78:79] neg_lo:[0,1] neg_hi:[0,1]
	v_mov_b32_e32 v73, v27
	v_pk_mul_f32 v[44:45], v[44:45], v[64:65] op_sel_hi:[0,1]
	v_pk_add_f32 v[26:27], v[68:69], v[78:79]
	v_pk_fma_f32 v[68:69], v[38:39], v[64:65], v[44:45] op_sel:[0,0,1] op_sel_hi:[1,1,0] neg_lo:[0,0,1] neg_hi:[0,0,1]
	v_pk_fma_f32 v[38:39], v[38:39], v[64:65], v[44:45] op_sel:[0,0,1] op_sel_hi:[0,1,0]
	v_mov_b32_e32 v69, v39
	v_pk_add_f32 v[38:39], v[42:43], v[36:37]
	v_pk_add_f32 v[36:37], v[42:43], v[36:37] neg_lo:[0,1] neg_hi:[0,1]
	v_mov_b32_e32 v29, v21
	v_pk_mul_f32 v[42:43], v[62:63], v[36:37] op_sel_hi:[0,1]
	v_pk_fma_f32 v[44:45], v[60:61], v[36:37], v[42:43] op_sel:[0,0,1] op_sel_hi:[1,1,0] neg_lo:[0,0,1] neg_hi:[0,0,1]
	v_pk_fma_f32 v[36:37], v[60:61], v[36:37], v[42:43] op_sel:[0,0,1] op_sel_hi:[0,1,0]
	v_pk_add_f32 v[42:43], v[74:75], v[52:53] neg_lo:[0,1] neg_hi:[0,1]
	v_mov_b32_e32 v45, v37
	v_pk_add_f32 v[36:37], v[74:75], v[52:53]
	v_pk_mul_f32 v[52:53], v[54:55], v[42:43] op_sel_hi:[0,1]
	v_pk_fma_f32 v[54:55], v[32:33], v[42:43], v[52:53] op_sel:[0,0,1] op_sel_hi:[1,1,0] neg_lo:[0,0,1] neg_hi:[0,0,1]
	v_pk_fma_f32 v[32:33], v[32:33], v[42:43], v[52:53] op_sel:[0,0,1] op_sel_hi:[0,1,0]
	v_mov_b32_e32 v55, v33
	v_pk_add_f32 v[32:33], v[80:81], v[34:35]
	v_pk_add_f32 v[34:35], v[80:81], v[34:35] neg_lo:[0,1] neg_hi:[0,1]
	v_pk_mul_f32 v[28:29], v[28:29], v[28:29]
	v_pk_mul_f32 v[42:43], v[50:51], v[34:35]
	v_pk_add_f32 v[28:29], v[28:29], v[28:29] op_sel:[0,1] op_sel_hi:[0,1] neg_lo:[0,1] neg_hi:[0,1]
	v_pk_fma_f32 v[50:51], v[62:63], v[34:35], v[42:43] op_sel:[0,0,1] op_sel_hi:[1,1,0] neg_lo:[0,0,1] neg_hi:[0,0,1]
	v_pk_fma_f32 v[34:35], v[62:63], v[34:35], v[42:43] op_sel:[0,0,1] op_sel_hi:[0,1,0]
	v_pk_add_f32 v[42:43], v[46:47], v[58:59] neg_lo:[0,1] neg_hi:[0,1]
	v_mov_b32_e32 v51, v35
	v_pk_add_f32 v[34:35], v[46:47], v[58:59]
	v_pk_mul_f32 v[46:47], v[20:21], v[42:43] op_sel:[1,0]
	s_nop 0
	v_pk_fma_f32 v[52:53], v[30:31], v[42:43], v[46:47] op_sel:[0,0,1] op_sel_hi:[1,1,0] neg_lo:[0,0,1] neg_hi:[0,0,1]
	v_pk_fma_f32 v[42:43], v[30:31], v[42:43], v[46:47] op_sel:[0,0,1] op_sel_hi:[0,1,0]
	v_mov_b32_e32 v53, v43
	v_pk_add_f32 v[42:43], v[48:49], v[24:25]
	v_pk_add_f32 v[24:25], v[48:49], v[24:25] neg_lo:[0,1] neg_hi:[0,1]
	s_nop 0
	v_pk_mul_f32 v[46:47], v[30:31], v[24:25] op_sel_hi:[0,1]
	v_pk_fma_f32 v[48:49], v[20:21], v[24:25], v[46:47] op_sel:[1,0,1] op_sel_hi:[1,1,0]
	v_pk_fma_f32 v[24:25], v[20:21], v[24:25], v[46:47] op_sel:[1,0,1] op_sel_hi:[1,1,0] neg_lo:[0,0,1] neg_hi:[0,0,1]
	v_pk_add_f32 v[46:47], v[56:57], v[66:67] neg_lo:[0,1] neg_hi:[0,1]
	v_mov_b32_e32 v49, v25
	v_pk_add_f32 v[24:25], v[56:57], v[66:67]
	v_pk_mul_f32 v[56:57], v[20:21], v[46:47] op_sel:[1,0]
	s_nop 0
	v_pk_fma_f32 v[58:59], v[30:31], v[46:47], v[56:57] op_sel:[0,0,1] op_sel_hi:[1,1,0] neg_lo:[0,0,1] neg_hi:[0,0,1]
	v_pk_fma_f32 v[46:47], v[30:31], v[46:47], v[56:57] op_sel:[0,0,1] op_sel_hi:[0,1,0]
	v_pk_add_f32 v[56:57], v[70:71], v[72:73] neg_lo:[0,1] neg_hi:[0,1]
	v_mov_b32_e32 v59, v47
	v_pk_mul_f32 v[60:61], v[30:31], v[56:57] op_sel_hi:[0,1]
	v_pk_fma_f32 v[62:63], v[20:21], v[56:57], v[60:61] op_sel:[1,0,1] op_sel_hi:[1,1,0]
	v_pk_fma_f32 v[56:57], v[20:21], v[56:57], v[60:61] op_sel:[1,0,1] op_sel_hi:[1,1,0] neg_lo:[0,0,1] neg_hi:[0,0,1]
	v_pk_add_f32 v[46:47], v[70:71], v[72:73]
	v_mov_b32_e32 v63, v57
	v_pk_add_f32 v[56:57], v[26:27], v[36:37]
	v_pk_add_f32 v[26:27], v[26:27], v[36:37] neg_lo:[0,1] neg_hi:[0,1]
	s_nop 0
	v_pk_mul_f32 v[36:37], v[20:21], v[26:27] op_sel:[1,0]
	s_nop 0
	v_pk_fma_f32 v[60:61], v[30:31], v[26:27], v[36:37] op_sel:[0,0,1] op_sel_hi:[1,1,0] neg_lo:[0,0,1] neg_hi:[0,0,1]
	v_pk_fma_f32 v[26:27], v[30:31], v[26:27], v[36:37] op_sel:[0,0,1] op_sel_hi:[0,1,0]
	v_mov_b32_e32 v61, v27
	v_pk_add_f32 v[26:27], v[38:39], v[32:33]
	v_pk_add_f32 v[32:33], v[38:39], v[32:33] neg_lo:[0,1] neg_hi:[0,1]
	s_nop 0
	v_pk_mul_f32 v[36:37], v[30:31], v[32:33] op_sel_hi:[0,1]
	v_pk_fma_f32 v[38:39], v[20:21], v[32:33], v[36:37] op_sel:[1,0,1] op_sel_hi:[1,1,0]
	v_pk_fma_f32 v[32:33], v[20:21], v[32:33], v[36:37] op_sel:[1,0,1] op_sel_hi:[1,1,0] neg_lo:[0,0,1] neg_hi:[0,0,1]
	v_pk_add_f32 v[36:37], v[68:69], v[54:55] neg_lo:[0,1] neg_hi:[0,1]
	v_mov_b32_e32 v39, v33
	v_pk_add_f32 v[32:33], v[68:69], v[54:55]
	v_pk_mul_f32 v[54:55], v[20:21], v[36:37] op_sel:[1,0]
	s_nop 0
	v_pk_fma_f32 v[64:65], v[30:31], v[36:37], v[54:55] op_sel:[0,0,1] op_sel_hi:[1,1,0] neg_lo:[0,0,1] neg_hi:[0,0,1]
	v_pk_fma_f32 v[36:37], v[30:31], v[36:37], v[54:55] op_sel:[0,0,1] op_sel_hi:[0,1,0]
	v_mov_b32_e32 v65, v37
	v_pk_add_f32 v[36:37], v[44:45], v[50:51]
	v_pk_add_f32 v[44:45], v[44:45], v[50:51] neg_lo:[0,1] neg_hi:[0,1]
	s_nop 0
	v_pk_mul_f32 v[50:51], v[30:31], v[44:45] op_sel_hi:[0,1]
	v_pk_fma_f32 v[54:55], v[20:21], v[44:45], v[50:51] op_sel:[1,0,1] op_sel_hi:[1,1,0]
	v_pk_fma_f32 v[44:45], v[20:21], v[44:45], v[50:51] op_sel:[1,0,1] op_sel_hi:[1,1,0] neg_lo:[0,0,1] neg_hi:[0,0,1]
	v_mul_f32_e32 v20, v30, v21
	v_mov_b32_e32 v55, v45
	v_pk_add_f32 v[44:45], v[34:35], v[42:43]
	v_pk_add_f32 v[34:35], v[34:35], v[42:43] neg_lo:[0,1] neg_hi:[0,1]
	v_add_f32_e32 v20, v20, v20
	v_pk_mul_f32 v[30:31], v[20:21], v[34:35] op_sel_hi:[0,1]
	v_pk_fma_f32 v[42:43], v[28:29], v[34:35], v[30:31] op_sel:[0,0,1] op_sel_hi:[1,1,0] neg_lo:[0,0,1] neg_hi:[0,0,1]
	v_pk_fma_f32 v[30:31], v[28:29], v[34:35], v[30:31] op_sel:[0,0,1] op_sel_hi:[1,1,0]
	v_pk_add_f32 v[34:35], v[52:53], v[48:49] neg_lo:[0,1] neg_hi:[0,1]
	v_mov_b32_e32 v43, v31
	v_pk_add_f32 v[30:31], v[52:53], v[48:49]
	v_pk_mul_f32 v[48:49], v[20:21], v[34:35] op_sel_hi:[0,1]
; #define LAS __attribute__((address_space(3)))
; __device__ __forceinline__ f32x2 cmul(f32x2 a, f32x2 b) { return (f32x2){a.x * b.x - a.y * b.y, a.x * b.y + a.y * b.x}; }
; template <bool INV, int ST> __device__ __forceinline__ void fft_pass16(LAS f32x2* buf, int base, int bl) {
;     constexpr float C16[8] = {1.f, 0.92387953251f, 0.70710678119f, 0.38268343237f, 0.f, -0.38268343237f, -0.70710678119f, -0.92387953251f};
;     constexpr float S16[8] = {0.f, 0.38268343237f, 0.70710678119f, 0.92387953251f, 1.f, 0.92387953251f, 0.70710678119f, 0.38268343237f};
;     f32x2 x[16];
;     constexpr int STEP = (1 << ST) + ((1 << ST) >> 4);
;     LAS f32x2* pb = buf + PADI(base);
; #pragma unroll
;     for (int d = 0; d < 16; ++d) x[d] = pb[d * STEP];
;     const float th = (float)bl * (1.f / (float)(16 << ST));
;     const f32x2 W1 = {__builtin_amdgcn_cosf(th), -__builtin_amdgcn_sinf(th)};
;     const f32x2 W2 = cmul(W1, W1), W4 = cmul(W2, W2), W8 = cmul(W4, W4);
;     if (!INV) {
; #pragma unroll
;         for (int d = 0; d < 8; ++d) { const f32x2 w = cmul(W1, (f32x2){C16[d], -S16[d]}); const f32x2 a = x[d], b = x[d + 8]; x[d] = a + b; x[d + 8] = cmul(a - b, w); }
; #pragma unroll
;         for (int g = 0; g < 16; g += 8)
; #pragma unroll
;             for (int dd = 0; dd < 4; ++dd) { const int d = g + dd; const f32x2 w = cmul(W2, (f32x2){C16[2 * dd], -S16[2 * dd]}); const f32x2 a = x[d], b = x[d + 4]; x[d] = a + b; x[d + 4] = cmul(a - b, w); }
;     ...
;         for (int g = 0; g < 16; g += 2) { const f32x2 a = x[g], b = x[g + 1]; x[g] = a + b; x[g + 1] = cmul(a - b, W8); }
;     ...
;     for (int d = 0; d < 16; ++d) pb[d * STEP] = x[d];
; __device__ __forceinline__ void fft_fwd_abc(LAS f32x2* buf, int tid) {
;     ...
;     fft_pass16<false, 1>(buf, ((tid >> 1) << 5) + (tid & 1), tid & 1); __syncthreads();
	v_pk_fma_f32 v[50:51], v[28:29], v[34:35], v[48:49] op_sel:[0,0,1] op_sel_hi:[1,1,0] neg_lo:[0,0,1] neg_hi:[0,0,1]
	v_pk_fma_f32 v[34:35], v[28:29], v[34:35], v[48:49] op_sel:[0,0,1] op_sel_hi:[1,1,0]
	s_nop 0
	v_mov_b32_e32 v51, v35
	v_pk_add_f32 v[34:35], v[24:25], v[46:47]
	v_pk_add_f32 v[24:25], v[24:25], v[46:47] neg_lo:[0,1] neg_hi:[0,1]
	s_nop 0
	v_pk_mul_f32 v[46:47], v[20:21], v[24:25] op_sel_hi:[0,1]
	v_pk_fma_f32 v[48:49], v[28:29], v[24:25], v[46:47] op_sel:[0,0,1] op_sel_hi:[1,1,0] neg_lo:[0,0,1] neg_hi:[0,0,1]
	v_pk_fma_f32 v[24:25], v[28:29], v[24:25], v[46:47] op_sel:[0,0,1] op_sel_hi:[1,1,0]
	v_pk_add_f32 v[46:47], v[58:59], v[62:63] neg_lo:[0,1] neg_hi:[0,1]
	v_mov_b32_e32 v49, v25
	v_pk_mul_f32 v[52:53], v[20:21], v[46:47] op_sel_hi:[0,1]
	v_pk_add_f32 v[24:25], v[58:59], v[62:63]
	v_pk_fma_f32 v[58:59], v[28:29], v[46:47], v[52:53] op_sel:[0,0,1] op_sel_hi:[1,1,0] neg_lo:[0,0,1] neg_hi:[0,0,1]
	v_pk_fma_f32 v[46:47], v[28:29], v[46:47], v[52:53] op_sel:[0,0,1] op_sel_hi:[1,1,0]
	s_nop 0
	v_mov_b32_e32 v59, v47
	v_pk_add_f32 v[46:47], v[56:57], v[26:27]
	v_pk_add_f32 v[26:27], v[56:57], v[26:27] neg_lo:[0,1] neg_hi:[0,1]
	s_nop 0
	v_pk_mul_f32 v[52:53], v[20:21], v[26:27] op_sel_hi:[0,1]
	v_pk_fma_f32 v[56:57], v[28:29], v[26:27], v[52:53] op_sel:[0,0,1] op_sel_hi:[1,1,0] neg_lo:[0,0,1] neg_hi:[0,0,1]
	v_pk_fma_f32 v[26:27], v[28:29], v[26:27], v[52:53] op_sel:[0,0,1] op_sel_hi:[1,1,0]
	s_nop 0
	v_mov_b32_e32 v57, v27
	v_pk_add_f32 v[26:27], v[60:61], v[38:39]
	v_pk_add_f32 v[38:39], v[60:61], v[38:39] neg_lo:[0,1] neg_hi:[0,1]
	s_nop 0
	v_pk_mul_f32 v[52:53], v[20:21], v[38:39] op_sel_hi:[0,1]
	v_pk_fma_f32 v[60:61], v[28:29], v[38:39], v[52:53] op_sel:[0,0,1] op_sel_hi:[1,1,0] neg_lo:[0,0,1] neg_hi:[0,0,1]
	v_pk_fma_f32 v[38:39], v[28:29], v[38:39], v[52:53] op_sel:[0,0,1] op_sel_hi:[1,1,0]
	s_nop 0
	v_mov_b32_e32 v61, v39
	v_pk_add_f32 v[38:39], v[32:33], v[36:37]
	v_pk_add_f32 v[32:33], v[32:33], v[36:37] neg_lo:[0,1] neg_hi:[0,1]
	s_nop 0
	v_pk_mul_f32 v[36:37], v[20:21], v[32:33] op_sel_hi:[0,1]
	v_pk_fma_f32 v[52:53], v[28:29], v[32:33], v[36:37] op_sel:[0,0,1] op_sel_hi:[1,1,0] neg_lo:[0,0,1] neg_hi:[0,0,1]
	v_pk_fma_f32 v[32:33], v[28:29], v[32:33], v[36:37] op_sel:[0,0,1] op_sel_hi:[1,1,0]
	v_pk_add_f32 v[36:37], v[64:65], v[54:55] neg_lo:[0,1] neg_hi:[0,1]
	v_mov_b32_e32 v53, v33
	v_pk_mul_f32 v[20:21], v[20:21], v[36:37] op_sel_hi:[0,1]
	v_pk_add_f32 v[32:33], v[64:65], v[54:55]
	v_pk_fma_f32 v[54:55], v[28:29], v[36:37], v[20:21] op_sel:[0,0,1] op_sel_hi:[1,1,0] neg_lo:[0,0,1] neg_hi:[0,0,1]
	v_pk_fma_f32 v[20:21], v[28:29], v[36:37], v[20:21] op_sel:[0,0,1] op_sel_hi:[1,1,0]
	s_nop 0
	v_mov_b32_e32 v55, v21
	v_and_b32_e32 v20, 1, v2
	v_bfe_i32 v21, v2, 0, 28
	v_lshlrev_b32_e32 v2, 7, v2
	v_and_b32_e32 v2, 0xffffff00, v2
	v_lshlrev_b32_e32 v21, 3, v21
	ds_write2_b64 v41, v[44:45], v[42:43] offset1:34
	ds_write2_b64 v41, v[30:31], v[50:51] offset0:68 offset1:102
	ds_write2_b64 v41, v[34:35], v[48:49] offset0:136 offset1:170
	ds_write2_b64 v41, v[24:25], v[58:59] offset0:204 offset1:238
	ds_write2_b64 v82, v[46:47], v[56:57] offset0:16 offset1:50
	ds_write2_b64 v82, v[26:27], v[60:61] offset0:84 offset1:118
	ds_write2_b64 v82, v[38:39], v[52:53] offset0:152 offset1:186
	ds_write2_b64 v82, v[32:33], v[54:55] offset0:220 offset1:254
	v_add_u32_e32 v2, 0, v2
	v_lshlrev_b32_e32 v24, 3, v20
	v_and_b32_e32 v21, -16, v21
	v_add3_u32 v41, v2, v24, v21
	v_cvt_f32_ubyte0_e32 v2, v20
	v_mul_f32_e32 v2, 0x3d000000, v2
	v_sin_f32_e32 v20, v2
	v_cos_f32_e32 v58, v2
	s_waitcnt lgkmcnt(0)
	s_barrier
	v_xor_b32_e32 v59, 0x80000000, v20
	ds_read2_b64 v[24:27], v41 offset1:2
	ds_read2_b64 v[28:31], v41 offset0:4 offset1:6
	ds_read2_b64 v[32:35], v41 offset0:8 offset1:10
	ds_read2_b64 v[36:39], v41 offset0:12 offset1:14
	ds_read2_b64 v[42:45], v41 offset0:16 offset1:18
	ds_read2_b64 v[46:49], v41 offset0:20 offset1:22
	v_mov_b32_e32 v21, v58
	v_mov_b32_e32 v60, v20
	v_mov_b32_e32 v61, v59
	v_pk_mul_f32 v[60:61], v[20:21], v[60:61]
	s_waitcnt lgkmcnt(1)
	v_pk_add_f32 v[68:69], v[24:25], v[42:43]
	v_pk_fma_f32 v[62:63], v[58:59], v[58:59], v[60:61] op_sel_hi:[0,1,1] neg_lo:[0,0,1] neg_hi:[0,0,1]
	v_pk_fma_f32 v[60:61], v[58:59], v[58:59], v[60:61] op_sel_hi:[0,1,1]
	v_mov_b32_e32 v63, v61
	v_pk_mul_f32 v[66:67], v[62:63], v[60:61] op_sel:[0,1] op_sel_hi:[1,0]
	v_fma_f32 v60, v58, s22, -v20
	v_pk_add_f32 v[24:25], v[24:25], v[42:43] neg_lo:[0,1] neg_hi:[0,1]
	v_fmamk_f32 v2, v20, 0x80000000, v58
	v_pk_mul_f32 v[42:43], v[60:61], v[24:25] op_sel:[0,1] op_sel_hi:[0,0]
	v_pk_fma_f32 v[70:71], v[2:3], v[24:25], v[42:43] neg_lo:[0,0,1] neg_hi:[0,0,1]
	v_pk_fma_f32 v[24:25], v[2:3], v[24:25], v[42:43] op_sel_hi:[0,1,1]
	v_pk_mul_f32 v[42:43], v[20:21], s[8:9] op_sel_hi:[1,0]
	v_mov_b32_e32 v71, v25
	v_pk_add_f32 v[24:25], v[26:27], v[44:45]
	v_pk_add_f32 v[26:27], v[26:27], v[44:45] neg_lo:[0,1] neg_hi:[0,1]
	v_fma_f32 v2, v20, s9, -v43
	s_waitcnt lgkmcnt(0)
	v_pk_add_f32 v[44:45], v[28:29], v[46:47]
	v_pk_add_f32 v[28:29], v[28:29], v[46:47] neg_lo:[0,1] neg_hi:[0,1]
	v_pk_add_f32 v[72:73], v[42:43], v[42:43] op_sel:[1,0] op_sel_hi:[1,0] neg_lo:[0,1] neg_hi:[0,1]
	v_pk_mul_f32 v[46:47], v[2:3], v[28:29] op_sel:[0,1] op_sel_hi:[0,0]
	ds_read2_b64 v[50:53], v41 offset0:24 offset1:26
	ds_read2_b64 v[54:57], v41 offset0:28 offset1:30
	v_pk_fma_f32 v[74:75], v[72:73], v[28:29], v[46:47] neg_lo:[0,0,1] neg_hi:[0,0,1]
	v_pk_fma_f32 v[28:29], v[72:73], v[28:29], v[46:47]
	v_pk_mul_f32 v[72:73], v[20:21], s[96:97]
	v_mov_b32_e32 v75, v29
	v_pk_mul_f32 v[28:29], v[20:21], s[10:11]
	v_pk_add_f32 v[76:77], v[30:31], v[48:49]
	v_pk_add_f32 v[30:31], v[30:31], v[48:49] neg_lo:[0,1] neg_hi:[0,1]
	v_pk_add_f32 v[48:49], v[72:73], v[72:73] op_sel:[0,1] op_sel_hi:[0,1] neg_lo:[0,1] neg_hi:[0,1]
	v_pk_mul_f32 v[48:49], v[48:49], v[30:31] op_sel:[0,1] op_sel_hi:[1,0]
	v_pk_add_f32 v[78:79], v[28:29], v[28:29] op_sel:[1,0] op_sel_hi:[1,0] neg_lo:[0,1] neg_hi:[0,1]
	v_fma_f32 v2, v20, s2, -v29
	v_pk_fma_f32 v[80:81], v[78:79], v[30:31], v[48:49] neg_lo:[0,0,1] neg_hi:[0,0,1]
	v_pk_fma_f32 v[30:31], v[78:79], v[30:31], v[48:49]
	s_waitcnt lgkmcnt(1)
; __device__ __forceinline__ f32x2 cmul(f32x2 a, f32x2 b) { return (f32x2){a.x * b.x - a.y * b.y, a.x * b.y + a.y * b.x}; }
; template <bool INV, int ST> __device__ __forceinline__ void fft_pass16(LAS f32x2* buf, int base, int bl) {
;     ...
;         for (int d = 0; d < 8; ++d) { const f32x2 w = cmul(W1, (f32x2){C16[d], -S16[d]}); const f32x2 a = x[d], b = x[d + 8]; x[d] = a + b; x[d + 8] = cmul(a - b, w); }
; #pragma unroll
;         for (int g = 0; g < 16; g += 8)
; #pragma unroll
;             for (int dd = 0; dd < 4; ++dd) { const int d = g + dd; const f32x2 w = cmul(W2, (f32x2){C16[2 * dd], -S16[2 * dd]}); const f32x2 a = x[d], b = x[d + 4]; x[d] = a + b; x[d + 4] = cmul(a - b, w); }
; #pragma unroll
;         for (int g = 0; g < 16; g += 4)
; #pragma unroll
;             for (int dd = 0; dd < 2; ++dd) { const int d = g + dd; const f32x2 w = dd ? (f32x2){W4.y, -W4.x} : W4; const f32x2 a = x[d], b = x[d + 2]; x[d] = a + b; x[d + 2] = cmul(a - b, w); }
	v_pk_add_f32 v[48:49], v[32:33], v[50:51]
	v_fma_f32 v30, v20, s22, -v58
	v_pk_add_f32 v[32:33], v[32:33], v[50:51] neg_lo:[0,1] neg_hi:[0,1]
	v_pk_mul_f32 v[46:47], v[2:3], v[26:27] op_sel:[0,1] op_sel_hi:[0,0]
	v_mov_b32_e32 v81, v31
	v_fma_f32 v2, v58, 0, -v20
	v_pk_mul_f32 v[30:31], v[30:31], v[32:33] op_sel:[0,1] op_sel_hi:[0,0]
	v_pk_fma_f32 v[50:51], v[2:3], v[32:33], v[30:31] neg_lo:[0,0,1] neg_hi:[0,0,1]
	v_pk_fma_f32 v[30:31], v[2:3], v[32:33], v[30:31] op_sel_hi:[0,1,1]
	v_mov_b32_e32 v51, v31
	v_pk_add_f32 v[30:31], v[34:35], v[52:53]
	v_pk_add_f32 v[32:33], v[34:35], v[52:53] neg_lo:[0,1] neg_hi:[0,1]
	v_fma_f32 v34, v58, s9, -v42
	s_waitcnt lgkmcnt(0)
	v_pk_add_f32 v[52:53], v[36:37], v[54:55]
	v_pk_add_f32 v[36:37], v[36:37], v[54:55] neg_lo:[0,1] neg_hi:[0,1]
	v_pk_add_f32 v[42:43], v[42:43], v[42:43] op_sel:[0,1] op_sel_hi:[0,1] neg_lo:[0,1] neg_hi:[0,1]
	v_pk_mul_f32 v[42:43], v[42:43], v[36:37] op_sel:[0,1] op_sel_hi:[1,0]
	v_mov_b32_e32 v59, v20
	v_pk_fma_f32 v[54:55], v[34:35], v[36:37], v[42:43] neg_lo:[0,0,1] neg_hi:[0,0,1]
	v_pk_fma_f32 v[34:35], v[34:35], v[36:37], v[42:43] op_sel_hi:[0,1,1]
	v_pk_mul_f32 v[20:21], v[58:59], s[2:3]
	v_fma_f32 v2, v58, s96, -v28
	v_sub_f32_e32 v34, v73, v21
	v_pk_fma_f32 v[36:37], v[34:35], v[26:27], v[46:47] op_sel_hi:[0,1,1] neg_lo:[0,0,1] neg_hi:[0,0,1]
	v_pk_fma_f32 v[26:27], v[34:35], v[26:27], v[46:47] op_sel_hi:[0,1,1]
	v_sub_f32_e32 v26, v21, v73
	v_mov_b32_e32 v37, v27
	v_pk_mul_f32 v[26:27], v[26:27], v[32:33] op_sel:[0,1] op_sel_hi:[0,0]
	v_mov_b32_e32 v55, v35
	v_pk_fma_f32 v[34:35], v[2:3], v[32:33], v[26:27] neg_lo:[0,0,1] neg_hi:[0,0,1]
	v_pk_fma_f32 v[26:27], v[2:3], v[32:33], v[26:27] op_sel_hi:[0,1,1]
	v_pk_add_f32 v[32:33], v[38:39], v[56:57] neg_lo:[0,1] neg_hi:[0,1]
	v_pk_add_f32 v[28:29], v[28:29], v[28:29] op_sel:[0,1] op_sel_hi:[0,1] neg_lo:[0,1] neg_hi:[0,1]
	v_pk_mul_f32 v[28:29], v[28:29], v[32:33] op_sel:[0,1] op_sel_hi:[1,0]
	v_pk_add_f32 v[20:21], v[20:21], v[20:21] op_sel:[0,1] op_sel_hi:[0,1] neg_lo:[0,1] neg_hi:[0,1]
	v_fmamk_f32 v42, v62, 0x80000000, v61
	v_pk_add_f32 v[46:47], v[68:69], v[48:49]
	v_pk_add_f32 v[48:49], v[68:69], v[48:49] neg_lo:[0,1] neg_hi:[0,1]
	v_pk_mul_f32 v[64:65], v[62:63], v[62:63]
	v_mov_b32_e32 v35, v27
	v_pk_add_f32 v[26:27], v[38:39], v[56:57]
	v_pk_fma_f32 v[38:39], v[20:21], v[32:33], v[28:29] neg_lo:[0,0,1] neg_hi:[0,0,1]
	v_pk_fma_f32 v[20:21], v[20:21], v[32:33], v[28:29]
	v_fma_f32 v2, 0, v61, v62
	v_pk_mul_f32 v[56:57], v[42:43], v[48:49] op_sel_hi:[0,1]
	v_mov_b32_e32 v20, v64
	v_pk_mov_b32 v[28:29], v[64:65], v[66:67] op_sel:[1,0]
	v_pk_fma_f32 v[58:59], v[2:3], v[48:49], v[56:57] op_sel:[0,0,1] op_sel_hi:[1,1,0] neg_lo:[0,0,1] neg_hi:[0,0,1]
	v_pk_fma_f32 v[48:49], v[2:3], v[48:49], v[56:57] op_sel:[0,0,1] op_sel_hi:[0,1,0]
	v_fma_f32 v56, v61, 0, -v62
	v_pk_add_f32 v[64:65], v[44:45], v[52:53]
	v_pk_add_f32 v[44:45], v[44:45], v[52:53] neg_lo:[0,1] neg_hi:[0,1]
	v_mov_b32_e32 v59, v49
	v_pk_add_f32 v[48:49], v[24:25], v[30:31]
	v_pk_add_f32 v[24:25], v[24:25], v[30:31] neg_lo:[0,1] neg_hi:[0,1]
	v_fma_f32 v30, 0, v62, v61
	v_pk_mul_f32 v[52:53], v[56:57], v[44:45] op_sel_hi:[0,1]
	v_mov_b32_e32 v39, v21
	v_mov_b32_e32 v21, v66
	v_pk_fma_f32 v[66:67], v[30:31], v[44:45], v[52:53] op_sel:[0,0,1] op_sel_hi:[1,1,0] neg_lo:[0,0,1] neg_hi:[0,0,1]
	v_pk_fma_f32 v[44:45], v[30:31], v[44:45], v[52:53] op_sel:[0,0,1] op_sel_hi:[0,1,0]
	v_mov_b32_e32 v67, v45
	v_pk_mul_f32 v[44:45], v[62:63], s[8:9]
	v_pk_add_f32 v[32:33], v[20:21], v[28:29] neg_lo:[0,1] neg_hi:[0,1]
	v_fma_f32 v60, v61, s8, -v44
	v_fmamk_f32 v52, v61, 0x3f3504f3, v44
	v_pk_mul_f32 v[62:63], v[60:61], v[24:25] op_sel_hi:[0,1]
	v_pk_fma_f32 v[68:69], v[52:53], v[24:25], v[62:63] op_sel:[0,0,1] op_sel_hi:[1,1,0] neg_lo:[0,0,1] neg_hi:[0,0,1]
	v_pk_fma_f32 v[24:25], v[52:53], v[24:25], v[62:63] op_sel:[0,0,1] op_sel_hi:[0,1,0]
	v_mov_b32_e32 v69, v25
	v_pk_add_f32 v[24:25], v[76:77], v[26:27]
	v_pk_add_f32 v[26:27], v[76:77], v[26:27] neg_lo:[0,1] neg_hi:[0,1]
	v_pk_add_f32 v[44:45], v[44:45], v[44:45] op_sel:[1,0] op_sel_hi:[1,0] neg_lo:[0,1] neg_hi:[0,1]
	v_pk_add_f32 v[20:21], v[20:21], v[28:29]
	v_pk_mul_f32 v[62:63], v[44:45], v[26:27]
	v_mov_b32_e32 v28, v32
	v_pk_fma_f32 v[72:73], v[60:61], v[26:27], v[62:63] op_sel:[0,0,1] op_sel_hi:[1,1,0] neg_lo:[0,0,1] neg_hi:[0,0,1]
	v_pk_fma_f32 v[26:27], v[60:61], v[26:27], v[62:63] op_sel:[0,0,1] op_sel_hi:[0,1,0]
	v_mov_b32_e32 v73, v27
	v_pk_add_f32 v[26:27], v[70:71], v[50:51]
	v_pk_add_f32 v[50:51], v[70:71], v[50:51] neg_lo:[0,1] neg_hi:[0,1]
	v_mov_b32_e32 v29, v21
	v_pk_mul_f32 v[42:43], v[42:43], v[50:51] op_sel_hi:[0,1]
	v_pk_fma_f32 v[62:63], v[2:3], v[50:51], v[42:43] op_sel:[0,0,1] op_sel_hi:[1,1,0] neg_lo:[0,0,1] neg_hi:[0,0,1]
	v_pk_fma_f32 v[42:43], v[2:3], v[50:51], v[42:43] op_sel:[0,0,1] op_sel_hi:[0,1,0]
	v_mov_b32_e32 v63, v43
	v_pk_add_f32 v[42:43], v[36:37], v[34:35]
	v_pk_add_f32 v[34:35], v[36:37], v[34:35] neg_lo:[0,1] neg_hi:[0,1]
	v_mul_f32_e32 v2, v32, v21
	v_pk_mul_f32 v[36:37], v[60:61], v[34:35] op_sel_hi:[0,1]
	v_pk_fma_f32 v[50:51], v[52:53], v[34:35], v[36:37] op_sel:[0,0,1] op_sel_hi:[1,1,0] neg_lo:[0,0,1] neg_hi:[0,0,1]
	v_pk_fma_f32 v[34:35], v[52:53], v[34:35], v[36:37] op_sel:[0,0,1] op_sel_hi:[0,1,0]
	v_pk_add_f32 v[36:37], v[74:75], v[54:55] neg_lo:[0,1] neg_hi:[0,1]
	v_mov_b32_e32 v51, v35
	v_pk_mul_f32 v[52:53], v[56:57], v[36:37] op_sel_hi:[0,1]
	v_pk_add_f32 v[34:35], v[74:75], v[54:55]
	v_pk_fma_f32 v[54:55], v[30:31], v[36:37], v[52:53] op_sel:[0,0,1] op_sel_hi:[1,1,0] neg_lo:[0,0,1] neg_hi:[0,0,1]
	v_pk_fma_f32 v[30:31], v[30:31], v[36:37], v[52:53] op_sel:[0,0,1] op_sel_hi:[0,1,0]
; __device__ __forceinline__ f32x2 cmul(f32x2 a, f32x2 b) { return (f32x2){a.x * b.x - a.y * b.y, a.x * b.y + a.y * b.x}; }
; template <bool INV, int ST> __device__ __forceinline__ void fft_pass16(LAS f32x2* buf, int base, int bl) {
;     ...
;             for (int dd = 0; dd < 4; ++dd) { const int d = g + dd; const f32x2 w = cmul(W2, (f32x2){C16[2 * dd], -S16[2 * dd]}); const f32x2 a = x[d], b = x[d + 4]; x[d] = a + b; x[d + 4] = cmul(a - b, w); }
; #pragma unroll
;         for (int g = 0; g < 16; g += 4)
; #pragma unroll
;             for (int dd = 0; dd < 2; ++dd) { const int d = g + dd; const f32x2 w = dd ? (f32x2){W4.y, -W4.x} : W4; const f32x2 a = x[d], b = x[d + 2]; x[d] = a + b; x[d + 2] = cmul(a - b, w); }
; #pragma unroll
;         for (int g = 0; g < 16; g += 2) { const f32x2 a = x[g], b = x[g + 1]; x[g] = a + b; x[g + 1] = cmul(a - b, W8); }
	v_pk_add_f32 v[36:37], v[80:81], v[38:39] neg_lo:[0,1] neg_hi:[0,1]
	v_mov_b32_e32 v55, v31
	v_pk_add_f32 v[30:31], v[80:81], v[38:39]
	v_pk_mul_f32 v[38:39], v[44:45], v[36:37]
	v_pk_mul_f32 v[28:29], v[28:29], v[28:29]
	v_pk_fma_f32 v[44:45], v[60:61], v[36:37], v[38:39] op_sel:[0,0,1] op_sel_hi:[1,1,0] neg_lo:[0,0,1] neg_hi:[0,0,1]
	v_pk_fma_f32 v[36:37], v[60:61], v[36:37], v[38:39] op_sel:[0,0,1] op_sel_hi:[0,1,0]
	v_pk_add_f32 v[38:39], v[46:47], v[64:65] neg_lo:[0,1] neg_hi:[0,1]
	v_mov_b32_e32 v45, v37
	v_pk_add_f32 v[36:37], v[46:47], v[64:65]
	v_pk_mul_f32 v[46:47], v[20:21], v[38:39] op_sel:[1,0]
	v_add_f32_e32 v2, v2, v2
	v_pk_fma_f32 v[52:53], v[32:33], v[38:39], v[46:47] op_sel:[0,0,1] op_sel_hi:[1,1,0] neg_lo:[0,0,1] neg_hi:[0,0,1]
	v_pk_fma_f32 v[38:39], v[32:33], v[38:39], v[46:47] op_sel:[0,0,1] op_sel_hi:[0,1,0]
	v_mov_b32_e32 v53, v39
	v_pk_add_f32 v[38:39], v[48:49], v[24:25]
	v_pk_add_f32 v[24:25], v[48:49], v[24:25] neg_lo:[0,1] neg_hi:[0,1]
	v_pk_add_f32 v[28:29], v[28:29], v[28:29] op_sel:[0,1] op_sel_hi:[0,1] neg_lo:[0,1] neg_hi:[0,1]
	v_pk_mul_f32 v[46:47], v[32:33], v[24:25] op_sel_hi:[0,1]
	v_pk_fma_f32 v[48:49], v[20:21], v[24:25], v[46:47] op_sel:[1,0,1] op_sel_hi:[1,1,0]
	v_pk_fma_f32 v[24:25], v[20:21], v[24:25], v[46:47] op_sel:[1,0,1] op_sel_hi:[1,1,0] neg_lo:[0,0,1] neg_hi:[0,0,1]
	v_pk_add_f32 v[46:47], v[58:59], v[66:67] neg_lo:[0,1] neg_hi:[0,1]
	v_mov_b32_e32 v49, v25
	v_pk_mul_f32 v[56:57], v[20:21], v[46:47] op_sel:[1,0]
	v_pk_add_f32 v[24:25], v[58:59], v[66:67]
	v_pk_fma_f32 v[58:59], v[32:33], v[46:47], v[56:57] op_sel:[0,0,1] op_sel_hi:[1,1,0] neg_lo:[0,0,1] neg_hi:[0,0,1]
	v_pk_fma_f32 v[46:47], v[32:33], v[46:47], v[56:57] op_sel:[0,0,1] op_sel_hi:[0,1,0]
	v_pk_add_f32 v[56:57], v[68:69], v[72:73] neg_lo:[0,1] neg_hi:[0,1]
	v_mov_b32_e32 v59, v47
	v_pk_mul_f32 v[60:61], v[32:33], v[56:57] op_sel_hi:[0,1]
	v_pk_fma_f32 v[64:65], v[20:21], v[56:57], v[60:61] op_sel:[1,0,1] op_sel_hi:[1,1,0]
	v_pk_fma_f32 v[56:57], v[20:21], v[56:57], v[60:61] op_sel:[1,0,1] op_sel_hi:[1,1,0] neg_lo:[0,0,1] neg_hi:[0,0,1]
	v_pk_add_f32 v[46:47], v[68:69], v[72:73]
	v_mov_b32_e32 v65, v57
	v_pk_add_f32 v[56:57], v[26:27], v[34:35]
	v_pk_add_f32 v[26:27], v[26:27], v[34:35] neg_lo:[0,1] neg_hi:[0,1]
	s_nop 0
	v_pk_mul_f32 v[34:35], v[20:21], v[26:27] op_sel:[1,0]
	s_nop 0
	v_pk_fma_f32 v[60:61], v[32:33], v[26:27], v[34:35] op_sel:[0,0,1] op_sel_hi:[1,1,0] neg_lo:[0,0,1] neg_hi:[0,0,1]
	v_pk_fma_f32 v[26:27], v[32:33], v[26:27], v[34:35] op_sel:[0,0,1] op_sel_hi:[0,1,0]
	v_mov_b32_e32 v61, v27
	v_pk_add_f32 v[26:27], v[42:43], v[30:31]
	v_pk_add_f32 v[30:31], v[42:43], v[30:31] neg_lo:[0,1] neg_hi:[0,1]
	s_nop 0
	v_pk_mul_f32 v[34:35], v[32:33], v[30:31] op_sel_hi:[0,1]
	v_pk_fma_f32 v[42:43], v[20:21], v[30:31], v[34:35] op_sel:[1,0,1] op_sel_hi:[1,1,0]
	v_pk_fma_f32 v[30:31], v[20:21], v[30:31], v[34:35] op_sel:[1,0,1] op_sel_hi:[1,1,0] neg_lo:[0,0,1] neg_hi:[0,0,1]
	v_pk_add_f32 v[34:35], v[62:63], v[54:55] neg_lo:[0,1] neg_hi:[0,1]
	v_mov_b32_e32 v43, v31
	v_pk_add_f32 v[30:31], v[62:63], v[54:55]
	v_pk_mul_f32 v[54:55], v[20:21], v[34:35] op_sel:[1,0]
	s_nop 0
	v_pk_fma_f32 v[62:63], v[32:33], v[34:35], v[54:55] op_sel:[0,0,1] op_sel_hi:[1,1,0] neg_lo:[0,0,1] neg_hi:[0,0,1]
	v_pk_fma_f32 v[34:35], v[32:33], v[34:35], v[54:55] op_sel:[0,0,1] op_sel_hi:[0,1,0]
	v_mov_b32_e32 v63, v35
	v_pk_add_f32 v[34:35], v[50:51], v[44:45]
	v_pk_add_f32 v[44:45], v[50:51], v[44:45] neg_lo:[0,1] neg_hi:[0,1]
	s_nop 0
	v_pk_mul_f32 v[50:51], v[32:33], v[44:45] op_sel_hi:[0,1]
	v_pk_fma_f32 v[54:55], v[20:21], v[44:45], v[50:51] op_sel:[1,0,1] op_sel_hi:[1,1,0]
	v_pk_fma_f32 v[44:45], v[20:21], v[44:45], v[50:51] op_sel:[1,0,1] op_sel_hi:[1,1,0] neg_lo:[0,0,1] neg_hi:[0,0,1]
	s_nop 0
	v_mov_b32_e32 v55, v45
	v_pk_add_f32 v[44:45], v[36:37], v[38:39]
	v_pk_add_f32 v[36:37], v[36:37], v[38:39] neg_lo:[0,1] neg_hi:[0,1]
	s_nop 0
	v_pk_mul_f32 v[20:21], v[2:3], v[36:37] op_sel_hi:[0,1]
	v_pk_fma_f32 v[32:33], v[28:29], v[36:37], v[20:21] op_sel:[0,0,1] op_sel_hi:[1,1,0] neg_lo:[0,0,1] neg_hi:[0,0,1]
	v_pk_fma_f32 v[20:21], v[28:29], v[36:37], v[20:21] op_sel:[0,0,1] op_sel_hi:[1,1,0]
	v_pk_add_f32 v[36:37], v[52:53], v[48:49] neg_lo:[0,1] neg_hi:[0,1]
	v_mov_b32_e32 v33, v21
	v_pk_mul_f32 v[38:39], v[2:3], v[36:37] op_sel_hi:[0,1]
	v_pk_add_f32 v[20:21], v[52:53], v[48:49]
	v_pk_fma_f32 v[48:49], v[28:29], v[36:37], v[38:39] op_sel:[0,0,1] op_sel_hi:[1,1,0] neg_lo:[0,0,1] neg_hi:[0,0,1]
	v_pk_fma_f32 v[36:37], v[28:29], v[36:37], v[38:39] op_sel:[0,0,1] op_sel_hi:[1,1,0]
	s_nop 0
	v_mov_b32_e32 v49, v37
	v_pk_add_f32 v[36:37], v[24:25], v[46:47]
	v_pk_add_f32 v[24:25], v[24:25], v[46:47] neg_lo:[0,1] neg_hi:[0,1]
	s_nop 0
	v_pk_mul_f32 v[38:39], v[2:3], v[24:25] op_sel_hi:[0,1]
	v_pk_fma_f32 v[46:47], v[28:29], v[24:25], v[38:39] op_sel:[0,0,1] op_sel_hi:[1,1,0] neg_lo:[0,0,1] neg_hi:[0,0,1]
	v_pk_fma_f32 v[24:25], v[28:29], v[24:25], v[38:39] op_sel:[0,0,1] op_sel_hi:[1,1,0]
	v_pk_add_f32 v[38:39], v[58:59], v[64:65] neg_lo:[0,1] neg_hi:[0,1]
	v_mov_b32_e32 v47, v25
	v_pk_mul_f32 v[50:51], v[2:3], v[38:39] op_sel_hi:[0,1]
	v_pk_fma_f32 v[52:53], v[28:29], v[38:39], v[50:51] op_sel:[0,0,1] op_sel_hi:[1,1,0] neg_lo:[0,0,1] neg_hi:[0,0,1]
	v_pk_fma_f32 v[38:39], v[28:29], v[38:39], v[50:51] op_sel:[0,0,1] op_sel_hi:[1,1,0]
	v_pk_add_f32 v[24:25], v[58:59], v[64:65]
	v_mov_b32_e32 v53, v39
	v_pk_add_f32 v[38:39], v[56:57], v[26:27]
	v_pk_add_f32 v[26:27], v[56:57], v[26:27] neg_lo:[0,1] neg_hi:[0,1]
	s_nop 0
	v_pk_mul_f32 v[50:51], v[2:3], v[26:27] op_sel_hi:[0,1]
	v_pk_fma_f32 v[56:57], v[28:29], v[26:27], v[50:51] op_sel:[0,0,1] op_sel_hi:[1,1,0] neg_lo:[0,0,1] neg_hi:[0,0,1]
; #define LAS __attribute__((address_space(3)))
; __device__ __forceinline__ f32x2 cmul(f32x2 a, f32x2 b) { return (f32x2){a.x * b.x - a.y * b.y, a.x * b.y + a.y * b.x}; }
; template <bool INV, int ST> __device__ __forceinline__ void fft_pass16(LAS f32x2* buf, int base, int bl) {
;     ...
;         for (int g = 0; g < 16; g += 2) { const f32x2 a = x[g], b = x[g + 1]; x[g] = a + b; x[g + 1] = cmul(a - b, W8); }
;     ...
;     for (int d = 0; d < 16; ++d) pb[d * STEP] = x[d];
; __device__ __forceinline__ void fft_fwd_abc(LAS f32x2* buf, int tid) {
;     ...
;     fft_pass16<false, 1>(buf, ((tid >> 1) << 5) + (tid & 1), tid & 1); __syncthreads();
; __device__ __forceinline__ void hyena_phase(const Params& P, int l, LAS unsigned char* lds) {
;     ...
; #pragma unroll 2
;                 for (int u = 0; u < 8; ++u) { const int i0 = 2 * (tid + 512 * u); LAS f32x4* pp = (LAS f32x4*)(bufA + PADI(2 * tid) + 1088 * u); const f32x4 v = *pp;
;                     f32x2 xs[2] = {(f32x2){v[0] + v[2], v[1] + v[3]}, (f32x2){v[0] - v[2], v[1] - v[3]}};
;                     const f32x4 zz = *(const LAS f32x4*)(bufB + PADI(2 * tid) + 1088 * u);
; #pragma unroll
;                     for (int q = 0; q < 2; ++q) { const unsigned f = __brev((unsigned)(i0 + q)) >> 19, fp = (8192u - f) & 8191u, ip = __brev(fp) >> 19;
;                         const f32x2 Z = q ? (f32x2){zz[2], zz[3]} : (f32x2){zz[0], zz[1]}; const f32x2 Zp = bufB[PADI((int)ip)]; f32x2 Kf;
;                         if (ord == 0) Kf = (f32x2){Z.x + Zp.x, Z.y - Zp.y}; else Kf = (f32x2){Z.y + Zp.y, Zp.x - Z.x};
;                         Kf *= (0.5f / 8192.f);
;                         xs[q] = cmul(xs[q], Kf); }
;                     *pp = (f32x4){xs[0].x + xs[1].x, xs[0].y + xs[1].y, xs[0].x - xs[1].x, xs[0].y - xs[1].y}; }
	v_pk_fma_f32 v[26:27], v[28:29], v[26:27], v[50:51] op_sel:[0,0,1] op_sel_hi:[1,1,0]
	s_nop 0
	v_mov_b32_e32 v57, v27
	v_pk_add_f32 v[26:27], v[60:61], v[42:43]
	v_pk_add_f32 v[42:43], v[60:61], v[42:43] neg_lo:[0,1] neg_hi:[0,1]
	s_nop 0
	v_pk_mul_f32 v[50:51], v[2:3], v[42:43] op_sel_hi:[0,1]
	v_pk_fma_f32 v[58:59], v[28:29], v[42:43], v[50:51] op_sel:[0,0,1] op_sel_hi:[1,1,0] neg_lo:[0,0,1] neg_hi:[0,0,1]
	v_pk_fma_f32 v[42:43], v[28:29], v[42:43], v[50:51] op_sel:[0,0,1] op_sel_hi:[1,1,0]
	s_nop 0
	v_mov_b32_e32 v59, v43
	v_pk_add_f32 v[42:43], v[30:31], v[34:35]
	v_pk_add_f32 v[30:31], v[30:31], v[34:35] neg_lo:[0,1] neg_hi:[0,1]
	s_nop 0
	v_pk_mul_f32 v[34:35], v[2:3], v[30:31] op_sel_hi:[0,1]
	v_pk_fma_f32 v[50:51], v[28:29], v[30:31], v[34:35] op_sel:[0,0,1] op_sel_hi:[1,1,0] neg_lo:[0,0,1] neg_hi:[0,0,1]
	v_pk_fma_f32 v[30:31], v[28:29], v[30:31], v[34:35] op_sel:[0,0,1] op_sel_hi:[1,1,0]
	v_pk_add_f32 v[34:35], v[62:63], v[54:55] neg_lo:[0,1] neg_hi:[0,1]
	v_mov_b32_e32 v51, v31
	v_pk_add_f32 v[30:31], v[62:63], v[54:55]
	v_pk_mul_f32 v[54:55], v[2:3], v[34:35] op_sel_hi:[0,1]
	v_pk_fma_f32 v[60:61], v[28:29], v[34:35], v[54:55] op_sel:[0,0,1] op_sel_hi:[1,1,0] neg_lo:[0,0,1] neg_hi:[0,0,1]
	v_pk_fma_f32 v[28:29], v[28:29], v[34:35], v[54:55] op_sel:[0,0,1] op_sel_hi:[1,1,0]
	v_mov_b32_e32 v2, v23
	v_mov_b32_e32 v61, v29
	ds_write2_b64 v41, v[44:45], v[32:33] offset1:2
	ds_write2_b64 v41, v[20:21], v[48:49] offset0:4 offset1:6
	ds_write2_b64 v41, v[36:37], v[46:47] offset0:8 offset1:10
	ds_write2_b64 v41, v[24:25], v[52:53] offset0:12 offset1:14
	ds_write2_b64 v41, v[38:39], v[56:57] offset0:16 offset1:18
	ds_write2_b64 v41, v[26:27], v[58:59] offset0:20 offset1:22
	ds_write2_b64 v41, v[42:43], v[50:51] offset0:24 offset1:26
	ds_write2_b64 v41, v[30:31], v[60:61] offset0:28 offset1:30
	s_waitcnt lgkmcnt(0)
	s_barrier
.LBB0_434:
	ds_read_b128 v[24:27], v2
	v_add_u32_e32 v31, s6, v40
	v_add_u32_e32 v21, 0x11000, v2
	s_addk_i32 s6, 0x800
	s_cmpk_eq_i32 s6, 0x2000
	s_waitcnt lgkmcnt(0)
	v_add_f32_e32 v20, v24, v26
	v_add_f32_e32 v28, v25, v27
	v_sub_f32_e32 v30, v24, v26
	v_sub_f32_e32 v32, v25, v27
	ds_read_b128 v[24:27], v21
	v_bfrev_b32_e32 v21, v31
	v_lshrrev_b32_e32 v21, 19, v21
	v_sub_u32_e32 v21, 0, v21
	v_and_b32_e32 v21, 0x1fff, v21
	v_bfrev_b32_e32 v21, v21
	v_lshrrev_b32_e32 v29, 16, v21
	v_lshlrev_b32_sdwa v21, v229, v21 dst_sel:DWORD dst_unused:UNUSED_PAD src0_sel:DWORD src1_sel:BYTE_3
	v_add3_u32 v21, s67, v29, v21
	ds_read_b64 v[34:35], v21
	v_add_u32_e32 v21, 1, v31
	v_bfrev_b32_e32 v21, v21
	v_lshrrev_b32_e32 v21, 19, v21
	v_sub_u32_e32 v21, 0, v21
	v_and_b32_e32 v21, 0x1fff, v21
	v_bfrev_b32_e32 v21, v21
	v_lshrrev_b32_e32 v29, 16, v21
	v_lshlrev_b32_sdwa v21, v229, v21 dst_sel:DWORD dst_unused:UNUSED_PAD src0_sel:DWORD src1_sel:BYTE_3
	v_add3_u32 v21, s67, v29, v21
	s_waitcnt lgkmcnt(0)
	v_add_f32_e32 v24, v24, v34
	v_sub_f32_e32 v25, v25, v35
	ds_read_b64 v[34:35], v21
	v_pk_mul_f32 v[24:25], v[24:25], s[0:1] op_sel_hi:[1,0]
	s_waitcnt lgkmcnt(0)
	v_add_f32_e32 v26, v26, v34
	v_sub_f32_e32 v27, v27, v35
	v_pk_mul_f32 v[28:29], v[28:29], v[24:25] op_sel:[0,1] op_sel_hi:[0,0]
	v_pk_mul_f32 v[26:27], v[26:27], s[0:1] op_sel_hi:[1,0]
	v_pk_fma_f32 v[34:35], v[20:21], v[24:25], v[28:29] neg_lo:[0,0,1] neg_hi:[0,0,1]
	v_pk_fma_f32 v[20:21], v[20:21], v[24:25], v[28:29] op_sel_hi:[0,1,1]
	v_mov_b32_e32 v35, v21
	v_pk_mul_f32 v[20:21], v[32:33], v[26:27] op_sel:[0,1] op_sel_hi:[0,0]
	v_pk_fma_f32 v[28:29], v[30:31], v[26:27], v[20:21] neg_lo:[0,0,1] neg_hi:[0,0,1]
	v_pk_fma_f32 v[20:21], v[30:31], v[26:27], v[20:21] op_sel_hi:[0,1,1]
	v_mov_b32_e32 v29, v21
	v_add_u32_e32 v21, 0x400, v31
	v_bfrev_b32_e32 v21, v21
	v_lshrrev_b32_e32 v21, 19, v21
	v_sub_u32_e32 v21, 0, v21
	v_pk_add_f32 v[24:25], v[34:35], v[28:29]
	v_pk_add_f32 v[26:27], v[34:35], v[28:29] neg_lo:[0,1] neg_hi:[0,1]
	v_and_b32_e32 v21, 0x1fff, v21
	ds_write_b128 v2, v[24:27]
	ds_read_b128 v[24:27], v2 offset:8704
	v_bfrev_b32_e32 v21, v21
	v_lshrrev_b32_e32 v29, 16, v21
	v_lshlrev_b32_sdwa v21, v229, v21 dst_sel:DWORD dst_unused:UNUSED_PAD src0_sel:DWORD src1_sel:BYTE_3
	v_add3_u32 v21, s67, v29, v21
	ds_read_b64 v[34:35], v21
	v_add_u32_e32 v21, 0x401, v31
	v_bfrev_b32_e32 v21, v21
	s_waitcnt lgkmcnt(1)
	v_add_f32_e32 v20, v24, v26
	v_sub_f32_e32 v30, v24, v26
	v_add_u32_e32 v24, 0x13200, v2
	v_lshrrev_b32_e32 v21, 19, v21
	v_add_f32_e32 v28, v25, v27
	v_sub_f32_e32 v32, v25, v27
	ds_read_b128 v[24:27], v24
	v_sub_u32_e32 v21, 0, v21
	v_and_b32_e32 v21, 0x1fff, v21
	v_bfrev_b32_e32 v21, v21
	v_lshrrev_b32_e32 v29, 16, v21
	v_lshlrev_b32_sdwa v21, v229, v21 dst_sel:DWORD dst_unused:UNUSED_PAD src0_sel:DWORD src1_sel:BYTE_3
	v_add3_u32 v21, s67, v29, v21
	s_waitcnt lgkmcnt(0)
	v_add_f32_e32 v24, v24, v34
	v_sub_f32_e32 v25, v25, v35
	ds_read_b64 v[34:35], v21
	v_pk_mul_f32 v[24:25], v[24:25], s[0:1] op_sel_hi:[1,0]
	s_waitcnt lgkmcnt(0)
	v_add_f32_e32 v26, v26, v34
	v_sub_f32_e32 v27, v27, v35
	v_pk_mul_f32 v[28:29], v[28:29], v[24:25] op_sel:[0,1] op_sel_hi:[0,0]
	v_pk_mul_f32 v[26:27], v[26:27], s[0:1] op_sel_hi:[1,0]
	v_pk_fma_f32 v[34:35], v[20:21], v[24:25], v[28:29] neg_lo:[0,0,1] neg_hi:[0,0,1]
	v_pk_fma_f32 v[20:21], v[20:21], v[24:25], v[28:29] op_sel_hi:[0,1,1]
	v_mov_b32_e32 v35, v21
	v_pk_mul_f32 v[20:21], v[32:33], v[26:27] op_sel:[0,1] op_sel_hi:[0,0]
	v_pk_fma_f32 v[28:29], v[30:31], v[26:27], v[20:21] neg_lo:[0,0,1] neg_hi:[0,0,1]
	v_pk_fma_f32 v[20:21], v[30:31], v[26:27], v[20:21] op_sel_hi:[0,1,1]
	v_mov_b32_e32 v29, v21
	v_pk_add_f32 v[24:25], v[34:35], v[28:29]
	v_pk_add_f32 v[26:27], v[34:35], v[28:29] neg_lo:[0,1] neg_hi:[0,1]
	ds_write_b128 v2, v[24:27] offset:8704
	v_add_u32_e32 v2, 0x4400, v2
	s_cbranch_scc0 .LBB0_434
; __device__ __forceinline__ f32x2 cmulc(f32x2 a, f32x2 b) { return (f32x2){a.x * b.x + a.y * b.y, a.y * b.x - a.x * b.y}; }
; template <bool INV, int ST> __device__ __forceinline__ void fft_pass16(LAS f32x2* buf, int base, int bl) {
;     ...
;     } else {
; #pragma unroll
;         for (int g = 0; g < 16; g += 2) { const f32x2 a = x[g], b = cmulc(x[g + 1], W8); x[g] = a + b; x[g + 1] = a - b; }
; #pragma unroll
;         for (int g = 0; g < 16; g += 4)
; #pragma unroll
;             for (int dd = 0; dd < 2; ++dd) { const int d = g + dd; const f32x2 w = dd ? (f32x2){W4.y, -W4.x} : W4; const f32x2 a = x[d], b = cmulc(x[d + 2], w); x[d] = a + b; x[d + 2] = a - b; }
; __device__ __forceinline__ void fft_inv_cba(LAS f32x2* buf, int tid) {
;     ...
;     fft_pass16<true, 1>(buf, ((tid >> 1) << 5) + (tid & 1), tid & 1); __syncthreads();
	v_mov_b32_e32 v2, v0
	s_waitcnt lgkmcnt(0)
	s_barrier
	s_mov_b32 s10, 0x3f3504f3
	v_bfe_i32 v21, v2, 0, 28
	v_lshlrev_b32_e32 v24, 7, v2
	v_and_b32_e32 v20, 1, v2
	v_and_b32_e32 v24, 0xffffff00, v24
	v_lshlrev_b32_e32 v21, 3, v21
	v_add_u32_e32 v24, 0, v24
	v_lshlrev_b32_e32 v25, 3, v20
	v_and_b32_e32 v21, -16, v21
	v_cvt_f32_ubyte0_e32 v20, v20
	v_add3_u32 v76, v24, v25, v21
	v_mul_f32_e32 v21, 0x3d000000, v20
	v_cos_f32_e32 v20, v21
	v_sin_f32_e32 v21, v21
	ds_read2_b64 v[24:27], v76 offset1:2
	ds_read2_b64 v[28:31], v76 offset0:4 offset1:6
	ds_read2_b64 v[32:35], v76 offset0:8 offset1:10
	ds_read2_b64 v[36:39], v76 offset0:12 offset1:14
	ds_read2_b64 v[42:45], v76 offset0:16 offset1:18
	ds_read2_b64 v[46:49], v76 offset0:20 offset1:22
	ds_read2_b64 v[50:53], v76 offset0:24 offset1:26
	ds_read2_b64 v[54:57], v76 offset0:28 offset1:30
	s_mov_b32 s11, 0xbf3504f3
	v_mov_b32_e32 v59, v20
	v_xor_b32_e32 v58, 0x80000000, v21
	v_mov_b32_e32 v60, v58
	v_mov_b32_e32 v61, v21
	v_pk_mul_f32 v[60:61], v[20:21], v[60:61]
	s_mov_b32 s20, 0x3f6c835e
	v_pk_fma_f32 v[62:63], v[20:21], v[58:59], v[60:61] op_sel_hi:[0,1,1]
	v_pk_fma_f32 v[58:59], v[20:21], v[58:59], v[60:61] op_sel_hi:[0,1,1] neg_lo:[0,0,1] neg_hi:[0,0,1]
	v_mov_b32_e32 v63, v59
	v_pk_mul_f32 v[60:61], v[62:63], v[62:63]
	v_pk_mul_f32 v[64:65], v[58:59], v[62:63] op_sel:[1,0] op_sel_hi:[0,1]
	v_pk_mov_b32 v[66:67], v[60:61], v[64:65] op_sel:[1,0]
	v_mov_b32_e32 v61, v64
	v_pk_add_f32 v[64:65], v[66:67], v[60:61] neg_lo:[0,1] neg_hi:[0,1]
	v_pk_add_f32 v[60:61], v[66:67], v[60:61]
	v_mov_b32_e32 v66, v64
	v_mov_b32_e32 v67, v61
	v_mul_f32_e32 v58, v64, v61
	v_pk_mul_f32 v[66:67], v[66:67], v[66:67]
	v_add_f32_e32 v58, v58, v58
	v_pk_add_f32 v[66:67], v[66:67], v[66:67] op_sel:[0,1] op_sel_hi:[0,1] neg_lo:[0,1] neg_hi:[0,1]
	s_waitcnt lgkmcnt(7)
	v_pk_mul_f32 v[68:69], v[26:27], v[58:59] op_sel_hi:[1,0]
	s_mov_b32 s6, s11
	v_pk_fma_f32 v[70:71], v[26:27], v[66:67], v[68:69] op_sel:[0,0,1] op_sel_hi:[1,1,0]
	v_pk_fma_f32 v[26:27], v[26:27], v[66:67], v[68:69] op_sel:[0,0,1] op_sel_hi:[1,1,0] neg_lo:[0,0,1] neg_hi:[0,0,1]
	s_waitcnt lgkmcnt(6)
	v_pk_mul_f32 v[68:69], v[30:31], v[58:59] op_sel_hi:[1,0]
	v_mov_b32_e32 v71, v27
	v_pk_add_f32 v[26:27], v[24:25], v[70:71]
	v_pk_add_f32 v[24:25], v[24:25], v[70:71] neg_lo:[0,1] neg_hi:[0,1]
	v_pk_fma_f32 v[70:71], v[30:31], v[66:67], v[68:69] op_sel:[0,0,1] op_sel_hi:[1,1,0]
	v_pk_fma_f32 v[30:31], v[30:31], v[66:67], v[68:69] op_sel:[0,0,1] op_sel_hi:[1,1,0] neg_lo:[0,0,1] neg_hi:[0,0,1]
	s_waitcnt lgkmcnt(5)
	v_pk_mul_f32 v[68:69], v[34:35], v[58:59] op_sel_hi:[1,0]
	v_mov_b32_e32 v71, v31
	v_pk_add_f32 v[30:31], v[28:29], v[70:71]
	v_pk_add_f32 v[28:29], v[28:29], v[70:71] neg_lo:[0,1] neg_hi:[0,1]
	v_pk_fma_f32 v[70:71], v[34:35], v[66:67], v[68:69] op_sel:[0,0,1] op_sel_hi:[1,1,0]
	v_pk_fma_f32 v[34:35], v[34:35], v[66:67], v[68:69] op_sel:[0,0,1] op_sel_hi:[1,1,0] neg_lo:[0,0,1] neg_hi:[0,0,1]
	s_waitcnt lgkmcnt(4)
	v_pk_mul_f32 v[68:69], v[38:39], v[58:59] op_sel_hi:[1,0]
	v_mov_b32_e32 v71, v35
	v_pk_add_f32 v[34:35], v[32:33], v[70:71]
	v_pk_add_f32 v[32:33], v[32:33], v[70:71] neg_lo:[0,1] neg_hi:[0,1]
	v_pk_fma_f32 v[70:71], v[38:39], v[66:67], v[68:69] op_sel:[0,0,1] op_sel_hi:[1,1,0]
	v_pk_fma_f32 v[38:39], v[38:39], v[66:67], v[68:69] op_sel:[0,0,1] op_sel_hi:[1,1,0] neg_lo:[0,0,1] neg_hi:[0,0,1]
	s_waitcnt lgkmcnt(3)
	v_pk_mul_f32 v[68:69], v[58:59], v[44:45] op_sel_hi:[0,1]
	v_mov_b32_e32 v71, v39
	v_pk_add_f32 v[38:39], v[36:37], v[70:71]
	v_pk_add_f32 v[36:37], v[36:37], v[70:71] neg_lo:[0,1] neg_hi:[0,1]
	v_pk_fma_f32 v[70:71], v[66:67], v[44:45], v[68:69] op_sel:[0,0,1] op_sel_hi:[1,1,0]
	v_pk_fma_f32 v[44:45], v[66:67], v[44:45], v[68:69] op_sel:[0,0,1] op_sel_hi:[1,1,0] neg_lo:[0,0,1] neg_hi:[0,0,1]
	s_waitcnt lgkmcnt(2)
	v_pk_mul_f32 v[68:69], v[58:59], v[48:49] op_sel_hi:[0,1]
	v_mov_b32_e32 v71, v45
	v_pk_add_f32 v[44:45], v[42:43], v[70:71]
	v_pk_add_f32 v[42:43], v[42:43], v[70:71] neg_lo:[0,1] neg_hi:[0,1]
	v_pk_fma_f32 v[70:71], v[66:67], v[48:49], v[68:69] op_sel:[0,0,1] op_sel_hi:[1,1,0]
	v_pk_fma_f32 v[48:49], v[66:67], v[48:49], v[68:69] op_sel:[0,0,1] op_sel_hi:[1,1,0] neg_lo:[0,0,1] neg_hi:[0,0,1]
	s_waitcnt lgkmcnt(1)
	v_pk_mul_f32 v[68:69], v[58:59], v[52:53] op_sel_hi:[0,1]
	v_mov_b32_e32 v71, v49
	v_pk_add_f32 v[48:49], v[46:47], v[70:71]
	v_pk_add_f32 v[46:47], v[46:47], v[70:71] neg_lo:[0,1] neg_hi:[0,1]
	v_pk_fma_f32 v[70:71], v[66:67], v[52:53], v[68:69] op_sel:[0,0,1] op_sel_hi:[1,1,0]
	v_pk_fma_f32 v[52:53], v[66:67], v[52:53], v[68:69] op_sel:[0,0,1] op_sel_hi:[1,1,0] neg_lo:[0,0,1] neg_hi:[0,0,1]
	s_waitcnt lgkmcnt(0)
; __device__ __forceinline__ f32x2 cmul(f32x2 a, f32x2 b) { return (f32x2){a.x * b.x - a.y * b.y, a.x * b.y + a.y * b.x}; }
; __device__ __forceinline__ f32x2 cmulc(f32x2 a, f32x2 b) { return (f32x2){a.x * b.x + a.y * b.y, a.y * b.x - a.x * b.y}; }
; template <bool INV, int ST> __device__ __forceinline__ void fft_pass16(LAS f32x2* buf, int base, int bl) {
;     ...
;         for (int g = 0; g < 16; g += 2) { const f32x2 a = x[g], b = cmulc(x[g + 1], W8); x[g] = a + b; x[g + 1] = a - b; }
; #pragma unroll
;         for (int g = 0; g < 16; g += 4)
; #pragma unroll
;             for (int dd = 0; dd < 2; ++dd) { const int d = g + dd; const f32x2 w = dd ? (f32x2){W4.y, -W4.x} : W4; const f32x2 a = x[d], b = cmulc(x[d + 2], w); x[d] = a + b; x[d + 2] = a - b; }
; #pragma unroll
;         for (int g = 0; g < 16; g += 8)
; #pragma unroll
;             for (int dd = 0; dd < 4; ++dd) { const int d = g + dd; const f32x2 w = cmul(W2, (f32x2){C16[2 * dd], -S16[2 * dd]}); const f32x2 a = x[d], b = cmulc(x[d + 4], w); x[d] = a + b; x[d + 4] = a - b; }
	v_pk_mul_f32 v[68:69], v[58:59], v[56:57] op_sel_hi:[0,1]
	v_mov_b32_e32 v71, v53
	v_pk_add_f32 v[52:53], v[50:51], v[70:71]
	v_pk_add_f32 v[50:51], v[50:51], v[70:71] neg_lo:[0,1] neg_hi:[0,1]
	v_pk_fma_f32 v[70:71], v[66:67], v[56:57], v[68:69] op_sel:[0,0,1] op_sel_hi:[1,1,0]
	v_pk_fma_f32 v[56:57], v[66:67], v[56:57], v[68:69] op_sel:[0,0,1] op_sel_hi:[1,1,0] neg_lo:[0,0,1] neg_hi:[0,0,1]
	v_pk_mul_f32 v[66:67], v[60:61], v[30:31] op_sel:[1,0]
	v_mov_b32_e32 v71, v57
	v_pk_fma_f32 v[68:69], v[64:65], v[30:31], v[66:67] op_sel:[0,0,1] op_sel_hi:[1,1,0]
	v_pk_fma_f32 v[30:31], v[64:65], v[30:31], v[66:67] op_sel:[0,0,1] op_sel_hi:[0,1,0] neg_lo:[0,0,1] neg_hi:[0,0,1]
	v_mov_b32_e32 v69, v31
	v_pk_mul_f32 v[66:67], v[64:65], v[28:29] op_sel_hi:[0,1]
	v_pk_add_f32 v[30:31], v[26:27], v[68:69]
	v_pk_add_f32 v[26:27], v[26:27], v[68:69] neg_lo:[0,1] neg_hi:[0,1]
	v_pk_fma_f32 v[68:69], v[60:61], v[28:29], v[66:67] op_sel:[1,0,1] op_sel_hi:[1,1,0] neg_lo:[0,0,1] neg_hi:[0,0,1]
	v_pk_fma_f32 v[28:29], v[60:61], v[28:29], v[66:67] op_sel:[1,0,1] op_sel_hi:[1,1,0]
	v_pk_mul_f32 v[66:67], v[60:61], v[38:39] op_sel:[1,0]
	v_mov_b32_e32 v69, v29
	v_pk_add_f32 v[28:29], v[24:25], v[68:69]
	v_pk_add_f32 v[24:25], v[24:25], v[68:69] neg_lo:[0,1] neg_hi:[0,1]
	v_pk_fma_f32 v[68:69], v[64:65], v[38:39], v[66:67] op_sel:[0,0,1] op_sel_hi:[1,1,0]
	v_pk_fma_f32 v[38:39], v[64:65], v[38:39], v[66:67] op_sel:[0,0,1] op_sel_hi:[0,1,0] neg_lo:[0,0,1] neg_hi:[0,0,1]
	v_mov_b32_e32 v69, v39
	v_pk_mul_f32 v[66:67], v[64:65], v[36:37] op_sel_hi:[0,1]
	v_pk_add_f32 v[38:39], v[34:35], v[68:69]
	v_pk_add_f32 v[34:35], v[34:35], v[68:69] neg_lo:[0,1] neg_hi:[0,1]
	v_pk_fma_f32 v[68:69], v[60:61], v[36:37], v[66:67] op_sel:[1,0,1] op_sel_hi:[1,1,0] neg_lo:[0,0,1] neg_hi:[0,0,1]
	v_pk_fma_f32 v[36:37], v[60:61], v[36:37], v[66:67] op_sel:[1,0,1] op_sel_hi:[1,1,0]
	v_pk_mul_f32 v[66:67], v[60:61], v[48:49] op_sel:[1,0]
	v_mov_b32_e32 v69, v37
	v_pk_add_f32 v[36:37], v[32:33], v[68:69]
	v_pk_add_f32 v[32:33], v[32:33], v[68:69] neg_lo:[0,1] neg_hi:[0,1]
	v_pk_fma_f32 v[68:69], v[64:65], v[48:49], v[66:67] op_sel:[0,0,1] op_sel_hi:[1,1,0]
	v_pk_fma_f32 v[48:49], v[64:65], v[48:49], v[66:67] op_sel:[0,0,1] op_sel_hi:[0,1,0] neg_lo:[0,0,1] neg_hi:[0,0,1]
	v_mov_b32_e32 v69, v49
	v_pk_mul_f32 v[66:67], v[64:65], v[46:47] op_sel_hi:[0,1]
	v_pk_add_f32 v[56:57], v[54:55], v[70:71]
	v_pk_add_f32 v[48:49], v[44:45], v[68:69]
	v_pk_add_f32 v[44:45], v[44:45], v[68:69] neg_lo:[0,1] neg_hi:[0,1]
	v_pk_fma_f32 v[68:69], v[60:61], v[46:47], v[66:67] op_sel:[1,0,1] op_sel_hi:[1,1,0] neg_lo:[0,0,1] neg_hi:[0,0,1]
	v_pk_fma_f32 v[46:47], v[60:61], v[46:47], v[66:67] op_sel:[1,0,1] op_sel_hi:[1,1,0]
	v_pk_add_f32 v[54:55], v[54:55], v[70:71] neg_lo:[0,1] neg_hi:[0,1]
	v_mov_b32_e32 v69, v47
	v_pk_mul_f32 v[66:67], v[60:61], v[56:57] op_sel:[1,0]
	v_pk_add_f32 v[46:47], v[42:43], v[68:69]
	v_pk_add_f32 v[42:43], v[42:43], v[68:69] neg_lo:[0,1] neg_hi:[0,1]
	v_pk_fma_f32 v[68:69], v[64:65], v[56:57], v[66:67] op_sel:[0,0,1] op_sel_hi:[1,1,0]
	v_pk_fma_f32 v[56:57], v[64:65], v[56:57], v[66:67] op_sel:[0,0,1] op_sel_hi:[0,1,0] neg_lo:[0,0,1] neg_hi:[0,0,1]
	v_pk_mul_f32 v[64:65], v[64:65], v[54:55] op_sel_hi:[0,1]
	v_pk_fma_f32 v[66:67], v[60:61], v[54:55], v[64:65] op_sel:[1,0,1] op_sel_hi:[1,1,0] neg_lo:[0,0,1] neg_hi:[0,0,1]
	v_pk_fma_f32 v[54:55], v[60:61], v[54:55], v[64:65] op_sel:[1,0,1] op_sel_hi:[1,1,0]
	v_fmamk_f32 v60, v59, 0x80000000, v62
	v_mov_b32_e32 v67, v55
	v_fma_f32 v58, 0, v62, v59
	v_pk_mul_f32 v[64:65], v[60:61], v[38:39] op_sel_hi:[0,1]
	v_mov_b32_e32 v69, v57
	v_pk_add_f32 v[54:55], v[50:51], v[66:67]
	v_pk_add_f32 v[50:51], v[50:51], v[66:67] neg_lo:[0,1] neg_hi:[0,1]
	v_pk_fma_f32 v[66:67], v[58:59], v[38:39], v[64:65] op_sel:[0,0,1] op_sel_hi:[1,1,0]
	v_pk_fma_f32 v[38:39], v[58:59], v[38:39], v[64:65] op_sel:[0,0,1] op_sel_hi:[0,1,0] neg_lo:[0,0,1] neg_hi:[0,0,1]
	v_pk_mul_f32 v[64:65], v[62:63], s[10:11] op_sel_hi:[1,0]
	v_pk_add_f32 v[56:57], v[52:53], v[68:69]
	v_pk_add_f32 v[52:53], v[52:53], v[68:69] neg_lo:[0,1] neg_hi:[0,1]
	v_mov_b32_e32 v67, v39
	v_pk_add_f32 v[68:69], v[64:65], v[64:65] op_sel:[0,1] op_sel_hi:[0,1] neg_lo:[0,1] neg_hi:[0,1]
	v_pk_add_f32 v[38:39], v[30:31], v[66:67]
	v_pk_add_f32 v[30:31], v[30:31], v[66:67] neg_lo:[0,1] neg_hi:[0,1]
	v_pk_add_f32 v[66:67], v[64:65], v[64:65] op_sel:[1,0] op_sel_hi:[1,0]
	v_pk_mul_f32 v[70:71], v[68:69], v[36:37]
	v_fma_f32 v64, 0, v59, v62
	v_pk_fma_f32 v[72:73], v[66:67], v[36:37], v[70:71] op_sel:[0,0,1] op_sel_hi:[1,1,0]
	v_pk_fma_f32 v[36:37], v[66:67], v[36:37], v[70:71] op_sel:[0,0,1] op_sel_hi:[1,1,0] neg_lo:[0,0,1] neg_hi:[0,0,1]
	v_fma_f32 v70, v62, 0, -v59
	v_mov_b32_e32 v73, v37
	v_pk_add_f32 v[36:37], v[28:29], v[72:73]
	v_pk_add_f32 v[28:29], v[28:29], v[72:73] neg_lo:[0,1] neg_hi:[0,1]
	v_pk_mul_f32 v[72:73], v[70:71], v[34:35] op_sel_hi:[0,1]
	v_pk_fma_f32 v[74:75], v[64:65], v[34:35], v[72:73] op_sel:[0,0,1] op_sel_hi:[1,1,0]
	v_pk_fma_f32 v[34:35], v[64:65], v[34:35], v[72:73] op_sel:[0,0,1] op_sel_hi:[0,1,0] neg_lo:[0,0,1] neg_hi:[0,0,1]
	v_fma_f32 v62, v62, s11, -v65
	v_mov_b32_e32 v75, v35
	v_pk_mul_f32 v[72:73], v[62:63], v[32:33] op_sel_hi:[0,1]
	v_pk_mul_f32 v[60:61], v[60:61], v[56:57] op_sel_hi:[0,1]
	v_pk_add_f32 v[34:35], v[26:27], v[74:75]
	v_pk_add_f32 v[26:27], v[26:27], v[74:75] neg_lo:[0,1] neg_hi:[0,1]
	v_pk_fma_f32 v[74:75], v[68:69], v[32:33], v[72:73] op_sel:[0,0,1] op_sel_hi:[1,1,0]
	v_pk_fma_f32 v[32:33], v[68:69], v[32:33], v[72:73] op_sel:[0,0,1] op_sel_hi:[1,1,0] neg_lo:[0,0,1] neg_hi:[0,0,1]
	v_pk_fma_f32 v[72:73], v[58:59], v[56:57], v[60:61] op_sel:[0,0,1] op_sel_hi:[1,1,0]
; #define LAS __attribute__((address_space(3)))
; __device__ __forceinline__ f32x2 cmul(f32x2 a, f32x2 b) { return (f32x2){a.x * b.x - a.y * b.y, a.x * b.y + a.y * b.x}; }
; __device__ __forceinline__ f32x2 cmulc(f32x2 a, f32x2 b) { return (f32x2){a.x * b.x + a.y * b.y, a.y * b.x - a.x * b.y}; }
; template <bool INV, int ST> __device__ __forceinline__ void fft_pass16(LAS f32x2* buf, int base, int bl) {
;     constexpr float C16[8] = {1.f, 0.92387953251f, 0.70710678119f, 0.38268343237f, 0.f, -0.38268343237f, -0.70710678119f, -0.92387953251f};
;     constexpr float S16[8] = {0.f, 0.38268343237f, 0.70710678119f, 0.92387953251f, 1.f, 0.92387953251f, 0.70710678119f, 0.38268343237f};
;     f32x2 x[16];
;     constexpr int STEP = (1 << ST) + ((1 << ST) >> 4);
;     LAS f32x2* pb = buf + PADI(base);
; #pragma unroll
;     for (int d = 0; d < 16; ++d) x[d] = pb[d * STEP];
;     const float th = (float)bl * (1.f / (float)(16 << ST));
;     const f32x2 W1 = {__builtin_amdgcn_cosf(th), -__builtin_amdgcn_sinf(th)};
;     ...
;         for (int g = 0; g < 16; g += 8)
; #pragma unroll
;             for (int dd = 0; dd < 4; ++dd) { const int d = g + dd; const f32x2 w = cmul(W2, (f32x2){C16[2 * dd], -S16[2 * dd]}); const f32x2 a = x[d], b = cmulc(x[d + 4], w); x[d] = a + b; x[d + 4] = a - b; }
; #pragma unroll
;         for (int d = 0; d < 8; ++d) { const f32x2 w = cmul(W1, (f32x2){C16[d], -S16[d]}); const f32x2 a = x[d], b = cmulc(x[d + 8], w); x[d] = a + b; x[d + 8] = a - b; }
;     }
; #pragma unroll
;     for (int d = 0; d < 16; ++d) pb[d * STEP] = x[d];
; __device__ __forceinline__ void fft_inv_cba(LAS f32x2* buf, int tid) {
;     ...
;     fft_pass16<true, 5>(buf, ((tid >> 5) << 9) + (tid & 31), tid & 31); __syncthreads();
	v_pk_fma_f32 v[56:57], v[58:59], v[56:57], v[60:61] op_sel:[0,0,1] op_sel_hi:[0,1,0] neg_lo:[0,0,1] neg_hi:[0,0,1]
	v_pk_mul_f32 v[58:59], v[68:69], v[54:55]
	v_mov_b32_e32 v73, v57
	v_pk_fma_f32 v[60:61], v[66:67], v[54:55], v[58:59] op_sel:[0,0,1] op_sel_hi:[1,1,0]
	v_pk_fma_f32 v[54:55], v[66:67], v[54:55], v[58:59] op_sel:[0,0,1] op_sel_hi:[1,1,0] neg_lo:[0,0,1] neg_hi:[0,0,1]
	v_pk_mul_f32 v[58:59], v[70:71], v[52:53] op_sel_hi:[0,1]
	v_mov_b32_e32 v61, v55
	v_pk_add_f32 v[54:55], v[46:47], v[60:61]
	v_pk_add_f32 v[46:47], v[46:47], v[60:61] neg_lo:[0,1] neg_hi:[0,1]
	v_pk_fma_f32 v[60:61], v[64:65], v[52:53], v[58:59] op_sel:[0,0,1] op_sel_hi:[1,1,0]
	v_pk_fma_f32 v[52:53], v[64:65], v[52:53], v[58:59] op_sel:[0,0,1] op_sel_hi:[0,1,0] neg_lo:[0,0,1] neg_hi:[0,0,1]
	v_mov_b32_e32 v61, v53
	v_pk_mul_f32 v[58:59], v[62:63], v[50:51] op_sel_hi:[0,1]
	v_pk_add_f32 v[52:53], v[44:45], v[60:61]
	v_pk_add_f32 v[44:45], v[44:45], v[60:61] neg_lo:[0,1] neg_hi:[0,1]
	v_pk_fma_f32 v[60:61], v[68:69], v[50:51], v[58:59] op_sel:[0,0,1] op_sel_hi:[1,1,0]
	v_pk_fma_f32 v[50:51], v[68:69], v[50:51], v[58:59] op_sel:[0,0,1] op_sel_hi:[1,1,0] neg_lo:[0,0,1] neg_hi:[0,0,1]
	v_pk_add_f32 v[56:57], v[48:49], v[72:73]
	v_mov_b32_e32 v61, v51
	v_pk_add_f32 v[50:51], v[42:43], v[60:61]
	v_pk_add_f32 v[42:43], v[42:43], v[60:61] neg_lo:[0,1] neg_hi:[0,1]
	v_fma_f32 v60, v20, s22, -v21
	v_fmamk_f32 v58, v21, 0x80000000, v20
	v_pk_mul_f32 v[60:61], v[60:61], v[56:57] op_sel:[0,1] op_sel_hi:[0,0]
	v_pk_fma_f32 v[62:63], v[58:59], v[56:57], v[60:61]
	v_pk_fma_f32 v[56:57], v[58:59], v[56:57], v[60:61] op_sel_hi:[0,1,1] neg_lo:[0,0,1] neg_hi:[0,0,1]
	v_mov_b32_e32 v58, v21
	v_mov_b32_e32 v59, v20
	s_mov_b32 s7, s10
	s_mov_b32 s21, 0x3ec3ef15
	s_mov_b32 s97, s20
	v_mov_b32_e32 v63, v57
	v_pk_mul_f32 v[60:61], v[58:59], s[6:7]
	v_pk_mul_f32 v[64:65], v[58:59], s[20:21]
	v_pk_mul_f32 v[58:59], v[58:59], s[96:97]
	v_pk_add_f32 v[56:57], v[38:39], v[62:63]
	v_pk_add_f32 v[38:39], v[38:39], v[62:63] neg_lo:[0,1] neg_hi:[0,1]
	v_pk_add_f32 v[62:63], v[60:61], v[60:61] op_sel:[0,1] op_sel_hi:[0,1] neg_lo:[0,1] neg_hi:[0,1]
	v_fma_f32 v60, v21, s2, -v65
	v_pk_add_f32 v[70:71], v[58:59], v[58:59] op_sel:[0,1] op_sel_hi:[0,1] neg_lo:[0,1] neg_hi:[0,1]
	v_pk_add_f32 v[48:49], v[48:49], v[72:73] neg_lo:[0,1] neg_hi:[0,1]
	v_pk_mul_f32 v[66:67], v[60:61], v[54:55] op_sel:[0,1] op_sel_hi:[0,0]
	v_pk_add_f32 v[68:69], v[64:65], v[64:65] op_sel:[1,0] op_sel_hi:[1,0] neg_lo:[0,1] neg_hi:[0,1]
	v_pk_mul_f32 v[70:71], v[70:71], v[50:51] op_sel:[0,1] op_sel_hi:[1,0]
	v_fma_f32 v60, v21, s22, -v20
	v_pk_fma_f32 v[72:73], v[68:69], v[50:51], v[70:71]
	v_pk_fma_f32 v[50:51], v[68:69], v[50:51], v[70:71] neg_lo:[0,0,1] neg_hi:[0,0,1]
	v_fma_f32 v58, v20, 0, -v21
	v_pk_mul_f32 v[68:69], v[60:61], v[48:49] op_sel:[0,1] op_sel_hi:[0,0]
	v_pk_fma_f32 v[70:71], v[58:59], v[48:49], v[68:69]
	v_pk_fma_f32 v[48:49], v[58:59], v[48:49], v[68:69] op_sel_hi:[0,1,1] neg_lo:[0,0,1] neg_hi:[0,0,1]
	v_pk_mul_f32 v[68:69], v[20:21], s[6:7]
	v_pk_mul_f32 v[62:63], v[62:63], v[52:53] op_sel:[0,1] op_sel_hi:[1,0]
	v_mov_b32_e32 v71, v49
	v_sub_f32_e32 v60, v61, v69
	v_pk_add_f32 v[48:49], v[30:31], v[70:71]
	v_pk_add_f32 v[30:31], v[30:31], v[70:71] neg_lo:[0,1] neg_hi:[0,1]
	v_pk_fma_f32 v[70:71], v[60:61], v[52:53], v[62:63] op_sel_hi:[0,1,1]
	v_pk_fma_f32 v[52:53], v[60:61], v[52:53], v[62:63] op_sel_hi:[0,1,1] neg_lo:[0,0,1] neg_hi:[0,0,1]
	v_sub_f32_e32 v60, v69, v61
	s_mov_b32 s3, s21
	v_fma_f32 v58, v20, s96, -v64
	v_pk_add_f32 v[62:63], v[68:69], v[68:69] op_sel:[0,1] op_sel_hi:[0,1] neg_lo:[0,1] neg_hi:[0,1]
	v_pk_mul_f32 v[60:61], v[60:61], v[44:45] op_sel:[0,1] op_sel_hi:[0,0]
	v_pk_mul_f32 v[20:21], v[20:21], s[2:3]
	v_pk_fma_f32 v[68:69], v[62:63], v[44:45], v[60:61]
	v_pk_fma_f32 v[44:45], v[62:63], v[44:45], v[60:61] neg_lo:[0,0,1] neg_hi:[0,0,1]
	v_sub_f32_e32 v60, v59, v21
	v_pk_fma_f32 v[62:63], v[60:61], v[54:55], v[66:67] op_sel_hi:[0,1,1]
	v_pk_fma_f32 v[54:55], v[60:61], v[54:55], v[66:67] op_sel_hi:[0,1,1] neg_lo:[0,0,1] neg_hi:[0,0,1]
	v_sub_f32_e32 v60, v21, v59
	v_mov_b32_e32 v63, v55
	v_pk_mul_f32 v[60:61], v[60:61], v[46:47] op_sel:[0,1] op_sel_hi:[0,0]
	v_pk_add_f32 v[54:55], v[36:37], v[62:63]
	v_pk_add_f32 v[36:37], v[36:37], v[62:63] neg_lo:[0,1] neg_hi:[0,1]
	v_pk_fma_f32 v[62:63], v[58:59], v[46:47], v[60:61]
	v_pk_fma_f32 v[46:47], v[58:59], v[46:47], v[60:61] op_sel_hi:[0,1,1] neg_lo:[0,0,1] neg_hi:[0,0,1]
	v_pk_add_f32 v[58:59], v[64:65], v[64:65] op_sel:[0,1] op_sel_hi:[0,1] neg_lo:[0,1] neg_hi:[0,1]
	v_pk_add_f32 v[20:21], v[20:21], v[20:21] op_sel:[0,1] op_sel_hi:[0,1] neg_lo:[0,1] neg_hi:[0,1]
	v_pk_mul_f32 v[58:59], v[58:59], v[42:43] op_sel:[0,1] op_sel_hi:[1,0]
	v_mov_b32_e32 v75, v33
	v_pk_fma_f32 v[60:61], v[20:21], v[42:43], v[58:59]
	v_pk_fma_f32 v[20:21], v[20:21], v[42:43], v[58:59] neg_lo:[0,0,1] neg_hi:[0,0,1]
	v_pk_add_f32 v[32:33], v[24:25], v[74:75]
	v_pk_add_f32 v[24:25], v[24:25], v[74:75] neg_lo:[0,1] neg_hi:[0,1]
	v_mov_b32_e32 v61, v21
	v_lshlrev_b32_e32 v41, 4, v2
	v_mov_b32_e32 v73, v51
	v_mov_b32_e32 v71, v53
	v_mov_b32_e32 v69, v45
	v_mov_b32_e32 v63, v47
	v_pk_add_f32 v[20:21], v[24:25], v[60:61]
	v_pk_add_f32 v[50:51], v[32:33], v[72:73]
	v_pk_add_f32 v[32:33], v[32:33], v[72:73] neg_lo:[0,1] neg_hi:[0,1]
	v_pk_add_f32 v[52:53], v[34:35], v[70:71]
	v_pk_add_f32 v[34:35], v[34:35], v[70:71] neg_lo:[0,1] neg_hi:[0,1]
	v_pk_add_f32 v[44:45], v[26:27], v[68:69]
	v_pk_add_f32 v[26:27], v[26:27], v[68:69] neg_lo:[0,1] neg_hi:[0,1]
	v_pk_add_f32 v[46:47], v[28:29], v[62:63]
	v_pk_add_f32 v[28:29], v[28:29], v[62:63] neg_lo:[0,1] neg_hi:[0,1]
	v_pk_add_f32 v[24:25], v[24:25], v[60:61] neg_lo:[0,1] neg_hi:[0,1]
	ds_write2_b64 v76, v[56:57], v[54:55] offset1:2
	ds_write2_b64 v76, v[52:53], v[50:51] offset0:4 offset1:6
	ds_write2_b64 v76, v[48:49], v[46:47] offset0:8 offset1:10
	ds_write2_b64 v76, v[44:45], v[20:21] offset0:12 offset1:14
	ds_write2_b64 v76, v[38:39], v[36:37] offset0:16 offset1:18
	ds_write2_b64 v76, v[34:35], v[32:33] offset0:20 offset1:22
	ds_write2_b64 v76, v[30:31], v[28:29] offset0:24 offset1:26
	ds_write2_b64 v76, v[26:27], v[24:25] offset0:28 offset1:30
	v_and_b32_e32 v20, 0xfffffe00, v41
	v_and_b32_e32 v21, 31, v2
	v_lshl_add_u32 v24, v20, 3, 0
	v_lshlrev_b32_e32 v25, 3, v21
	v_ashrrev_i32_e32 v20, 1, v20
	v_add3_u32 v41, v24, v25, v20
	v_cvt_f32_ubyte0_e32 v20, v21
	v_mul_f32_e32 v21, 0x3b000000, v20
	v_cos_f32_e32 v20, v21
	v_sin_f32_e32 v21, v21
	s_waitcnt lgkmcnt(0)
	s_barrier
; #define LAS __attribute__((address_space(3)))
; __device__ __forceinline__ f32x2 cmul(f32x2 a, f32x2 b) { return (f32x2){a.x * b.x - a.y * b.y, a.x * b.y + a.y * b.x}; }
; template <bool INV, int ST> __device__ __forceinline__ void fft_pass16(LAS f32x2* buf, int base, int bl) {
;     constexpr float C16[8] = {1.f, 0.92387953251f, 0.70710678119f, 0.38268343237f, 0.f, -0.38268343237f, -0.70710678119f, -0.92387953251f};
;     constexpr float S16[8] = {0.f, 0.38268343237f, 0.70710678119f, 0.92387953251f, 1.f, 0.92387953251f, 0.70710678119f, 0.38268343237f};
;     f32x2 x[16];
;     constexpr int STEP = (1 << ST) + ((1 << ST) >> 4);
;     LAS f32x2* pb = buf + PADI(base);
; #pragma unroll
;     for (int d = 0; d < 16; ++d) x[d] = pb[d * STEP];
;     const float th = (float)bl * (1.f / (float)(16 << ST));
;     const f32x2 W1 = {__builtin_amdgcn_cosf(th), -__builtin_amdgcn_sinf(th)};
;     const f32x2 W2 = cmul(W1, W1), W4 = cmul(W2, W2), W8 = cmul(W4, W4);
;     if (!INV) {
; #pragma unroll
;         for (int d = 0; d < 8; ++d) { const f32x2 w = cmul(W1, (f32x2){C16[d], -S16[d]}); const f32x2 a = x[d], b = x[d + 8]; x[d] = a + b; x[d + 8] = cmul(a - b, w); }
; #pragma unroll
;         for (int g = 0; g < 16; g += 8)
; #pragma unroll
;             for (int dd = 0; dd < 4; ++dd) { const int d = g + dd; const f32x2 w = cmul(W2, (f32x2){C16[2 * dd], -S16[2 * dd]}); const f32x2 a = x[d], b = x[d + 4]; x[d] = a + b; x[d + 4] = cmul(a - b, w); }
; #pragma unroll
;         for (int g = 0; g < 16; g += 4)
; #pragma unroll
;             for (int dd = 0; dd < 2; ++dd) { const int d = g + dd; const f32x2 w = dd ? (f32x2){W4.y, -W4.x} : W4; const f32x2 a = x[d], b = x[d + 2]; x[d] = a + b; x[d + 2] = cmul(a - b, w); }
; #pragma unroll
;         for (int g = 0; g < 16; g += 2) { const f32x2 a = x[g], b = x[g + 1]; x[g] = a + b; x[g + 1] = cmul(a - b, W8); }
;     } else {
; #pragma unroll
;         for (int g = 0; g < 16; g += 2) { const f32x2 a = x[g], b = cmulc(x[g + 1], W8); x[g] = a + b; x[g + 1] = a - b; }
; #pragma unroll
;         for (int g = 0; g < 16; g += 4)
; #pragma unroll
;             for (int dd = 0; dd < 2; ++dd) { const int d = g + dd; const f32x2 w = dd ? (f32x2){W4.y, -W4.x} : W4; const f32x2 a = x[d], b = cmulc(x[d + 2], w); x[d] = a + b; x[d + 2] = a - b; }
	v_mov_b32_e32 v59, v20
	v_xor_b32_e32 v58, 0x80000000, v21
	v_mov_b32_e32 v60, v58
	v_mov_b32_e32 v61, v21
	v_pk_mul_f32 v[60:61], v[20:21], v[60:61]
	s_nop 0
	v_pk_fma_f32 v[62:63], v[20:21], v[58:59], v[60:61] op_sel_hi:[0,1,1]
	v_pk_fma_f32 v[58:59], v[20:21], v[58:59], v[60:61] op_sel_hi:[0,1,1] neg_lo:[0,0,1] neg_hi:[0,0,1]
	v_mov_b32_e32 v63, v59
	v_pk_mul_f32 v[60:61], v[62:63], v[62:63]
	v_pk_mul_f32 v[64:65], v[58:59], v[62:63] op_sel:[1,0] op_sel_hi:[0,1]
	v_pk_mov_b32 v[66:67], v[60:61], v[64:65] op_sel:[1,0]
	v_mov_b32_e32 v61, v64
	v_pk_add_f32 v[64:65], v[66:67], v[60:61] neg_lo:[0,1] neg_hi:[0,1]
	v_pk_add_f32 v[60:61], v[66:67], v[60:61]
	ds_read2_b64 v[24:27], v41 offset1:34
	ds_read2_b64 v[28:31], v41 offset0:68 offset1:102
	ds_read2_b64 v[32:35], v41 offset0:136 offset1:170
	ds_read2_b64 v[36:39], v41 offset0:204 offset1:238
	v_mov_b32_e32 v66, v64
	v_mov_b32_e32 v67, v61
	v_mul_f32_e32 v58, v64, v61
	v_pk_mul_f32 v[66:67], v[66:67], v[66:67]
	v_add_f32_e32 v58, v58, v58
	v_pk_add_f32 v[66:67], v[66:67], v[66:67] op_sel:[0,1] op_sel_hi:[0,1] neg_lo:[0,1] neg_hi:[0,1]
	s_waitcnt lgkmcnt(3)
	v_pk_mul_f32 v[68:69], v[58:59], v[26:27] op_sel_hi:[0,1]
	v_pk_fma_f32 v[70:71], v[66:67], v[26:27], v[68:69] op_sel:[0,0,1] op_sel_hi:[1,1,0]
	v_pk_fma_f32 v[26:27], v[66:67], v[26:27], v[68:69] op_sel:[0,0,1] op_sel_hi:[1,1,0] neg_lo:[0,0,1] neg_hi:[0,0,1]
	s_waitcnt lgkmcnt(2)
	v_pk_mul_f32 v[68:69], v[58:59], v[30:31] op_sel_hi:[0,1]
	v_mov_b32_e32 v71, v27
	v_pk_add_f32 v[26:27], v[24:25], v[70:71]
	v_pk_add_f32 v[24:25], v[24:25], v[70:71] neg_lo:[0,1] neg_hi:[0,1]
	v_pk_fma_f32 v[70:71], v[66:67], v[30:31], v[68:69] op_sel:[0,0,1] op_sel_hi:[1,1,0]
	v_pk_fma_f32 v[30:31], v[66:67], v[30:31], v[68:69] op_sel:[0,0,1] op_sel_hi:[1,1,0] neg_lo:[0,0,1] neg_hi:[0,0,1]
	s_waitcnt lgkmcnt(1)
	v_pk_mul_f32 v[68:69], v[58:59], v[34:35] op_sel_hi:[0,1]
	v_mov_b32_e32 v71, v31
	v_add_u32_e32 v76, 0x800, v41
	v_pk_add_f32 v[30:31], v[28:29], v[70:71]
	v_pk_add_f32 v[28:29], v[28:29], v[70:71] neg_lo:[0,1] neg_hi:[0,1]
	v_pk_fma_f32 v[70:71], v[66:67], v[34:35], v[68:69] op_sel:[0,0,1] op_sel_hi:[1,1,0]
	v_pk_fma_f32 v[34:35], v[66:67], v[34:35], v[68:69] op_sel:[0,0,1] op_sel_hi:[1,1,0] neg_lo:[0,0,1] neg_hi:[0,0,1]
	ds_read2_b64 v[42:45], v76 offset0:16 offset1:50
	ds_read2_b64 v[46:49], v76 offset0:84 offset1:118
	ds_read2_b64 v[50:53], v76 offset0:152 offset1:186
	ds_read2_b64 v[54:57], v76 offset0:220 offset1:254
	v_mov_b32_e32 v71, v35
	s_waitcnt lgkmcnt(4)
	v_pk_mul_f32 v[68:69], v[58:59], v[38:39] op_sel_hi:[0,1]
	v_pk_add_f32 v[34:35], v[32:33], v[70:71]
	v_pk_add_f32 v[32:33], v[32:33], v[70:71] neg_lo:[0,1] neg_hi:[0,1]
	v_pk_fma_f32 v[70:71], v[66:67], v[38:39], v[68:69] op_sel:[0,0,1] op_sel_hi:[1,1,0]
	v_pk_fma_f32 v[38:39], v[66:67], v[38:39], v[68:69] op_sel:[0,0,1] op_sel_hi:[1,1,0] neg_lo:[0,0,1] neg_hi:[0,0,1]
	s_waitcnt lgkmcnt(3)
	v_pk_mul_f32 v[68:69], v[58:59], v[44:45] op_sel_hi:[0,1]
	v_mov_b32_e32 v71, v39
	v_pk_add_f32 v[38:39], v[36:37], v[70:71]
	v_pk_add_f32 v[36:37], v[36:37], v[70:71] neg_lo:[0,1] neg_hi:[0,1]
	v_pk_fma_f32 v[70:71], v[66:67], v[44:45], v[68:69] op_sel:[0,0,1] op_sel_hi:[1,1,0]
	v_pk_fma_f32 v[44:45], v[66:67], v[44:45], v[68:69] op_sel:[0,0,1] op_sel_hi:[1,1,0] neg_lo:[0,0,1] neg_hi:[0,0,1]
	s_waitcnt lgkmcnt(2)
	v_pk_mul_f32 v[68:69], v[58:59], v[48:49] op_sel_hi:[0,1]
	v_mov_b32_e32 v71, v45
	v_pk_add_f32 v[44:45], v[42:43], v[70:71]
	v_pk_add_f32 v[42:43], v[42:43], v[70:71] neg_lo:[0,1] neg_hi:[0,1]
	v_pk_fma_f32 v[70:71], v[66:67], v[48:49], v[68:69] op_sel:[0,0,1] op_sel_hi:[1,1,0]
	v_pk_fma_f32 v[48:49], v[66:67], v[48:49], v[68:69] op_sel:[0,0,1] op_sel_hi:[1,1,0] neg_lo:[0,0,1] neg_hi:[0,0,1]
	s_waitcnt lgkmcnt(1)
	v_pk_mul_f32 v[68:69], v[58:59], v[52:53] op_sel_hi:[0,1]
	v_mov_b32_e32 v71, v49
	v_pk_add_f32 v[48:49], v[46:47], v[70:71]
	v_pk_add_f32 v[46:47], v[46:47], v[70:71] neg_lo:[0,1] neg_hi:[0,1]
	v_pk_fma_f32 v[70:71], v[66:67], v[52:53], v[68:69] op_sel:[0,0,1] op_sel_hi:[1,1,0]
	v_pk_fma_f32 v[52:53], v[66:67], v[52:53], v[68:69] op_sel:[0,0,1] op_sel_hi:[1,1,0] neg_lo:[0,0,1] neg_hi:[0,0,1]
	s_waitcnt lgkmcnt(0)
	v_pk_mul_f32 v[68:69], v[58:59], v[56:57] op_sel_hi:[0,1]
	v_mov_b32_e32 v71, v53
	v_pk_add_f32 v[52:53], v[50:51], v[70:71]
	v_pk_add_f32 v[50:51], v[50:51], v[70:71] neg_lo:[0,1] neg_hi:[0,1]
	v_pk_fma_f32 v[70:71], v[66:67], v[56:57], v[68:69] op_sel:[0,0,1] op_sel_hi:[1,1,0]
	v_pk_fma_f32 v[56:57], v[66:67], v[56:57], v[68:69] op_sel:[0,0,1] op_sel_hi:[1,1,0] neg_lo:[0,0,1] neg_hi:[0,0,1]
	v_pk_mul_f32 v[66:67], v[60:61], v[30:31] op_sel:[1,0]
	v_mov_b32_e32 v71, v57
	v_pk_fma_f32 v[68:69], v[64:65], v[30:31], v[66:67] op_sel:[0,0,1] op_sel_hi:[1,1,0]
	v_pk_fma_f32 v[30:31], v[64:65], v[30:31], v[66:67] op_sel:[0,0,1] op_sel_hi:[0,1,0] neg_lo:[0,0,1] neg_hi:[0,0,1]
	v_mov_b32_e32 v69, v31
	v_pk_mul_f32 v[66:67], v[64:65], v[28:29] op_sel_hi:[0,1]
	v_pk_add_f32 v[30:31], v[26:27], v[68:69]
	v_pk_add_f32 v[26:27], v[26:27], v[68:69] neg_lo:[0,1] neg_hi:[0,1]
	v_pk_fma_f32 v[68:69], v[60:61], v[28:29], v[66:67] op_sel:[1,0,1] op_sel_hi:[1,1,0] neg_lo:[0,0,1] neg_hi:[0,0,1]
	v_pk_fma_f32 v[28:29], v[60:61], v[28:29], v[66:67] op_sel:[1,0,1] op_sel_hi:[1,1,0]
	v_pk_mul_f32 v[66:67], v[60:61], v[38:39] op_sel:[1,0]
	v_mov_b32_e32 v69, v29
	v_pk_add_f32 v[28:29], v[24:25], v[68:69]
	v_pk_add_f32 v[24:25], v[24:25], v[68:69] neg_lo:[0,1] neg_hi:[0,1]
	v_pk_fma_f32 v[68:69], v[64:65], v[38:39], v[66:67] op_sel:[0,0,1] op_sel_hi:[1,1,0]
	v_pk_fma_f32 v[38:39], v[64:65], v[38:39], v[66:67] op_sel:[0,0,1] op_sel_hi:[0,1,0] neg_lo:[0,0,1] neg_hi:[0,0,1]
; __device__ __forceinline__ f32x2 cmul(f32x2 a, f32x2 b) { return (f32x2){a.x * b.x - a.y * b.y, a.x * b.y + a.y * b.x}; }
; __device__ __forceinline__ f32x2 cmulc(f32x2 a, f32x2 b) { return (f32x2){a.x * b.x + a.y * b.y, a.y * b.x - a.x * b.y}; }
; template <bool INV, int ST> __device__ __forceinline__ void fft_pass16(LAS f32x2* buf, int base, int bl) {
;     ...
;         for (int g = 0; g < 16; g += 4)
; #pragma unroll
;             for (int dd = 0; dd < 2; ++dd) { const int d = g + dd; const f32x2 w = dd ? (f32x2){W4.y, -W4.x} : W4; const f32x2 a = x[d], b = cmulc(x[d + 2], w); x[d] = a + b; x[d + 2] = a - b; }
; #pragma unroll
;         for (int g = 0; g < 16; g += 8)
; #pragma unroll
;             for (int dd = 0; dd < 4; ++dd) { const int d = g + dd; const f32x2 w = cmul(W2, (f32x2){C16[2 * dd], -S16[2 * dd]}); const f32x2 a = x[d], b = cmulc(x[d + 4], w); x[d] = a + b; x[d + 4] = a - b; }
; #pragma unroll
;         for (int d = 0; d < 8; ++d) { const f32x2 w = cmul(W1, (f32x2){C16[d], -S16[d]}); const f32x2 a = x[d], b = cmulc(x[d + 8], w); x[d] = a + b; x[d + 8] = a - b; }
	v_mov_b32_e32 v69, v39
	v_pk_mul_f32 v[66:67], v[64:65], v[36:37] op_sel_hi:[0,1]
	v_pk_add_f32 v[38:39], v[34:35], v[68:69]
	v_pk_add_f32 v[34:35], v[34:35], v[68:69] neg_lo:[0,1] neg_hi:[0,1]
	v_pk_fma_f32 v[68:69], v[60:61], v[36:37], v[66:67] op_sel:[1,0,1] op_sel_hi:[1,1,0] neg_lo:[0,0,1] neg_hi:[0,0,1]
	v_pk_fma_f32 v[36:37], v[60:61], v[36:37], v[66:67] op_sel:[1,0,1] op_sel_hi:[1,1,0]
	v_pk_mul_f32 v[66:67], v[60:61], v[48:49] op_sel:[1,0]
	v_mov_b32_e32 v69, v37
	v_pk_add_f32 v[36:37], v[32:33], v[68:69]
	v_pk_add_f32 v[32:33], v[32:33], v[68:69] neg_lo:[0,1] neg_hi:[0,1]
	v_pk_fma_f32 v[68:69], v[64:65], v[48:49], v[66:67] op_sel:[0,0,1] op_sel_hi:[1,1,0]
	v_pk_fma_f32 v[48:49], v[64:65], v[48:49], v[66:67] op_sel:[0,0,1] op_sel_hi:[0,1,0] neg_lo:[0,0,1] neg_hi:[0,0,1]
	v_mov_b32_e32 v69, v49
	v_pk_mul_f32 v[66:67], v[64:65], v[46:47] op_sel_hi:[0,1]
	v_pk_add_f32 v[56:57], v[54:55], v[70:71]
	v_pk_add_f32 v[48:49], v[44:45], v[68:69]
	v_pk_add_f32 v[44:45], v[44:45], v[68:69] neg_lo:[0,1] neg_hi:[0,1]
	v_pk_fma_f32 v[68:69], v[60:61], v[46:47], v[66:67] op_sel:[1,0,1] op_sel_hi:[1,1,0] neg_lo:[0,0,1] neg_hi:[0,0,1]
	v_pk_fma_f32 v[46:47], v[60:61], v[46:47], v[66:67] op_sel:[1,0,1] op_sel_hi:[1,1,0]
	v_pk_add_f32 v[54:55], v[54:55], v[70:71] neg_lo:[0,1] neg_hi:[0,1]
	v_mov_b32_e32 v69, v47
	v_pk_mul_f32 v[66:67], v[60:61], v[56:57] op_sel:[1,0]
	v_pk_add_f32 v[46:47], v[42:43], v[68:69]
	v_pk_add_f32 v[42:43], v[42:43], v[68:69] neg_lo:[0,1] neg_hi:[0,1]
	v_pk_fma_f32 v[68:69], v[64:65], v[56:57], v[66:67] op_sel:[0,0,1] op_sel_hi:[1,1,0]
	v_pk_fma_f32 v[56:57], v[64:65], v[56:57], v[66:67] op_sel:[0,0,1] op_sel_hi:[0,1,0] neg_lo:[0,0,1] neg_hi:[0,0,1]
	v_pk_mul_f32 v[64:65], v[64:65], v[54:55] op_sel_hi:[0,1]
	v_pk_fma_f32 v[66:67], v[60:61], v[54:55], v[64:65] op_sel:[1,0,1] op_sel_hi:[1,1,0] neg_lo:[0,0,1] neg_hi:[0,0,1]
	v_pk_fma_f32 v[54:55], v[60:61], v[54:55], v[64:65] op_sel:[1,0,1] op_sel_hi:[1,1,0]
	v_fmamk_f32 v60, v59, 0x80000000, v62
	v_mov_b32_e32 v67, v55
	v_fma_f32 v58, 0, v62, v59
	v_pk_mul_f32 v[64:65], v[60:61], v[38:39] op_sel_hi:[0,1]
	v_mov_b32_e32 v69, v57
	v_pk_add_f32 v[54:55], v[50:51], v[66:67]
	v_pk_add_f32 v[50:51], v[50:51], v[66:67] neg_lo:[0,1] neg_hi:[0,1]
	v_pk_fma_f32 v[66:67], v[58:59], v[38:39], v[64:65] op_sel:[0,0,1] op_sel_hi:[1,1,0]
	v_pk_fma_f32 v[38:39], v[58:59], v[38:39], v[64:65] op_sel:[0,0,1] op_sel_hi:[0,1,0] neg_lo:[0,0,1] neg_hi:[0,0,1]
	v_pk_mul_f32 v[64:65], v[62:63], s[10:11] op_sel_hi:[1,0]
	v_pk_add_f32 v[56:57], v[52:53], v[68:69]
	v_pk_add_f32 v[52:53], v[52:53], v[68:69] neg_lo:[0,1] neg_hi:[0,1]
	v_mov_b32_e32 v67, v39
	v_pk_add_f32 v[68:69], v[64:65], v[64:65] op_sel:[0,1] op_sel_hi:[0,1] neg_lo:[0,1] neg_hi:[0,1]
	v_pk_add_f32 v[38:39], v[30:31], v[66:67]
	v_pk_add_f32 v[30:31], v[30:31], v[66:67] neg_lo:[0,1] neg_hi:[0,1]
	v_pk_add_f32 v[66:67], v[64:65], v[64:65] op_sel:[1,0] op_sel_hi:[1,0]
	v_pk_mul_f32 v[70:71], v[68:69], v[36:37]
	v_fma_f32 v64, 0, v59, v62
	v_pk_fma_f32 v[72:73], v[66:67], v[36:37], v[70:71] op_sel:[0,0,1] op_sel_hi:[1,1,0]
	v_pk_fma_f32 v[36:37], v[66:67], v[36:37], v[70:71] op_sel:[0,0,1] op_sel_hi:[1,1,0] neg_lo:[0,0,1] neg_hi:[0,0,1]
	v_fma_f32 v70, v62, 0, -v59
	v_mov_b32_e32 v73, v37
	v_pk_add_f32 v[36:37], v[28:29], v[72:73]
	v_pk_add_f32 v[28:29], v[28:29], v[72:73] neg_lo:[0,1] neg_hi:[0,1]
	v_pk_mul_f32 v[72:73], v[70:71], v[34:35] op_sel_hi:[0,1]
	v_pk_fma_f32 v[74:75], v[64:65], v[34:35], v[72:73] op_sel:[0,0,1] op_sel_hi:[1,1,0]
	v_pk_fma_f32 v[34:35], v[64:65], v[34:35], v[72:73] op_sel:[0,0,1] op_sel_hi:[0,1,0] neg_lo:[0,0,1] neg_hi:[0,0,1]
	v_fma_f32 v62, v62, s11, -v65
	v_mov_b32_e32 v75, v35
	v_pk_mul_f32 v[72:73], v[62:63], v[32:33] op_sel_hi:[0,1]
	v_pk_mul_f32 v[60:61], v[60:61], v[56:57] op_sel_hi:[0,1]
	v_pk_add_f32 v[34:35], v[26:27], v[74:75]
	v_pk_add_f32 v[26:27], v[26:27], v[74:75] neg_lo:[0,1] neg_hi:[0,1]
	v_pk_fma_f32 v[74:75], v[68:69], v[32:33], v[72:73] op_sel:[0,0,1] op_sel_hi:[1,1,0]
	v_pk_fma_f32 v[32:33], v[68:69], v[32:33], v[72:73] op_sel:[0,0,1] op_sel_hi:[1,1,0] neg_lo:[0,0,1] neg_hi:[0,0,1]
	v_pk_fma_f32 v[72:73], v[58:59], v[56:57], v[60:61] op_sel:[0,0,1] op_sel_hi:[1,1,0]
	v_pk_fma_f32 v[56:57], v[58:59], v[56:57], v[60:61] op_sel:[0,0,1] op_sel_hi:[0,1,0] neg_lo:[0,0,1] neg_hi:[0,0,1]
	v_pk_mul_f32 v[58:59], v[68:69], v[54:55]
	v_mov_b32_e32 v73, v57
	v_pk_fma_f32 v[60:61], v[66:67], v[54:55], v[58:59] op_sel:[0,0,1] op_sel_hi:[1,1,0]
	v_pk_fma_f32 v[54:55], v[66:67], v[54:55], v[58:59] op_sel:[0,0,1] op_sel_hi:[1,1,0] neg_lo:[0,0,1] neg_hi:[0,0,1]
	v_pk_mul_f32 v[58:59], v[70:71], v[52:53] op_sel_hi:[0,1]
	v_mov_b32_e32 v61, v55
	v_pk_add_f32 v[54:55], v[46:47], v[60:61]
	v_pk_add_f32 v[46:47], v[46:47], v[60:61] neg_lo:[0,1] neg_hi:[0,1]
	v_pk_fma_f32 v[60:61], v[64:65], v[52:53], v[58:59] op_sel:[0,0,1] op_sel_hi:[1,1,0]
	v_pk_fma_f32 v[52:53], v[64:65], v[52:53], v[58:59] op_sel:[0,0,1] op_sel_hi:[0,1,0] neg_lo:[0,0,1] neg_hi:[0,0,1]
	v_mov_b32_e32 v61, v53
	v_pk_mul_f32 v[58:59], v[62:63], v[50:51] op_sel_hi:[0,1]
	v_pk_add_f32 v[52:53], v[44:45], v[60:61]
	v_pk_add_f32 v[44:45], v[44:45], v[60:61] neg_lo:[0,1] neg_hi:[0,1]
	v_pk_fma_f32 v[60:61], v[68:69], v[50:51], v[58:59] op_sel:[0,0,1] op_sel_hi:[1,1,0]
	v_pk_fma_f32 v[50:51], v[68:69], v[50:51], v[58:59] op_sel:[0,0,1] op_sel_hi:[1,1,0] neg_lo:[0,0,1] neg_hi:[0,0,1]
	v_pk_add_f32 v[56:57], v[48:49], v[72:73]
	v_mov_b32_e32 v61, v51
	v_pk_add_f32 v[50:51], v[42:43], v[60:61]
	v_pk_add_f32 v[42:43], v[42:43], v[60:61] neg_lo:[0,1] neg_hi:[0,1]
	v_fma_f32 v60, v20, s22, -v21
	v_fmamk_f32 v58, v21, 0x80000000, v20
; #define LAS __attribute__((address_space(3)))
; __device__ __forceinline__ f32x2 cmul(f32x2 a, f32x2 b) { return (f32x2){a.x * b.x - a.y * b.y, a.x * b.y + a.y * b.x}; }
; __device__ __forceinline__ f32x2 cmulc(f32x2 a, f32x2 b) { return (f32x2){a.x * b.x + a.y * b.y, a.y * b.x - a.x * b.y}; }
; template <bool INV, int ST> __device__ __forceinline__ void fft_pass16(LAS f32x2* buf, int base, int bl) {
;     constexpr float C16[8] = {1.f, 0.92387953251f, 0.70710678119f, 0.38268343237f, 0.f, -0.38268343237f, -0.70710678119f, -0.92387953251f};
;     constexpr float S16[8] = {0.f, 0.38268343237f, 0.70710678119f, 0.92387953251f, 1.f, 0.92387953251f, 0.70710678119f, 0.38268343237f};
;     f32x2 x[16];
;     constexpr int STEP = (1 << ST) + ((1 << ST) >> 4);
;     LAS f32x2* pb = buf + PADI(base);
; #pragma unroll
;     for (int d = 0; d < 16; ++d) x[d] = pb[d * STEP];
;     const float th = (float)bl * (1.f / (float)(16 << ST));
;     const f32x2 W1 = {__builtin_amdgcn_cosf(th), -__builtin_amdgcn_sinf(th)};
;     ...
;             for (int dd = 0; dd < 4; ++dd) { const int d = g + dd; const f32x2 w = cmul(W2, (f32x2){C16[2 * dd], -S16[2 * dd]}); const f32x2 a = x[d], b = cmulc(x[d + 4], w); x[d] = a + b; x[d + 4] = a - b; }
; #pragma unroll
;         for (int d = 0; d < 8; ++d) { const f32x2 w = cmul(W1, (f32x2){C16[d], -S16[d]}); const f32x2 a = x[d], b = cmulc(x[d + 8], w); x[d] = a + b; x[d + 8] = a - b; }
;     }
; #pragma unroll
;     for (int d = 0; d < 16; ++d) pb[d * STEP] = x[d];
; __device__ __forceinline__ void fft_inv_cba(LAS f32x2* buf, int tid) {
;     ...
;     fft_pass16<true, 9>(buf, tid, tid); __syncthreads();
	v_pk_mul_f32 v[60:61], v[60:61], v[56:57] op_sel:[0,1] op_sel_hi:[0,0]
	v_pk_fma_f32 v[62:63], v[58:59], v[56:57], v[60:61]
	v_pk_fma_f32 v[56:57], v[58:59], v[56:57], v[60:61] op_sel_hi:[0,1,1] neg_lo:[0,0,1] neg_hi:[0,0,1]
	v_mov_b32_e32 v58, v21
	v_mov_b32_e32 v59, v20
	v_mov_b32_e32 v63, v57
	v_pk_mul_f32 v[60:61], v[58:59], s[6:7]
	v_pk_mul_f32 v[64:65], v[58:59], s[20:21]
	v_pk_mul_f32 v[58:59], v[58:59], s[96:97]
	v_pk_add_f32 v[56:57], v[38:39], v[62:63]
	v_pk_add_f32 v[38:39], v[38:39], v[62:63] neg_lo:[0,1] neg_hi:[0,1]
	v_pk_add_f32 v[62:63], v[60:61], v[60:61] op_sel:[0,1] op_sel_hi:[0,1] neg_lo:[0,1] neg_hi:[0,1]
	v_fma_f32 v60, v21, s2, -v65
	v_pk_add_f32 v[70:71], v[58:59], v[58:59] op_sel:[0,1] op_sel_hi:[0,1] neg_lo:[0,1] neg_hi:[0,1]
	v_pk_add_f32 v[48:49], v[48:49], v[72:73] neg_lo:[0,1] neg_hi:[0,1]
	v_pk_mul_f32 v[66:67], v[60:61], v[54:55] op_sel:[0,1] op_sel_hi:[0,0]
	v_pk_add_f32 v[68:69], v[64:65], v[64:65] op_sel:[1,0] op_sel_hi:[1,0] neg_lo:[0,1] neg_hi:[0,1]
	v_pk_mul_f32 v[70:71], v[70:71], v[50:51] op_sel:[0,1] op_sel_hi:[1,0]
	v_fma_f32 v60, v21, s22, -v20
	v_pk_fma_f32 v[72:73], v[68:69], v[50:51], v[70:71]
	v_pk_fma_f32 v[50:51], v[68:69], v[50:51], v[70:71] neg_lo:[0,0,1] neg_hi:[0,0,1]
	v_fma_f32 v58, v20, 0, -v21
	v_pk_mul_f32 v[68:69], v[60:61], v[48:49] op_sel:[0,1] op_sel_hi:[0,0]
	v_pk_fma_f32 v[70:71], v[58:59], v[48:49], v[68:69]
	v_pk_fma_f32 v[48:49], v[58:59], v[48:49], v[68:69] op_sel_hi:[0,1,1] neg_lo:[0,0,1] neg_hi:[0,0,1]
	v_pk_mul_f32 v[68:69], v[20:21], s[6:7]
	v_pk_mul_f32 v[62:63], v[62:63], v[52:53] op_sel:[0,1] op_sel_hi:[1,0]
	v_mov_b32_e32 v71, v49
	v_sub_f32_e32 v60, v61, v69
	v_pk_add_f32 v[48:49], v[30:31], v[70:71]
	v_pk_add_f32 v[30:31], v[30:31], v[70:71] neg_lo:[0,1] neg_hi:[0,1]
	v_pk_fma_f32 v[70:71], v[60:61], v[52:53], v[62:63] op_sel_hi:[0,1,1]
	v_pk_fma_f32 v[52:53], v[60:61], v[52:53], v[62:63] op_sel_hi:[0,1,1] neg_lo:[0,0,1] neg_hi:[0,0,1]
	v_sub_f32_e32 v60, v69, v61
	v_fma_f32 v58, v20, s96, -v64
	v_pk_add_f32 v[62:63], v[68:69], v[68:69] op_sel:[0,1] op_sel_hi:[0,1] neg_lo:[0,1] neg_hi:[0,1]
	v_pk_mul_f32 v[60:61], v[60:61], v[44:45] op_sel:[0,1] op_sel_hi:[0,0]
	v_pk_mul_f32 v[20:21], v[20:21], s[2:3]
	v_pk_fma_f32 v[68:69], v[62:63], v[44:45], v[60:61]
	v_pk_fma_f32 v[44:45], v[62:63], v[44:45], v[60:61] neg_lo:[0,0,1] neg_hi:[0,0,1]
	v_sub_f32_e32 v60, v59, v21
	v_pk_fma_f32 v[62:63], v[60:61], v[54:55], v[66:67] op_sel_hi:[0,1,1]
	v_pk_fma_f32 v[54:55], v[60:61], v[54:55], v[66:67] op_sel_hi:[0,1,1] neg_lo:[0,0,1] neg_hi:[0,0,1]
	v_sub_f32_e32 v60, v21, v59
	v_mov_b32_e32 v63, v55
	v_pk_mul_f32 v[60:61], v[60:61], v[46:47] op_sel:[0,1] op_sel_hi:[0,0]
	v_pk_add_f32 v[54:55], v[36:37], v[62:63]
	v_pk_add_f32 v[36:37], v[36:37], v[62:63] neg_lo:[0,1] neg_hi:[0,1]
	v_pk_fma_f32 v[62:63], v[58:59], v[46:47], v[60:61]
	v_pk_fma_f32 v[46:47], v[58:59], v[46:47], v[60:61] op_sel_hi:[0,1,1] neg_lo:[0,0,1] neg_hi:[0,0,1]
	v_pk_add_f32 v[58:59], v[64:65], v[64:65] op_sel:[0,1] op_sel_hi:[0,1] neg_lo:[0,1] neg_hi:[0,1]
	v_pk_add_f32 v[20:21], v[20:21], v[20:21] op_sel:[0,1] op_sel_hi:[0,1] neg_lo:[0,1] neg_hi:[0,1]
	v_pk_mul_f32 v[58:59], v[58:59], v[42:43] op_sel:[0,1] op_sel_hi:[1,0]
	v_mov_b32_e32 v75, v33
	v_pk_fma_f32 v[60:61], v[20:21], v[42:43], v[58:59]
	v_pk_fma_f32 v[20:21], v[20:21], v[42:43], v[58:59] neg_lo:[0,0,1] neg_hi:[0,0,1]
	v_pk_add_f32 v[32:33], v[24:25], v[74:75]
	v_pk_add_f32 v[24:25], v[24:25], v[74:75] neg_lo:[0,1] neg_hi:[0,1]
	v_mov_b32_e32 v61, v21
	v_mov_b32_e32 v73, v51
	v_mov_b32_e32 v71, v53
	v_mov_b32_e32 v69, v45
	v_mov_b32_e32 v63, v47
	v_pk_add_f32 v[20:21], v[24:25], v[60:61]
	v_pk_add_f32 v[50:51], v[32:33], v[72:73]
	v_pk_add_f32 v[32:33], v[32:33], v[72:73] neg_lo:[0,1] neg_hi:[0,1]
	v_pk_add_f32 v[52:53], v[34:35], v[70:71]
	v_pk_add_f32 v[34:35], v[34:35], v[70:71] neg_lo:[0,1] neg_hi:[0,1]
	v_pk_add_f32 v[44:45], v[26:27], v[68:69]
	v_pk_add_f32 v[26:27], v[26:27], v[68:69] neg_lo:[0,1] neg_hi:[0,1]
	v_pk_add_f32 v[46:47], v[28:29], v[62:63]
	v_pk_add_f32 v[28:29], v[28:29], v[62:63] neg_lo:[0,1] neg_hi:[0,1]
	v_pk_add_f32 v[24:25], v[24:25], v[60:61] neg_lo:[0,1] neg_hi:[0,1]
	ds_write2_b64 v41, v[56:57], v[54:55] offset1:34
	ds_write2_b64 v41, v[52:53], v[50:51] offset0:68 offset1:102
	ds_write2_b64 v41, v[48:49], v[46:47] offset0:136 offset1:170
	ds_write2_b64 v41, v[44:45], v[20:21] offset0:204 offset1:238
	ds_write2_b64 v76, v[38:39], v[36:37] offset0:16 offset1:50
	ds_write2_b64 v76, v[34:35], v[32:33] offset0:84 offset1:118
	ds_write2_b64 v76, v[30:31], v[28:29] offset0:152 offset1:186
	ds_write2_b64 v76, v[26:27], v[24:25] offset0:220 offset1:254
	v_ashrrev_i32_e32 v20, 4, v2
	v_lshlrev_b32_e32 v21, 3, v2
	v_cvt_f32_i32_e32 v2, v2
	v_lshlrev_b32_e32 v20, 3, v20
	v_and_b32_e32 v20, -16, v20
	v_add3_u32 v41, 0, v21, v20
	v_mul_f32_e32 v2, 0x39000000, v2
	v_sin_f32_e32 v21, v2
	v_cos_f32_e32 v20, v2
	s_waitcnt lgkmcnt(0)
	s_barrier
; #define LAS __attribute__((address_space(3)))
; __device__ __forceinline__ f32x2 cmul(f32x2 a, f32x2 b) { return (f32x2){a.x * b.x - a.y * b.y, a.x * b.y + a.y * b.x}; }
; __device__ __forceinline__ f32x2 cmulc(f32x2 a, f32x2 b) { return (f32x2){a.x * b.x + a.y * b.y, a.y * b.x - a.x * b.y}; }
; template <bool INV, int ST> __device__ __forceinline__ void fft_pass16(LAS f32x2* buf, int base, int bl) {
;     ...
;     constexpr int STEP = (1 << ST) + ((1 << ST) >> 4);
;     LAS f32x2* pb = buf + PADI(base);
; #pragma unroll
;     for (int d = 0; d < 16; ++d) x[d] = pb[d * STEP];
;     const float th = (float)bl * (1.f / (float)(16 << ST));
;     const f32x2 W1 = {__builtin_amdgcn_cosf(th), -__builtin_amdgcn_sinf(th)};
;     const f32x2 W2 = cmul(W1, W1), W4 = cmul(W2, W2), W8 = cmul(W4, W4);
;     if (!INV) {
; #pragma unroll
;         for (int d = 0; d < 8; ++d) { const f32x2 w = cmul(W1, (f32x2){C16[d], -S16[d]}); const f32x2 a = x[d], b = x[d + 8]; x[d] = a + b; x[d + 8] = cmul(a - b, w); }
; #pragma unroll
;         for (int g = 0; g < 16; g += 8)
; #pragma unroll
;             for (int dd = 0; dd < 4; ++dd) { const int d = g + dd; const f32x2 w = cmul(W2, (f32x2){C16[2 * dd], -S16[2 * dd]}); const f32x2 a = x[d], b = x[d + 4]; x[d] = a + b; x[d + 4] = cmul(a - b, w); }
; #pragma unroll
;         for (int g = 0; g < 16; g += 4)
; #pragma unroll
;             for (int dd = 0; dd < 2; ++dd) { const int d = g + dd; const f32x2 w = dd ? (f32x2){W4.y, -W4.x} : W4; const f32x2 a = x[d], b = x[d + 2]; x[d] = a + b; x[d + 2] = cmul(a - b, w); }
; #pragma unroll
;         for (int g = 0; g < 16; g += 2) { const f32x2 a = x[g], b = x[g + 1]; x[g] = a + b; x[g + 1] = cmul(a - b, W8); }
;     } else {
; #pragma unroll
;         for (int g = 0; g < 16; g += 2) { const f32x2 a = x[g], b = cmulc(x[g + 1], W8); x[g] = a + b; x[g + 1] = a - b; }
; #pragma unroll
;         for (int g = 0; g < 16; g += 4)
; #pragma unroll
;             for (int dd = 0; dd < 2; ++dd) { const int d = g + dd; const f32x2 w = dd ? (f32x2){W4.y, -W4.x} : W4; const f32x2 a = x[d], b = cmulc(x[d + 2], w); x[d] = a + b; x[d + 2] = a - b; }
	v_xor_b32_e32 v58, 0x80000000, v21
	v_mov_b32_e32 v60, v58
	v_mov_b32_e32 v61, v21
	v_mov_b32_e32 v59, v20
	v_pk_mul_f32 v[60:61], v[20:21], v[60:61]
	s_nop 0
	v_pk_fma_f32 v[62:63], v[20:21], v[58:59], v[60:61] op_sel_hi:[0,1,1]
	v_pk_fma_f32 v[58:59], v[20:21], v[58:59], v[60:61] op_sel_hi:[0,1,1] neg_lo:[0,0,1] neg_hi:[0,0,1]
	v_mov_b32_e32 v63, v59
	v_pk_mul_f32 v[60:61], v[62:63], v[62:63]
	v_pk_mul_f32 v[64:65], v[58:59], v[62:63] op_sel:[1,0] op_sel_hi:[0,1]
	v_pk_mov_b32 v[66:67], v[60:61], v[64:65] op_sel:[1,0]
	v_mov_b32_e32 v61, v64
	v_pk_add_f32 v[64:65], v[66:67], v[60:61] neg_lo:[0,1] neg_hi:[0,1]
	v_pk_add_f32 v[60:61], v[66:67], v[60:61]
	v_mov_b32_e32 v66, v64
	v_mov_b32_e32 v67, v61
	v_mul_f32_e32 v2, v64, v61
	v_pk_mul_f32 v[66:67], v[66:67], v[66:67]
	v_add_f32_e32 v2, v2, v2
	ds_read_b64 v[24:25], v41
	ds_read_b64 v[26:27], v41 offset:4352
	ds_read_b64 v[28:29], v41 offset:8704
	ds_read_b64 v[30:31], v41 offset:13056
	ds_read_b64 v[32:33], v41 offset:17408
	ds_read_b64 v[34:35], v41 offset:21760
	ds_read_b64 v[36:37], v41 offset:26112
	ds_read_b64 v[38:39], v41 offset:30464
	ds_read_b64 v[42:43], v41 offset:34816
	ds_read_b64 v[44:45], v41 offset:39168
	ds_read_b64 v[46:47], v41 offset:43520
	ds_read_b64 v[48:49], v41 offset:47872
	ds_read_b64 v[50:51], v41 offset:52224
	ds_read_b64 v[52:53], v41 offset:56576
	ds_read_b64 v[54:55], v41 offset:60928
	ds_read_b64 v[56:57], v41 offset:65280
	v_pk_add_f32 v[66:67], v[66:67], v[66:67] op_sel:[0,1] op_sel_hi:[0,1] neg_lo:[0,1] neg_hi:[0,1]
	s_waitcnt lgkmcnt(14)
	v_pk_mul_f32 v[68:69], v[2:3], v[26:27] op_sel_hi:[0,1]
	v_pk_fma_f32 v[70:71], v[66:67], v[26:27], v[68:69] op_sel:[0,0,1] op_sel_hi:[1,1,0]
	v_pk_fma_f32 v[26:27], v[66:67], v[26:27], v[68:69] op_sel:[0,0,1] op_sel_hi:[1,1,0] neg_lo:[0,0,1] neg_hi:[0,0,1]
	s_waitcnt lgkmcnt(12)
	v_pk_mul_f32 v[68:69], v[2:3], v[30:31] op_sel_hi:[0,1]
	v_mov_b32_e32 v71, v27
	v_pk_add_f32 v[26:27], v[24:25], v[70:71]
	v_pk_add_f32 v[24:25], v[24:25], v[70:71] neg_lo:[0,1] neg_hi:[0,1]
	v_pk_fma_f32 v[70:71], v[66:67], v[30:31], v[68:69] op_sel:[0,0,1] op_sel_hi:[1,1,0]
	v_pk_fma_f32 v[30:31], v[66:67], v[30:31], v[68:69] op_sel:[0,0,1] op_sel_hi:[1,1,0] neg_lo:[0,0,1] neg_hi:[0,0,1]
	s_waitcnt lgkmcnt(10)
	v_pk_mul_f32 v[68:69], v[2:3], v[34:35] op_sel_hi:[0,1]
	v_mov_b32_e32 v71, v31
	v_pk_add_f32 v[30:31], v[28:29], v[70:71]
	v_pk_add_f32 v[28:29], v[28:29], v[70:71] neg_lo:[0,1] neg_hi:[0,1]
	v_pk_fma_f32 v[70:71], v[66:67], v[34:35], v[68:69] op_sel:[0,0,1] op_sel_hi:[1,1,0]
	v_pk_fma_f32 v[34:35], v[66:67], v[34:35], v[68:69] op_sel:[0,0,1] op_sel_hi:[1,1,0] neg_lo:[0,0,1] neg_hi:[0,0,1]
	s_waitcnt lgkmcnt(8)
	v_pk_mul_f32 v[68:69], v[2:3], v[38:39] op_sel_hi:[0,1]
	v_mov_b32_e32 v71, v35
	v_pk_add_f32 v[34:35], v[32:33], v[70:71]
	v_pk_add_f32 v[32:33], v[32:33], v[70:71] neg_lo:[0,1] neg_hi:[0,1]
	v_pk_fma_f32 v[70:71], v[66:67], v[38:39], v[68:69] op_sel:[0,0,1] op_sel_hi:[1,1,0]
	v_pk_fma_f32 v[38:39], v[66:67], v[38:39], v[68:69] op_sel:[0,0,1] op_sel_hi:[1,1,0] neg_lo:[0,0,1] neg_hi:[0,0,1]
	s_waitcnt lgkmcnt(6)
	v_pk_mul_f32 v[68:69], v[2:3], v[44:45] op_sel_hi:[0,1]
	v_mov_b32_e32 v71, v39
	v_pk_add_f32 v[38:39], v[36:37], v[70:71]
	v_pk_add_f32 v[36:37], v[36:37], v[70:71] neg_lo:[0,1] neg_hi:[0,1]
	v_pk_fma_f32 v[70:71], v[66:67], v[44:45], v[68:69] op_sel:[0,0,1] op_sel_hi:[1,1,0]
	v_pk_fma_f32 v[44:45], v[66:67], v[44:45], v[68:69] op_sel:[0,0,1] op_sel_hi:[1,1,0] neg_lo:[0,0,1] neg_hi:[0,0,1]
	s_waitcnt lgkmcnt(4)
	v_pk_mul_f32 v[68:69], v[2:3], v[48:49] op_sel_hi:[0,1]
	v_mov_b32_e32 v71, v45
	v_pk_add_f32 v[44:45], v[42:43], v[70:71]
	v_pk_add_f32 v[42:43], v[42:43], v[70:71] neg_lo:[0,1] neg_hi:[0,1]
	v_pk_fma_f32 v[70:71], v[66:67], v[48:49], v[68:69] op_sel:[0,0,1] op_sel_hi:[1,1,0]
	v_pk_fma_f32 v[48:49], v[66:67], v[48:49], v[68:69] op_sel:[0,0,1] op_sel_hi:[1,1,0] neg_lo:[0,0,1] neg_hi:[0,0,1]
	s_waitcnt lgkmcnt(2)
	v_pk_mul_f32 v[68:69], v[2:3], v[52:53] op_sel_hi:[0,1]
	v_mov_b32_e32 v71, v49
	v_pk_add_f32 v[48:49], v[46:47], v[70:71]
	v_pk_add_f32 v[46:47], v[46:47], v[70:71] neg_lo:[0,1] neg_hi:[0,1]
	v_pk_fma_f32 v[70:71], v[66:67], v[52:53], v[68:69] op_sel:[0,0,1] op_sel_hi:[1,1,0]
	v_pk_fma_f32 v[52:53], v[66:67], v[52:53], v[68:69] op_sel:[0,0,1] op_sel_hi:[1,1,0] neg_lo:[0,0,1] neg_hi:[0,0,1]
	s_waitcnt lgkmcnt(0)
; __device__ __forceinline__ f32x2 cmul(f32x2 a, f32x2 b) { return (f32x2){a.x * b.x - a.y * b.y, a.x * b.y + a.y * b.x}; }
; __device__ __forceinline__ f32x2 cmulc(f32x2 a, f32x2 b) { return (f32x2){a.x * b.x + a.y * b.y, a.y * b.x - a.x * b.y}; }
; template <bool INV, int ST> __device__ __forceinline__ void fft_pass16(LAS f32x2* buf, int base, int bl) {
;     ...
;         for (int g = 0; g < 16; g += 4)
; #pragma unroll
;             for (int dd = 0; dd < 2; ++dd) { const int d = g + dd; const f32x2 w = dd ? (f32x2){W4.y, -W4.x} : W4; const f32x2 a = x[d], b = cmulc(x[d + 2], w); x[d] = a + b; x[d + 2] = a - b; }
; #pragma unroll
;         for (int g = 0; g < 16; g += 8)
; #pragma unroll
;             for (int dd = 0; dd < 4; ++dd) { const int d = g + dd; const f32x2 w = cmul(W2, (f32x2){C16[2 * dd], -S16[2 * dd]}); const f32x2 a = x[d], b = cmulc(x[d + 4], w); x[d] = a + b; x[d + 4] = a - b; }
	v_pk_mul_f32 v[68:69], v[2:3], v[56:57] op_sel_hi:[0,1]
	v_mov_b32_e32 v71, v53
	v_pk_add_f32 v[52:53], v[50:51], v[70:71]
	v_pk_add_f32 v[50:51], v[50:51], v[70:71] neg_lo:[0,1] neg_hi:[0,1]
	v_pk_fma_f32 v[70:71], v[66:67], v[56:57], v[68:69] op_sel:[0,0,1] op_sel_hi:[1,1,0]
	v_pk_fma_f32 v[56:57], v[66:67], v[56:57], v[68:69] op_sel:[0,0,1] op_sel_hi:[1,1,0] neg_lo:[0,0,1] neg_hi:[0,0,1]
	v_pk_mul_f32 v[66:67], v[60:61], v[30:31] op_sel:[1,0]
	v_mov_b32_e32 v71, v57
	v_pk_fma_f32 v[68:69], v[64:65], v[30:31], v[66:67] op_sel:[0,0,1] op_sel_hi:[1,1,0]
	v_pk_fma_f32 v[30:31], v[64:65], v[30:31], v[66:67] op_sel:[0,0,1] op_sel_hi:[0,1,0] neg_lo:[0,0,1] neg_hi:[0,0,1]
	v_mov_b32_e32 v69, v31
	v_pk_mul_f32 v[66:67], v[64:65], v[28:29] op_sel_hi:[0,1]
	v_pk_add_f32 v[30:31], v[26:27], v[68:69]
	v_pk_add_f32 v[26:27], v[26:27], v[68:69] neg_lo:[0,1] neg_hi:[0,1]
	v_pk_fma_f32 v[68:69], v[60:61], v[28:29], v[66:67] op_sel:[1,0,1] op_sel_hi:[1,1,0] neg_lo:[0,0,1] neg_hi:[0,0,1]
	v_pk_fma_f32 v[28:29], v[60:61], v[28:29], v[66:67] op_sel:[1,0,1] op_sel_hi:[1,1,0]
	v_pk_mul_f32 v[66:67], v[60:61], v[38:39] op_sel:[1,0]
	v_mov_b32_e32 v69, v29
	v_pk_add_f32 v[28:29], v[24:25], v[68:69]
	v_pk_add_f32 v[24:25], v[24:25], v[68:69] neg_lo:[0,1] neg_hi:[0,1]
	v_pk_fma_f32 v[68:69], v[64:65], v[38:39], v[66:67] op_sel:[0,0,1] op_sel_hi:[1,1,0]
	v_pk_fma_f32 v[38:39], v[64:65], v[38:39], v[66:67] op_sel:[0,0,1] op_sel_hi:[0,1,0] neg_lo:[0,0,1] neg_hi:[0,0,1]
	v_mov_b32_e32 v69, v39
	v_pk_mul_f32 v[66:67], v[64:65], v[36:37] op_sel_hi:[0,1]
	v_pk_add_f32 v[38:39], v[34:35], v[68:69]
	v_pk_add_f32 v[34:35], v[34:35], v[68:69] neg_lo:[0,1] neg_hi:[0,1]
	v_pk_fma_f32 v[68:69], v[60:61], v[36:37], v[66:67] op_sel:[1,0,1] op_sel_hi:[1,1,0] neg_lo:[0,0,1] neg_hi:[0,0,1]
	v_pk_fma_f32 v[36:37], v[60:61], v[36:37], v[66:67] op_sel:[1,0,1] op_sel_hi:[1,1,0]
	v_pk_mul_f32 v[66:67], v[60:61], v[48:49] op_sel:[1,0]
	v_mov_b32_e32 v69, v37
	v_pk_add_f32 v[36:37], v[32:33], v[68:69]
	v_pk_add_f32 v[32:33], v[32:33], v[68:69] neg_lo:[0,1] neg_hi:[0,1]
	v_pk_fma_f32 v[68:69], v[64:65], v[48:49], v[66:67] op_sel:[0,0,1] op_sel_hi:[1,1,0]
	v_pk_fma_f32 v[48:49], v[64:65], v[48:49], v[66:67] op_sel:[0,0,1] op_sel_hi:[0,1,0] neg_lo:[0,0,1] neg_hi:[0,0,1]
	v_mov_b32_e32 v69, v49
	v_pk_mul_f32 v[66:67], v[64:65], v[46:47] op_sel_hi:[0,1]
	v_pk_add_f32 v[56:57], v[54:55], v[70:71]
	v_pk_add_f32 v[48:49], v[44:45], v[68:69]
	v_pk_add_f32 v[44:45], v[44:45], v[68:69] neg_lo:[0,1] neg_hi:[0,1]
	v_pk_fma_f32 v[68:69], v[60:61], v[46:47], v[66:67] op_sel:[1,0,1] op_sel_hi:[1,1,0] neg_lo:[0,0,1] neg_hi:[0,0,1]
	v_pk_fma_f32 v[46:47], v[60:61], v[46:47], v[66:67] op_sel:[1,0,1] op_sel_hi:[1,1,0]
	v_pk_add_f32 v[54:55], v[54:55], v[70:71] neg_lo:[0,1] neg_hi:[0,1]
	v_mov_b32_e32 v69, v47
	v_pk_mul_f32 v[66:67], v[60:61], v[56:57] op_sel:[1,0]
	v_pk_add_f32 v[46:47], v[42:43], v[68:69]
	v_pk_add_f32 v[42:43], v[42:43], v[68:69] neg_lo:[0,1] neg_hi:[0,1]
	v_pk_fma_f32 v[68:69], v[64:65], v[56:57], v[66:67] op_sel:[0,0,1] op_sel_hi:[1,1,0]
	v_pk_fma_f32 v[56:57], v[64:65], v[56:57], v[66:67] op_sel:[0,0,1] op_sel_hi:[0,1,0] neg_lo:[0,0,1] neg_hi:[0,0,1]
	v_pk_mul_f32 v[64:65], v[64:65], v[54:55] op_sel_hi:[0,1]
	v_fmamk_f32 v58, v59, 0x80000000, v62
	v_pk_fma_f32 v[66:67], v[60:61], v[54:55], v[64:65] op_sel:[1,0,1] op_sel_hi:[1,1,0] neg_lo:[0,0,1] neg_hi:[0,0,1]
	v_pk_fma_f32 v[54:55], v[60:61], v[54:55], v[64:65] op_sel:[1,0,1] op_sel_hi:[1,1,0]
	v_fma_f32 v2, 0, v62, v59
	v_pk_mul_f32 v[60:61], v[58:59], v[38:39] op_sel_hi:[0,1]
	v_mov_b32_e32 v67, v55
	v_pk_fma_f32 v[64:65], v[2:3], v[38:39], v[60:61] op_sel:[0,0,1] op_sel_hi:[1,1,0]
	v_pk_fma_f32 v[38:39], v[2:3], v[38:39], v[60:61] op_sel:[0,0,1] op_sel_hi:[0,1,0] neg_lo:[0,0,1] neg_hi:[0,0,1]
	v_pk_mul_f32 v[60:61], v[62:63], s[10:11] op_sel_hi:[1,0]
	v_mov_b32_e32 v69, v57
	v_pk_add_f32 v[54:55], v[50:51], v[66:67]
	v_pk_add_f32 v[50:51], v[50:51], v[66:67] neg_lo:[0,1] neg_hi:[0,1]
	v_mov_b32_e32 v65, v39
	v_pk_add_f32 v[66:67], v[60:61], v[60:61] op_sel:[0,1] op_sel_hi:[0,1] neg_lo:[0,1] neg_hi:[0,1]
	v_pk_add_f32 v[56:57], v[52:53], v[68:69]
	v_pk_add_f32 v[52:53], v[52:53], v[68:69] neg_lo:[0,1] neg_hi:[0,1]
	v_pk_add_f32 v[38:39], v[30:31], v[64:65]
	v_pk_add_f32 v[30:31], v[30:31], v[64:65] neg_lo:[0,1] neg_hi:[0,1]
	v_pk_add_f32 v[64:65], v[60:61], v[60:61] op_sel:[1,0] op_sel_hi:[1,0]
	v_pk_mul_f32 v[68:69], v[66:67], v[36:37]
	v_fma_f32 v60, 0, v59, v62
	v_pk_fma_f32 v[70:71], v[64:65], v[36:37], v[68:69] op_sel:[0,0,1] op_sel_hi:[1,1,0]
	v_pk_fma_f32 v[36:37], v[64:65], v[36:37], v[68:69] op_sel:[0,0,1] op_sel_hi:[1,1,0] neg_lo:[0,0,1] neg_hi:[0,0,1]
	v_fma_f32 v68, v62, 0, -v59
	v_mov_b32_e32 v71, v37
	v_pk_add_f32 v[36:37], v[28:29], v[70:71]
	v_pk_add_f32 v[28:29], v[28:29], v[70:71] neg_lo:[0,1] neg_hi:[0,1]
	v_pk_mul_f32 v[70:71], v[68:69], v[34:35] op_sel_hi:[0,1]
	v_pk_fma_f32 v[72:73], v[60:61], v[34:35], v[70:71] op_sel:[0,0,1] op_sel_hi:[1,1,0]
	v_pk_fma_f32 v[34:35], v[60:61], v[34:35], v[70:71] op_sel:[0,0,1] op_sel_hi:[0,1,0] neg_lo:[0,0,1] neg_hi:[0,0,1]
	v_fma_f32 v62, v62, s11, -v61
	v_mov_b32_e32 v73, v35
	v_pk_mul_f32 v[70:71], v[62:63], v[32:33] op_sel_hi:[0,1]
	v_pk_mul_f32 v[58:59], v[58:59], v[56:57] op_sel_hi:[0,1]
	v_pk_add_f32 v[34:35], v[26:27], v[72:73]
	v_pk_add_f32 v[26:27], v[26:27], v[72:73] neg_lo:[0,1] neg_hi:[0,1]
	v_pk_fma_f32 v[72:73], v[66:67], v[32:33], v[70:71] op_sel:[0,0,1] op_sel_hi:[1,1,0]
	v_pk_fma_f32 v[32:33], v[66:67], v[32:33], v[70:71] op_sel:[0,0,1] op_sel_hi:[1,1,0] neg_lo:[0,0,1] neg_hi:[0,0,1]
	v_pk_fma_f32 v[70:71], v[2:3], v[56:57], v[58:59] op_sel:[0,0,1] op_sel_hi:[1,1,0]
; __device__ __forceinline__ f32x2 cmul(f32x2 a, f32x2 b) { return (f32x2){a.x * b.x - a.y * b.y, a.x * b.y + a.y * b.x}; }
; __device__ __forceinline__ f32x2 cmulc(f32x2 a, f32x2 b) { return (f32x2){a.x * b.x + a.y * b.y, a.y * b.x - a.x * b.y}; }
; template <bool INV, int ST> __device__ __forceinline__ void fft_pass16(LAS f32x2* buf, int base, int bl) {
;     ...
;         for (int d = 0; d < 8; ++d) { const f32x2 w = cmul(W1, (f32x2){C16[d], -S16[d]}); const f32x2 a = x[d], b = cmulc(x[d + 8], w); x[d] = a + b; x[d + 8] = a - b; }
;     }
; #pragma unroll
;     for (int d = 0; d < 16; ++d) pb[d * STEP] = x[d];
; __device__ __forceinline__ void fft_inv_cba(LAS f32x2* buf, int tid) {
;     ...
;     fft_pass16<true, 9>(buf, tid, tid); __syncthreads();
; __device__ __forceinline__ void hyena_phase(const Params& P, int l, LAS unsigned char* lds) {
;     ...
;                 const float skip = P.in[14][(size_t)(l * 2 + ord) * 1024 + c];
	v_pk_fma_f32 v[56:57], v[2:3], v[56:57], v[58:59] op_sel:[0,0,1] op_sel_hi:[0,1,0] neg_lo:[0,0,1] neg_hi:[0,0,1]
	v_mov_b32_e32 v71, v57
	v_pk_mul_f32 v[58:59], v[66:67], v[54:55]
	v_pk_add_f32 v[56:57], v[48:49], v[70:71]
	v_pk_add_f32 v[48:49], v[48:49], v[70:71] neg_lo:[0,1] neg_hi:[0,1]
	v_pk_fma_f32 v[70:71], v[64:65], v[54:55], v[58:59] op_sel:[0,0,1] op_sel_hi:[1,1,0]
	v_pk_fma_f32 v[54:55], v[64:65], v[54:55], v[58:59] op_sel:[0,0,1] op_sel_hi:[1,1,0] neg_lo:[0,0,1] neg_hi:[0,0,1]
	v_pk_mul_f32 v[58:59], v[68:69], v[52:53] op_sel_hi:[0,1]
	v_pk_fma_f32 v[64:65], v[60:61], v[52:53], v[58:59] op_sel:[0,0,1] op_sel_hi:[1,1,0]
	v_pk_fma_f32 v[52:53], v[60:61], v[52:53], v[58:59] op_sel:[0,0,1] op_sel_hi:[0,1,0] neg_lo:[0,0,1] neg_hi:[0,0,1]
	v_pk_mul_f32 v[58:59], v[62:63], v[50:51] op_sel_hi:[0,1]
	v_pk_fma_f32 v[60:61], v[66:67], v[50:51], v[58:59] op_sel:[0,0,1] op_sel_hi:[1,1,0]
	v_pk_fma_f32 v[50:51], v[66:67], v[50:51], v[58:59] op_sel:[0,0,1] op_sel_hi:[1,1,0] neg_lo:[0,0,1] neg_hi:[0,0,1]
	v_fma_f32 v58, v20, s22, -v21
	v_mov_b32_e32 v61, v51
	v_fmamk_f32 v2, v21, 0x80000000, v20
	v_pk_mul_f32 v[58:59], v[58:59], v[56:57] op_sel:[0,1] op_sel_hi:[0,0]
	v_pk_add_f32 v[50:51], v[42:43], v[60:61]
	v_pk_add_f32 v[42:43], v[42:43], v[60:61] neg_lo:[0,1] neg_hi:[0,1]
	v_pk_fma_f32 v[60:61], v[2:3], v[56:57], v[58:59]
	v_pk_fma_f32 v[56:57], v[2:3], v[56:57], v[58:59] op_sel_hi:[0,1,1] neg_lo:[0,0,1] neg_hi:[0,0,1]
	v_mov_b32_e32 v65, v53
	v_mov_b32_e32 v61, v57
	v_mov_b32_e32 v58, v21
	v_mov_b32_e32 v59, v20
	v_mov_b32_e32 v71, v55
	v_pk_add_f32 v[52:53], v[44:45], v[64:65]
	v_pk_add_f32 v[44:45], v[44:45], v[64:65] neg_lo:[0,1] neg_hi:[0,1]
	v_pk_add_f32 v[56:57], v[38:39], v[60:61]
	v_pk_add_f32 v[38:39], v[38:39], v[60:61] neg_lo:[0,1] neg_hi:[0,1]
	v_pk_mul_f32 v[60:61], v[58:59], s[6:7]
	v_pk_mul_f32 v[64:65], v[58:59], s[20:21]
	v_pk_mul_f32 v[58:59], v[58:59], s[96:97]
	v_pk_add_f32 v[54:55], v[46:47], v[70:71]
	v_pk_add_f32 v[46:47], v[46:47], v[70:71] neg_lo:[0,1] neg_hi:[0,1]
	v_pk_add_f32 v[70:71], v[58:59], v[58:59] op_sel:[0,1] op_sel_hi:[0,1] neg_lo:[0,1] neg_hi:[0,1]
	v_mov_b32_e32 v73, v33
	v_fma_f32 v2, v21, s2, -v65
	v_pk_add_f32 v[68:69], v[64:65], v[64:65] op_sel:[1,0] op_sel_hi:[1,0] neg_lo:[0,1] neg_hi:[0,1]
	v_pk_mul_f32 v[70:71], v[70:71], v[50:51] op_sel:[0,1] op_sel_hi:[1,0]
	v_fma_f32 v58, v21, s22, -v20
	v_pk_add_f32 v[32:33], v[24:25], v[72:73]
	v_pk_add_f32 v[24:25], v[24:25], v[72:73] neg_lo:[0,1] neg_hi:[0,1]
	v_pk_mul_f32 v[66:67], v[2:3], v[54:55] op_sel:[0,1] op_sel_hi:[0,0]
	v_pk_fma_f32 v[72:73], v[68:69], v[50:51], v[70:71]
	v_pk_fma_f32 v[50:51], v[68:69], v[50:51], v[70:71] neg_lo:[0,0,1] neg_hi:[0,0,1]
	v_fma_f32 v2, v20, 0, -v21
	v_pk_mul_f32 v[68:69], v[58:59], v[48:49] op_sel:[0,1] op_sel_hi:[0,0]
	v_pk_add_f32 v[62:63], v[60:61], v[60:61] op_sel:[0,1] op_sel_hi:[0,1] neg_lo:[0,1] neg_hi:[0,1]
	v_pk_fma_f32 v[70:71], v[2:3], v[48:49], v[68:69]
	v_pk_fma_f32 v[48:49], v[2:3], v[48:49], v[68:69] op_sel_hi:[0,1,1] neg_lo:[0,0,1] neg_hi:[0,0,1]
	v_pk_mul_f32 v[68:69], v[20:21], s[6:7]
	v_pk_mul_f32 v[62:63], v[62:63], v[52:53] op_sel:[0,1] op_sel_hi:[1,0]
	v_mov_b32_e32 v71, v49
	v_sub_f32_e32 v58, v61, v69
	v_pk_add_f32 v[48:49], v[30:31], v[70:71]
	v_pk_add_f32 v[30:31], v[30:31], v[70:71] neg_lo:[0,1] neg_hi:[0,1]
	v_fma_f32 v2, v20, s96, -v64
	v_pk_fma_f32 v[70:71], v[58:59], v[52:53], v[62:63] op_sel_hi:[0,1,1]
	v_pk_fma_f32 v[52:53], v[58:59], v[52:53], v[62:63] op_sel_hi:[0,1,1] neg_lo:[0,0,1] neg_hi:[0,0,1]
	v_sub_f32_e32 v58, v69, v61
	v_pk_mul_f32 v[20:21], v[20:21], s[2:3]
	v_pk_add_f32 v[62:63], v[68:69], v[68:69] op_sel:[0,1] op_sel_hi:[0,1] neg_lo:[0,1] neg_hi:[0,1]
	v_pk_mul_f32 v[60:61], v[58:59], v[44:45] op_sel:[0,1] op_sel_hi:[0,0]
	v_sub_f32_e32 v58, v59, v21
	v_pk_fma_f32 v[68:69], v[62:63], v[44:45], v[60:61]
	v_pk_fma_f32 v[44:45], v[62:63], v[44:45], v[60:61] neg_lo:[0,0,1] neg_hi:[0,0,1]
	v_pk_fma_f32 v[60:61], v[58:59], v[54:55], v[66:67] op_sel_hi:[0,1,1]
	v_pk_fma_f32 v[54:55], v[58:59], v[54:55], v[66:67] op_sel_hi:[0,1,1] neg_lo:[0,0,1] neg_hi:[0,0,1]
	v_sub_f32_e32 v58, v21, v59
	v_mov_b32_e32 v61, v55
	v_pk_mul_f32 v[58:59], v[58:59], v[46:47] op_sel:[0,1] op_sel_hi:[0,0]
	v_pk_add_f32 v[54:55], v[36:37], v[60:61]
	v_pk_add_f32 v[36:37], v[36:37], v[60:61] neg_lo:[0,1] neg_hi:[0,1]
	v_pk_fma_f32 v[60:61], v[2:3], v[46:47], v[58:59]
	v_pk_fma_f32 v[46:47], v[2:3], v[46:47], v[58:59] op_sel_hi:[0,1,1] neg_lo:[0,0,1] neg_hi:[0,0,1]
	v_pk_add_f32 v[58:59], v[64:65], v[64:65] op_sel:[0,1] op_sel_hi:[0,1] neg_lo:[0,1] neg_hi:[0,1]
	v_mov_b32_e32 v61, v47
	v_pk_add_f32 v[20:21], v[20:21], v[20:21] op_sel:[0,1] op_sel_hi:[0,1] neg_lo:[0,1] neg_hi:[0,1]
	v_pk_mul_f32 v[58:59], v[58:59], v[42:43] op_sel:[0,1] op_sel_hi:[1,0]
	s_lshl_b64 s[6:7], s[18:19], 2
	v_pk_add_f32 v[46:47], v[28:29], v[60:61]
	v_pk_add_f32 v[28:29], v[28:29], v[60:61] neg_lo:[0,1] neg_hi:[0,1]
	v_pk_fma_f32 v[60:61], v[20:21], v[42:43], v[58:59]
	v_pk_fma_f32 v[20:21], v[20:21], v[42:43], v[58:59] neg_lo:[0,0,1] neg_hi:[0,0,1]
	s_add_u32 s8, s25, s6
	v_mov_b32_e32 v73, v51
	v_mov_b32_e32 v71, v53
	v_mov_b32_e32 v69, v45
	v_mov_b32_e32 v61, v21
	s_addc_u32 s9, s26, s7
	v_pk_add_f32 v[50:51], v[32:33], v[72:73]
	v_pk_add_f32 v[32:33], v[32:33], v[72:73] neg_lo:[0,1] neg_hi:[0,1]
	v_pk_add_f32 v[52:53], v[34:35], v[70:71]
	v_pk_add_f32 v[34:35], v[34:35], v[70:71] neg_lo:[0,1] neg_hi:[0,1]
	v_pk_add_f32 v[44:45], v[26:27], v[68:69]
	v_pk_add_f32 v[26:27], v[26:27], v[68:69] neg_lo:[0,1] neg_hi:[0,1]
	v_pk_add_f32 v[20:21], v[24:25], v[60:61]
	v_pk_add_f32 v[24:25], v[24:25], v[60:61] neg_lo:[0,1] neg_hi:[0,1]
	ds_write_b64 v41, v[56:57]
	ds_write_b64 v41, v[54:55] offset:4352
	ds_write_b64 v41, v[52:53] offset:8704
	ds_write_b64 v41, v[50:51] offset:13056
	ds_write_b64 v41, v[48:49] offset:17408
	ds_write_b64 v41, v[46:47] offset:21760
	ds_write_b64 v41, v[44:45] offset:26112
	ds_write_b64 v41, v[20:21] offset:30464
	ds_write_b64 v41, v[38:39] offset:34816
	ds_write_b64 v41, v[36:37] offset:39168
	ds_write_b64 v41, v[34:35] offset:43520
	ds_write_b64 v41, v[32:33] offset:47872
	ds_write_b64 v41, v[30:31] offset:52224
	ds_write_b64 v41, v[28:29] offset:56576
	ds_write_b64 v41, v[26:27] offset:60928
	ds_write_b64 v41, v[24:25] offset:65280
	s_waitcnt lgkmcnt(0)
	s_barrier
; #define LAS __attribute__((address_space(3)))
; __device__ __forceinline__ float bflo(unsigned u) { return __uint_as_float(u << 16); }
; __device__ __forceinline__ float bfhi(unsigned u) { return __uint_as_float(u & 0xffff0000u); }
; __device__ __forceinline__ f32x2 cmul(f32x2 a, f32x2 b) { return (f32x2){a.x * b.x - a.y * b.y, a.x * b.y + a.y * b.x}; }
; template <bool INV, int ST> __device__ __forceinline__ void fft_pass16(LAS f32x2* buf, int base, int bl) {
;     constexpr float C16[8] = {1.f, 0.92387953251f, 0.70710678119f, 0.38268343237f, 0.f, -0.38268343237f, -0.70710678119f, -0.92387953251f};
;     constexpr float S16[8] = {0.f, 0.38268343237f, 0.70710678119f, 0.92387953251f, 1.f, 0.92387953251f, 0.70710678119f, 0.38268343237f};
;     f32x2 x[16];
;     constexpr int STEP = (1 << ST) + ((1 << ST) >> 4);
;     LAS f32x2* pb = buf + PADI(base);
; #pragma unroll
;     for (int d = 0; d < 16; ++d) x[d] = pb[d * STEP];
;     const float th = (float)bl * (1.f / (float)(16 << ST));
;     const f32x2 W1 = {__builtin_amdgcn_cosf(th), -__builtin_amdgcn_sinf(th)};
;     const f32x2 W2 = cmul(W1, W1), W4 = cmul(W2, W2), W8 = cmul(W4, W4);
;     if (!INV) {
; #pragma unroll
;         for (int d = 0; d < 8; ++d) { const f32x2 w = cmul(W1, (f32x2){C16[d], -S16[d]}); const f32x2 a = x[d], b = x[d + 8]; x[d] = a + b; x[d + 8] = cmul(a - b, w); }
; __device__ __forceinline__ void hyena_phase(const Params& P, int l, LAS unsigned char* lds) {
;     ...
;                 fft_fwd_abc(bufA, tid);
;     ...
;                 const float skip = P.in[14][(size_t)(l * 2 + ord) * 1024 + c];
; #pragma unroll
;                 for (int u = 0; u < 8; ++u) { const int t = tid + 512 * u; const f32x2 cv = bufA[PADI(tid) + 544 * u]; const unsigned gw_ = ZT[(size_t)((ord + 1) * 1024 + c) * 4096 + t]; const f32x2 gt = {bflo(gw_), bfhi(gw_)};
;                     if (ord == 0) { y1[u] = gt * (cv + skip * vv[u]); bufA[PADI(tid) + 544 * u] = y1[u]; bufA[PADI(tid) + 544 * u + 4352] = (f32x2){0.f, 0.f}; }
	global_load_dword v2, v3, s[8:9]
	s_lshl_b64 s[8:9], s[18:19], 14
	s_add_u32 s8, s28, s8
	s_addc_u32 s9, s29, s9
	v_lshl_add_u64 v[24:25], v[0:1], 2, s[8:9]
	s_mov_b64 s[8:9], 0x1000000
	v_lshl_add_u64 v[26:27], v[24:25], 0, s[8:9]
	s_mov_b32 s9, 0x1001000
	v_add_co_u32_e32 v28, vcc, s9, v24
	s_nop 0
	v_addc_co_u32_e32 v29, vcc, 0, v25, vcc
	ds_read_b64 v[30:31], v22
	s_mov_b32 s8, 0
	s_mov_b32 s9, s8
	s_waitcnt vmcnt(0) lgkmcnt(0)
	v_mov_b32_e32 v27, v193
	v_mov_b32_e32 v21, v192
	v_pk_fma_f32 v[14:15], v[2:3], v[14:15], v[30:31] op_sel_hi:[0,1,1]
	ds_read_b64 v[30:31], v22 offset:4352
	s_waitcnt lgkmcnt(0)
	v_pk_fma_f32 v[18:19], v[2:3], v[18:19], v[30:31] op_sel_hi:[0,1,1]
	s_waitcnt vmcnt(1)
	v_lshlrev_b32_e32 v26, 16, v27
	v_and_b32_e32 v27, 0xffff0000, v27
	v_pk_mul_f32 v[18:19], v[18:19], v[26:27]
	s_waitcnt vmcnt(0)
	v_lshlrev_b32_e32 v20, 16, v21
	v_and_b32_e32 v21, 0xffff0000, v21
	v_pk_mul_f32 v[14:15], v[14:15], v[20:21]
	v_mov_b64_e32 v[20:21], s[8:9]
	ds_write_b64 v22, v[14:15]
	ds_write_b64 v22, v[20:21] offset:34816
	ds_write_b64 v22, v[18:19] offset:4352
	ds_write_b64 v22, v[20:21] offset:39168
	v_mov_b32_e32 v31, v194
	ds_read_b64 v[26:27], v22 offset:8704
	s_mov_b32 s9, 0x1002000
	s_waitcnt lgkmcnt(0)
	v_pk_fma_f32 v[16:17], v[2:3], v[16:17], v[26:27] op_sel_hi:[0,1,1]
	s_waitcnt vmcnt(0)
	v_lshlrev_b32_e32 v30, 16, v31
	v_and_b32_e32 v31, 0xffff0000, v31
	v_pk_mul_f32 v[16:17], v[16:17], v[30:31]
	ds_write_b64 v22, v[16:17] offset:8704
	ds_write_b64 v22, v[20:21] offset:43520
	v_mov_b32_e32 v29, v195
	ds_read_b64 v[26:27], v22 offset:13056
	s_waitcnt lgkmcnt(0)
	v_pk_fma_f32 v[12:13], v[2:3], v[12:13], v[26:27] op_sel_hi:[0,1,1]
	s_waitcnt vmcnt(0)
	v_lshlrev_b32_e32 v28, 16, v29
	v_and_b32_e32 v29, 0xffff0000, v29
	v_pk_mul_f32 v[12:13], v[12:13], v[28:29]
	v_add_co_u32_e32 v28, vcc, s9, v24
	s_mov_b32 s9, 0x1003000
	s_nop 0
	v_addc_co_u32_e32 v29, vcc, 0, v25, vcc
	v_add_co_u32_e32 v24, vcc, s9, v24
	ds_write_b64 v22, v[12:13] offset:13056
	ds_write_b64 v22, v[20:21] offset:47872
	v_addc_co_u32_e32 v25, vcc, 0, v25, vcc
	v_mov_b32_e32 v31, v202
	ds_read_b64 v[26:27], v22 offset:17408
	s_waitcnt lgkmcnt(0)
	v_pk_fma_f32 v[10:11], v[2:3], v[10:11], v[26:27] op_sel_hi:[0,1,1]
	s_waitcnt vmcnt(0)
	v_lshlrev_b32_e32 v30, 16, v31
	v_and_b32_e32 v31, 0xffff0000, v31
	v_pk_mul_f32 v[10:11], v[10:11], v[30:31]
	ds_write_b64 v22, v[10:11] offset:17408
	ds_write_b64 v22, v[20:21] offset:52224
	v_mov_b32_e32 v29, v203
	ds_read_b64 v[26:27], v22 offset:21760
	s_waitcnt lgkmcnt(0)
	v_pk_fma_f32 v[8:9], v[2:3], v[8:9], v[26:27] op_sel_hi:[0,1,1]
	s_waitcnt vmcnt(0)
	v_lshlrev_b32_e32 v28, 16, v29
	v_and_b32_e32 v29, 0xffff0000, v29
	v_pk_mul_f32 v[8:9], v[8:9], v[28:29]
	ds_write_b64 v22, v[8:9] offset:21760
	ds_write_b64 v22, v[20:21] offset:56576
	v_mov_b32_e32 v29, v204
	ds_read_b64 v[26:27], v22 offset:26112
	s_waitcnt lgkmcnt(0)
	v_pk_fma_f32 v[6:7], v[2:3], v[6:7], v[26:27] op_sel_hi:[0,1,1]
	s_waitcnt vmcnt(0)
	v_lshlrev_b32_e32 v28, 16, v29
	v_and_b32_e32 v29, 0xffff0000, v29
	v_pk_mul_f32 v[6:7], v[6:7], v[28:29]
	ds_write_b64 v22, v[6:7] offset:26112
	ds_write_b64 v22, v[20:21] offset:60928
	v_mov_b32_e32 v25, v205
	ds_read_b64 v[26:27], v22 offset:30464
	s_waitcnt lgkmcnt(0)
	v_pk_fma_f32 v[4:5], v[2:3], v[4:5], v[26:27] op_sel_hi:[0,1,1]
	v_mov_b32_e32 v2, v0
	s_waitcnt vmcnt(0)
	v_lshlrev_b32_e32 v24, 16, v25
	global_load_dword v192, v[212:213], off
	global_load_dword v193, v[212:213], off offset:2048
	global_load_dword v194, v[214:215], off offset:-4096
	global_load_dword v195, v[214:215], off offset:-2048
	global_load_dword v202, v[214:215], off
	global_load_dword v203, v[214:215], off offset:2048
	global_load_dword v204, v[216:217], off offset:-4096
	global_load_dword v205, v[216:217], off offset:-2048
	v_and_b32_e32 v25, 0xffff0000, v25
	v_pk_mul_f32 v[4:5], v[4:5], v[24:25]
	ds_write_b64 v22, v[4:5] offset:30464
	ds_write_b64 v22, v[20:21] offset:65280
	s_waitcnt lgkmcnt(0)
	s_barrier
	s_nop 0
	v_cvt_f32_i32_e32 v56, v2
	v_ashrrev_i32_e32 v20, 4, v2
	v_lshlrev_b32_e32 v20, 3, v20
	v_lshlrev_b32_e32 v21, 3, v2
	v_mul_f32_e32 v57, 0x39000000, v56
	v_sin_f32_e32 v58, v57
	v_cos_f32_e32 v56, v57
	v_and_b32_e32 v20, -16, v20
	v_add3_u32 v41, 0, v21, v20
	v_xor_b32_e32 v57, 0x80000000, v58
	v_mov_b32_e32 v59, v56
	v_mov_b32_e32 v60, v58
	v_mov_b32_e32 v61, v57
	v_pk_mul_f32 v[60:61], v[58:59], v[60:61]
	ds_read_b64 v[20:21], v41
	ds_read_b64 v[24:25], v41 offset:4352
	ds_read_b64 v[26:27], v41 offset:8704
	ds_read_b64 v[28:29], v41 offset:13056
	ds_read_b64 v[30:31], v41 offset:17408
	ds_read_b64 v[32:33], v41 offset:21760
	ds_read_b64 v[34:35], v41 offset:26112
	ds_read_b64 v[36:37], v41 offset:30464
	ds_read_b64 v[38:39], v41 offset:34816
	ds_read_b64 v[42:43], v41 offset:39168
	ds_read_b64 v[44:45], v41 offset:43520
	ds_read_b64 v[46:47], v41 offset:47872
	ds_read_b64 v[48:49], v41 offset:52224
	ds_read_b64 v[50:51], v41 offset:56576
	ds_read_b64 v[52:53], v41 offset:60928
	ds_read_b64 v[54:55], v41 offset:65280
	v_pk_fma_f32 v[62:63], v[56:57], v[56:57], v[60:61] op_sel_hi:[0,1,1] neg_lo:[0,0,1] neg_hi:[0,0,1]
	v_pk_fma_f32 v[60:61], v[56:57], v[56:57], v[60:61] op_sel_hi:[0,1,1]
	v_mov_b32_e32 v63, v61
	v_fma_f32 v68, v56, s22, -v58
	s_waitcnt lgkmcnt(7)
	v_pk_add_f32 v[70:71], v[20:21], v[38:39]
	v_pk_add_f32 v[20:21], v[20:21], v[38:39] neg_lo:[0,1] neg_hi:[0,1]
	v_pk_mul_f32 v[66:67], v[62:63], v[60:61] op_sel:[0,1] op_sel_hi:[1,0]
	v_fmamk_f32 v60, v58, 0x80000000, v56
	v_pk_mul_f32 v[38:39], v[68:69], v[20:21] op_sel:[0,1] op_sel_hi:[0,0]
	v_pk_fma_f32 v[68:69], v[60:61], v[20:21], v[38:39] neg_lo:[0,0,1] neg_hi:[0,0,1]
	v_pk_fma_f32 v[20:21], v[60:61], v[20:21], v[38:39] op_sel_hi:[0,1,1]
	v_pk_mul_f32 v[38:39], v[58:59], s[10:11] op_sel_hi:[1,0]
	v_mov_b32_e32 v69, v21
	s_waitcnt lgkmcnt(6)
; __device__ __forceinline__ f32x2 cmul(f32x2 a, f32x2 b) { return (f32x2){a.x * b.x - a.y * b.y, a.x * b.y + a.y * b.x}; }
; template <bool INV, int ST> __device__ __forceinline__ void fft_pass16(LAS f32x2* buf, int base, int bl) {
;     ...
;         for (int d = 0; d < 8; ++d) { const f32x2 w = cmul(W1, (f32x2){C16[d], -S16[d]}); const f32x2 a = x[d], b = x[d + 8]; x[d] = a + b; x[d + 8] = cmul(a - b, w); }
; #pragma unroll
;         for (int g = 0; g < 16; g += 8)
; #pragma unroll
;             for (int dd = 0; dd < 4; ++dd) { const int d = g + dd; const f32x2 w = cmul(W2, (f32x2){C16[2 * dd], -S16[2 * dd]}); const f32x2 a = x[d], b = x[d + 4]; x[d] = a + b; x[d + 4] = cmul(a - b, w); }
; #pragma unroll
;         for (int g = 0; g < 16; g += 4)
; #pragma unroll
;             for (int dd = 0; dd < 2; ++dd) { const int d = g + dd; const f32x2 w = dd ? (f32x2){W4.y, -W4.x} : W4; const f32x2 a = x[d], b = x[d + 2]; x[d] = a + b; x[d + 2] = cmul(a - b, w); }
; #pragma unroll
;         for (int g = 0; g < 16; g += 2) { const f32x2 a = x[g], b = x[g + 1]; x[g] = a + b; x[g + 1] = cmul(a - b, W8); }
	v_pk_add_f32 v[20:21], v[24:25], v[42:43]
	v_pk_add_f32 v[24:25], v[24:25], v[42:43] neg_lo:[0,1] neg_hi:[0,1]
	v_fma_f32 v42, v58, s11, -v39
	s_waitcnt lgkmcnt(5)
	v_pk_add_f32 v[72:73], v[26:27], v[44:45]
	v_pk_add_f32 v[26:27], v[26:27], v[44:45] neg_lo:[0,1] neg_hi:[0,1]
	v_pk_add_f32 v[44:45], v[38:39], v[38:39] op_sel:[1,0] op_sel_hi:[1,0] neg_lo:[0,1] neg_hi:[0,1]
	v_pk_mul_f32 v[42:43], v[42:43], v[26:27] op_sel:[0,1] op_sel_hi:[0,0]
	v_pk_fma_f32 v[74:75], v[44:45], v[26:27], v[42:43] neg_lo:[0,0,1] neg_hi:[0,0,1]
	v_pk_fma_f32 v[26:27], v[44:45], v[26:27], v[42:43]
	v_pk_mul_f32 v[44:45], v[58:59], s[96:97]
	v_mov_b32_e32 v75, v27
	v_pk_mul_f32 v[26:27], v[58:59], s[20:21]
	s_waitcnt lgkmcnt(4)
	v_pk_add_f32 v[76:77], v[28:29], v[46:47]
	v_pk_add_f32 v[28:29], v[28:29], v[46:47] neg_lo:[0,1] neg_hi:[0,1]
	v_pk_add_f32 v[46:47], v[44:45], v[44:45] op_sel:[0,1] op_sel_hi:[0,1] neg_lo:[0,1] neg_hi:[0,1]
	v_pk_mul_f32 v[46:47], v[46:47], v[28:29] op_sel:[0,1] op_sel_hi:[1,0]
	v_pk_add_f32 v[78:79], v[26:27], v[26:27] op_sel:[1,0] op_sel_hi:[1,0] neg_lo:[0,1] neg_hi:[0,1]
	v_fma_f32 v44, v58, s22, -v56
	v_pk_fma_f32 v[80:81], v[78:79], v[28:29], v[46:47] neg_lo:[0,0,1] neg_hi:[0,0,1]
	v_pk_fma_f32 v[28:29], v[78:79], v[28:29], v[46:47]
	s_waitcnt lgkmcnt(3)
	v_pk_add_f32 v[46:47], v[30:31], v[48:49]
	v_pk_add_f32 v[30:31], v[30:31], v[48:49] neg_lo:[0,1] neg_hi:[0,1]
	v_fma_f32 v28, v56, 0, -v58
	v_pk_mul_f32 v[48:49], v[44:45], v[30:31] op_sel:[0,1] op_sel_hi:[0,0]
	v_mov_b32_e32 v81, v29
	v_pk_fma_f32 v[78:79], v[28:29], v[30:31], v[48:49] neg_lo:[0,0,1] neg_hi:[0,0,1]
	v_pk_fma_f32 v[28:29], v[28:29], v[30:31], v[48:49] op_sel_hi:[0,1,1]
	v_fma_f32 v44, v56, s11, -v38
	s_waitcnt lgkmcnt(1)
	v_pk_add_f32 v[48:49], v[34:35], v[52:53]
	v_pk_add_f32 v[34:35], v[34:35], v[52:53] neg_lo:[0,1] neg_hi:[0,1]
	v_pk_add_f32 v[38:39], v[38:39], v[38:39] op_sel:[0,1] op_sel_hi:[0,1] neg_lo:[0,1] neg_hi:[0,1]
	v_pk_mul_f32 v[38:39], v[38:39], v[34:35] op_sel:[0,1] op_sel_hi:[1,0]
	v_pk_add_f32 v[30:31], v[32:33], v[50:51]
	v_pk_add_f32 v[32:33], v[32:33], v[50:51] neg_lo:[0,1] neg_hi:[0,1]
	v_pk_fma_f32 v[50:51], v[44:45], v[34:35], v[38:39] neg_lo:[0,0,1] neg_hi:[0,0,1]
	v_pk_fma_f32 v[34:35], v[44:45], v[34:35], v[38:39] op_sel_hi:[0,1,1]
	v_mov_b32_e32 v57, v58
	v_fma_f32 v42, v58, s2, -v27
	v_mov_b32_e32 v51, v35
	v_pk_mul_f32 v[34:35], v[56:57], s[2:3]
	v_pk_mul_f32 v[42:43], v[42:43], v[24:25] op_sel:[0,1] op_sel_hi:[0,0]
	v_sub_f32_e32 v38, v45, v35
	v_pk_fma_f32 v[52:53], v[38:39], v[24:25], v[42:43] op_sel_hi:[0,1,1] neg_lo:[0,0,1] neg_hi:[0,0,1]
	v_pk_fma_f32 v[24:25], v[38:39], v[24:25], v[42:43] op_sel_hi:[0,1,1]
	v_sub_f32_e32 v24, v35, v45
	v_fma_f32 v28, v56, s96, -v26
	v_mov_b32_e32 v53, v25
	v_pk_mul_f32 v[24:25], v[24:25], v[32:33] op_sel:[0,1] op_sel_hi:[0,0]
	v_mov_b32_e32 v79, v29
	v_pk_fma_f32 v[38:39], v[28:29], v[32:33], v[24:25] neg_lo:[0,0,1] neg_hi:[0,0,1]
	v_pk_fma_f32 v[24:25], v[28:29], v[32:33], v[24:25] op_sel_hi:[0,1,1]
	s_waitcnt lgkmcnt(0)
	v_pk_add_f32 v[28:29], v[36:37], v[54:55] neg_lo:[0,1] neg_hi:[0,1]
	v_pk_add_f32 v[26:27], v[26:27], v[26:27] op_sel:[0,1] op_sel_hi:[0,1] neg_lo:[0,1] neg_hi:[0,1]
	v_fmamk_f32 v42, v62, 0x80000000, v61
	v_pk_add_f32 v[44:45], v[70:71], v[46:47]
	v_pk_add_f32 v[46:47], v[70:71], v[46:47] neg_lo:[0,1] neg_hi:[0,1]
	v_mov_b32_e32 v39, v25
	v_pk_add_f32 v[24:25], v[36:37], v[54:55]
	v_pk_mul_f32 v[26:27], v[26:27], v[28:29] op_sel:[0,1] op_sel_hi:[1,0]
	v_pk_add_f32 v[32:33], v[34:35], v[34:35] op_sel:[0,1] op_sel_hi:[0,1] neg_lo:[0,1] neg_hi:[0,1]
	v_fma_f32 v36, 0, v61, v62
	v_pk_mul_f32 v[54:55], v[42:43], v[46:47] op_sel_hi:[0,1]
	v_pk_mul_f32 v[64:65], v[62:63], v[62:63]
	v_pk_fma_f32 v[34:35], v[32:33], v[28:29], v[26:27] neg_lo:[0,0,1] neg_hi:[0,0,1]
	v_pk_fma_f32 v[26:27], v[32:33], v[28:29], v[26:27]
	v_pk_fma_f32 v[56:57], v[36:37], v[46:47], v[54:55] op_sel:[0,0,1] op_sel_hi:[1,1,0] neg_lo:[0,0,1] neg_hi:[0,0,1]
	v_pk_fma_f32 v[46:47], v[36:37], v[46:47], v[54:55] op_sel:[0,0,1] op_sel_hi:[0,1,0]
	v_fma_f32 v54, v61, 0, -v62
	v_pk_add_f32 v[58:59], v[72:73], v[48:49]
	v_pk_add_f32 v[48:49], v[72:73], v[48:49] neg_lo:[0,1] neg_hi:[0,1]
	v_mov_b32_e32 v26, v64
	v_pk_mov_b32 v[28:29], v[64:65], v[66:67] op_sel:[1,0]
	v_mov_b32_e32 v57, v47
	v_pk_add_f32 v[46:47], v[20:21], v[30:31]
	v_pk_add_f32 v[20:21], v[20:21], v[30:31] neg_lo:[0,1] neg_hi:[0,1]
	v_fma_f32 v30, 0, v62, v61
	v_pk_mul_f32 v[64:65], v[54:55], v[48:49] op_sel_hi:[0,1]
	v_mov_b32_e32 v35, v27
	v_mov_b32_e32 v27, v66
	v_pk_fma_f32 v[66:67], v[30:31], v[48:49], v[64:65] op_sel:[0,0,1] op_sel_hi:[1,1,0] neg_lo:[0,0,1] neg_hi:[0,0,1]
	v_pk_fma_f32 v[48:49], v[30:31], v[48:49], v[64:65] op_sel:[0,0,1] op_sel_hi:[0,1,0]
	v_mov_b32_e32 v67, v49
	v_pk_mul_f32 v[48:49], v[62:63], s[10:11]
	v_pk_add_f32 v[32:33], v[26:27], v[28:29] neg_lo:[0,1] neg_hi:[0,1]
	v_fma_f32 v62, v61, s10, -v48
	v_fmamk_f32 v60, v61, 0x3f3504f3, v48
	v_pk_mul_f32 v[64:65], v[62:63], v[20:21] op_sel_hi:[0,1]
	v_pk_fma_f32 v[70:71], v[60:61], v[20:21], v[64:65] op_sel:[0,0,1] op_sel_hi:[1,1,0] neg_lo:[0,0,1] neg_hi:[0,0,1]
	v_pk_fma_f32 v[20:21], v[60:61], v[20:21], v[64:65] op_sel:[0,0,1] op_sel_hi:[0,1,0]
	v_mov_b32_e32 v71, v21
	v_pk_add_f32 v[20:21], v[76:77], v[24:25]
	v_pk_add_f32 v[24:25], v[76:77], v[24:25] neg_lo:[0,1] neg_hi:[0,1]
	v_pk_add_f32 v[48:49], v[48:49], v[48:49] op_sel:[1,0] op_sel_hi:[1,0] neg_lo:[0,1] neg_hi:[0,1]
	v_pk_add_f32 v[26:27], v[26:27], v[28:29]
	v_pk_mul_f32 v[64:65], v[48:49], v[24:25]
	v_mov_b32_e32 v28, v32
	v_pk_fma_f32 v[72:73], v[62:63], v[24:25], v[64:65] op_sel:[0,0,1] op_sel_hi:[1,1,0] neg_lo:[0,0,1] neg_hi:[0,0,1]
; __device__ __forceinline__ f32x2 cmul(f32x2 a, f32x2 b) { return (f32x2){a.x * b.x - a.y * b.y, a.x * b.y + a.y * b.x}; }
; template <bool INV, int ST> __device__ __forceinline__ void fft_pass16(LAS f32x2* buf, int base, int bl) {
;     ...
;             for (int dd = 0; dd < 4; ++dd) { const int d = g + dd; const f32x2 w = cmul(W2, (f32x2){C16[2 * dd], -S16[2 * dd]}); const f32x2 a = x[d], b = x[d + 4]; x[d] = a + b; x[d + 4] = cmul(a - b, w); }
; #pragma unroll
;         for (int g = 0; g < 16; g += 4)
; #pragma unroll
;             for (int dd = 0; dd < 2; ++dd) { const int d = g + dd; const f32x2 w = dd ? (f32x2){W4.y, -W4.x} : W4; const f32x2 a = x[d], b = x[d + 2]; x[d] = a + b; x[d + 2] = cmul(a - b, w); }
; #pragma unroll
;         for (int g = 0; g < 16; g += 2) { const f32x2 a = x[g], b = x[g + 1]; x[g] = a + b; x[g + 1] = cmul(a - b, W8); }
	v_pk_fma_f32 v[24:25], v[62:63], v[24:25], v[64:65] op_sel:[0,0,1] op_sel_hi:[0,1,0]
	v_pk_add_f32 v[64:65], v[68:69], v[78:79] neg_lo:[0,1] neg_hi:[0,1]
	v_mov_b32_e32 v73, v25
	v_pk_mul_f32 v[42:43], v[42:43], v[64:65] op_sel_hi:[0,1]
	v_pk_add_f32 v[24:25], v[68:69], v[78:79]
	v_pk_fma_f32 v[68:69], v[36:37], v[64:65], v[42:43] op_sel:[0,0,1] op_sel_hi:[1,1,0] neg_lo:[0,0,1] neg_hi:[0,0,1]
	v_pk_fma_f32 v[36:37], v[36:37], v[64:65], v[42:43] op_sel:[0,0,1] op_sel_hi:[0,1,0]
	v_mov_b32_e32 v69, v37
	v_pk_add_f32 v[36:37], v[52:53], v[38:39]
	v_pk_add_f32 v[38:39], v[52:53], v[38:39] neg_lo:[0,1] neg_hi:[0,1]
	v_mov_b32_e32 v29, v27
	v_pk_mul_f32 v[42:43], v[62:63], v[38:39] op_sel_hi:[0,1]
	v_pk_fma_f32 v[52:53], v[60:61], v[38:39], v[42:43] op_sel:[0,0,1] op_sel_hi:[1,1,0] neg_lo:[0,0,1] neg_hi:[0,0,1]
	v_pk_fma_f32 v[38:39], v[60:61], v[38:39], v[42:43] op_sel:[0,0,1] op_sel_hi:[0,1,0]
	v_pk_add_f32 v[42:43], v[74:75], v[50:51] neg_lo:[0,1] neg_hi:[0,1]
	v_mov_b32_e32 v53, v39
	v_pk_add_f32 v[38:39], v[74:75], v[50:51]
	v_pk_mul_f32 v[50:51], v[54:55], v[42:43] op_sel_hi:[0,1]
	v_pk_fma_f32 v[54:55], v[30:31], v[42:43], v[50:51] op_sel:[0,0,1] op_sel_hi:[1,1,0] neg_lo:[0,0,1] neg_hi:[0,0,1]
	v_pk_fma_f32 v[30:31], v[30:31], v[42:43], v[50:51] op_sel:[0,0,1] op_sel_hi:[0,1,0]
	v_mov_b32_e32 v55, v31
	v_pk_add_f32 v[30:31], v[80:81], v[34:35]
	v_pk_add_f32 v[34:35], v[80:81], v[34:35] neg_lo:[0,1] neg_hi:[0,1]
	v_pk_mul_f32 v[28:29], v[28:29], v[28:29]
	v_pk_mul_f32 v[42:43], v[48:49], v[34:35]
	v_pk_add_f32 v[28:29], v[28:29], v[28:29] op_sel:[0,1] op_sel_hi:[0,1] neg_lo:[0,1] neg_hi:[0,1]
	v_pk_fma_f32 v[48:49], v[62:63], v[34:35], v[42:43] op_sel:[0,0,1] op_sel_hi:[1,1,0] neg_lo:[0,0,1] neg_hi:[0,0,1]
	v_pk_fma_f32 v[34:35], v[62:63], v[34:35], v[42:43] op_sel:[0,0,1] op_sel_hi:[0,1,0]
	v_pk_add_f32 v[42:43], v[44:45], v[58:59] neg_lo:[0,1] neg_hi:[0,1]
	v_mov_b32_e32 v49, v35
	v_pk_add_f32 v[34:35], v[44:45], v[58:59]
	v_pk_mul_f32 v[44:45], v[26:27], v[42:43] op_sel:[1,0]
	s_nop 0
	v_pk_fma_f32 v[50:51], v[32:33], v[42:43], v[44:45] op_sel:[0,0,1] op_sel_hi:[1,1,0] neg_lo:[0,0,1] neg_hi:[0,0,1]
	v_pk_fma_f32 v[42:43], v[32:33], v[42:43], v[44:45] op_sel:[0,0,1] op_sel_hi:[0,1,0]
	v_mov_b32_e32 v51, v43
	v_pk_add_f32 v[42:43], v[46:47], v[20:21]
	v_pk_add_f32 v[20:21], v[46:47], v[20:21] neg_lo:[0,1] neg_hi:[0,1]
	s_nop 0
	v_pk_mul_f32 v[44:45], v[32:33], v[20:21] op_sel_hi:[0,1]
	v_pk_fma_f32 v[46:47], v[26:27], v[20:21], v[44:45] op_sel:[1,0,1] op_sel_hi:[1,1,0]
	v_pk_fma_f32 v[20:21], v[26:27], v[20:21], v[44:45] op_sel:[1,0,1] op_sel_hi:[1,1,0] neg_lo:[0,0,1] neg_hi:[0,0,1]
	v_pk_add_f32 v[44:45], v[56:57], v[66:67] neg_lo:[0,1] neg_hi:[0,1]
	v_mov_b32_e32 v47, v21
	v_pk_add_f32 v[20:21], v[56:57], v[66:67]
	v_pk_mul_f32 v[56:57], v[26:27], v[44:45] op_sel:[1,0]
	s_nop 0
	v_pk_fma_f32 v[58:59], v[32:33], v[44:45], v[56:57] op_sel:[0,0,1] op_sel_hi:[1,1,0] neg_lo:[0,0,1] neg_hi:[0,0,1]
	v_pk_fma_f32 v[44:45], v[32:33], v[44:45], v[56:57] op_sel:[0,0,1] op_sel_hi:[0,1,0]
	v_pk_add_f32 v[56:57], v[70:71], v[72:73] neg_lo:[0,1] neg_hi:[0,1]
	v_mov_b32_e32 v59, v45
	v_pk_mul_f32 v[60:61], v[32:33], v[56:57] op_sel_hi:[0,1]
	v_pk_fma_f32 v[62:63], v[26:27], v[56:57], v[60:61] op_sel:[1,0,1] op_sel_hi:[1,1,0]
	v_pk_fma_f32 v[56:57], v[26:27], v[56:57], v[60:61] op_sel:[1,0,1] op_sel_hi:[1,1,0] neg_lo:[0,0,1] neg_hi:[0,0,1]
	v_pk_add_f32 v[44:45], v[70:71], v[72:73]
	v_mov_b32_e32 v63, v57
	v_pk_add_f32 v[56:57], v[24:25], v[38:39]
	v_pk_add_f32 v[24:25], v[24:25], v[38:39] neg_lo:[0,1] neg_hi:[0,1]
	s_nop 0
	v_pk_mul_f32 v[38:39], v[26:27], v[24:25] op_sel:[1,0]
	s_nop 0
	v_pk_fma_f32 v[60:61], v[32:33], v[24:25], v[38:39] op_sel:[0,0,1] op_sel_hi:[1,1,0] neg_lo:[0,0,1] neg_hi:[0,0,1]
	v_pk_fma_f32 v[24:25], v[32:33], v[24:25], v[38:39] op_sel:[0,0,1] op_sel_hi:[0,1,0]
	v_mov_b32_e32 v61, v25
	v_pk_add_f32 v[24:25], v[36:37], v[30:31]
	v_pk_add_f32 v[30:31], v[36:37], v[30:31] neg_lo:[0,1] neg_hi:[0,1]
	s_nop 0
	v_pk_mul_f32 v[36:37], v[32:33], v[30:31] op_sel_hi:[0,1]
	v_pk_fma_f32 v[38:39], v[26:27], v[30:31], v[36:37] op_sel:[1,0,1] op_sel_hi:[1,1,0]
	v_pk_fma_f32 v[30:31], v[26:27], v[30:31], v[36:37] op_sel:[1,0,1] op_sel_hi:[1,1,0] neg_lo:[0,0,1] neg_hi:[0,0,1]
	v_pk_add_f32 v[36:37], v[68:69], v[54:55] neg_lo:[0,1] neg_hi:[0,1]
	v_mov_b32_e32 v39, v31
	v_pk_add_f32 v[30:31], v[68:69], v[54:55]
	v_pk_mul_f32 v[54:55], v[26:27], v[36:37] op_sel:[1,0]
	s_nop 0
	v_pk_fma_f32 v[64:65], v[32:33], v[36:37], v[54:55] op_sel:[0,0,1] op_sel_hi:[1,1,0] neg_lo:[0,0,1] neg_hi:[0,0,1]
	v_pk_fma_f32 v[36:37], v[32:33], v[36:37], v[54:55] op_sel:[0,0,1] op_sel_hi:[0,1,0]
	v_mov_b32_e32 v65, v37
	v_pk_add_f32 v[36:37], v[52:53], v[48:49]
	v_pk_add_f32 v[48:49], v[52:53], v[48:49] neg_lo:[0,1] neg_hi:[0,1]
	s_nop 0
	v_pk_mul_f32 v[52:53], v[32:33], v[48:49] op_sel_hi:[0,1]
	v_pk_fma_f32 v[54:55], v[26:27], v[48:49], v[52:53] op_sel:[1,0,1] op_sel_hi:[1,1,0]
	v_pk_fma_f32 v[48:49], v[26:27], v[48:49], v[52:53] op_sel:[1,0,1] op_sel_hi:[1,1,0] neg_lo:[0,0,1] neg_hi:[0,0,1]
	v_mul_f32_e32 v26, v32, v27
	v_mov_b32_e32 v55, v49
	v_pk_add_f32 v[48:49], v[34:35], v[42:43]
	v_pk_add_f32 v[34:35], v[34:35], v[42:43] neg_lo:[0,1] neg_hi:[0,1]
	v_add_f32_e32 v26, v26, v26
	v_pk_mul_f32 v[32:33], v[26:27], v[34:35] op_sel_hi:[0,1]
	v_pk_fma_f32 v[42:43], v[28:29], v[34:35], v[32:33] op_sel:[0,0,1] op_sel_hi:[1,1,0] neg_lo:[0,0,1] neg_hi:[0,0,1]
	v_pk_fma_f32 v[32:33], v[28:29], v[34:35], v[32:33] op_sel:[0,0,1] op_sel_hi:[1,1,0]
	v_pk_add_f32 v[34:35], v[50:51], v[46:47] neg_lo:[0,1] neg_hi:[0,1]
	v_mov_b32_e32 v43, v33
	v_pk_add_f32 v[32:33], v[50:51], v[46:47]
; #define LAS __attribute__((address_space(3)))
; __device__ __forceinline__ f32x2 cmul(f32x2 a, f32x2 b) { return (f32x2){a.x * b.x - a.y * b.y, a.x * b.y + a.y * b.x}; }
; template <bool INV, int ST> __device__ __forceinline__ void fft_pass16(LAS f32x2* buf, int base, int bl) {
;     constexpr float C16[8] = {1.f, 0.92387953251f, 0.70710678119f, 0.38268343237f, 0.f, -0.38268343237f, -0.70710678119f, -0.92387953251f};
;     constexpr float S16[8] = {0.f, 0.38268343237f, 0.70710678119f, 0.92387953251f, 1.f, 0.92387953251f, 0.70710678119f, 0.38268343237f};
;     f32x2 x[16];
;     constexpr int STEP = (1 << ST) + ((1 << ST) >> 4);
;     LAS f32x2* pb = buf + PADI(base);
; #pragma unroll
;     for (int d = 0; d < 16; ++d) x[d] = pb[d * STEP];
;     const float th = (float)bl * (1.f / (float)(16 << ST));
;     const f32x2 W1 = {__builtin_amdgcn_cosf(th), -__builtin_amdgcn_sinf(th)};
;     const f32x2 W2 = cmul(W1, W1), W4 = cmul(W2, W2), W8 = cmul(W4, W4);
;     if (!INV) {
; #pragma unroll
;         for (int d = 0; d < 8; ++d) { const f32x2 w = cmul(W1, (f32x2){C16[d], -S16[d]}); const f32x2 a = x[d], b = x[d + 8]; x[d] = a + b; x[d + 8] = cmul(a - b, w); }
;     ...
;         for (int g = 0; g < 16; g += 2) { const f32x2 a = x[g], b = x[g + 1]; x[g] = a + b; x[g + 1] = cmul(a - b, W8); }
;     ...
;     for (int d = 0; d < 16; ++d) pb[d * STEP] = x[d];
; __device__ __forceinline__ void fft_fwd_abc(LAS f32x2* buf, int tid) {
;     ...
;     fft_pass16<false, 5>(buf, ((tid >> 5) << 9) + (tid & 31), tid & 31); __syncthreads();
	v_pk_mul_f32 v[46:47], v[26:27], v[34:35] op_sel_hi:[0,1]
	v_pk_fma_f32 v[50:51], v[28:29], v[34:35], v[46:47] op_sel:[0,0,1] op_sel_hi:[1,1,0] neg_lo:[0,0,1] neg_hi:[0,0,1]
	v_pk_fma_f32 v[34:35], v[28:29], v[34:35], v[46:47] op_sel:[0,0,1] op_sel_hi:[1,1,0]
	s_nop 0
	v_mov_b32_e32 v51, v35
	v_pk_add_f32 v[34:35], v[20:21], v[44:45]
	v_pk_add_f32 v[20:21], v[20:21], v[44:45] neg_lo:[0,1] neg_hi:[0,1]
	s_nop 0
	v_pk_mul_f32 v[44:45], v[26:27], v[20:21] op_sel_hi:[0,1]
	v_pk_fma_f32 v[46:47], v[28:29], v[20:21], v[44:45] op_sel:[0,0,1] op_sel_hi:[1,1,0] neg_lo:[0,0,1] neg_hi:[0,0,1]
	v_pk_fma_f32 v[20:21], v[28:29], v[20:21], v[44:45] op_sel:[0,0,1] op_sel_hi:[1,1,0]
	v_pk_add_f32 v[44:45], v[58:59], v[62:63] neg_lo:[0,1] neg_hi:[0,1]
	v_mov_b32_e32 v47, v21
	v_pk_mul_f32 v[52:53], v[26:27], v[44:45] op_sel_hi:[0,1]
	v_pk_add_f32 v[20:21], v[58:59], v[62:63]
	v_pk_fma_f32 v[58:59], v[28:29], v[44:45], v[52:53] op_sel:[0,0,1] op_sel_hi:[1,1,0] neg_lo:[0,0,1] neg_hi:[0,0,1]
	v_pk_fma_f32 v[44:45], v[28:29], v[44:45], v[52:53] op_sel:[0,0,1] op_sel_hi:[1,1,0]
	s_nop 0
	v_mov_b32_e32 v59, v45
	v_pk_add_f32 v[44:45], v[56:57], v[24:25]
	v_pk_add_f32 v[24:25], v[56:57], v[24:25] neg_lo:[0,1] neg_hi:[0,1]
	s_nop 0
	v_pk_mul_f32 v[52:53], v[26:27], v[24:25] op_sel_hi:[0,1]
	v_pk_fma_f32 v[56:57], v[28:29], v[24:25], v[52:53] op_sel:[0,0,1] op_sel_hi:[1,1,0] neg_lo:[0,0,1] neg_hi:[0,0,1]
	v_pk_fma_f32 v[24:25], v[28:29], v[24:25], v[52:53] op_sel:[0,0,1] op_sel_hi:[1,1,0]
	s_nop 0
	v_mov_b32_e32 v57, v25
	v_pk_add_f32 v[24:25], v[60:61], v[38:39]
	v_pk_add_f32 v[38:39], v[60:61], v[38:39] neg_lo:[0,1] neg_hi:[0,1]
	s_nop 0
	v_pk_mul_f32 v[52:53], v[26:27], v[38:39] op_sel_hi:[0,1]
	v_pk_fma_f32 v[60:61], v[28:29], v[38:39], v[52:53] op_sel:[0,0,1] op_sel_hi:[1,1,0] neg_lo:[0,0,1] neg_hi:[0,0,1]
	v_pk_fma_f32 v[38:39], v[28:29], v[38:39], v[52:53] op_sel:[0,0,1] op_sel_hi:[1,1,0]
	s_nop 0
	v_mov_b32_e32 v61, v39
	v_pk_add_f32 v[38:39], v[30:31], v[36:37]
	v_pk_add_f32 v[30:31], v[30:31], v[36:37] neg_lo:[0,1] neg_hi:[0,1]
	s_nop 0
	v_pk_mul_f32 v[36:37], v[26:27], v[30:31] op_sel_hi:[0,1]
	v_pk_fma_f32 v[52:53], v[28:29], v[30:31], v[36:37] op_sel:[0,0,1] op_sel_hi:[1,1,0] neg_lo:[0,0,1] neg_hi:[0,0,1]
	v_pk_fma_f32 v[30:31], v[28:29], v[30:31], v[36:37] op_sel:[0,0,1] op_sel_hi:[1,1,0]
	v_pk_add_f32 v[36:37], v[64:65], v[54:55] neg_lo:[0,1] neg_hi:[0,1]
	v_mov_b32_e32 v53, v31
	v_pk_mul_f32 v[26:27], v[26:27], v[36:37] op_sel_hi:[0,1]
	v_pk_add_f32 v[30:31], v[64:65], v[54:55]
	v_pk_fma_f32 v[54:55], v[28:29], v[36:37], v[26:27] op_sel:[0,0,1] op_sel_hi:[1,1,0] neg_lo:[0,0,1] neg_hi:[0,0,1]
	v_pk_fma_f32 v[26:27], v[28:29], v[36:37], v[26:27] op_sel:[0,0,1] op_sel_hi:[1,1,0]
	s_nop 0
	v_mov_b32_e32 v55, v27
	ds_write_b64 v41, v[48:49]
	ds_write_b64 v41, v[42:43] offset:4352
	ds_write_b64 v41, v[32:33] offset:8704
	ds_write_b64 v41, v[50:51] offset:13056
	ds_write_b64 v41, v[34:35] offset:17408
	ds_write_b64 v41, v[46:47] offset:21760
	ds_write_b64 v41, v[20:21] offset:26112
	ds_write_b64 v41, v[58:59] offset:30464
	ds_write_b64 v41, v[44:45] offset:34816
	ds_write_b64 v41, v[56:57] offset:39168
	ds_write_b64 v41, v[24:25] offset:43520
	ds_write_b64 v41, v[60:61] offset:47872
	ds_write_b64 v41, v[38:39] offset:52224
	ds_write_b64 v41, v[52:53] offset:56576
	ds_write_b64 v41, v[30:31] offset:60928
	ds_write_b64 v41, v[54:55] offset:65280
	v_lshlrev_b32_e32 v20, 4, v2
	v_and_b32_e32 v20, 0xfffffe00, v20
	v_and_b32_e32 v21, 31, v2
	v_lshl_add_u32 v24, v20, 3, 0
	v_lshlrev_b32_e32 v25, 3, v21
	v_ashrrev_i32_e32 v20, 1, v20
	v_add3_u32 v41, v24, v25, v20
	v_cvt_f32_ubyte0_e32 v20, v21
	v_mul_f32_e32 v21, 0x3b000000, v20
	v_sin_f32_e32 v58, v21
	v_cos_f32_e32 v20, v21
	v_add_u32_e32 v82, 0x800, v41
	s_waitcnt lgkmcnt(0)
	v_xor_b32_e32 v21, 0x80000000, v58
	v_mov_b32_e32 v59, v20
	v_mov_b32_e32 v60, v58
	v_mov_b32_e32 v61, v21
	s_barrier
	ds_read2_b64 v[24:27], v41 offset1:34
	ds_read2_b64 v[28:31], v41 offset0:68 offset1:102
	ds_read2_b64 v[32:35], v41 offset0:136 offset1:170
	ds_read2_b64 v[36:39], v41 offset0:204 offset1:238
	ds_read2_b64 v[42:45], v82 offset0:16 offset1:50
	ds_read2_b64 v[46:49], v82 offset0:84 offset1:118
	ds_read2_b64 v[50:53], v82 offset0:152 offset1:186
	ds_read2_b64 v[54:57], v82 offset0:220 offset1:254
	v_pk_mul_f32 v[60:61], v[58:59], v[60:61]
	v_fma_f32 v68, v20, s22, -v58
	v_pk_fma_f32 v[62:63], v[20:21], v[20:21], v[60:61] op_sel_hi:[0,1,1] neg_lo:[0,0,1] neg_hi:[0,0,1]
	v_pk_fma_f32 v[60:61], v[20:21], v[20:21], v[60:61] op_sel_hi:[0,1,1]
	v_mov_b32_e32 v63, v61
	s_waitcnt lgkmcnt(3)
	v_pk_add_f32 v[70:71], v[24:25], v[42:43]
	v_pk_add_f32 v[24:25], v[24:25], v[42:43] neg_lo:[0,1] neg_hi:[0,1]
	v_pk_mul_f32 v[66:67], v[62:63], v[60:61] op_sel:[0,1] op_sel_hi:[1,0]
	v_fmamk_f32 v60, v58, 0x80000000, v20
	v_pk_mul_f32 v[42:43], v[68:69], v[24:25] op_sel:[0,1] op_sel_hi:[0,0]
	v_pk_fma_f32 v[68:69], v[60:61], v[24:25], v[42:43] neg_lo:[0,0,1] neg_hi:[0,0,1]
	v_pk_fma_f32 v[24:25], v[60:61], v[24:25], v[42:43] op_sel_hi:[0,1,1]
	v_pk_mul_f32 v[42:43], v[58:59], s[10:11] op_sel_hi:[1,0]
	v_mov_b32_e32 v69, v25
	v_pk_add_f32 v[24:25], v[26:27], v[44:45]
	v_pk_add_f32 v[26:27], v[26:27], v[44:45] neg_lo:[0,1] neg_hi:[0,1]
	v_fma_f32 v44, v58, s11, -v43
	s_waitcnt lgkmcnt(2)
; __device__ __forceinline__ f32x2 cmul(f32x2 a, f32x2 b) { return (f32x2){a.x * b.x - a.y * b.y, a.x * b.y + a.y * b.x}; }
; template <bool INV, int ST> __device__ __forceinline__ void fft_pass16(LAS f32x2* buf, int base, int bl) {
;     ...
;     if (!INV) {
; #pragma unroll
;         for (int d = 0; d < 8; ++d) { const f32x2 w = cmul(W1, (f32x2){C16[d], -S16[d]}); const f32x2 a = x[d], b = x[d + 8]; x[d] = a + b; x[d + 8] = cmul(a - b, w); }
; #pragma unroll
;         for (int g = 0; g < 16; g += 8)
; #pragma unroll
;             for (int dd = 0; dd < 4; ++dd) { const int d = g + dd; const f32x2 w = cmul(W2, (f32x2){C16[2 * dd], -S16[2 * dd]}); const f32x2 a = x[d], b = x[d + 4]; x[d] = a + b; x[d + 4] = cmul(a - b, w); }
; #pragma unroll
;         for (int g = 0; g < 16; g += 4)
; #pragma unroll
;             for (int dd = 0; dd < 2; ++dd) { const int d = g + dd; const f32x2 w = dd ? (f32x2){W4.y, -W4.x} : W4; const f32x2 a = x[d], b = x[d + 2]; x[d] = a + b; x[d + 2] = cmul(a - b, w); }
	v_pk_add_f32 v[72:73], v[28:29], v[46:47]
	v_pk_add_f32 v[28:29], v[28:29], v[46:47] neg_lo:[0,1] neg_hi:[0,1]
	v_pk_add_f32 v[46:47], v[42:43], v[42:43] op_sel:[1,0] op_sel_hi:[1,0] neg_lo:[0,1] neg_hi:[0,1]
	v_pk_mul_f32 v[44:45], v[44:45], v[28:29] op_sel:[0,1] op_sel_hi:[0,0]
	v_pk_fma_f32 v[74:75], v[46:47], v[28:29], v[44:45] neg_lo:[0,0,1] neg_hi:[0,0,1]
	v_pk_fma_f32 v[28:29], v[46:47], v[28:29], v[44:45]
	v_pk_mul_f32 v[46:47], v[58:59], s[96:97]
	v_mov_b32_e32 v75, v29
	v_pk_mul_f32 v[28:29], v[58:59], s[20:21]
	v_pk_add_f32 v[76:77], v[30:31], v[48:49]
	v_pk_add_f32 v[30:31], v[30:31], v[48:49] neg_lo:[0,1] neg_hi:[0,1]
	v_pk_add_f32 v[48:49], v[46:47], v[46:47] op_sel:[0,1] op_sel_hi:[0,1] neg_lo:[0,1] neg_hi:[0,1]
	v_pk_mul_f32 v[48:49], v[48:49], v[30:31] op_sel:[0,1] op_sel_hi:[1,0]
	v_pk_add_f32 v[78:79], v[28:29], v[28:29] op_sel:[1,0] op_sel_hi:[1,0] neg_lo:[0,1] neg_hi:[0,1]
	v_fma_f32 v46, v58, s22, -v20
	v_pk_fma_f32 v[80:81], v[78:79], v[30:31], v[48:49] neg_lo:[0,0,1] neg_hi:[0,0,1]
	v_pk_fma_f32 v[30:31], v[78:79], v[30:31], v[48:49]
	s_waitcnt lgkmcnt(1)
	v_pk_add_f32 v[48:49], v[32:33], v[50:51]
	v_pk_add_f32 v[32:33], v[32:33], v[50:51] neg_lo:[0,1] neg_hi:[0,1]
	v_fma_f32 v30, v20, 0, -v58
	v_pk_mul_f32 v[50:51], v[46:47], v[32:33] op_sel:[0,1] op_sel_hi:[0,0]
	v_mov_b32_e32 v81, v31
	v_pk_fma_f32 v[78:79], v[30:31], v[32:33], v[50:51] neg_lo:[0,0,1] neg_hi:[0,0,1]
	v_pk_fma_f32 v[30:31], v[30:31], v[32:33], v[50:51] op_sel_hi:[0,1,1]
	v_fma_f32 v46, v20, s11, -v42
	s_waitcnt lgkmcnt(0)
	v_pk_add_f32 v[50:51], v[36:37], v[54:55]
	v_pk_add_f32 v[36:37], v[36:37], v[54:55] neg_lo:[0,1] neg_hi:[0,1]
	v_pk_add_f32 v[42:43], v[42:43], v[42:43] op_sel:[0,1] op_sel_hi:[0,1] neg_lo:[0,1] neg_hi:[0,1]
	v_pk_mul_f32 v[42:43], v[42:43], v[36:37] op_sel:[0,1] op_sel_hi:[1,0]
	v_mov_b32_e32 v21, v58
	v_fma_f32 v44, v58, s2, -v29
	v_fma_f32 v30, v20, s96, -v28
	v_pk_add_f32 v[32:33], v[34:35], v[52:53]
	v_pk_add_f32 v[34:35], v[34:35], v[52:53] neg_lo:[0,1] neg_hi:[0,1]
	v_pk_fma_f32 v[52:53], v[46:47], v[36:37], v[42:43] neg_lo:[0,0,1] neg_hi:[0,0,1]
	v_pk_fma_f32 v[36:37], v[46:47], v[36:37], v[42:43] op_sel_hi:[0,1,1]
	v_pk_mul_f32 v[20:21], v[20:21], s[2:3]
	v_pk_mul_f32 v[44:45], v[44:45], v[26:27] op_sel:[0,1] op_sel_hi:[0,0]
	v_sub_f32_e32 v36, v47, v21
	v_pk_fma_f32 v[42:43], v[36:37], v[26:27], v[44:45] op_sel_hi:[0,1,1] neg_lo:[0,0,1] neg_hi:[0,0,1]
	v_pk_fma_f32 v[26:27], v[36:37], v[26:27], v[44:45] op_sel_hi:[0,1,1]
	v_sub_f32_e32 v26, v21, v47
	v_mov_b32_e32 v43, v27
	v_pk_mul_f32 v[26:27], v[26:27], v[34:35] op_sel:[0,1] op_sel_hi:[0,0]
	v_mov_b32_e32 v79, v31
	v_mov_b32_e32 v53, v37
	v_pk_fma_f32 v[36:37], v[30:31], v[34:35], v[26:27] neg_lo:[0,0,1] neg_hi:[0,0,1]
	v_pk_fma_f32 v[26:27], v[30:31], v[34:35], v[26:27] op_sel_hi:[0,1,1]
	v_pk_add_f32 v[30:31], v[38:39], v[56:57] neg_lo:[0,1] neg_hi:[0,1]
	v_pk_add_f32 v[28:29], v[28:29], v[28:29] op_sel:[0,1] op_sel_hi:[0,1] neg_lo:[0,1] neg_hi:[0,1]
	v_fmamk_f32 v44, v62, 0x80000000, v61
	v_pk_add_f32 v[46:47], v[70:71], v[48:49]
	v_pk_add_f32 v[48:49], v[70:71], v[48:49] neg_lo:[0,1] neg_hi:[0,1]
	v_mov_b32_e32 v37, v27
	v_pk_add_f32 v[26:27], v[38:39], v[56:57]
	v_pk_mul_f32 v[28:29], v[28:29], v[30:31] op_sel:[0,1] op_sel_hi:[1,0]
	v_pk_add_f32 v[20:21], v[20:21], v[20:21] op_sel:[0,1] op_sel_hi:[0,1] neg_lo:[0,1] neg_hi:[0,1]
	v_fma_f32 v38, 0, v61, v62
	v_pk_mul_f32 v[54:55], v[44:45], v[48:49] op_sel_hi:[0,1]
	v_pk_mul_f32 v[64:65], v[62:63], v[62:63]
	v_pk_fma_f32 v[34:35], v[20:21], v[30:31], v[28:29] neg_lo:[0,0,1] neg_hi:[0,0,1]
	v_pk_fma_f32 v[20:21], v[20:21], v[30:31], v[28:29]
	v_pk_fma_f32 v[56:57], v[38:39], v[48:49], v[54:55] op_sel:[0,0,1] op_sel_hi:[1,1,0] neg_lo:[0,0,1] neg_hi:[0,0,1]
	v_pk_fma_f32 v[48:49], v[38:39], v[48:49], v[54:55] op_sel:[0,0,1] op_sel_hi:[0,1,0]
	v_fma_f32 v54, v61, 0, -v62
	v_pk_add_f32 v[58:59], v[72:73], v[50:51]
	v_pk_add_f32 v[50:51], v[72:73], v[50:51] neg_lo:[0,1] neg_hi:[0,1]
	v_mov_b32_e32 v20, v64
	v_pk_mov_b32 v[28:29], v[64:65], v[66:67] op_sel:[1,0]
	v_mov_b32_e32 v57, v49
	v_pk_add_f32 v[48:49], v[24:25], v[32:33]
	v_pk_add_f32 v[24:25], v[24:25], v[32:33] neg_lo:[0,1] neg_hi:[0,1]
	v_fma_f32 v32, 0, v62, v61
	v_pk_mul_f32 v[64:65], v[54:55], v[50:51] op_sel_hi:[0,1]
	v_mov_b32_e32 v35, v21
	v_mov_b32_e32 v21, v66
	v_pk_fma_f32 v[66:67], v[32:33], v[50:51], v[64:65] op_sel:[0,0,1] op_sel_hi:[1,1,0] neg_lo:[0,0,1] neg_hi:[0,0,1]
	v_pk_fma_f32 v[50:51], v[32:33], v[50:51], v[64:65] op_sel:[0,0,1] op_sel_hi:[0,1,0]
	v_mov_b32_e32 v67, v51
	v_pk_mul_f32 v[50:51], v[62:63], s[10:11]
	v_pk_add_f32 v[30:31], v[20:21], v[28:29] neg_lo:[0,1] neg_hi:[0,1]
	v_fma_f32 v62, v61, s10, -v50
	v_fmamk_f32 v60, v61, 0x3f3504f3, v50
	v_pk_mul_f32 v[64:65], v[62:63], v[24:25] op_sel_hi:[0,1]
	v_pk_fma_f32 v[70:71], v[60:61], v[24:25], v[64:65] op_sel:[0,0,1] op_sel_hi:[1,1,0] neg_lo:[0,0,1] neg_hi:[0,0,1]
	v_pk_fma_f32 v[24:25], v[60:61], v[24:25], v[64:65] op_sel:[0,0,1] op_sel_hi:[0,1,0]
	v_mov_b32_e32 v71, v25
	v_pk_add_f32 v[24:25], v[76:77], v[26:27]
	v_pk_add_f32 v[26:27], v[76:77], v[26:27] neg_lo:[0,1] neg_hi:[0,1]
	v_pk_add_f32 v[50:51], v[50:51], v[50:51] op_sel:[1,0] op_sel_hi:[1,0] neg_lo:[0,1] neg_hi:[0,1]
	v_pk_add_f32 v[20:21], v[20:21], v[28:29]
	v_pk_mul_f32 v[64:65], v[50:51], v[26:27]
	v_mov_b32_e32 v28, v30
	v_pk_fma_f32 v[72:73], v[62:63], v[26:27], v[64:65] op_sel:[0,0,1] op_sel_hi:[1,1,0] neg_lo:[0,0,1] neg_hi:[0,0,1]
	v_pk_fma_f32 v[26:27], v[62:63], v[26:27], v[64:65] op_sel:[0,0,1] op_sel_hi:[0,1,0]
	v_pk_add_f32 v[64:65], v[68:69], v[78:79] neg_lo:[0,1] neg_hi:[0,1]
	v_mov_b32_e32 v73, v27
; __device__ __forceinline__ f32x2 cmul(f32x2 a, f32x2 b) { return (f32x2){a.x * b.x - a.y * b.y, a.x * b.y + a.y * b.x}; }
; template <bool INV, int ST> __device__ __forceinline__ void fft_pass16(LAS f32x2* buf, int base, int bl) {
;     ...
;         for (int g = 0; g < 16; g += 8)
; #pragma unroll
;             for (int dd = 0; dd < 4; ++dd) { const int d = g + dd; const f32x2 w = cmul(W2, (f32x2){C16[2 * dd], -S16[2 * dd]}); const f32x2 a = x[d], b = x[d + 4]; x[d] = a + b; x[d + 4] = cmul(a - b, w); }
; #pragma unroll
;         for (int g = 0; g < 16; g += 4)
; #pragma unroll
;             for (int dd = 0; dd < 2; ++dd) { const int d = g + dd; const f32x2 w = dd ? (f32x2){W4.y, -W4.x} : W4; const f32x2 a = x[d], b = x[d + 2]; x[d] = a + b; x[d + 2] = cmul(a - b, w); }
; #pragma unroll
;         for (int g = 0; g < 16; g += 2) { const f32x2 a = x[g], b = x[g + 1]; x[g] = a + b; x[g + 1] = cmul(a - b, W8); }
	v_pk_mul_f32 v[44:45], v[44:45], v[64:65] op_sel_hi:[0,1]
	v_pk_add_f32 v[26:27], v[68:69], v[78:79]
	v_pk_fma_f32 v[68:69], v[38:39], v[64:65], v[44:45] op_sel:[0,0,1] op_sel_hi:[1,1,0] neg_lo:[0,0,1] neg_hi:[0,0,1]
	v_pk_fma_f32 v[38:39], v[38:39], v[64:65], v[44:45] op_sel:[0,0,1] op_sel_hi:[0,1,0]
	v_mov_b32_e32 v69, v39
	v_pk_add_f32 v[38:39], v[42:43], v[36:37]
	v_pk_add_f32 v[36:37], v[42:43], v[36:37] neg_lo:[0,1] neg_hi:[0,1]
	v_mov_b32_e32 v29, v21
	v_pk_mul_f32 v[42:43], v[62:63], v[36:37] op_sel_hi:[0,1]
	v_pk_fma_f32 v[44:45], v[60:61], v[36:37], v[42:43] op_sel:[0,0,1] op_sel_hi:[1,1,0] neg_lo:[0,0,1] neg_hi:[0,0,1]
	v_pk_fma_f32 v[36:37], v[60:61], v[36:37], v[42:43] op_sel:[0,0,1] op_sel_hi:[0,1,0]
	v_pk_add_f32 v[42:43], v[74:75], v[52:53] neg_lo:[0,1] neg_hi:[0,1]
	v_mov_b32_e32 v45, v37
	v_pk_add_f32 v[36:37], v[74:75], v[52:53]
	v_pk_mul_f32 v[52:53], v[54:55], v[42:43] op_sel_hi:[0,1]
	v_pk_fma_f32 v[54:55], v[32:33], v[42:43], v[52:53] op_sel:[0,0,1] op_sel_hi:[1,1,0] neg_lo:[0,0,1] neg_hi:[0,0,1]
	v_pk_fma_f32 v[32:33], v[32:33], v[42:43], v[52:53] op_sel:[0,0,1] op_sel_hi:[0,1,0]
	v_mov_b32_e32 v55, v33
	v_pk_add_f32 v[32:33], v[80:81], v[34:35]
	v_pk_add_f32 v[34:35], v[80:81], v[34:35] neg_lo:[0,1] neg_hi:[0,1]
	v_pk_mul_f32 v[28:29], v[28:29], v[28:29]
	v_pk_mul_f32 v[42:43], v[50:51], v[34:35]
	v_pk_add_f32 v[28:29], v[28:29], v[28:29] op_sel:[0,1] op_sel_hi:[0,1] neg_lo:[0,1] neg_hi:[0,1]
	v_pk_fma_f32 v[50:51], v[62:63], v[34:35], v[42:43] op_sel:[0,0,1] op_sel_hi:[1,1,0] neg_lo:[0,0,1] neg_hi:[0,0,1]
	v_pk_fma_f32 v[34:35], v[62:63], v[34:35], v[42:43] op_sel:[0,0,1] op_sel_hi:[0,1,0]
	v_pk_add_f32 v[42:43], v[46:47], v[58:59] neg_lo:[0,1] neg_hi:[0,1]
	v_mov_b32_e32 v51, v35
	v_pk_add_f32 v[34:35], v[46:47], v[58:59]
	v_pk_mul_f32 v[46:47], v[20:21], v[42:43] op_sel:[1,0]
	s_nop 0
	v_pk_fma_f32 v[52:53], v[30:31], v[42:43], v[46:47] op_sel:[0,0,1] op_sel_hi:[1,1,0] neg_lo:[0,0,1] neg_hi:[0,0,1]
	v_pk_fma_f32 v[42:43], v[30:31], v[42:43], v[46:47] op_sel:[0,0,1] op_sel_hi:[0,1,0]
	v_mov_b32_e32 v53, v43
	v_pk_add_f32 v[42:43], v[48:49], v[24:25]
	v_pk_add_f32 v[24:25], v[48:49], v[24:25] neg_lo:[0,1] neg_hi:[0,1]
	s_nop 0
	v_pk_mul_f32 v[46:47], v[30:31], v[24:25] op_sel_hi:[0,1]
	v_pk_fma_f32 v[48:49], v[20:21], v[24:25], v[46:47] op_sel:[1,0,1] op_sel_hi:[1,1,0]
	v_pk_fma_f32 v[24:25], v[20:21], v[24:25], v[46:47] op_sel:[1,0,1] op_sel_hi:[1,1,0] neg_lo:[0,0,1] neg_hi:[0,0,1]
	v_pk_add_f32 v[46:47], v[56:57], v[66:67] neg_lo:[0,1] neg_hi:[0,1]
	v_mov_b32_e32 v49, v25
	v_pk_add_f32 v[24:25], v[56:57], v[66:67]
	v_pk_mul_f32 v[56:57], v[20:21], v[46:47] op_sel:[1,0]
	s_nop 0
	v_pk_fma_f32 v[58:59], v[30:31], v[46:47], v[56:57] op_sel:[0,0,1] op_sel_hi:[1,1,0] neg_lo:[0,0,1] neg_hi:[0,0,1]
	v_pk_fma_f32 v[46:47], v[30:31], v[46:47], v[56:57] op_sel:[0,0,1] op_sel_hi:[0,1,0]
	v_pk_add_f32 v[56:57], v[70:71], v[72:73] neg_lo:[0,1] neg_hi:[0,1]
	v_mov_b32_e32 v59, v47
	v_pk_mul_f32 v[60:61], v[30:31], v[56:57] op_sel_hi:[0,1]
	v_pk_fma_f32 v[62:63], v[20:21], v[56:57], v[60:61] op_sel:[1,0,1] op_sel_hi:[1,1,0]
	v_pk_fma_f32 v[56:57], v[20:21], v[56:57], v[60:61] op_sel:[1,0,1] op_sel_hi:[1,1,0] neg_lo:[0,0,1] neg_hi:[0,0,1]
	v_pk_add_f32 v[46:47], v[70:71], v[72:73]
	v_mov_b32_e32 v63, v57
	v_pk_add_f32 v[56:57], v[26:27], v[36:37]
	v_pk_add_f32 v[26:27], v[26:27], v[36:37] neg_lo:[0,1] neg_hi:[0,1]
	s_nop 0
	v_pk_mul_f32 v[36:37], v[20:21], v[26:27] op_sel:[1,0]
	s_nop 0
	v_pk_fma_f32 v[60:61], v[30:31], v[26:27], v[36:37] op_sel:[0,0,1] op_sel_hi:[1,1,0] neg_lo:[0,0,1] neg_hi:[0,0,1]
	v_pk_fma_f32 v[26:27], v[30:31], v[26:27], v[36:37] op_sel:[0,0,1] op_sel_hi:[0,1,0]
	v_mov_b32_e32 v61, v27
	v_pk_add_f32 v[26:27], v[38:39], v[32:33]
	v_pk_add_f32 v[32:33], v[38:39], v[32:33] neg_lo:[0,1] neg_hi:[0,1]
	s_nop 0
	v_pk_mul_f32 v[36:37], v[30:31], v[32:33] op_sel_hi:[0,1]
	v_pk_fma_f32 v[38:39], v[20:21], v[32:33], v[36:37] op_sel:[1,0,1] op_sel_hi:[1,1,0]
	v_pk_fma_f32 v[32:33], v[20:21], v[32:33], v[36:37] op_sel:[1,0,1] op_sel_hi:[1,1,0] neg_lo:[0,0,1] neg_hi:[0,0,1]
	v_pk_add_f32 v[36:37], v[68:69], v[54:55] neg_lo:[0,1] neg_hi:[0,1]
	v_mov_b32_e32 v39, v33
	v_pk_add_f32 v[32:33], v[68:69], v[54:55]
	v_pk_mul_f32 v[54:55], v[20:21], v[36:37] op_sel:[1,0]
	s_nop 0
	v_pk_fma_f32 v[64:65], v[30:31], v[36:37], v[54:55] op_sel:[0,0,1] op_sel_hi:[1,1,0] neg_lo:[0,0,1] neg_hi:[0,0,1]
	v_pk_fma_f32 v[36:37], v[30:31], v[36:37], v[54:55] op_sel:[0,0,1] op_sel_hi:[0,1,0]
	v_mov_b32_e32 v65, v37
	v_pk_add_f32 v[36:37], v[44:45], v[50:51]
	v_pk_add_f32 v[44:45], v[44:45], v[50:51] neg_lo:[0,1] neg_hi:[0,1]
	s_nop 0
	v_pk_mul_f32 v[50:51], v[30:31], v[44:45] op_sel_hi:[0,1]
	v_pk_fma_f32 v[54:55], v[20:21], v[44:45], v[50:51] op_sel:[1,0,1] op_sel_hi:[1,1,0]
	v_pk_fma_f32 v[44:45], v[20:21], v[44:45], v[50:51] op_sel:[1,0,1] op_sel_hi:[1,1,0] neg_lo:[0,0,1] neg_hi:[0,0,1]
	v_mul_f32_e32 v20, v30, v21
	v_mov_b32_e32 v55, v45
	v_pk_add_f32 v[44:45], v[34:35], v[42:43]
	v_pk_add_f32 v[34:35], v[34:35], v[42:43] neg_lo:[0,1] neg_hi:[0,1]
	v_add_f32_e32 v20, v20, v20
	v_pk_mul_f32 v[30:31], v[20:21], v[34:35] op_sel_hi:[0,1]
	v_pk_fma_f32 v[42:43], v[28:29], v[34:35], v[30:31] op_sel:[0,0,1] op_sel_hi:[1,1,0] neg_lo:[0,0,1] neg_hi:[0,0,1]
	v_pk_fma_f32 v[30:31], v[28:29], v[34:35], v[30:31] op_sel:[0,0,1] op_sel_hi:[1,1,0]
	v_pk_add_f32 v[34:35], v[52:53], v[48:49] neg_lo:[0,1] neg_hi:[0,1]
	v_mov_b32_e32 v43, v31
	v_pk_add_f32 v[30:31], v[52:53], v[48:49]
	v_pk_mul_f32 v[48:49], v[20:21], v[34:35] op_sel_hi:[0,1]
	v_pk_fma_f32 v[50:51], v[28:29], v[34:35], v[48:49] op_sel:[0,0,1] op_sel_hi:[1,1,0] neg_lo:[0,0,1] neg_hi:[0,0,1]
; #define LAS __attribute__((address_space(3)))
; __device__ __forceinline__ f32x2 cmul(f32x2 a, f32x2 b) { return (f32x2){a.x * b.x - a.y * b.y, a.x * b.y + a.y * b.x}; }
; template <bool INV, int ST> __device__ __forceinline__ void fft_pass16(LAS f32x2* buf, int base, int bl) {
;     constexpr float C16[8] = {1.f, 0.92387953251f, 0.70710678119f, 0.38268343237f, 0.f, -0.38268343237f, -0.70710678119f, -0.92387953251f};
;     constexpr float S16[8] = {0.f, 0.38268343237f, 0.70710678119f, 0.92387953251f, 1.f, 0.92387953251f, 0.70710678119f, 0.38268343237f};
;     f32x2 x[16];
;     constexpr int STEP = (1 << ST) + ((1 << ST) >> 4);
;     LAS f32x2* pb = buf + PADI(base);
; #pragma unroll
;     for (int d = 0; d < 16; ++d) x[d] = pb[d * STEP];
;     const float th = (float)bl * (1.f / (float)(16 << ST));
;     const f32x2 W1 = {__builtin_amdgcn_cosf(th), -__builtin_amdgcn_sinf(th)};
;     const f32x2 W2 = cmul(W1, W1), W4 = cmul(W2, W2), W8 = cmul(W4, W4);
;     if (!INV) {
; #pragma unroll
;         for (int d = 0; d < 8; ++d) { const f32x2 w = cmul(W1, (f32x2){C16[d], -S16[d]}); const f32x2 a = x[d], b = x[d + 8]; x[d] = a + b; x[d + 8] = cmul(a - b, w); }
; #pragma unroll
;         for (int g = 0; g < 16; g += 8)
; #pragma unroll
;             for (int dd = 0; dd < 4; ++dd) { const int d = g + dd; const f32x2 w = cmul(W2, (f32x2){C16[2 * dd], -S16[2 * dd]}); const f32x2 a = x[d], b = x[d + 4]; x[d] = a + b; x[d + 4] = cmul(a - b, w); }
; #pragma unroll
;         for (int g = 0; g < 16; g += 4)
; #pragma unroll
;             for (int dd = 0; dd < 2; ++dd) { const int d = g + dd; const f32x2 w = dd ? (f32x2){W4.y, -W4.x} : W4; const f32x2 a = x[d], b = x[d + 2]; x[d] = a + b; x[d + 2] = cmul(a - b, w); }
; #pragma unroll
;         for (int g = 0; g < 16; g += 2) { const f32x2 a = x[g], b = x[g + 1]; x[g] = a + b; x[g + 1] = cmul(a - b, W8); }
; __device__ __forceinline__ void fft_fwd_abc(LAS f32x2* buf, int tid) {
;     ...
;     fft_pass16<false, 9>(buf, tid, tid); __syncthreads();
;     fft_pass16<false, 5>(buf, ((tid >> 5) << 9) + (tid & 31), tid & 31); __syncthreads();
;     fft_pass16<false, 1>(buf, ((tid >> 1) << 5) + (tid & 1), tid & 1); __syncthreads();
	v_pk_fma_f32 v[34:35], v[28:29], v[34:35], v[48:49] op_sel:[0,0,1] op_sel_hi:[1,1,0]
	s_nop 0
	v_mov_b32_e32 v51, v35
	v_pk_add_f32 v[34:35], v[24:25], v[46:47]
	v_pk_add_f32 v[24:25], v[24:25], v[46:47] neg_lo:[0,1] neg_hi:[0,1]
	s_nop 0
	v_pk_mul_f32 v[46:47], v[20:21], v[24:25] op_sel_hi:[0,1]
	v_pk_fma_f32 v[48:49], v[28:29], v[24:25], v[46:47] op_sel:[0,0,1] op_sel_hi:[1,1,0] neg_lo:[0,0,1] neg_hi:[0,0,1]
	v_pk_fma_f32 v[24:25], v[28:29], v[24:25], v[46:47] op_sel:[0,0,1] op_sel_hi:[1,1,0]
	v_pk_add_f32 v[46:47], v[58:59], v[62:63] neg_lo:[0,1] neg_hi:[0,1]
	v_mov_b32_e32 v49, v25
	v_pk_mul_f32 v[52:53], v[20:21], v[46:47] op_sel_hi:[0,1]
	v_pk_add_f32 v[24:25], v[58:59], v[62:63]
	v_pk_fma_f32 v[58:59], v[28:29], v[46:47], v[52:53] op_sel:[0,0,1] op_sel_hi:[1,1,0] neg_lo:[0,0,1] neg_hi:[0,0,1]
	v_pk_fma_f32 v[46:47], v[28:29], v[46:47], v[52:53] op_sel:[0,0,1] op_sel_hi:[1,1,0]
	s_nop 0
	v_mov_b32_e32 v59, v47
	v_pk_add_f32 v[46:47], v[56:57], v[26:27]
	v_pk_add_f32 v[26:27], v[56:57], v[26:27] neg_lo:[0,1] neg_hi:[0,1]
	s_nop 0
	v_pk_mul_f32 v[52:53], v[20:21], v[26:27] op_sel_hi:[0,1]
	v_pk_fma_f32 v[56:57], v[28:29], v[26:27], v[52:53] op_sel:[0,0,1] op_sel_hi:[1,1,0] neg_lo:[0,0,1] neg_hi:[0,0,1]
	v_pk_fma_f32 v[26:27], v[28:29], v[26:27], v[52:53] op_sel:[0,0,1] op_sel_hi:[1,1,0]
	s_nop 0
	v_mov_b32_e32 v57, v27
	v_pk_add_f32 v[26:27], v[60:61], v[38:39]
	v_pk_add_f32 v[38:39], v[60:61], v[38:39] neg_lo:[0,1] neg_hi:[0,1]
	s_nop 0
	v_pk_mul_f32 v[52:53], v[20:21], v[38:39] op_sel_hi:[0,1]
	v_pk_fma_f32 v[60:61], v[28:29], v[38:39], v[52:53] op_sel:[0,0,1] op_sel_hi:[1,1,0] neg_lo:[0,0,1] neg_hi:[0,0,1]
	v_pk_fma_f32 v[38:39], v[28:29], v[38:39], v[52:53] op_sel:[0,0,1] op_sel_hi:[1,1,0]
	s_nop 0
	v_mov_b32_e32 v61, v39
	v_pk_add_f32 v[38:39], v[32:33], v[36:37]
	v_pk_add_f32 v[32:33], v[32:33], v[36:37] neg_lo:[0,1] neg_hi:[0,1]
	s_nop 0
	v_pk_mul_f32 v[36:37], v[20:21], v[32:33] op_sel_hi:[0,1]
	v_pk_fma_f32 v[52:53], v[28:29], v[32:33], v[36:37] op_sel:[0,0,1] op_sel_hi:[1,1,0] neg_lo:[0,0,1] neg_hi:[0,0,1]
	v_pk_fma_f32 v[32:33], v[28:29], v[32:33], v[36:37] op_sel:[0,0,1] op_sel_hi:[1,1,0]
	v_pk_add_f32 v[36:37], v[64:65], v[54:55] neg_lo:[0,1] neg_hi:[0,1]
	v_mov_b32_e32 v53, v33
	v_pk_mul_f32 v[20:21], v[20:21], v[36:37] op_sel_hi:[0,1]
	v_pk_add_f32 v[32:33], v[64:65], v[54:55]
	v_pk_fma_f32 v[54:55], v[28:29], v[36:37], v[20:21] op_sel:[0,0,1] op_sel_hi:[1,1,0] neg_lo:[0,0,1] neg_hi:[0,0,1]
	v_pk_fma_f32 v[20:21], v[28:29], v[36:37], v[20:21] op_sel:[0,0,1] op_sel_hi:[1,1,0]
	s_nop 0
	v_mov_b32_e32 v55, v21
	v_and_b32_e32 v20, 1, v2
	v_bfe_i32 v21, v2, 0, 28
	v_lshlrev_b32_e32 v2, 7, v2
	v_and_b32_e32 v2, 0xffffff00, v2
	v_lshlrev_b32_e32 v21, 3, v21
	ds_write2_b64 v41, v[44:45], v[42:43] offset1:34
	ds_write2_b64 v41, v[30:31], v[50:51] offset0:68 offset1:102
	ds_write2_b64 v41, v[34:35], v[48:49] offset0:136 offset1:170
	ds_write2_b64 v41, v[24:25], v[58:59] offset0:204 offset1:238
	ds_write2_b64 v82, v[46:47], v[56:57] offset0:16 offset1:50
	ds_write2_b64 v82, v[26:27], v[60:61] offset0:84 offset1:118
	ds_write2_b64 v82, v[38:39], v[52:53] offset0:152 offset1:186
	ds_write2_b64 v82, v[32:33], v[54:55] offset0:220 offset1:254
	v_add_u32_e32 v2, 0, v2
	v_lshlrev_b32_e32 v24, 3, v20
	v_and_b32_e32 v21, -16, v21
	v_add3_u32 v41, v2, v24, v21
	v_cvt_f32_ubyte0_e32 v2, v20
	v_mul_f32_e32 v2, 0x3d000000, v2
	v_sin_f32_e32 v58, v2
	v_cos_f32_e32 v20, v2
	s_waitcnt lgkmcnt(0)
	s_barrier
	v_xor_b32_e32 v21, 0x80000000, v58
	v_mov_b32_e32 v59, v20
	v_mov_b32_e32 v60, v58
	v_mov_b32_e32 v61, v21
	v_pk_mul_f32 v[60:61], v[58:59], v[60:61]
	ds_read2_b64 v[24:27], v41 offset1:2
	ds_read2_b64 v[28:31], v41 offset0:4 offset1:6
	ds_read2_b64 v[32:35], v41 offset0:8 offset1:10
	ds_read2_b64 v[36:39], v41 offset0:12 offset1:14
	ds_read2_b64 v[42:45], v41 offset0:16 offset1:18
	ds_read2_b64 v[46:49], v41 offset0:20 offset1:22
	ds_read2_b64 v[50:53], v41 offset0:24 offset1:26
	ds_read2_b64 v[54:57], v41 offset0:28 offset1:30
	v_pk_fma_f32 v[62:63], v[20:21], v[20:21], v[60:61] op_sel_hi:[0,1,1] neg_lo:[0,0,1] neg_hi:[0,0,1]
	v_pk_fma_f32 v[60:61], v[20:21], v[20:21], v[60:61] op_sel_hi:[0,1,1]
	v_mov_b32_e32 v63, v61
	v_pk_mul_f32 v[66:67], v[62:63], v[60:61] op_sel:[0,1] op_sel_hi:[1,0]
	v_fma_f32 v60, v20, s22, -v58
	s_waitcnt lgkmcnt(3)
	v_pk_add_f32 v[68:69], v[24:25], v[42:43]
	v_pk_add_f32 v[24:25], v[24:25], v[42:43] neg_lo:[0,1] neg_hi:[0,1]
	v_fmamk_f32 v2, v58, 0x80000000, v20
	v_pk_mul_f32 v[42:43], v[60:61], v[24:25] op_sel:[0,1] op_sel_hi:[0,0]
	v_pk_fma_f32 v[70:71], v[2:3], v[24:25], v[42:43] neg_lo:[0,0,1] neg_hi:[0,0,1]
	v_pk_fma_f32 v[24:25], v[2:3], v[24:25], v[42:43] op_sel_hi:[0,1,1]
	v_pk_mul_f32 v[42:43], v[58:59], s[10:11] op_sel_hi:[1,0]
	v_mov_b32_e32 v71, v25
	v_pk_add_f32 v[24:25], v[26:27], v[44:45]
	v_pk_add_f32 v[26:27], v[26:27], v[44:45] neg_lo:[0,1] neg_hi:[0,1]
	v_fma_f32 v2, v58, s11, -v43
	s_waitcnt lgkmcnt(2)
	v_pk_add_f32 v[44:45], v[28:29], v[46:47]
	v_pk_add_f32 v[28:29], v[28:29], v[46:47] neg_lo:[0,1] neg_hi:[0,1]
	v_pk_add_f32 v[72:73], v[42:43], v[42:43] op_sel:[1,0] op_sel_hi:[1,0] neg_lo:[0,1] neg_hi:[0,1]
	v_pk_mul_f32 v[46:47], v[2:3], v[28:29] op_sel:[0,1] op_sel_hi:[0,0]
	v_pk_fma_f32 v[74:75], v[72:73], v[28:29], v[46:47] neg_lo:[0,0,1] neg_hi:[0,0,1]
	v_pk_fma_f32 v[28:29], v[72:73], v[28:29], v[46:47]
	v_pk_mul_f32 v[72:73], v[58:59], s[96:97]
	v_mov_b32_e32 v75, v29
	v_pk_mul_f32 v[28:29], v[58:59], s[20:21]
	v_pk_add_f32 v[76:77], v[30:31], v[48:49]
	v_pk_add_f32 v[30:31], v[30:31], v[48:49] neg_lo:[0,1] neg_hi:[0,1]
	v_pk_add_f32 v[48:49], v[72:73], v[72:73] op_sel:[0,1] op_sel_hi:[0,1] neg_lo:[0,1] neg_hi:[0,1]
	v_pk_mul_f32 v[48:49], v[48:49], v[30:31] op_sel:[0,1] op_sel_hi:[1,0]
	v_pk_add_f32 v[78:79], v[28:29], v[28:29] op_sel:[1,0] op_sel_hi:[1,0] neg_lo:[0,1] neg_hi:[0,1]
	v_fma_f32 v2, v58, s2, -v29
	v_pk_fma_f32 v[80:81], v[78:79], v[30:31], v[48:49] neg_lo:[0,0,1] neg_hi:[0,0,1]
	v_pk_fma_f32 v[30:31], v[78:79], v[30:31], v[48:49]
	s_waitcnt lgkmcnt(1)
; __device__ __forceinline__ f32x2 cmul(f32x2 a, f32x2 b) { return (f32x2){a.x * b.x - a.y * b.y, a.x * b.y + a.y * b.x}; }
; template <bool INV, int ST> __device__ __forceinline__ void fft_pass16(LAS f32x2* buf, int base, int bl) {
;     ...
;     if (!INV) {
; #pragma unroll
;         for (int d = 0; d < 8; ++d) { const f32x2 w = cmul(W1, (f32x2){C16[d], -S16[d]}); const f32x2 a = x[d], b = x[d + 8]; x[d] = a + b; x[d + 8] = cmul(a - b, w); }
; #pragma unroll
;         for (int g = 0; g < 16; g += 8)
; #pragma unroll
;             for (int dd = 0; dd < 4; ++dd) { const int d = g + dd; const f32x2 w = cmul(W2, (f32x2){C16[2 * dd], -S16[2 * dd]}); const f32x2 a = x[d], b = x[d + 4]; x[d] = a + b; x[d + 4] = cmul(a - b, w); }
; #pragma unroll
;         for (int g = 0; g < 16; g += 4)
; #pragma unroll
;             for (int dd = 0; dd < 2; ++dd) { const int d = g + dd; const f32x2 w = dd ? (f32x2){W4.y, -W4.x} : W4; const f32x2 a = x[d], b = x[d + 2]; x[d] = a + b; x[d + 2] = cmul(a - b, w); }
	v_pk_add_f32 v[48:49], v[32:33], v[50:51]
	v_fma_f32 v30, v58, s22, -v20
	v_pk_add_f32 v[32:33], v[32:33], v[50:51] neg_lo:[0,1] neg_hi:[0,1]
	v_pk_mul_f32 v[46:47], v[2:3], v[26:27] op_sel:[0,1] op_sel_hi:[0,0]
	v_mov_b32_e32 v81, v31
	v_fma_f32 v2, v20, 0, -v58
	v_pk_mul_f32 v[30:31], v[30:31], v[32:33] op_sel:[0,1] op_sel_hi:[0,0]
	v_pk_fma_f32 v[50:51], v[2:3], v[32:33], v[30:31] neg_lo:[0,0,1] neg_hi:[0,0,1]
	v_pk_fma_f32 v[30:31], v[2:3], v[32:33], v[30:31] op_sel_hi:[0,1,1]
	v_mov_b32_e32 v51, v31
	v_pk_add_f32 v[30:31], v[34:35], v[52:53]
	v_pk_add_f32 v[32:33], v[34:35], v[52:53] neg_lo:[0,1] neg_hi:[0,1]
	v_fma_f32 v34, v20, s11, -v42
	s_waitcnt lgkmcnt(0)
	v_pk_add_f32 v[52:53], v[36:37], v[54:55]
	v_pk_add_f32 v[36:37], v[36:37], v[54:55] neg_lo:[0,1] neg_hi:[0,1]
	v_pk_add_f32 v[42:43], v[42:43], v[42:43] op_sel:[0,1] op_sel_hi:[0,1] neg_lo:[0,1] neg_hi:[0,1]
	v_pk_mul_f32 v[42:43], v[42:43], v[36:37] op_sel:[0,1] op_sel_hi:[1,0]
	v_mov_b32_e32 v21, v58
	v_fma_f32 v2, v20, s96, -v28
	v_pk_fma_f32 v[54:55], v[34:35], v[36:37], v[42:43] neg_lo:[0,0,1] neg_hi:[0,0,1]
	v_pk_fma_f32 v[34:35], v[34:35], v[36:37], v[42:43] op_sel_hi:[0,1,1]
	v_pk_mul_f32 v[20:21], v[20:21], s[2:3]
	v_mov_b32_e32 v55, v35
	v_sub_f32_e32 v34, v73, v21
	v_pk_fma_f32 v[36:37], v[34:35], v[26:27], v[46:47] op_sel_hi:[0,1,1] neg_lo:[0,0,1] neg_hi:[0,0,1]
	v_pk_fma_f32 v[26:27], v[34:35], v[26:27], v[46:47] op_sel_hi:[0,1,1]
	v_sub_f32_e32 v26, v21, v73
	v_mov_b32_e32 v37, v27
	v_pk_mul_f32 v[26:27], v[26:27], v[32:33] op_sel:[0,1] op_sel_hi:[0,0]
	v_pk_fma_f32 v[34:35], v[2:3], v[32:33], v[26:27] neg_lo:[0,0,1] neg_hi:[0,0,1]
	v_pk_fma_f32 v[26:27], v[2:3], v[32:33], v[26:27] op_sel_hi:[0,1,1]
	v_pk_add_f32 v[32:33], v[38:39], v[56:57] neg_lo:[0,1] neg_hi:[0,1]
	v_pk_add_f32 v[28:29], v[28:29], v[28:29] op_sel:[0,1] op_sel_hi:[0,1] neg_lo:[0,1] neg_hi:[0,1]
	v_pk_mul_f32 v[28:29], v[28:29], v[32:33] op_sel:[0,1] op_sel_hi:[1,0]
	v_pk_add_f32 v[20:21], v[20:21], v[20:21] op_sel:[0,1] op_sel_hi:[0,1] neg_lo:[0,1] neg_hi:[0,1]
	v_fmamk_f32 v42, v62, 0x80000000, v61
	v_pk_add_f32 v[46:47], v[68:69], v[48:49]
	v_pk_add_f32 v[48:49], v[68:69], v[48:49] neg_lo:[0,1] neg_hi:[0,1]
	v_pk_mul_f32 v[64:65], v[62:63], v[62:63]
	v_mov_b32_e32 v35, v27
	v_pk_add_f32 v[26:27], v[38:39], v[56:57]
	v_pk_fma_f32 v[38:39], v[20:21], v[32:33], v[28:29] neg_lo:[0,0,1] neg_hi:[0,0,1]
	v_pk_fma_f32 v[20:21], v[20:21], v[32:33], v[28:29]
	v_fma_f32 v2, 0, v61, v62
	v_pk_mul_f32 v[56:57], v[42:43], v[48:49] op_sel_hi:[0,1]
	v_mov_b32_e32 v20, v64
	v_pk_mov_b32 v[28:29], v[64:65], v[66:67] op_sel:[1,0]
	v_pk_fma_f32 v[58:59], v[2:3], v[48:49], v[56:57] op_sel:[0,0,1] op_sel_hi:[1,1,0] neg_lo:[0,0,1] neg_hi:[0,0,1]
	v_pk_fma_f32 v[48:49], v[2:3], v[48:49], v[56:57] op_sel:[0,0,1] op_sel_hi:[0,1,0]
	v_fma_f32 v56, v61, 0, -v62
	v_pk_add_f32 v[64:65], v[44:45], v[52:53]
	v_pk_add_f32 v[44:45], v[44:45], v[52:53] neg_lo:[0,1] neg_hi:[0,1]
	v_mov_b32_e32 v59, v49
	v_pk_add_f32 v[48:49], v[24:25], v[30:31]
	v_pk_add_f32 v[24:25], v[24:25], v[30:31] neg_lo:[0,1] neg_hi:[0,1]
	v_fma_f32 v30, 0, v62, v61
	v_pk_mul_f32 v[52:53], v[56:57], v[44:45] op_sel_hi:[0,1]
	v_mov_b32_e32 v39, v21
	v_mov_b32_e32 v21, v66
	v_pk_fma_f32 v[66:67], v[30:31], v[44:45], v[52:53] op_sel:[0,0,1] op_sel_hi:[1,1,0] neg_lo:[0,0,1] neg_hi:[0,0,1]
	v_pk_fma_f32 v[44:45], v[30:31], v[44:45], v[52:53] op_sel:[0,0,1] op_sel_hi:[0,1,0]
	v_mov_b32_e32 v67, v45
	v_pk_mul_f32 v[44:45], v[62:63], s[10:11]
	v_pk_add_f32 v[32:33], v[20:21], v[28:29] neg_lo:[0,1] neg_hi:[0,1]
	v_fma_f32 v60, v61, s10, -v44
	v_fmamk_f32 v52, v61, 0x3f3504f3, v44
	v_pk_mul_f32 v[62:63], v[60:61], v[24:25] op_sel_hi:[0,1]
	v_pk_fma_f32 v[68:69], v[52:53], v[24:25], v[62:63] op_sel:[0,0,1] op_sel_hi:[1,1,0] neg_lo:[0,0,1] neg_hi:[0,0,1]
	v_pk_fma_f32 v[24:25], v[52:53], v[24:25], v[62:63] op_sel:[0,0,1] op_sel_hi:[0,1,0]
	v_mov_b32_e32 v69, v25
	v_pk_add_f32 v[24:25], v[76:77], v[26:27]
	v_pk_add_f32 v[26:27], v[76:77], v[26:27] neg_lo:[0,1] neg_hi:[0,1]
	v_pk_add_f32 v[44:45], v[44:45], v[44:45] op_sel:[1,0] op_sel_hi:[1,0] neg_lo:[0,1] neg_hi:[0,1]
	v_pk_add_f32 v[20:21], v[20:21], v[28:29]
	v_pk_mul_f32 v[62:63], v[44:45], v[26:27]
	v_mov_b32_e32 v28, v32
	v_pk_fma_f32 v[72:73], v[60:61], v[26:27], v[62:63] op_sel:[0,0,1] op_sel_hi:[1,1,0] neg_lo:[0,0,1] neg_hi:[0,0,1]
	v_pk_fma_f32 v[26:27], v[60:61], v[26:27], v[62:63] op_sel:[0,0,1] op_sel_hi:[0,1,0]
	v_mov_b32_e32 v73, v27
	v_pk_add_f32 v[26:27], v[70:71], v[50:51]
	v_pk_add_f32 v[50:51], v[70:71], v[50:51] neg_lo:[0,1] neg_hi:[0,1]
	v_mov_b32_e32 v29, v21
	v_pk_mul_f32 v[42:43], v[42:43], v[50:51] op_sel_hi:[0,1]
	v_pk_fma_f32 v[62:63], v[2:3], v[50:51], v[42:43] op_sel:[0,0,1] op_sel_hi:[1,1,0] neg_lo:[0,0,1] neg_hi:[0,0,1]
	v_pk_fma_f32 v[42:43], v[2:3], v[50:51], v[42:43] op_sel:[0,0,1] op_sel_hi:[0,1,0]
	v_mov_b32_e32 v63, v43
	v_pk_add_f32 v[42:43], v[36:37], v[34:35]
	v_pk_add_f32 v[34:35], v[36:37], v[34:35] neg_lo:[0,1] neg_hi:[0,1]
	v_mul_f32_e32 v2, v32, v21
	v_pk_mul_f32 v[36:37], v[60:61], v[34:35] op_sel_hi:[0,1]
	v_pk_fma_f32 v[50:51], v[52:53], v[34:35], v[36:37] op_sel:[0,0,1] op_sel_hi:[1,1,0] neg_lo:[0,0,1] neg_hi:[0,0,1]
	v_pk_fma_f32 v[34:35], v[52:53], v[34:35], v[36:37] op_sel:[0,0,1] op_sel_hi:[0,1,0]
	v_pk_add_f32 v[36:37], v[74:75], v[54:55] neg_lo:[0,1] neg_hi:[0,1]
	v_mov_b32_e32 v51, v35
	v_pk_mul_f32 v[52:53], v[56:57], v[36:37] op_sel_hi:[0,1]
	v_pk_add_f32 v[34:35], v[74:75], v[54:55]
	v_pk_fma_f32 v[54:55], v[30:31], v[36:37], v[52:53] op_sel:[0,0,1] op_sel_hi:[1,1,0] neg_lo:[0,0,1] neg_hi:[0,0,1]
	v_pk_fma_f32 v[30:31], v[30:31], v[36:37], v[52:53] op_sel:[0,0,1] op_sel_hi:[0,1,0]
; __device__ __forceinline__ f32x2 cmul(f32x2 a, f32x2 b) { return (f32x2){a.x * b.x - a.y * b.y, a.x * b.y + a.y * b.x}; }
; template <bool INV, int ST> __device__ __forceinline__ void fft_pass16(LAS f32x2* buf, int base, int bl) {
;     ...
;         for (int g = 0; g < 16; g += 8)
; #pragma unroll
;             for (int dd = 0; dd < 4; ++dd) { const int d = g + dd; const f32x2 w = cmul(W2, (f32x2){C16[2 * dd], -S16[2 * dd]}); const f32x2 a = x[d], b = x[d + 4]; x[d] = a + b; x[d + 4] = cmul(a - b, w); }
; #pragma unroll
;         for (int g = 0; g < 16; g += 4)
; #pragma unroll
;             for (int dd = 0; dd < 2; ++dd) { const int d = g + dd; const f32x2 w = dd ? (f32x2){W4.y, -W4.x} : W4; const f32x2 a = x[d], b = x[d + 2]; x[d] = a + b; x[d + 2] = cmul(a - b, w); }
; #pragma unroll
;         for (int g = 0; g < 16; g += 2) { const f32x2 a = x[g], b = x[g + 1]; x[g] = a + b; x[g + 1] = cmul(a - b, W8); }
	v_pk_add_f32 v[36:37], v[80:81], v[38:39] neg_lo:[0,1] neg_hi:[0,1]
	v_mov_b32_e32 v55, v31
	v_pk_add_f32 v[30:31], v[80:81], v[38:39]
	v_pk_mul_f32 v[38:39], v[44:45], v[36:37]
	v_pk_mul_f32 v[28:29], v[28:29], v[28:29]
	v_pk_fma_f32 v[44:45], v[60:61], v[36:37], v[38:39] op_sel:[0,0,1] op_sel_hi:[1,1,0] neg_lo:[0,0,1] neg_hi:[0,0,1]
	v_pk_fma_f32 v[36:37], v[60:61], v[36:37], v[38:39] op_sel:[0,0,1] op_sel_hi:[0,1,0]
	v_pk_add_f32 v[38:39], v[46:47], v[64:65] neg_lo:[0,1] neg_hi:[0,1]
	v_mov_b32_e32 v45, v37
	v_pk_add_f32 v[36:37], v[46:47], v[64:65]
	v_pk_mul_f32 v[46:47], v[20:21], v[38:39] op_sel:[1,0]
	v_add_f32_e32 v2, v2, v2
	v_pk_fma_f32 v[52:53], v[32:33], v[38:39], v[46:47] op_sel:[0,0,1] op_sel_hi:[1,1,0] neg_lo:[0,0,1] neg_hi:[0,0,1]
	v_pk_fma_f32 v[38:39], v[32:33], v[38:39], v[46:47] op_sel:[0,0,1] op_sel_hi:[0,1,0]
	v_mov_b32_e32 v53, v39
	v_pk_add_f32 v[38:39], v[48:49], v[24:25]
	v_pk_add_f32 v[24:25], v[48:49], v[24:25] neg_lo:[0,1] neg_hi:[0,1]
	v_pk_add_f32 v[28:29], v[28:29], v[28:29] op_sel:[0,1] op_sel_hi:[0,1] neg_lo:[0,1] neg_hi:[0,1]
	v_pk_mul_f32 v[46:47], v[32:33], v[24:25] op_sel_hi:[0,1]
	v_pk_fma_f32 v[48:49], v[20:21], v[24:25], v[46:47] op_sel:[1,0,1] op_sel_hi:[1,1,0]
	v_pk_fma_f32 v[24:25], v[20:21], v[24:25], v[46:47] op_sel:[1,0,1] op_sel_hi:[1,1,0] neg_lo:[0,0,1] neg_hi:[0,0,1]
	v_pk_add_f32 v[46:47], v[58:59], v[66:67] neg_lo:[0,1] neg_hi:[0,1]
	v_mov_b32_e32 v49, v25
	v_pk_mul_f32 v[56:57], v[20:21], v[46:47] op_sel:[1,0]
	v_pk_add_f32 v[24:25], v[58:59], v[66:67]
	v_pk_fma_f32 v[58:59], v[32:33], v[46:47], v[56:57] op_sel:[0,0,1] op_sel_hi:[1,1,0] neg_lo:[0,0,1] neg_hi:[0,0,1]
	v_pk_fma_f32 v[46:47], v[32:33], v[46:47], v[56:57] op_sel:[0,0,1] op_sel_hi:[0,1,0]
	v_pk_add_f32 v[56:57], v[68:69], v[72:73] neg_lo:[0,1] neg_hi:[0,1]
	v_mov_b32_e32 v59, v47
	v_pk_mul_f32 v[60:61], v[32:33], v[56:57] op_sel_hi:[0,1]
	v_pk_fma_f32 v[64:65], v[20:21], v[56:57], v[60:61] op_sel:[1,0,1] op_sel_hi:[1,1,0]
	v_pk_fma_f32 v[56:57], v[20:21], v[56:57], v[60:61] op_sel:[1,0,1] op_sel_hi:[1,1,0] neg_lo:[0,0,1] neg_hi:[0,0,1]
	v_pk_add_f32 v[46:47], v[68:69], v[72:73]
	v_mov_b32_e32 v65, v57
	v_pk_add_f32 v[56:57], v[26:27], v[34:35]
	v_pk_add_f32 v[26:27], v[26:27], v[34:35] neg_lo:[0,1] neg_hi:[0,1]
	s_nop 0
	v_pk_mul_f32 v[34:35], v[20:21], v[26:27] op_sel:[1,0]
	s_nop 0
	v_pk_fma_f32 v[60:61], v[32:33], v[26:27], v[34:35] op_sel:[0,0,1] op_sel_hi:[1,1,0] neg_lo:[0,0,1] neg_hi:[0,0,1]
	v_pk_fma_f32 v[26:27], v[32:33], v[26:27], v[34:35] op_sel:[0,0,1] op_sel_hi:[0,1,0]
	v_mov_b32_e32 v61, v27
	v_pk_add_f32 v[26:27], v[42:43], v[30:31]
	v_pk_add_f32 v[30:31], v[42:43], v[30:31] neg_lo:[0,1] neg_hi:[0,1]
	s_nop 0
	v_pk_mul_f32 v[34:35], v[32:33], v[30:31] op_sel_hi:[0,1]
	v_pk_fma_f32 v[42:43], v[20:21], v[30:31], v[34:35] op_sel:[1,0,1] op_sel_hi:[1,1,0]
	v_pk_fma_f32 v[30:31], v[20:21], v[30:31], v[34:35] op_sel:[1,0,1] op_sel_hi:[1,1,0] neg_lo:[0,0,1] neg_hi:[0,0,1]
	v_pk_add_f32 v[34:35], v[62:63], v[54:55] neg_lo:[0,1] neg_hi:[0,1]
	v_mov_b32_e32 v43, v31
	v_pk_add_f32 v[30:31], v[62:63], v[54:55]
	v_pk_mul_f32 v[54:55], v[20:21], v[34:35] op_sel:[1,0]
	s_nop 0
	v_pk_fma_f32 v[62:63], v[32:33], v[34:35], v[54:55] op_sel:[0,0,1] op_sel_hi:[1,1,0] neg_lo:[0,0,1] neg_hi:[0,0,1]
	v_pk_fma_f32 v[34:35], v[32:33], v[34:35], v[54:55] op_sel:[0,0,1] op_sel_hi:[0,1,0]
	v_mov_b32_e32 v63, v35
	v_pk_add_f32 v[34:35], v[50:51], v[44:45]
	v_pk_add_f32 v[44:45], v[50:51], v[44:45] neg_lo:[0,1] neg_hi:[0,1]
	s_nop 0
	v_pk_mul_f32 v[50:51], v[32:33], v[44:45] op_sel_hi:[0,1]
	v_pk_fma_f32 v[54:55], v[20:21], v[44:45], v[50:51] op_sel:[1,0,1] op_sel_hi:[1,1,0]
	v_pk_fma_f32 v[44:45], v[20:21], v[44:45], v[50:51] op_sel:[1,0,1] op_sel_hi:[1,1,0] neg_lo:[0,0,1] neg_hi:[0,0,1]
	s_nop 0
	v_mov_b32_e32 v55, v45
	v_pk_add_f32 v[44:45], v[36:37], v[38:39]
	v_pk_add_f32 v[36:37], v[36:37], v[38:39] neg_lo:[0,1] neg_hi:[0,1]
	s_nop 0
	v_pk_mul_f32 v[20:21], v[2:3], v[36:37] op_sel_hi:[0,1]
	v_pk_fma_f32 v[32:33], v[28:29], v[36:37], v[20:21] op_sel:[0,0,1] op_sel_hi:[1,1,0] neg_lo:[0,0,1] neg_hi:[0,0,1]
	v_pk_fma_f32 v[20:21], v[28:29], v[36:37], v[20:21] op_sel:[0,0,1] op_sel_hi:[1,1,0]
	v_pk_add_f32 v[36:37], v[52:53], v[48:49] neg_lo:[0,1] neg_hi:[0,1]
	v_mov_b32_e32 v33, v21
	v_pk_mul_f32 v[38:39], v[2:3], v[36:37] op_sel_hi:[0,1]
	v_pk_add_f32 v[20:21], v[52:53], v[48:49]
	v_pk_fma_f32 v[48:49], v[28:29], v[36:37], v[38:39] op_sel:[0,0,1] op_sel_hi:[1,1,0] neg_lo:[0,0,1] neg_hi:[0,0,1]
	v_pk_fma_f32 v[36:37], v[28:29], v[36:37], v[38:39] op_sel:[0,0,1] op_sel_hi:[1,1,0]
	s_nop 0
	v_mov_b32_e32 v49, v37
	v_pk_add_f32 v[36:37], v[24:25], v[46:47]
	v_pk_add_f32 v[24:25], v[24:25], v[46:47] neg_lo:[0,1] neg_hi:[0,1]
	s_nop 0
	v_pk_mul_f32 v[38:39], v[2:3], v[24:25] op_sel_hi:[0,1]
	v_pk_fma_f32 v[46:47], v[28:29], v[24:25], v[38:39] op_sel:[0,0,1] op_sel_hi:[1,1,0] neg_lo:[0,0,1] neg_hi:[0,0,1]
	v_pk_fma_f32 v[24:25], v[28:29], v[24:25], v[38:39] op_sel:[0,0,1] op_sel_hi:[1,1,0]
	v_pk_add_f32 v[38:39], v[58:59], v[64:65] neg_lo:[0,1] neg_hi:[0,1]
	v_mov_b32_e32 v47, v25
	v_pk_mul_f32 v[50:51], v[2:3], v[38:39] op_sel_hi:[0,1]
	v_pk_fma_f32 v[52:53], v[28:29], v[38:39], v[50:51] op_sel:[0,0,1] op_sel_hi:[1,1,0] neg_lo:[0,0,1] neg_hi:[0,0,1]
	v_pk_fma_f32 v[38:39], v[28:29], v[38:39], v[50:51] op_sel:[0,0,1] op_sel_hi:[1,1,0]
	v_pk_add_f32 v[24:25], v[58:59], v[64:65]
	v_mov_b32_e32 v53, v39
	v_pk_add_f32 v[38:39], v[56:57], v[26:27]
	v_pk_add_f32 v[26:27], v[56:57], v[26:27] neg_lo:[0,1] neg_hi:[0,1]
	s_nop 0
	v_pk_mul_f32 v[50:51], v[2:3], v[26:27] op_sel_hi:[0,1]
	v_pk_fma_f32 v[56:57], v[28:29], v[26:27], v[50:51] op_sel:[0,0,1] op_sel_hi:[1,1,0] neg_lo:[0,0,1] neg_hi:[0,0,1]
; template <bool INV, int ST> __device__ __forceinline__ void fft_pass16(LAS f32x2* buf, int base, int bl) {
;     ...
;         for (int g = 0; g < 16; g += 2) { const f32x2 a = x[g], b = x[g + 1]; x[g] = a + b; x[g + 1] = cmul(a - b, W8); }
;     } else {
; #pragma unroll
;         for (int g = 0; g < 16; g += 2) { const f32x2 a = x[g], b = cmulc(x[g + 1], W8); x[g] = a + b; x[g + 1] = a - b; }
; #pragma unroll
;         for (int g = 0; g < 16; g += 4)
; #pragma unroll
;             for (int dd = 0; dd < 2; ++dd) { const int d = g + dd; const f32x2 w = dd ? (f32x2){W4.y, -W4.x} : W4; const f32x2 a = x[d], b = cmulc(x[d + 2], w); x[d] = a + b; x[d + 2] = a - b; }
; #pragma unroll
;         for (int g = 0; g < 16; g += 8)
; #pragma unroll
;             for (int dd = 0; dd < 4; ++dd) { const int d = g + dd; const f32x2 w = cmul(W2, (f32x2){C16[2 * dd], -S16[2 * dd]}); const f32x2 a = x[d], b = cmulc(x[d + 4], w); x[d] = a + b; x[d + 4] = a - b; }
; #pragma unroll
;         for (int d = 0; d < 8; ++d) { const f32x2 w = cmul(W1, (f32x2){C16[d], -S16[d]}); const f32x2 a = x[d], b = cmulc(x[d + 8], w); x[d] = a + b; x[d + 8] = a - b; }
;     }
; #pragma unroll
;     for (int d = 0; d < 16; ++d) pb[d * STEP] = x[d];
; __device__ __forceinline__ void hyena_phase(const Params& P, int l, LAS unsigned char* lds) {
;     ...
;                 fft_fwd_abc(bufA, tid);
; #pragma unroll 2
;                 for (int u = 0; u < 8; ++u) { const int i0 = 2 * (tid + 512 * u); LAS f32x4* pp = (LAS f32x4*)(bufA + PADI(2 * tid) + 1088 * u); const f32x4 v = *pp;
;                     f32x2 xs[2] = {(f32x2){v[0] + v[2], v[1] + v[3]}, (f32x2){v[0] - v[2], v[1] - v[3]}};
;                     const f32x4 zz = *(const LAS f32x4*)(bufB + PADI(2 * tid) + 1088 * u);
; #pragma unroll
;                     for (int q = 0; q < 2; ++q) { const unsigned f = __brev((unsigned)(i0 + q)) >> 19, fp = (8192u - f) & 8191u, ip = __brev(fp) >> 19;
;                         const f32x2 Z = q ? (f32x2){zz[2], zz[3]} : (f32x2){zz[0], zz[1]}; const f32x2 Zp = bufB[PADI((int)ip)]; f32x2 Kf;
;                         if (ord == 0) Kf = (f32x2){Z.x + Zp.x, Z.y - Zp.y}; else Kf = (f32x2){Z.y + Zp.y, Zp.x - Z.x};
;                         Kf *= (0.5f / 8192.f);
;                         xs[q] = cmul(xs[q], Kf); }
;                     *pp = (f32x4){xs[0].x + xs[1].x, xs[0].y + xs[1].y, xs[0].x - xs[1].x, xs[0].y - xs[1].y}; }
	v_pk_fma_f32 v[26:27], v[28:29], v[26:27], v[50:51] op_sel:[0,0,1] op_sel_hi:[1,1,0]
	s_nop 0
	v_mov_b32_e32 v57, v27
	v_pk_add_f32 v[26:27], v[60:61], v[42:43]
	v_pk_add_f32 v[42:43], v[60:61], v[42:43] neg_lo:[0,1] neg_hi:[0,1]
	s_nop 0
	v_pk_mul_f32 v[50:51], v[2:3], v[42:43] op_sel_hi:[0,1]
	v_pk_fma_f32 v[58:59], v[28:29], v[42:43], v[50:51] op_sel:[0,0,1] op_sel_hi:[1,1,0] neg_lo:[0,0,1] neg_hi:[0,0,1]
	v_pk_fma_f32 v[42:43], v[28:29], v[42:43], v[50:51] op_sel:[0,0,1] op_sel_hi:[1,1,0]
	s_nop 0
	v_mov_b32_e32 v59, v43
	v_pk_add_f32 v[42:43], v[30:31], v[34:35]
	v_pk_add_f32 v[30:31], v[30:31], v[34:35] neg_lo:[0,1] neg_hi:[0,1]
	s_nop 0
	v_pk_mul_f32 v[34:35], v[2:3], v[30:31] op_sel_hi:[0,1]
	v_pk_fma_f32 v[50:51], v[28:29], v[30:31], v[34:35] op_sel:[0,0,1] op_sel_hi:[1,1,0] neg_lo:[0,0,1] neg_hi:[0,0,1]
	v_pk_fma_f32 v[30:31], v[28:29], v[30:31], v[34:35] op_sel:[0,0,1] op_sel_hi:[1,1,0]
	v_pk_add_f32 v[34:35], v[62:63], v[54:55] neg_lo:[0,1] neg_hi:[0,1]
	v_mov_b32_e32 v51, v31
	v_pk_add_f32 v[30:31], v[62:63], v[54:55]
	v_pk_mul_f32 v[54:55], v[2:3], v[34:35] op_sel_hi:[0,1]
	v_pk_fma_f32 v[60:61], v[28:29], v[34:35], v[54:55] op_sel:[0,0,1] op_sel_hi:[1,1,0] neg_lo:[0,0,1] neg_hi:[0,0,1]
	v_pk_fma_f32 v[28:29], v[28:29], v[34:35], v[54:55] op_sel:[0,0,1] op_sel_hi:[1,1,0]
	s_nop 0
	v_mov_b32_e32 v61, v29
	ds_write2_b64 v41, v[44:45], v[32:33] offset1:2
	ds_write2_b64 v41, v[20:21], v[48:49] offset0:4 offset1:6
	ds_write2_b64 v41, v[36:37], v[46:47] offset0:8 offset1:10
	ds_write2_b64 v41, v[24:25], v[52:53] offset0:12 offset1:14
	ds_write2_b64 v41, v[38:39], v[56:57] offset0:16 offset1:18
	ds_write2_b64 v41, v[26:27], v[58:59] offset0:20 offset1:22
	ds_write2_b64 v41, v[42:43], v[50:51] offset0:24 offset1:26
	ds_write2_b64 v41, v[30:31], v[60:61] offset0:28 offset1:30
	s_waitcnt lgkmcnt(0)
	s_barrier
.LBB0_436:
	ds_read_b128 v[24:27], v23
	v_add_u32_e32 v29, s8, v40
	v_add_u32_e32 v21, 0x11000, v23
	s_addk_i32 s8, 0x800
	s_cmpk_lg_i32 s8, 0x2000
	s_waitcnt lgkmcnt(0)
	v_add_f32_e32 v2, v24, v26
	v_add_f32_e32 v20, v25, v27
	v_sub_f32_e32 v28, v24, v26
	v_sub_f32_e32 v30, v25, v27
	ds_read_b128 v[24:27], v21
	v_bfrev_b32_e32 v21, v29
	v_lshrrev_b32_e32 v21, 19, v21
	v_sub_u32_e32 v21, 0, v21
	v_and_b32_e32 v21, 0x1fff, v21
	v_bfrev_b32_e32 v21, v21
	v_lshrrev_b32_e32 v31, 16, v21
	v_lshlrev_b32_sdwa v21, v229, v21 dst_sel:DWORD dst_unused:UNUSED_PAD src0_sel:DWORD src1_sel:BYTE_3
	v_add3_u32 v21, s67, v31, v21
	ds_read_b64 v[32:33], v21
	v_add_u32_e32 v21, 1, v29
	v_bfrev_b32_e32 v21, v21
	v_lshrrev_b32_e32 v21, 19, v21
	v_sub_u32_e32 v21, 0, v21
	v_and_b32_e32 v21, 0x1fff, v21
	v_bfrev_b32_e32 v21, v21
	v_lshrrev_b32_e32 v31, 16, v21
	v_lshlrev_b32_sdwa v21, v229, v21 dst_sel:DWORD dst_unused:UNUSED_PAD src0_sel:DWORD src1_sel:BYTE_3
	v_add3_u32 v21, s67, v31, v21
	s_waitcnt lgkmcnt(0)
	v_add_f32_e32 v34, v25, v33
	v_sub_f32_e32 v35, v32, v24
	ds_read_b64 v[32:33], v21
	v_pk_mul_f32 v[24:25], v[34:35], s[0:1] op_sel_hi:[1,0]
	s_waitcnt lgkmcnt(0)
	v_add_f32_e32 v34, v27, v33
	v_sub_f32_e32 v35, v32, v26
	v_pk_mul_f32 v[20:21], v[20:21], v[24:25] op_sel:[0,1] op_sel_hi:[0,0]
	v_pk_mul_f32 v[26:27], v[34:35], s[0:1] op_sel_hi:[1,0]
	v_pk_fma_f32 v[32:33], v[2:3], v[24:25], v[20:21] neg_lo:[0,0,1] neg_hi:[0,0,1]
	v_pk_fma_f32 v[20:21], v[2:3], v[24:25], v[20:21] op_sel_hi:[0,1,1]
	v_mov_b32_e32 v33, v21
	v_pk_mul_f32 v[20:21], v[30:31], v[26:27] op_sel:[0,1] op_sel_hi:[0,0]
	v_pk_fma_f32 v[30:31], v[28:29], v[26:27], v[20:21] neg_lo:[0,0,1] neg_hi:[0,0,1]
	v_pk_fma_f32 v[20:21], v[28:29], v[26:27], v[20:21] op_sel_hi:[0,1,1]
	v_mov_b32_e32 v31, v21
	v_add_u32_e32 v21, 0x400, v29
	v_bfrev_b32_e32 v21, v21
	v_lshrrev_b32_e32 v21, 19, v21
	v_sub_u32_e32 v21, 0, v21
	v_pk_add_f32 v[24:25], v[32:33], v[30:31]
	v_pk_add_f32 v[26:27], v[32:33], v[30:31] neg_lo:[0,1] neg_hi:[0,1]
	v_and_b32_e32 v21, 0x1fff, v21
	ds_write_b128 v23, v[24:27]
	ds_read_b128 v[24:27], v23 offset:8704
	v_bfrev_b32_e32 v21, v21
	v_lshrrev_b32_e32 v31, 16, v21
	v_lshlrev_b32_sdwa v21, v229, v21 dst_sel:DWORD dst_unused:UNUSED_PAD src0_sel:DWORD src1_sel:BYTE_3
	v_add3_u32 v21, s67, v31, v21
	ds_read_b64 v[32:33], v21
	v_add_u32_e32 v21, 0x401, v29
	v_bfrev_b32_e32 v21, v21
	s_waitcnt lgkmcnt(1)
	v_add_f32_e32 v2, v24, v26
	v_sub_f32_e32 v28, v24, v26
	v_add_u32_e32 v24, 0x13200, v23
	v_lshrrev_b32_e32 v21, 19, v21
	v_add_f32_e32 v20, v25, v27
	v_sub_f32_e32 v30, v25, v27
	ds_read_b128 v[24:27], v24
	v_sub_u32_e32 v21, 0, v21
	v_and_b32_e32 v21, 0x1fff, v21
	v_bfrev_b32_e32 v21, v21
	v_lshrrev_b32_e32 v29, 16, v21
	v_lshlrev_b32_sdwa v21, v229, v21 dst_sel:DWORD dst_unused:UNUSED_PAD src0_sel:DWORD src1_sel:BYTE_3
	v_add3_u32 v21, s67, v29, v21
	s_waitcnt lgkmcnt(0)
	v_add_f32_e32 v34, v25, v33
	v_sub_f32_e32 v35, v32, v24
	ds_read_b64 v[32:33], v21
	v_pk_mul_f32 v[24:25], v[34:35], s[0:1] op_sel_hi:[1,0]
	s_waitcnt lgkmcnt(0)
	v_add_f32_e32 v34, v27, v33
	v_sub_f32_e32 v35, v32, v26
	v_pk_mul_f32 v[20:21], v[20:21], v[24:25] op_sel:[0,1] op_sel_hi:[0,0]
	v_pk_mul_f32 v[26:27], v[34:35], s[0:1] op_sel_hi:[1,0]
	v_pk_fma_f32 v[32:33], v[2:3], v[24:25], v[20:21] neg_lo:[0,0,1] neg_hi:[0,0,1]
	v_pk_fma_f32 v[20:21], v[2:3], v[24:25], v[20:21] op_sel_hi:[0,1,1]
	v_mov_b32_e32 v33, v21
	v_pk_mul_f32 v[20:21], v[30:31], v[26:27] op_sel:[0,1] op_sel_hi:[0,0]
	v_pk_fma_f32 v[30:31], v[28:29], v[26:27], v[20:21] neg_lo:[0,0,1] neg_hi:[0,0,1]
	v_pk_fma_f32 v[20:21], v[28:29], v[26:27], v[20:21] op_sel_hi:[0,1,1]
	v_mov_b32_e32 v31, v21
	v_pk_add_f32 v[24:25], v[32:33], v[30:31]
	v_pk_add_f32 v[26:27], v[32:33], v[30:31] neg_lo:[0,1] neg_hi:[0,1]
	ds_write_b128 v23, v[24:27] offset:8704
	v_add_u32_e32 v23, 0x4400, v23
	s_cbranch_scc1 .LBB0_436
; #define LAS __attribute__((address_space(3)))
; __device__ __forceinline__ f32x2 cmul(f32x2 a, f32x2 b) { return (f32x2){a.x * b.x - a.y * b.y, a.x * b.y + a.y * b.x}; }
; template <bool INV, int ST> __device__ __forceinline__ void fft_pass16(LAS f32x2* buf, int base, int bl) {
;     constexpr float C16[8] = {1.f, 0.92387953251f, 0.70710678119f, 0.38268343237f, 0.f, -0.38268343237f, -0.70710678119f, -0.92387953251f};
;     constexpr float S16[8] = {0.f, 0.38268343237f, 0.70710678119f, 0.92387953251f, 1.f, 0.92387953251f, 0.70710678119f, 0.38268343237f};
;     f32x2 x[16];
;     constexpr int STEP = (1 << ST) + ((1 << ST) >> 4);
;     LAS f32x2* pb = buf + PADI(base);
; #pragma unroll
;     for (int d = 0; d < 16; ++d) x[d] = pb[d * STEP];
;     const float th = (float)bl * (1.f / (float)(16 << ST));
;     const f32x2 W1 = {__builtin_amdgcn_cosf(th), -__builtin_amdgcn_sinf(th)};
;     const f32x2 W2 = cmul(W1, W1), W4 = cmul(W2, W2), W8 = cmul(W4, W4);
;     if (!INV) {
; #pragma unroll
;         for (int d = 0; d < 8; ++d) { const f32x2 w = cmul(W1, (f32x2){C16[d], -S16[d]}); const f32x2 a = x[d], b = x[d + 8]; x[d] = a + b; x[d + 8] = cmul(a - b, w); }
; #pragma unroll
;         for (int g = 0; g < 16; g += 8)
; #pragma unroll
;             for (int dd = 0; dd < 4; ++dd) { const int d = g + dd; const f32x2 w = cmul(W2, (f32x2){C16[2 * dd], -S16[2 * dd]}); const f32x2 a = x[d], b = x[d + 4]; x[d] = a + b; x[d + 4] = cmul(a - b, w); }
; #pragma unroll
;         for (int g = 0; g < 16; g += 4)
; #pragma unroll
;             for (int dd = 0; dd < 2; ++dd) { const int d = g + dd; const f32x2 w = dd ? (f32x2){W4.y, -W4.x} : W4; const f32x2 a = x[d], b = x[d + 2]; x[d] = a + b; x[d + 2] = cmul(a - b, w); }
; #pragma unroll
;         for (int g = 0; g < 16; g += 2) { const f32x2 a = x[g], b = x[g + 1]; x[g] = a + b; x[g + 1] = cmul(a - b, W8); }
;     } else {
; #pragma unroll
;         for (int g = 0; g < 16; g += 2) { const f32x2 a = x[g], b = cmulc(x[g + 1], W8); x[g] = a + b; x[g + 1] = a - b; }
; #pragma unroll
;         for (int g = 0; g < 16; g += 4)
; #pragma unroll
;             for (int dd = 0; dd < 2; ++dd) { const int d = g + dd; const f32x2 w = dd ? (f32x2){W4.y, -W4.x} : W4; const f32x2 a = x[d], b = cmulc(x[d + 2], w); x[d] = a + b; x[d + 2] = a - b; }
	v_mov_b32_e32 v2, v0
	s_waitcnt lgkmcnt(0)
	s_barrier
	s_mov_b32 s10, 0x3f3504f3
	v_bfe_i32 v21, v2, 0, 28
	v_lshlrev_b32_e32 v24, 7, v2
	v_and_b32_e32 v20, 1, v2
	v_and_b32_e32 v24, 0xffffff00, v24
	v_lshlrev_b32_e32 v21, 3, v21
	v_add_u32_e32 v24, 0, v24
	v_lshlrev_b32_e32 v25, 3, v20
	v_and_b32_e32 v21, -16, v21
	v_cvt_f32_ubyte0_e32 v20, v20
	v_add3_u32 v74, v24, v25, v21
	v_mul_f32_e32 v21, 0x3d000000, v20
	v_cos_f32_e32 v20, v21
	v_sin_f32_e32 v21, v21
	ds_read2_b64 v[24:27], v74 offset1:2
	ds_read2_b64 v[28:31], v74 offset0:4 offset1:6
	ds_read2_b64 v[32:35], v74 offset0:8 offset1:10
	ds_read2_b64 v[36:39], v74 offset0:12 offset1:14
	ds_read2_b64 v[40:43], v74 offset0:16 offset1:18
	ds_read2_b64 v[44:47], v74 offset0:20 offset1:22
	ds_read2_b64 v[48:51], v74 offset0:24 offset1:26
	ds_read2_b64 v[52:55], v74 offset0:28 offset1:30
	s_mov_b32 s11, 0xbf3504f3
	v_mov_b32_e32 v57, v20
	v_xor_b32_e32 v56, 0x80000000, v21
	v_mov_b32_e32 v58, v56
	v_mov_b32_e32 v59, v21
	v_pk_mul_f32 v[58:59], v[20:21], v[58:59]
	v_readlane_b32 s8, v251, 1
	v_pk_fma_f32 v[60:61], v[20:21], v[56:57], v[58:59] op_sel_hi:[0,1,1]
	v_pk_fma_f32 v[56:57], v[20:21], v[56:57], v[58:59] op_sel_hi:[0,1,1] neg_lo:[0,0,1] neg_hi:[0,0,1]
	v_mov_b32_e32 v61, v57
	v_pk_mul_f32 v[58:59], v[60:61], v[60:61]
	v_pk_mul_f32 v[62:63], v[56:57], v[60:61] op_sel:[1,0] op_sel_hi:[0,1]
	v_pk_mov_b32 v[64:65], v[58:59], v[62:63] op_sel:[1,0]
	v_mov_b32_e32 v59, v62
	v_pk_add_f32 v[62:63], v[64:65], v[58:59] neg_lo:[0,1] neg_hi:[0,1]
	v_pk_add_f32 v[58:59], v[64:65], v[58:59]
	v_mov_b32_e32 v64, v62
	v_mov_b32_e32 v65, v59
	v_mul_f32_e32 v56, v62, v59
	v_pk_mul_f32 v[64:65], v[64:65], v[64:65]
	v_add_f32_e32 v56, v56, v56
	v_pk_add_f32 v[64:65], v[64:65], v[64:65] op_sel:[0,1] op_sel_hi:[0,1] neg_lo:[0,1] neg_hi:[0,1]
	s_waitcnt lgkmcnt(7)
	v_pk_mul_f32 v[66:67], v[26:27], v[56:57] op_sel_hi:[1,0]
	v_readlane_b32 s9, v251, 2
	v_pk_fma_f32 v[68:69], v[26:27], v[64:65], v[66:67] op_sel:[0,0,1] op_sel_hi:[1,1,0]
	v_pk_fma_f32 v[26:27], v[26:27], v[64:65], v[66:67] op_sel:[0,0,1] op_sel_hi:[1,1,0] neg_lo:[0,0,1] neg_hi:[0,0,1]
	s_waitcnt lgkmcnt(6)
	v_pk_mul_f32 v[66:67], v[30:31], v[56:57] op_sel_hi:[1,0]
	v_mov_b32_e32 v69, v27
	v_pk_add_f32 v[26:27], v[24:25], v[68:69]
	v_pk_add_f32 v[24:25], v[24:25], v[68:69] neg_lo:[0,1] neg_hi:[0,1]
	v_pk_fma_f32 v[68:69], v[30:31], v[64:65], v[66:67] op_sel:[0,0,1] op_sel_hi:[1,1,0]
	v_pk_fma_f32 v[30:31], v[30:31], v[64:65], v[66:67] op_sel:[0,0,1] op_sel_hi:[1,1,0] neg_lo:[0,0,1] neg_hi:[0,0,1]
	s_waitcnt lgkmcnt(5)
	v_pk_mul_f32 v[66:67], v[34:35], v[56:57] op_sel_hi:[1,0]
	v_mov_b32_e32 v69, v31
	v_pk_add_f32 v[30:31], v[28:29], v[68:69]
	v_pk_add_f32 v[28:29], v[28:29], v[68:69] neg_lo:[0,1] neg_hi:[0,1]
	v_pk_fma_f32 v[68:69], v[34:35], v[64:65], v[66:67] op_sel:[0,0,1] op_sel_hi:[1,1,0]
	v_pk_fma_f32 v[34:35], v[34:35], v[64:65], v[66:67] op_sel:[0,0,1] op_sel_hi:[1,1,0] neg_lo:[0,0,1] neg_hi:[0,0,1]
	s_waitcnt lgkmcnt(4)
	v_pk_mul_f32 v[66:67], v[38:39], v[56:57] op_sel_hi:[1,0]
	v_mov_b32_e32 v69, v35
	v_pk_add_f32 v[34:35], v[32:33], v[68:69]
	v_pk_add_f32 v[32:33], v[32:33], v[68:69] neg_lo:[0,1] neg_hi:[0,1]
	v_pk_fma_f32 v[68:69], v[38:39], v[64:65], v[66:67] op_sel:[0,0,1] op_sel_hi:[1,1,0]
	v_pk_fma_f32 v[38:39], v[38:39], v[64:65], v[66:67] op_sel:[0,0,1] op_sel_hi:[1,1,0] neg_lo:[0,0,1] neg_hi:[0,0,1]
	s_waitcnt lgkmcnt(3)
	v_pk_mul_f32 v[66:67], v[56:57], v[42:43] op_sel_hi:[0,1]
	v_mov_b32_e32 v69, v39
	v_pk_add_f32 v[38:39], v[36:37], v[68:69]
	v_pk_add_f32 v[36:37], v[36:37], v[68:69] neg_lo:[0,1] neg_hi:[0,1]
	v_pk_fma_f32 v[68:69], v[64:65], v[42:43], v[66:67] op_sel:[0,0,1] op_sel_hi:[1,1,0]
	v_pk_fma_f32 v[42:43], v[64:65], v[42:43], v[66:67] op_sel:[0,0,1] op_sel_hi:[1,1,0] neg_lo:[0,0,1] neg_hi:[0,0,1]
	s_waitcnt lgkmcnt(2)
	v_pk_mul_f32 v[66:67], v[56:57], v[46:47] op_sel_hi:[0,1]
	v_mov_b32_e32 v69, v43
	v_pk_add_f32 v[42:43], v[40:41], v[68:69]
	v_pk_add_f32 v[40:41], v[40:41], v[68:69] neg_lo:[0,1] neg_hi:[0,1]
	v_pk_fma_f32 v[68:69], v[64:65], v[46:47], v[66:67] op_sel:[0,0,1] op_sel_hi:[1,1,0]
	v_pk_fma_f32 v[46:47], v[64:65], v[46:47], v[66:67] op_sel:[0,0,1] op_sel_hi:[1,1,0] neg_lo:[0,0,1] neg_hi:[0,0,1]
	s_waitcnt lgkmcnt(1)
	v_pk_mul_f32 v[66:67], v[56:57], v[50:51] op_sel_hi:[0,1]
	v_mov_b32_e32 v69, v47
	v_pk_add_f32 v[46:47], v[44:45], v[68:69]
	v_pk_add_f32 v[44:45], v[44:45], v[68:69] neg_lo:[0,1] neg_hi:[0,1]
	v_pk_fma_f32 v[68:69], v[64:65], v[50:51], v[66:67] op_sel:[0,0,1] op_sel_hi:[1,1,0]
	v_pk_fma_f32 v[50:51], v[64:65], v[50:51], v[66:67] op_sel:[0,0,1] op_sel_hi:[1,1,0] neg_lo:[0,0,1] neg_hi:[0,0,1]
	s_waitcnt lgkmcnt(0)
; __device__ __forceinline__ f32x2 cmul(f32x2 a, f32x2 b) { return (f32x2){a.x * b.x - a.y * b.y, a.x * b.y + a.y * b.x}; }
; __device__ __forceinline__ f32x2 cmulc(f32x2 a, f32x2 b) { return (f32x2){a.x * b.x + a.y * b.y, a.y * b.x - a.x * b.y}; }
; template <bool INV, int ST> __device__ __forceinline__ void fft_pass16(LAS f32x2* buf, int base, int bl) {
;     ...
;         for (int g = 0; g < 16; g += 2) { const f32x2 a = x[g], b = cmulc(x[g + 1], W8); x[g] = a + b; x[g + 1] = a - b; }
; #pragma unroll
;         for (int g = 0; g < 16; g += 4)
; #pragma unroll
;             for (int dd = 0; dd < 2; ++dd) { const int d = g + dd; const f32x2 w = dd ? (f32x2){W4.y, -W4.x} : W4; const f32x2 a = x[d], b = cmulc(x[d + 2], w); x[d] = a + b; x[d + 2] = a - b; }
; #pragma unroll
;         for (int g = 0; g < 16; g += 8)
; #pragma unroll
;             for (int dd = 0; dd < 4; ++dd) { const int d = g + dd; const f32x2 w = cmul(W2, (f32x2){C16[2 * dd], -S16[2 * dd]}); const f32x2 a = x[d], b = cmulc(x[d + 4], w); x[d] = a + b; x[d + 4] = a - b; }
	v_pk_mul_f32 v[66:67], v[56:57], v[54:55] op_sel_hi:[0,1]
	v_mov_b32_e32 v69, v51
	v_pk_add_f32 v[50:51], v[48:49], v[68:69]
	v_pk_add_f32 v[48:49], v[48:49], v[68:69] neg_lo:[0,1] neg_hi:[0,1]
	v_pk_fma_f32 v[68:69], v[64:65], v[54:55], v[66:67] op_sel:[0,0,1] op_sel_hi:[1,1,0]
	v_pk_fma_f32 v[54:55], v[64:65], v[54:55], v[66:67] op_sel:[0,0,1] op_sel_hi:[1,1,0] neg_lo:[0,0,1] neg_hi:[0,0,1]
	v_pk_mul_f32 v[64:65], v[58:59], v[30:31] op_sel:[1,0]
	v_mov_b32_e32 v69, v55
	v_pk_fma_f32 v[66:67], v[62:63], v[30:31], v[64:65] op_sel:[0,0,1] op_sel_hi:[1,1,0]
	v_pk_fma_f32 v[30:31], v[62:63], v[30:31], v[64:65] op_sel:[0,0,1] op_sel_hi:[0,1,0] neg_lo:[0,0,1] neg_hi:[0,0,1]
	v_mov_b32_e32 v67, v31
	v_pk_mul_f32 v[64:65], v[62:63], v[28:29] op_sel_hi:[0,1]
	v_pk_add_f32 v[30:31], v[26:27], v[66:67]
	v_pk_add_f32 v[26:27], v[26:27], v[66:67] neg_lo:[0,1] neg_hi:[0,1]
	v_pk_fma_f32 v[66:67], v[58:59], v[28:29], v[64:65] op_sel:[1,0,1] op_sel_hi:[1,1,0] neg_lo:[0,0,1] neg_hi:[0,0,1]
	v_pk_fma_f32 v[28:29], v[58:59], v[28:29], v[64:65] op_sel:[1,0,1] op_sel_hi:[1,1,0]
	v_pk_mul_f32 v[64:65], v[58:59], v[38:39] op_sel:[1,0]
	v_mov_b32_e32 v67, v29
	v_pk_add_f32 v[28:29], v[24:25], v[66:67]
	v_pk_add_f32 v[24:25], v[24:25], v[66:67] neg_lo:[0,1] neg_hi:[0,1]
	v_pk_fma_f32 v[66:67], v[62:63], v[38:39], v[64:65] op_sel:[0,0,1] op_sel_hi:[1,1,0]
	v_pk_fma_f32 v[38:39], v[62:63], v[38:39], v[64:65] op_sel:[0,0,1] op_sel_hi:[0,1,0] neg_lo:[0,0,1] neg_hi:[0,0,1]
	v_mov_b32_e32 v67, v39
	v_pk_mul_f32 v[64:65], v[62:63], v[36:37] op_sel_hi:[0,1]
	v_pk_add_f32 v[38:39], v[34:35], v[66:67]
	v_pk_add_f32 v[34:35], v[34:35], v[66:67] neg_lo:[0,1] neg_hi:[0,1]
	v_pk_fma_f32 v[66:67], v[58:59], v[36:37], v[64:65] op_sel:[1,0,1] op_sel_hi:[1,1,0] neg_lo:[0,0,1] neg_hi:[0,0,1]
	v_pk_fma_f32 v[36:37], v[58:59], v[36:37], v[64:65] op_sel:[1,0,1] op_sel_hi:[1,1,0]
	v_pk_mul_f32 v[64:65], v[58:59], v[46:47] op_sel:[1,0]
	v_mov_b32_e32 v67, v37
	v_pk_add_f32 v[36:37], v[32:33], v[66:67]
	v_pk_add_f32 v[32:33], v[32:33], v[66:67] neg_lo:[0,1] neg_hi:[0,1]
	v_pk_fma_f32 v[66:67], v[62:63], v[46:47], v[64:65] op_sel:[0,0,1] op_sel_hi:[1,1,0]
	v_pk_fma_f32 v[46:47], v[62:63], v[46:47], v[64:65] op_sel:[0,0,1] op_sel_hi:[0,1,0] neg_lo:[0,0,1] neg_hi:[0,0,1]
	v_mov_b32_e32 v67, v47
	v_pk_mul_f32 v[64:65], v[62:63], v[44:45] op_sel_hi:[0,1]
	v_pk_add_f32 v[54:55], v[52:53], v[68:69]
	v_pk_add_f32 v[46:47], v[42:43], v[66:67]
	v_pk_add_f32 v[42:43], v[42:43], v[66:67] neg_lo:[0,1] neg_hi:[0,1]
	v_pk_fma_f32 v[66:67], v[58:59], v[44:45], v[64:65] op_sel:[1,0,1] op_sel_hi:[1,1,0] neg_lo:[0,0,1] neg_hi:[0,0,1]
	v_pk_fma_f32 v[44:45], v[58:59], v[44:45], v[64:65] op_sel:[1,0,1] op_sel_hi:[1,1,0]
	v_pk_add_f32 v[52:53], v[52:53], v[68:69] neg_lo:[0,1] neg_hi:[0,1]
	v_mov_b32_e32 v67, v45
	v_pk_mul_f32 v[64:65], v[58:59], v[54:55] op_sel:[1,0]
	v_pk_add_f32 v[44:45], v[40:41], v[66:67]
	v_pk_add_f32 v[40:41], v[40:41], v[66:67] neg_lo:[0,1] neg_hi:[0,1]
	v_pk_fma_f32 v[66:67], v[62:63], v[54:55], v[64:65] op_sel:[0,0,1] op_sel_hi:[1,1,0]
	v_pk_fma_f32 v[54:55], v[62:63], v[54:55], v[64:65] op_sel:[0,0,1] op_sel_hi:[0,1,0] neg_lo:[0,0,1] neg_hi:[0,0,1]
	v_pk_mul_f32 v[62:63], v[62:63], v[52:53] op_sel_hi:[0,1]
	v_pk_fma_f32 v[64:65], v[58:59], v[52:53], v[62:63] op_sel:[1,0,1] op_sel_hi:[1,1,0] neg_lo:[0,0,1] neg_hi:[0,0,1]
	v_pk_fma_f32 v[52:53], v[58:59], v[52:53], v[62:63] op_sel:[1,0,1] op_sel_hi:[1,1,0]
	v_fmamk_f32 v58, v57, 0x80000000, v60
	v_mov_b32_e32 v65, v53
	v_fma_f32 v56, 0, v60, v57
	v_pk_mul_f32 v[62:63], v[58:59], v[38:39] op_sel_hi:[0,1]
	v_mov_b32_e32 v67, v55
	v_pk_add_f32 v[52:53], v[48:49], v[64:65]
	v_pk_add_f32 v[48:49], v[48:49], v[64:65] neg_lo:[0,1] neg_hi:[0,1]
	v_pk_fma_f32 v[64:65], v[56:57], v[38:39], v[62:63] op_sel:[0,0,1] op_sel_hi:[1,1,0]
	v_pk_fma_f32 v[38:39], v[56:57], v[38:39], v[62:63] op_sel:[0,0,1] op_sel_hi:[0,1,0] neg_lo:[0,0,1] neg_hi:[0,0,1]
	v_pk_mul_f32 v[62:63], v[60:61], s[10:11] op_sel_hi:[1,0]
	v_pk_add_f32 v[54:55], v[50:51], v[66:67]
	v_pk_add_f32 v[50:51], v[50:51], v[66:67] neg_lo:[0,1] neg_hi:[0,1]
	v_mov_b32_e32 v65, v39
	v_pk_add_f32 v[66:67], v[62:63], v[62:63] op_sel:[0,1] op_sel_hi:[0,1] neg_lo:[0,1] neg_hi:[0,1]
	v_pk_add_f32 v[38:39], v[30:31], v[64:65]
	v_pk_add_f32 v[30:31], v[30:31], v[64:65] neg_lo:[0,1] neg_hi:[0,1]
	v_pk_add_f32 v[64:65], v[62:63], v[62:63] op_sel:[1,0] op_sel_hi:[1,0]
	v_pk_mul_f32 v[68:69], v[66:67], v[36:37]
	v_fma_f32 v62, 0, v57, v60
	v_pk_fma_f32 v[70:71], v[64:65], v[36:37], v[68:69] op_sel:[0,0,1] op_sel_hi:[1,1,0]
	v_pk_fma_f32 v[36:37], v[64:65], v[36:37], v[68:69] op_sel:[0,0,1] op_sel_hi:[1,1,0] neg_lo:[0,0,1] neg_hi:[0,0,1]
	v_fma_f32 v68, v60, 0, -v57
	v_mov_b32_e32 v71, v37
	v_pk_add_f32 v[36:37], v[28:29], v[70:71]
	v_pk_add_f32 v[28:29], v[28:29], v[70:71] neg_lo:[0,1] neg_hi:[0,1]
	v_pk_mul_f32 v[70:71], v[68:69], v[34:35] op_sel_hi:[0,1]
	v_pk_fma_f32 v[72:73], v[62:63], v[34:35], v[70:71] op_sel:[0,0,1] op_sel_hi:[1,1,0]
	v_pk_fma_f32 v[34:35], v[62:63], v[34:35], v[70:71] op_sel:[0,0,1] op_sel_hi:[0,1,0] neg_lo:[0,0,1] neg_hi:[0,0,1]
	v_fma_f32 v60, v60, s11, -v63
	v_mov_b32_e32 v73, v35
	v_pk_mul_f32 v[70:71], v[60:61], v[32:33] op_sel_hi:[0,1]
	v_pk_mul_f32 v[58:59], v[58:59], v[54:55] op_sel_hi:[0,1]
	v_pk_add_f32 v[34:35], v[26:27], v[72:73]
	v_pk_add_f32 v[26:27], v[26:27], v[72:73] neg_lo:[0,1] neg_hi:[0,1]
	v_pk_fma_f32 v[72:73], v[66:67], v[32:33], v[70:71] op_sel:[0,0,1] op_sel_hi:[1,1,0]
	v_pk_fma_f32 v[32:33], v[66:67], v[32:33], v[70:71] op_sel:[0,0,1] op_sel_hi:[1,1,0] neg_lo:[0,0,1] neg_hi:[0,0,1]
	v_pk_fma_f32 v[70:71], v[56:57], v[54:55], v[58:59] op_sel:[0,0,1] op_sel_hi:[1,1,0]
; __device__ __forceinline__ f32x2 cmul(f32x2 a, f32x2 b) { return (f32x2){a.x * b.x - a.y * b.y, a.x * b.y + a.y * b.x}; }
; __device__ __forceinline__ f32x2 cmulc(f32x2 a, f32x2 b) { return (f32x2){a.x * b.x + a.y * b.y, a.y * b.x - a.x * b.y}; }
; template <bool INV, int ST> __device__ __forceinline__ void fft_pass16(LAS f32x2* buf, int base, int bl) {
;     ...
;         for (int g = 0; g < 16; g += 8)
; #pragma unroll
;             for (int dd = 0; dd < 4; ++dd) { const int d = g + dd; const f32x2 w = cmul(W2, (f32x2){C16[2 * dd], -S16[2 * dd]}); const f32x2 a = x[d], b = cmulc(x[d + 4], w); x[d] = a + b; x[d + 4] = a - b; }
; #pragma unroll
;         for (int d = 0; d < 8; ++d) { const f32x2 w = cmul(W1, (f32x2){C16[d], -S16[d]}); const f32x2 a = x[d], b = cmulc(x[d + 8], w); x[d] = a + b; x[d + 8] = a - b; }
;     }
; #pragma unroll
;     for (int d = 0; d < 16; ++d) pb[d * STEP] = x[d];
; __device__ __forceinline__ void fft_inv_cba(LAS f32x2* buf, int tid) {
;     ...
;     fft_pass16<true, 1>(buf, ((tid >> 1) << 5) + (tid & 1), tid & 1); __syncthreads();
;     fft_pass16<true, 5>(buf, ((tid >> 5) << 9) + (tid & 31), tid & 31); __syncthreads();
	v_pk_fma_f32 v[54:55], v[56:57], v[54:55], v[58:59] op_sel:[0,0,1] op_sel_hi:[0,1,0] neg_lo:[0,0,1] neg_hi:[0,0,1]
	v_pk_mul_f32 v[56:57], v[66:67], v[52:53]
	v_mov_b32_e32 v71, v55
	v_pk_fma_f32 v[58:59], v[64:65], v[52:53], v[56:57] op_sel:[0,0,1] op_sel_hi:[1,1,0]
	v_pk_fma_f32 v[52:53], v[64:65], v[52:53], v[56:57] op_sel:[0,0,1] op_sel_hi:[1,1,0] neg_lo:[0,0,1] neg_hi:[0,0,1]
	v_pk_mul_f32 v[56:57], v[68:69], v[50:51] op_sel_hi:[0,1]
	v_mov_b32_e32 v59, v53
	v_pk_add_f32 v[52:53], v[44:45], v[58:59]
	v_pk_add_f32 v[44:45], v[44:45], v[58:59] neg_lo:[0,1] neg_hi:[0,1]
	v_pk_fma_f32 v[58:59], v[62:63], v[50:51], v[56:57] op_sel:[0,0,1] op_sel_hi:[1,1,0]
	v_pk_fma_f32 v[50:51], v[62:63], v[50:51], v[56:57] op_sel:[0,0,1] op_sel_hi:[0,1,0] neg_lo:[0,0,1] neg_hi:[0,0,1]
	v_mov_b32_e32 v59, v51
	v_pk_mul_f32 v[56:57], v[60:61], v[48:49] op_sel_hi:[0,1]
	v_pk_add_f32 v[50:51], v[42:43], v[58:59]
	v_pk_add_f32 v[42:43], v[42:43], v[58:59] neg_lo:[0,1] neg_hi:[0,1]
	v_pk_fma_f32 v[58:59], v[66:67], v[48:49], v[56:57] op_sel:[0,0,1] op_sel_hi:[1,1,0]
	v_pk_fma_f32 v[48:49], v[66:67], v[48:49], v[56:57] op_sel:[0,0,1] op_sel_hi:[1,1,0] neg_lo:[0,0,1] neg_hi:[0,0,1]
	v_pk_add_f32 v[54:55], v[46:47], v[70:71]
	v_mov_b32_e32 v59, v49
	v_pk_add_f32 v[48:49], v[40:41], v[58:59]
	v_pk_add_f32 v[40:41], v[40:41], v[58:59] neg_lo:[0,1] neg_hi:[0,1]
	v_fma_f32 v58, v20, s22, -v21
	s_add_u32 s4, s8, s4
	v_fmamk_f32 v56, v21, 0x80000000, v20
	v_pk_mul_f32 v[58:59], v[58:59], v[54:55] op_sel:[0,1] op_sel_hi:[0,0]
	s_mov_b32 s20, 0x3f6c835e
	s_addc_u32 s5, s9, s5
	v_pk_fma_f32 v[60:61], v[56:57], v[54:55], v[58:59]
	v_pk_fma_f32 v[54:55], v[56:57], v[54:55], v[58:59] op_sel_hi:[0,1,1] neg_lo:[0,0,1] neg_hi:[0,0,1]
	v_mov_b32_e32 v56, v21
	v_mov_b32_e32 v57, v20
	s_mov_b32 s8, s11
	s_mov_b32 s9, s10
	s_mov_b32 s21, 0x3ec3ef15
	s_mov_b32 s97, s20
	v_mov_b32_e32 v61, v55
	v_pk_mul_f32 v[58:59], v[56:57], s[8:9]
	v_pk_mul_f32 v[62:63], v[56:57], s[20:21]
	v_pk_mul_f32 v[56:57], v[56:57], s[96:97]
	v_pk_add_f32 v[54:55], v[38:39], v[60:61]
	v_pk_add_f32 v[38:39], v[38:39], v[60:61] neg_lo:[0,1] neg_hi:[0,1]
	v_pk_add_f32 v[60:61], v[58:59], v[58:59] op_sel:[0,1] op_sel_hi:[0,1] neg_lo:[0,1] neg_hi:[0,1]
	v_fma_f32 v58, v21, s2, -v63
	v_pk_add_f32 v[68:69], v[56:57], v[56:57] op_sel:[0,1] op_sel_hi:[0,1] neg_lo:[0,1] neg_hi:[0,1]
	v_pk_add_f32 v[46:47], v[46:47], v[70:71] neg_lo:[0,1] neg_hi:[0,1]
	v_pk_mul_f32 v[64:65], v[58:59], v[52:53] op_sel:[0,1] op_sel_hi:[0,0]
	v_pk_add_f32 v[66:67], v[62:63], v[62:63] op_sel:[1,0] op_sel_hi:[1,0] neg_lo:[0,1] neg_hi:[0,1]
	v_pk_mul_f32 v[68:69], v[68:69], v[48:49] op_sel:[0,1] op_sel_hi:[1,0]
	v_fma_f32 v58, v21, s22, -v20
	v_pk_fma_f32 v[70:71], v[66:67], v[48:49], v[68:69]
	v_pk_fma_f32 v[48:49], v[66:67], v[48:49], v[68:69] neg_lo:[0,0,1] neg_hi:[0,0,1]
	v_fma_f32 v56, v20, 0, -v21
	v_pk_mul_f32 v[66:67], v[58:59], v[46:47] op_sel:[0,1] op_sel_hi:[0,0]
	v_pk_fma_f32 v[68:69], v[56:57], v[46:47], v[66:67]
	v_pk_fma_f32 v[46:47], v[56:57], v[46:47], v[66:67] op_sel_hi:[0,1,1] neg_lo:[0,0,1] neg_hi:[0,0,1]
	v_pk_mul_f32 v[66:67], v[20:21], s[8:9]
	v_pk_mul_f32 v[60:61], v[60:61], v[50:51] op_sel:[0,1] op_sel_hi:[1,0]
	v_mov_b32_e32 v69, v47
	v_sub_f32_e32 v58, v59, v67
	v_pk_add_f32 v[46:47], v[30:31], v[68:69]
	v_pk_add_f32 v[30:31], v[30:31], v[68:69] neg_lo:[0,1] neg_hi:[0,1]
	v_pk_fma_f32 v[68:69], v[58:59], v[50:51], v[60:61] op_sel_hi:[0,1,1]
	v_pk_fma_f32 v[50:51], v[58:59], v[50:51], v[60:61] op_sel_hi:[0,1,1] neg_lo:[0,0,1] neg_hi:[0,0,1]
	v_sub_f32_e32 v58, v67, v59
	s_mov_b32 s3, s21
	v_fma_f32 v56, v20, s96, -v62
	v_pk_add_f32 v[60:61], v[66:67], v[66:67] op_sel:[0,1] op_sel_hi:[0,1] neg_lo:[0,1] neg_hi:[0,1]
	v_pk_mul_f32 v[58:59], v[58:59], v[42:43] op_sel:[0,1] op_sel_hi:[0,0]
	v_pk_mul_f32 v[20:21], v[20:21], s[2:3]
	v_pk_fma_f32 v[66:67], v[60:61], v[42:43], v[58:59]
	v_pk_fma_f32 v[42:43], v[60:61], v[42:43], v[58:59] neg_lo:[0,0,1] neg_hi:[0,0,1]
	v_sub_f32_e32 v58, v57, v21
	v_pk_fma_f32 v[60:61], v[58:59], v[52:53], v[64:65] op_sel_hi:[0,1,1]
	v_pk_fma_f32 v[52:53], v[58:59], v[52:53], v[64:65] op_sel_hi:[0,1,1] neg_lo:[0,0,1] neg_hi:[0,0,1]
	v_sub_f32_e32 v58, v21, v57
	v_mov_b32_e32 v61, v53
	v_pk_mul_f32 v[58:59], v[58:59], v[44:45] op_sel:[0,1] op_sel_hi:[0,0]
	v_pk_add_f32 v[52:53], v[36:37], v[60:61]
	v_pk_add_f32 v[36:37], v[36:37], v[60:61] neg_lo:[0,1] neg_hi:[0,1]
	v_pk_fma_f32 v[60:61], v[56:57], v[44:45], v[58:59]
	v_pk_fma_f32 v[44:45], v[56:57], v[44:45], v[58:59] op_sel_hi:[0,1,1] neg_lo:[0,0,1] neg_hi:[0,0,1]
	v_pk_add_f32 v[56:57], v[62:63], v[62:63] op_sel:[0,1] op_sel_hi:[0,1] neg_lo:[0,1] neg_hi:[0,1]
	v_pk_add_f32 v[20:21], v[20:21], v[20:21] op_sel:[0,1] op_sel_hi:[0,1] neg_lo:[0,1] neg_hi:[0,1]
	v_pk_mul_f32 v[56:57], v[56:57], v[40:41] op_sel:[0,1] op_sel_hi:[1,0]
	v_mov_b32_e32 v73, v33
	v_pk_fma_f32 v[58:59], v[20:21], v[40:41], v[56:57]
	v_pk_fma_f32 v[20:21], v[20:21], v[40:41], v[56:57] neg_lo:[0,0,1] neg_hi:[0,0,1]
	v_pk_add_f32 v[32:33], v[24:25], v[72:73]
	v_pk_add_f32 v[24:25], v[24:25], v[72:73] neg_lo:[0,1] neg_hi:[0,1]
	v_mov_b32_e32 v59, v21
	v_lshlrev_b32_e32 v23, 4, v2
	v_mov_b32_e32 v71, v49
	v_mov_b32_e32 v69, v51
	v_mov_b32_e32 v67, v43
	v_mov_b32_e32 v61, v45
	v_pk_add_f32 v[20:21], v[24:25], v[58:59]
	v_pk_add_f32 v[48:49], v[32:33], v[70:71]
	v_pk_add_f32 v[32:33], v[32:33], v[70:71] neg_lo:[0,1] neg_hi:[0,1]
	v_pk_add_f32 v[50:51], v[34:35], v[68:69]
	v_pk_add_f32 v[34:35], v[34:35], v[68:69] neg_lo:[0,1] neg_hi:[0,1]
	v_pk_add_f32 v[42:43], v[26:27], v[66:67]
	v_pk_add_f32 v[26:27], v[26:27], v[66:67] neg_lo:[0,1] neg_hi:[0,1]
	v_pk_add_f32 v[44:45], v[28:29], v[60:61]
	v_pk_add_f32 v[28:29], v[28:29], v[60:61] neg_lo:[0,1] neg_hi:[0,1]
	v_pk_add_f32 v[24:25], v[24:25], v[58:59] neg_lo:[0,1] neg_hi:[0,1]
	ds_write2_b64 v74, v[54:55], v[52:53] offset1:2
	ds_write2_b64 v74, v[50:51], v[48:49] offset0:4 offset1:6
	ds_write2_b64 v74, v[46:47], v[44:45] offset0:8 offset1:10
	ds_write2_b64 v74, v[42:43], v[20:21] offset0:12 offset1:14
	ds_write2_b64 v74, v[38:39], v[36:37] offset0:16 offset1:18
	ds_write2_b64 v74, v[34:35], v[32:33] offset0:20 offset1:22
	ds_write2_b64 v74, v[30:31], v[28:29] offset0:24 offset1:26
	ds_write2_b64 v74, v[26:27], v[24:25] offset0:28 offset1:30
	v_and_b32_e32 v20, 0xfffffe00, v23
	v_and_b32_e32 v21, 31, v2
	v_lshl_add_u32 v23, v20, 3, 0
	v_lshlrev_b32_e32 v24, 3, v21
	v_ashrrev_i32_e32 v20, 1, v20
	v_add3_u32 v23, v23, v24, v20
	v_cvt_f32_ubyte0_e32 v20, v21
	v_mul_f32_e32 v21, 0x3b000000, v20
	v_cos_f32_e32 v20, v21
	v_sin_f32_e32 v21, v21
	s_waitcnt lgkmcnt(0)
	s_barrier
; #define LAS __attribute__((address_space(3)))
; __device__ __forceinline__ f32x2 cmul(f32x2 a, f32x2 b) { return (f32x2){a.x * b.x - a.y * b.y, a.x * b.y + a.y * b.x}; }
; template <bool INV, int ST> __device__ __forceinline__ void fft_pass16(LAS f32x2* buf, int base, int bl) {
;     constexpr float C16[8] = {1.f, 0.92387953251f, 0.70710678119f, 0.38268343237f, 0.f, -0.38268343237f, -0.70710678119f, -0.92387953251f};
;     constexpr float S16[8] = {0.f, 0.38268343237f, 0.70710678119f, 0.92387953251f, 1.f, 0.92387953251f, 0.70710678119f, 0.38268343237f};
;     f32x2 x[16];
;     constexpr int STEP = (1 << ST) + ((1 << ST) >> 4);
;     LAS f32x2* pb = buf + PADI(base);
; #pragma unroll
;     for (int d = 0; d < 16; ++d) x[d] = pb[d * STEP];
;     const float th = (float)bl * (1.f / (float)(16 << ST));
;     const f32x2 W1 = {__builtin_amdgcn_cosf(th), -__builtin_amdgcn_sinf(th)};
;     const f32x2 W2 = cmul(W1, W1), W4 = cmul(W2, W2), W8 = cmul(W4, W4);
;     if (!INV) {
; #pragma unroll
;         for (int d = 0; d < 8; ++d) { const f32x2 w = cmul(W1, (f32x2){C16[d], -S16[d]}); const f32x2 a = x[d], b = x[d + 8]; x[d] = a + b; x[d + 8] = cmul(a - b, w); }
; #pragma unroll
;         for (int g = 0; g < 16; g += 8)
; #pragma unroll
;             for (int dd = 0; dd < 4; ++dd) { const int d = g + dd; const f32x2 w = cmul(W2, (f32x2){C16[2 * dd], -S16[2 * dd]}); const f32x2 a = x[d], b = x[d + 4]; x[d] = a + b; x[d + 4] = cmul(a - b, w); }
; #pragma unroll
;         for (int g = 0; g < 16; g += 4)
; #pragma unroll
;             for (int dd = 0; dd < 2; ++dd) { const int d = g + dd; const f32x2 w = dd ? (f32x2){W4.y, -W4.x} : W4; const f32x2 a = x[d], b = x[d + 2]; x[d] = a + b; x[d + 2] = cmul(a - b, w); }
; #pragma unroll
;         for (int g = 0; g < 16; g += 2) { const f32x2 a = x[g], b = x[g + 1]; x[g] = a + b; x[g + 1] = cmul(a - b, W8); }
;     } else {
; #pragma unroll
;         for (int g = 0; g < 16; g += 2) { const f32x2 a = x[g], b = cmulc(x[g + 1], W8); x[g] = a + b; x[g + 1] = a - b; }
; #pragma unroll
;         for (int g = 0; g < 16; g += 4)
; #pragma unroll
;             for (int dd = 0; dd < 2; ++dd) { const int d = g + dd; const f32x2 w = dd ? (f32x2){W4.y, -W4.x} : W4; const f32x2 a = x[d], b = cmulc(x[d + 2], w); x[d] = a + b; x[d + 2] = a - b; }
	v_mov_b32_e32 v57, v20
	v_xor_b32_e32 v56, 0x80000000, v21
	v_mov_b32_e32 v58, v56
	v_mov_b32_e32 v59, v21
	v_pk_mul_f32 v[58:59], v[20:21], v[58:59]
	s_nop 0
	v_pk_fma_f32 v[60:61], v[20:21], v[56:57], v[58:59] op_sel_hi:[0,1,1]
	v_pk_fma_f32 v[56:57], v[20:21], v[56:57], v[58:59] op_sel_hi:[0,1,1] neg_lo:[0,0,1] neg_hi:[0,0,1]
	v_mov_b32_e32 v61, v57
	v_pk_mul_f32 v[58:59], v[60:61], v[60:61]
	v_pk_mul_f32 v[62:63], v[56:57], v[60:61] op_sel:[1,0] op_sel_hi:[0,1]
	v_pk_mov_b32 v[64:65], v[58:59], v[62:63] op_sel:[1,0]
	v_mov_b32_e32 v59, v62
	v_pk_add_f32 v[62:63], v[64:65], v[58:59] neg_lo:[0,1] neg_hi:[0,1]
	v_pk_add_f32 v[58:59], v[64:65], v[58:59]
	ds_read2_b64 v[24:27], v23 offset1:34
	ds_read2_b64 v[28:31], v23 offset0:68 offset1:102
	ds_read2_b64 v[32:35], v23 offset0:136 offset1:170
	ds_read2_b64 v[36:39], v23 offset0:204 offset1:238
	v_mov_b32_e32 v64, v62
	v_mov_b32_e32 v65, v59
	v_mul_f32_e32 v56, v62, v59
	v_pk_mul_f32 v[64:65], v[64:65], v[64:65]
	v_add_f32_e32 v56, v56, v56
	v_pk_add_f32 v[64:65], v[64:65], v[64:65] op_sel:[0,1] op_sel_hi:[0,1] neg_lo:[0,1] neg_hi:[0,1]
	s_waitcnt lgkmcnt(3)
	v_pk_mul_f32 v[66:67], v[56:57], v[26:27] op_sel_hi:[0,1]
	v_pk_fma_f32 v[68:69], v[64:65], v[26:27], v[66:67] op_sel:[0,0,1] op_sel_hi:[1,1,0]
	v_pk_fma_f32 v[26:27], v[64:65], v[26:27], v[66:67] op_sel:[0,0,1] op_sel_hi:[1,1,0] neg_lo:[0,0,1] neg_hi:[0,0,1]
	s_waitcnt lgkmcnt(2)
	v_pk_mul_f32 v[66:67], v[56:57], v[30:31] op_sel_hi:[0,1]
	v_mov_b32_e32 v69, v27
	v_pk_add_f32 v[26:27], v[24:25], v[68:69]
	v_pk_add_f32 v[24:25], v[24:25], v[68:69] neg_lo:[0,1] neg_hi:[0,1]
	v_pk_fma_f32 v[68:69], v[64:65], v[30:31], v[66:67] op_sel:[0,0,1] op_sel_hi:[1,1,0]
	v_pk_fma_f32 v[30:31], v[64:65], v[30:31], v[66:67] op_sel:[0,0,1] op_sel_hi:[1,1,0] neg_lo:[0,0,1] neg_hi:[0,0,1]
	s_waitcnt lgkmcnt(1)
	v_pk_mul_f32 v[66:67], v[56:57], v[34:35] op_sel_hi:[0,1]
	v_mov_b32_e32 v69, v31
	v_add_u32_e32 v74, 0x800, v23
	v_pk_add_f32 v[30:31], v[28:29], v[68:69]
	v_pk_add_f32 v[28:29], v[28:29], v[68:69] neg_lo:[0,1] neg_hi:[0,1]
	v_pk_fma_f32 v[68:69], v[64:65], v[34:35], v[66:67] op_sel:[0,0,1] op_sel_hi:[1,1,0]
	v_pk_fma_f32 v[34:35], v[64:65], v[34:35], v[66:67] op_sel:[0,0,1] op_sel_hi:[1,1,0] neg_lo:[0,0,1] neg_hi:[0,0,1]
	ds_read2_b64 v[40:43], v74 offset0:16 offset1:50
	ds_read2_b64 v[44:47], v74 offset0:84 offset1:118
	ds_read2_b64 v[48:51], v74 offset0:152 offset1:186
	ds_read2_b64 v[52:55], v74 offset0:220 offset1:254
	v_mov_b32_e32 v69, v35
	s_waitcnt lgkmcnt(4)
	v_pk_mul_f32 v[66:67], v[56:57], v[38:39] op_sel_hi:[0,1]
	v_pk_add_f32 v[34:35], v[32:33], v[68:69]
	v_pk_add_f32 v[32:33], v[32:33], v[68:69] neg_lo:[0,1] neg_hi:[0,1]
	v_pk_fma_f32 v[68:69], v[64:65], v[38:39], v[66:67] op_sel:[0,0,1] op_sel_hi:[1,1,0]
	v_pk_fma_f32 v[38:39], v[64:65], v[38:39], v[66:67] op_sel:[0,0,1] op_sel_hi:[1,1,0] neg_lo:[0,0,1] neg_hi:[0,0,1]
	s_waitcnt lgkmcnt(3)
	v_pk_mul_f32 v[66:67], v[56:57], v[42:43] op_sel_hi:[0,1]
	v_mov_b32_e32 v69, v39
	v_pk_add_f32 v[38:39], v[36:37], v[68:69]
	v_pk_add_f32 v[36:37], v[36:37], v[68:69] neg_lo:[0,1] neg_hi:[0,1]
	v_pk_fma_f32 v[68:69], v[64:65], v[42:43], v[66:67] op_sel:[0,0,1] op_sel_hi:[1,1,0]
	v_pk_fma_f32 v[42:43], v[64:65], v[42:43], v[66:67] op_sel:[0,0,1] op_sel_hi:[1,1,0] neg_lo:[0,0,1] neg_hi:[0,0,1]
	s_waitcnt lgkmcnt(2)
	v_pk_mul_f32 v[66:67], v[56:57], v[46:47] op_sel_hi:[0,1]
	v_mov_b32_e32 v69, v43
	v_pk_add_f32 v[42:43], v[40:41], v[68:69]
	v_pk_add_f32 v[40:41], v[40:41], v[68:69] neg_lo:[0,1] neg_hi:[0,1]
	v_pk_fma_f32 v[68:69], v[64:65], v[46:47], v[66:67] op_sel:[0,0,1] op_sel_hi:[1,1,0]
	v_pk_fma_f32 v[46:47], v[64:65], v[46:47], v[66:67] op_sel:[0,0,1] op_sel_hi:[1,1,0] neg_lo:[0,0,1] neg_hi:[0,0,1]
	s_waitcnt lgkmcnt(1)
	v_pk_mul_f32 v[66:67], v[56:57], v[50:51] op_sel_hi:[0,1]
	v_mov_b32_e32 v69, v47
	v_pk_add_f32 v[46:47], v[44:45], v[68:69]
	v_pk_add_f32 v[44:45], v[44:45], v[68:69] neg_lo:[0,1] neg_hi:[0,1]
	v_pk_fma_f32 v[68:69], v[64:65], v[50:51], v[66:67] op_sel:[0,0,1] op_sel_hi:[1,1,0]
	v_pk_fma_f32 v[50:51], v[64:65], v[50:51], v[66:67] op_sel:[0,0,1] op_sel_hi:[1,1,0] neg_lo:[0,0,1] neg_hi:[0,0,1]
	s_waitcnt lgkmcnt(0)
	v_pk_mul_f32 v[66:67], v[56:57], v[54:55] op_sel_hi:[0,1]
	v_mov_b32_e32 v69, v51
	v_pk_add_f32 v[50:51], v[48:49], v[68:69]
	v_pk_add_f32 v[48:49], v[48:49], v[68:69] neg_lo:[0,1] neg_hi:[0,1]
	v_pk_fma_f32 v[68:69], v[64:65], v[54:55], v[66:67] op_sel:[0,0,1] op_sel_hi:[1,1,0]
	v_pk_fma_f32 v[54:55], v[64:65], v[54:55], v[66:67] op_sel:[0,0,1] op_sel_hi:[1,1,0] neg_lo:[0,0,1] neg_hi:[0,0,1]
	v_pk_mul_f32 v[64:65], v[58:59], v[30:31] op_sel:[1,0]
	v_mov_b32_e32 v69, v55
	v_pk_fma_f32 v[66:67], v[62:63], v[30:31], v[64:65] op_sel:[0,0,1] op_sel_hi:[1,1,0]
	v_pk_fma_f32 v[30:31], v[62:63], v[30:31], v[64:65] op_sel:[0,0,1] op_sel_hi:[0,1,0] neg_lo:[0,0,1] neg_hi:[0,0,1]
	v_mov_b32_e32 v67, v31
	v_pk_mul_f32 v[64:65], v[62:63], v[28:29] op_sel_hi:[0,1]
	v_pk_add_f32 v[30:31], v[26:27], v[66:67]
	v_pk_add_f32 v[26:27], v[26:27], v[66:67] neg_lo:[0,1] neg_hi:[0,1]
	v_pk_fma_f32 v[66:67], v[58:59], v[28:29], v[64:65] op_sel:[1,0,1] op_sel_hi:[1,1,0] neg_lo:[0,0,1] neg_hi:[0,0,1]
	v_pk_fma_f32 v[28:29], v[58:59], v[28:29], v[64:65] op_sel:[1,0,1] op_sel_hi:[1,1,0]
	v_pk_mul_f32 v[64:65], v[58:59], v[38:39] op_sel:[1,0]
	v_mov_b32_e32 v67, v29
	v_pk_add_f32 v[28:29], v[24:25], v[66:67]
	v_pk_add_f32 v[24:25], v[24:25], v[66:67] neg_lo:[0,1] neg_hi:[0,1]
	v_pk_fma_f32 v[66:67], v[62:63], v[38:39], v[64:65] op_sel:[0,0,1] op_sel_hi:[1,1,0]
	v_pk_fma_f32 v[38:39], v[62:63], v[38:39], v[64:65] op_sel:[0,0,1] op_sel_hi:[0,1,0] neg_lo:[0,0,1] neg_hi:[0,0,1]
; __device__ __forceinline__ f32x2 cmul(f32x2 a, f32x2 b) { return (f32x2){a.x * b.x - a.y * b.y, a.x * b.y + a.y * b.x}; }
; __device__ __forceinline__ f32x2 cmulc(f32x2 a, f32x2 b) { return (f32x2){a.x * b.x + a.y * b.y, a.y * b.x - a.x * b.y}; }
; template <bool INV, int ST> __device__ __forceinline__ void fft_pass16(LAS f32x2* buf, int base, int bl) {
;     ...
;         for (int g = 0; g < 16; g += 4)
; #pragma unroll
;             for (int dd = 0; dd < 2; ++dd) { const int d = g + dd; const f32x2 w = dd ? (f32x2){W4.y, -W4.x} : W4; const f32x2 a = x[d], b = cmulc(x[d + 2], w); x[d] = a + b; x[d + 2] = a - b; }
; #pragma unroll
;         for (int g = 0; g < 16; g += 8)
; #pragma unroll
;             for (int dd = 0; dd < 4; ++dd) { const int d = g + dd; const f32x2 w = cmul(W2, (f32x2){C16[2 * dd], -S16[2 * dd]}); const f32x2 a = x[d], b = cmulc(x[d + 4], w); x[d] = a + b; x[d + 4] = a - b; }
; #pragma unroll
;         for (int d = 0; d < 8; ++d) { const f32x2 w = cmul(W1, (f32x2){C16[d], -S16[d]}); const f32x2 a = x[d], b = cmulc(x[d + 8], w); x[d] = a + b; x[d + 8] = a - b; }
	v_mov_b32_e32 v67, v39
	v_pk_mul_f32 v[64:65], v[62:63], v[36:37] op_sel_hi:[0,1]
	v_pk_add_f32 v[38:39], v[34:35], v[66:67]
	v_pk_add_f32 v[34:35], v[34:35], v[66:67] neg_lo:[0,1] neg_hi:[0,1]
	v_pk_fma_f32 v[66:67], v[58:59], v[36:37], v[64:65] op_sel:[1,0,1] op_sel_hi:[1,1,0] neg_lo:[0,0,1] neg_hi:[0,0,1]
	v_pk_fma_f32 v[36:37], v[58:59], v[36:37], v[64:65] op_sel:[1,0,1] op_sel_hi:[1,1,0]
	v_pk_mul_f32 v[64:65], v[58:59], v[46:47] op_sel:[1,0]
	v_mov_b32_e32 v67, v37
	v_pk_add_f32 v[36:37], v[32:33], v[66:67]
	v_pk_add_f32 v[32:33], v[32:33], v[66:67] neg_lo:[0,1] neg_hi:[0,1]
	v_pk_fma_f32 v[66:67], v[62:63], v[46:47], v[64:65] op_sel:[0,0,1] op_sel_hi:[1,1,0]
	v_pk_fma_f32 v[46:47], v[62:63], v[46:47], v[64:65] op_sel:[0,0,1] op_sel_hi:[0,1,0] neg_lo:[0,0,1] neg_hi:[0,0,1]
	v_mov_b32_e32 v67, v47
	v_pk_mul_f32 v[64:65], v[62:63], v[44:45] op_sel_hi:[0,1]
	v_pk_add_f32 v[54:55], v[52:53], v[68:69]
	v_pk_add_f32 v[46:47], v[42:43], v[66:67]
	v_pk_add_f32 v[42:43], v[42:43], v[66:67] neg_lo:[0,1] neg_hi:[0,1]
	v_pk_fma_f32 v[66:67], v[58:59], v[44:45], v[64:65] op_sel:[1,0,1] op_sel_hi:[1,1,0] neg_lo:[0,0,1] neg_hi:[0,0,1]
	v_pk_fma_f32 v[44:45], v[58:59], v[44:45], v[64:65] op_sel:[1,0,1] op_sel_hi:[1,1,0]
	v_pk_add_f32 v[52:53], v[52:53], v[68:69] neg_lo:[0,1] neg_hi:[0,1]
	v_mov_b32_e32 v67, v45
	v_pk_mul_f32 v[64:65], v[58:59], v[54:55] op_sel:[1,0]
	v_pk_add_f32 v[44:45], v[40:41], v[66:67]
	v_pk_add_f32 v[40:41], v[40:41], v[66:67] neg_lo:[0,1] neg_hi:[0,1]
	v_pk_fma_f32 v[66:67], v[62:63], v[54:55], v[64:65] op_sel:[0,0,1] op_sel_hi:[1,1,0]
	v_pk_fma_f32 v[54:55], v[62:63], v[54:55], v[64:65] op_sel:[0,0,1] op_sel_hi:[0,1,0] neg_lo:[0,0,1] neg_hi:[0,0,1]
	v_pk_mul_f32 v[62:63], v[62:63], v[52:53] op_sel_hi:[0,1]
	v_pk_fma_f32 v[64:65], v[58:59], v[52:53], v[62:63] op_sel:[1,0,1] op_sel_hi:[1,1,0] neg_lo:[0,0,1] neg_hi:[0,0,1]
	v_pk_fma_f32 v[52:53], v[58:59], v[52:53], v[62:63] op_sel:[1,0,1] op_sel_hi:[1,1,0]
	v_fmamk_f32 v58, v57, 0x80000000, v60
	v_mov_b32_e32 v65, v53
	v_fma_f32 v56, 0, v60, v57
	v_pk_mul_f32 v[62:63], v[58:59], v[38:39] op_sel_hi:[0,1]
	v_mov_b32_e32 v67, v55
	v_pk_add_f32 v[52:53], v[48:49], v[64:65]
	v_pk_add_f32 v[48:49], v[48:49], v[64:65] neg_lo:[0,1] neg_hi:[0,1]
	v_pk_fma_f32 v[64:65], v[56:57], v[38:39], v[62:63] op_sel:[0,0,1] op_sel_hi:[1,1,0]
	v_pk_fma_f32 v[38:39], v[56:57], v[38:39], v[62:63] op_sel:[0,0,1] op_sel_hi:[0,1,0] neg_lo:[0,0,1] neg_hi:[0,0,1]
	v_pk_mul_f32 v[62:63], v[60:61], s[10:11] op_sel_hi:[1,0]
	v_pk_add_f32 v[54:55], v[50:51], v[66:67]
	v_pk_add_f32 v[50:51], v[50:51], v[66:67] neg_lo:[0,1] neg_hi:[0,1]
	v_mov_b32_e32 v65, v39
	v_pk_add_f32 v[66:67], v[62:63], v[62:63] op_sel:[0,1] op_sel_hi:[0,1] neg_lo:[0,1] neg_hi:[0,1]
	v_pk_add_f32 v[38:39], v[30:31], v[64:65]
	v_pk_add_f32 v[30:31], v[30:31], v[64:65] neg_lo:[0,1] neg_hi:[0,1]
	v_pk_add_f32 v[64:65], v[62:63], v[62:63] op_sel:[1,0] op_sel_hi:[1,0]
	v_pk_mul_f32 v[68:69], v[66:67], v[36:37]
	v_fma_f32 v62, 0, v57, v60
	v_pk_fma_f32 v[70:71], v[64:65], v[36:37], v[68:69] op_sel:[0,0,1] op_sel_hi:[1,1,0]
	v_pk_fma_f32 v[36:37], v[64:65], v[36:37], v[68:69] op_sel:[0,0,1] op_sel_hi:[1,1,0] neg_lo:[0,0,1] neg_hi:[0,0,1]
	v_fma_f32 v68, v60, 0, -v57
	v_mov_b32_e32 v71, v37
	v_pk_add_f32 v[36:37], v[28:29], v[70:71]
	v_pk_add_f32 v[28:29], v[28:29], v[70:71] neg_lo:[0,1] neg_hi:[0,1]
	v_pk_mul_f32 v[70:71], v[68:69], v[34:35] op_sel_hi:[0,1]
	v_pk_fma_f32 v[72:73], v[62:63], v[34:35], v[70:71] op_sel:[0,0,1] op_sel_hi:[1,1,0]
	v_pk_fma_f32 v[34:35], v[62:63], v[34:35], v[70:71] op_sel:[0,0,1] op_sel_hi:[0,1,0] neg_lo:[0,0,1] neg_hi:[0,0,1]
	v_fma_f32 v60, v60, s11, -v63
	v_mov_b32_e32 v73, v35
	v_pk_mul_f32 v[70:71], v[60:61], v[32:33] op_sel_hi:[0,1]
	v_pk_mul_f32 v[58:59], v[58:59], v[54:55] op_sel_hi:[0,1]
	v_pk_add_f32 v[34:35], v[26:27], v[72:73]
	v_pk_add_f32 v[26:27], v[26:27], v[72:73] neg_lo:[0,1] neg_hi:[0,1]
	v_pk_fma_f32 v[72:73], v[66:67], v[32:33], v[70:71] op_sel:[0,0,1] op_sel_hi:[1,1,0]
	v_pk_fma_f32 v[32:33], v[66:67], v[32:33], v[70:71] op_sel:[0,0,1] op_sel_hi:[1,1,0] neg_lo:[0,0,1] neg_hi:[0,0,1]
	v_pk_fma_f32 v[70:71], v[56:57], v[54:55], v[58:59] op_sel:[0,0,1] op_sel_hi:[1,1,0]
	v_pk_fma_f32 v[54:55], v[56:57], v[54:55], v[58:59] op_sel:[0,0,1] op_sel_hi:[0,1,0] neg_lo:[0,0,1] neg_hi:[0,0,1]
	v_pk_mul_f32 v[56:57], v[66:67], v[52:53]
	v_mov_b32_e32 v71, v55
	v_pk_fma_f32 v[58:59], v[64:65], v[52:53], v[56:57] op_sel:[0,0,1] op_sel_hi:[1,1,0]
	v_pk_fma_f32 v[52:53], v[64:65], v[52:53], v[56:57] op_sel:[0,0,1] op_sel_hi:[1,1,0] neg_lo:[0,0,1] neg_hi:[0,0,1]
	v_pk_mul_f32 v[56:57], v[68:69], v[50:51] op_sel_hi:[0,1]
	v_mov_b32_e32 v59, v53
	v_pk_add_f32 v[52:53], v[44:45], v[58:59]
	v_pk_add_f32 v[44:45], v[44:45], v[58:59] neg_lo:[0,1] neg_hi:[0,1]
	v_pk_fma_f32 v[58:59], v[62:63], v[50:51], v[56:57] op_sel:[0,0,1] op_sel_hi:[1,1,0]
	v_pk_fma_f32 v[50:51], v[62:63], v[50:51], v[56:57] op_sel:[0,0,1] op_sel_hi:[0,1,0] neg_lo:[0,0,1] neg_hi:[0,0,1]
	v_mov_b32_e32 v59, v51
	v_pk_mul_f32 v[56:57], v[60:61], v[48:49] op_sel_hi:[0,1]
	v_pk_add_f32 v[50:51], v[42:43], v[58:59]
	v_pk_add_f32 v[42:43], v[42:43], v[58:59] neg_lo:[0,1] neg_hi:[0,1]
	v_pk_fma_f32 v[58:59], v[66:67], v[48:49], v[56:57] op_sel:[0,0,1] op_sel_hi:[1,1,0]
	v_pk_fma_f32 v[48:49], v[66:67], v[48:49], v[56:57] op_sel:[0,0,1] op_sel_hi:[1,1,0] neg_lo:[0,0,1] neg_hi:[0,0,1]
	v_pk_add_f32 v[54:55], v[46:47], v[70:71]
	v_mov_b32_e32 v59, v49
	v_pk_add_f32 v[48:49], v[40:41], v[58:59]
	v_pk_add_f32 v[40:41], v[40:41], v[58:59] neg_lo:[0,1] neg_hi:[0,1]
	v_fma_f32 v58, v20, s22, -v21
	v_fmamk_f32 v56, v21, 0x80000000, v20
; __device__ __forceinline__ f32x2 cmul(f32x2 a, f32x2 b) { return (f32x2){a.x * b.x - a.y * b.y, a.x * b.y + a.y * b.x}; }
; __device__ __forceinline__ f32x2 cmulc(f32x2 a, f32x2 b) { return (f32x2){a.x * b.x + a.y * b.y, a.y * b.x - a.x * b.y}; }
; template <bool INV, int ST> __device__ __forceinline__ void fft_pass16(LAS f32x2* buf, int base, int bl) {
;     ...
;             for (int dd = 0; dd < 4; ++dd) { const int d = g + dd; const f32x2 w = cmul(W2, (f32x2){C16[2 * dd], -S16[2 * dd]}); const f32x2 a = x[d], b = cmulc(x[d + 4], w); x[d] = a + b; x[d + 4] = a - b; }
; #pragma unroll
;         for (int d = 0; d < 8; ++d) { const f32x2 w = cmul(W1, (f32x2){C16[d], -S16[d]}); const f32x2 a = x[d], b = cmulc(x[d + 8], w); x[d] = a + b; x[d + 8] = a - b; }
;     }
; #pragma unroll
;     for (int d = 0; d < 16; ++d) pb[d * STEP] = x[d];
; __device__ __forceinline__ void fft_inv_cba(LAS f32x2* buf, int tid) {
;     ...
;     fft_pass16<true, 5>(buf, ((tid >> 5) << 9) + (tid & 31), tid & 31); __syncthreads();
;     fft_pass16<true, 9>(buf, tid, tid); __syncthreads();
	v_pk_mul_f32 v[58:59], v[58:59], v[54:55] op_sel:[0,1] op_sel_hi:[0,0]
	v_pk_fma_f32 v[60:61], v[56:57], v[54:55], v[58:59]
	v_pk_fma_f32 v[54:55], v[56:57], v[54:55], v[58:59] op_sel_hi:[0,1,1] neg_lo:[0,0,1] neg_hi:[0,0,1]
	v_mov_b32_e32 v56, v21
	v_mov_b32_e32 v57, v20
	v_mov_b32_e32 v61, v55
	v_pk_mul_f32 v[58:59], v[56:57], s[8:9]
	v_pk_mul_f32 v[62:63], v[56:57], s[20:21]
	v_pk_mul_f32 v[56:57], v[56:57], s[96:97]
	v_pk_add_f32 v[54:55], v[38:39], v[60:61]
	v_pk_add_f32 v[38:39], v[38:39], v[60:61] neg_lo:[0,1] neg_hi:[0,1]
	v_pk_add_f32 v[60:61], v[58:59], v[58:59] op_sel:[0,1] op_sel_hi:[0,1] neg_lo:[0,1] neg_hi:[0,1]
	v_fma_f32 v58, v21, s2, -v63
	v_pk_add_f32 v[68:69], v[56:57], v[56:57] op_sel:[0,1] op_sel_hi:[0,1] neg_lo:[0,1] neg_hi:[0,1]
	v_pk_add_f32 v[46:47], v[46:47], v[70:71] neg_lo:[0,1] neg_hi:[0,1]
	v_pk_mul_f32 v[64:65], v[58:59], v[52:53] op_sel:[0,1] op_sel_hi:[0,0]
	v_pk_add_f32 v[66:67], v[62:63], v[62:63] op_sel:[1,0] op_sel_hi:[1,0] neg_lo:[0,1] neg_hi:[0,1]
	v_pk_mul_f32 v[68:69], v[68:69], v[48:49] op_sel:[0,1] op_sel_hi:[1,0]
	v_fma_f32 v58, v21, s22, -v20
	v_pk_fma_f32 v[70:71], v[66:67], v[48:49], v[68:69]
	v_pk_fma_f32 v[48:49], v[66:67], v[48:49], v[68:69] neg_lo:[0,0,1] neg_hi:[0,0,1]
	v_fma_f32 v56, v20, 0, -v21
	v_pk_mul_f32 v[66:67], v[58:59], v[46:47] op_sel:[0,1] op_sel_hi:[0,0]
	v_pk_fma_f32 v[68:69], v[56:57], v[46:47], v[66:67]
	v_pk_fma_f32 v[46:47], v[56:57], v[46:47], v[66:67] op_sel_hi:[0,1,1] neg_lo:[0,0,1] neg_hi:[0,0,1]
	v_pk_mul_f32 v[66:67], v[20:21], s[8:9]
	v_pk_mul_f32 v[60:61], v[60:61], v[50:51] op_sel:[0,1] op_sel_hi:[1,0]
	v_mov_b32_e32 v69, v47
	v_sub_f32_e32 v58, v59, v67
	v_pk_add_f32 v[46:47], v[30:31], v[68:69]
	v_pk_add_f32 v[30:31], v[30:31], v[68:69] neg_lo:[0,1] neg_hi:[0,1]
	v_pk_fma_f32 v[68:69], v[58:59], v[50:51], v[60:61] op_sel_hi:[0,1,1]
	v_pk_fma_f32 v[50:51], v[58:59], v[50:51], v[60:61] op_sel_hi:[0,1,1] neg_lo:[0,0,1] neg_hi:[0,0,1]
	v_sub_f32_e32 v58, v67, v59
	v_fma_f32 v56, v20, s96, -v62
	v_pk_add_f32 v[60:61], v[66:67], v[66:67] op_sel:[0,1] op_sel_hi:[0,1] neg_lo:[0,1] neg_hi:[0,1]
	v_pk_mul_f32 v[58:59], v[58:59], v[42:43] op_sel:[0,1] op_sel_hi:[0,0]
	v_pk_mul_f32 v[20:21], v[20:21], s[2:3]
	v_pk_fma_f32 v[66:67], v[60:61], v[42:43], v[58:59]
	v_pk_fma_f32 v[42:43], v[60:61], v[42:43], v[58:59] neg_lo:[0,0,1] neg_hi:[0,0,1]
	v_sub_f32_e32 v58, v57, v21
	v_pk_fma_f32 v[60:61], v[58:59], v[52:53], v[64:65] op_sel_hi:[0,1,1]
	v_pk_fma_f32 v[52:53], v[58:59], v[52:53], v[64:65] op_sel_hi:[0,1,1] neg_lo:[0,0,1] neg_hi:[0,0,1]
	v_sub_f32_e32 v58, v21, v57
	v_mov_b32_e32 v61, v53
	v_pk_mul_f32 v[58:59], v[58:59], v[44:45] op_sel:[0,1] op_sel_hi:[0,0]
	v_pk_add_f32 v[52:53], v[36:37], v[60:61]
	v_pk_add_f32 v[36:37], v[36:37], v[60:61] neg_lo:[0,1] neg_hi:[0,1]
	v_pk_fma_f32 v[60:61], v[56:57], v[44:45], v[58:59]
	v_pk_fma_f32 v[44:45], v[56:57], v[44:45], v[58:59] op_sel_hi:[0,1,1] neg_lo:[0,0,1] neg_hi:[0,0,1]
	v_pk_add_f32 v[56:57], v[62:63], v[62:63] op_sel:[0,1] op_sel_hi:[0,1] neg_lo:[0,1] neg_hi:[0,1]
	v_pk_add_f32 v[20:21], v[20:21], v[20:21] op_sel:[0,1] op_sel_hi:[0,1] neg_lo:[0,1] neg_hi:[0,1]
	v_pk_mul_f32 v[56:57], v[56:57], v[40:41] op_sel:[0,1] op_sel_hi:[1,0]
	v_mov_b32_e32 v73, v33
	v_pk_fma_f32 v[58:59], v[20:21], v[40:41], v[56:57]
	v_pk_fma_f32 v[20:21], v[20:21], v[40:41], v[56:57] neg_lo:[0,0,1] neg_hi:[0,0,1]
	v_pk_add_f32 v[32:33], v[24:25], v[72:73]
	v_pk_add_f32 v[24:25], v[24:25], v[72:73] neg_lo:[0,1] neg_hi:[0,1]
	v_mov_b32_e32 v59, v21
	v_mov_b32_e32 v71, v49
	v_mov_b32_e32 v69, v51
	v_mov_b32_e32 v67, v43
	v_mov_b32_e32 v61, v45
	v_pk_add_f32 v[20:21], v[24:25], v[58:59]
	v_pk_add_f32 v[48:49], v[32:33], v[70:71]
	v_pk_add_f32 v[32:33], v[32:33], v[70:71] neg_lo:[0,1] neg_hi:[0,1]
	v_pk_add_f32 v[50:51], v[34:35], v[68:69]
	v_pk_add_f32 v[34:35], v[34:35], v[68:69] neg_lo:[0,1] neg_hi:[0,1]
	v_pk_add_f32 v[42:43], v[26:27], v[66:67]
	v_pk_add_f32 v[26:27], v[26:27], v[66:67] neg_lo:[0,1] neg_hi:[0,1]
	v_pk_add_f32 v[44:45], v[28:29], v[60:61]
	v_pk_add_f32 v[28:29], v[28:29], v[60:61] neg_lo:[0,1] neg_hi:[0,1]
	v_pk_add_f32 v[24:25], v[24:25], v[58:59] neg_lo:[0,1] neg_hi:[0,1]
	ds_write2_b64 v23, v[54:55], v[52:53] offset1:34
	ds_write2_b64 v23, v[50:51], v[48:49] offset0:68 offset1:102
	ds_write2_b64 v23, v[46:47], v[44:45] offset0:136 offset1:170
	ds_write2_b64 v23, v[42:43], v[20:21] offset0:204 offset1:238
	ds_write2_b64 v74, v[38:39], v[36:37] offset0:16 offset1:50
	ds_write2_b64 v74, v[34:35], v[32:33] offset0:84 offset1:118
	ds_write2_b64 v74, v[30:31], v[28:29] offset0:152 offset1:186
	ds_write2_b64 v74, v[26:27], v[24:25] offset0:220 offset1:254
	v_ashrrev_i32_e32 v20, 4, v2
	v_lshlrev_b32_e32 v21, 3, v2
	v_cvt_f32_i32_e32 v2, v2
	v_lshlrev_b32_e32 v20, 3, v20
	v_and_b32_e32 v20, -16, v20
	v_add3_u32 v23, 0, v21, v20
	v_mul_f32_e32 v2, 0x39000000, v2
	v_sin_f32_e32 v21, v2
	v_cos_f32_e32 v20, v2
	s_waitcnt lgkmcnt(0)
	s_barrier
; #define LAS __attribute__((address_space(3)))
; __device__ __forceinline__ f32x2 cmul(f32x2 a, f32x2 b) { return (f32x2){a.x * b.x - a.y * b.y, a.x * b.y + a.y * b.x}; }
; template <bool INV, int ST> __device__ __forceinline__ void fft_pass16(LAS f32x2* buf, int base, int bl) {
;     constexpr float C16[8] = {1.f, 0.92387953251f, 0.70710678119f, 0.38268343237f, 0.f, -0.38268343237f, -0.70710678119f, -0.92387953251f};
;     constexpr float S16[8] = {0.f, 0.38268343237f, 0.70710678119f, 0.92387953251f, 1.f, 0.92387953251f, 0.70710678119f, 0.38268343237f};
;     f32x2 x[16];
;     constexpr int STEP = (1 << ST) + ((1 << ST) >> 4);
;     LAS f32x2* pb = buf + PADI(base);
; #pragma unroll
;     for (int d = 0; d < 16; ++d) x[d] = pb[d * STEP];
;     const float th = (float)bl * (1.f / (float)(16 << ST));
;     const f32x2 W1 = {__builtin_amdgcn_cosf(th), -__builtin_amdgcn_sinf(th)};
;     const f32x2 W2 = cmul(W1, W1), W4 = cmul(W2, W2), W8 = cmul(W4, W4);
;     if (!INV) {
; #pragma unroll
;         for (int d = 0; d < 8; ++d) { const f32x2 w = cmul(W1, (f32x2){C16[d], -S16[d]}); const f32x2 a = x[d], b = x[d + 8]; x[d] = a + b; x[d + 8] = cmul(a - b, w); }
; #pragma unroll
;         for (int g = 0; g < 16; g += 8)
; #pragma unroll
;             for (int dd = 0; dd < 4; ++dd) { const int d = g + dd; const f32x2 w = cmul(W2, (f32x2){C16[2 * dd], -S16[2 * dd]}); const f32x2 a = x[d], b = x[d + 4]; x[d] = a + b; x[d + 4] = cmul(a - b, w); }
; #pragma unroll
;         for (int g = 0; g < 16; g += 4)
; #pragma unroll
;             for (int dd = 0; dd < 2; ++dd) { const int d = g + dd; const f32x2 w = dd ? (f32x2){W4.y, -W4.x} : W4; const f32x2 a = x[d], b = x[d + 2]; x[d] = a + b; x[d + 2] = cmul(a - b, w); }
; #pragma unroll
;         for (int g = 0; g < 16; g += 2) { const f32x2 a = x[g], b = x[g + 1]; x[g] = a + b; x[g + 1] = cmul(a - b, W8); }
;     } else {
; #pragma unroll
;         for (int g = 0; g < 16; g += 2) { const f32x2 a = x[g], b = cmulc(x[g + 1], W8); x[g] = a + b; x[g + 1] = a - b; }
; #pragma unroll
;         for (int g = 0; g < 16; g += 4)
; #pragma unroll
;             for (int dd = 0; dd < 2; ++dd) { const int d = g + dd; const f32x2 w = dd ? (f32x2){W4.y, -W4.x} : W4; const f32x2 a = x[d], b = cmulc(x[d + 2], w); x[d] = a + b; x[d + 2] = a - b; }
	v_xor_b32_e32 v56, 0x80000000, v21
	v_mov_b32_e32 v58, v56
	v_mov_b32_e32 v59, v21
	v_mov_b32_e32 v57, v20
	v_pk_mul_f32 v[58:59], v[20:21], v[58:59]
	s_nop 0
	v_pk_fma_f32 v[60:61], v[20:21], v[56:57], v[58:59] op_sel_hi:[0,1,1]
	v_pk_fma_f32 v[56:57], v[20:21], v[56:57], v[58:59] op_sel_hi:[0,1,1] neg_lo:[0,0,1] neg_hi:[0,0,1]
	v_mov_b32_e32 v61, v57
	v_pk_mul_f32 v[58:59], v[60:61], v[60:61]
	v_pk_mul_f32 v[62:63], v[56:57], v[60:61] op_sel:[1,0] op_sel_hi:[0,1]
	v_pk_mov_b32 v[64:65], v[58:59], v[62:63] op_sel:[1,0]
	v_mov_b32_e32 v59, v62
	v_pk_add_f32 v[62:63], v[64:65], v[58:59] neg_lo:[0,1] neg_hi:[0,1]
	v_pk_add_f32 v[58:59], v[64:65], v[58:59]
	v_mov_b32_e32 v64, v62
	v_mov_b32_e32 v65, v59
	v_mul_f32_e32 v2, v62, v59
	v_pk_mul_f32 v[64:65], v[64:65], v[64:65]
	v_add_f32_e32 v2, v2, v2
	ds_read_b64 v[24:25], v23
	ds_read_b64 v[26:27], v23 offset:4352
	ds_read_b64 v[28:29], v23 offset:8704
	ds_read_b64 v[30:31], v23 offset:13056
	ds_read_b64 v[32:33], v23 offset:17408
	ds_read_b64 v[34:35], v23 offset:21760
	ds_read_b64 v[36:37], v23 offset:26112
	ds_read_b64 v[38:39], v23 offset:30464
	ds_read_b64 v[40:41], v23 offset:34816
	ds_read_b64 v[42:43], v23 offset:39168
	ds_read_b64 v[44:45], v23 offset:43520
	ds_read_b64 v[46:47], v23 offset:47872
	ds_read_b64 v[48:49], v23 offset:52224
	ds_read_b64 v[50:51], v23 offset:56576
	ds_read_b64 v[52:53], v23 offset:60928
	ds_read_b64 v[54:55], v23 offset:65280
	v_pk_add_f32 v[64:65], v[64:65], v[64:65] op_sel:[0,1] op_sel_hi:[0,1] neg_lo:[0,1] neg_hi:[0,1]
	s_waitcnt lgkmcnt(14)
	v_pk_mul_f32 v[66:67], v[2:3], v[26:27] op_sel_hi:[0,1]
	v_pk_fma_f32 v[68:69], v[64:65], v[26:27], v[66:67] op_sel:[0,0,1] op_sel_hi:[1,1,0]
	v_pk_fma_f32 v[26:27], v[64:65], v[26:27], v[66:67] op_sel:[0,0,1] op_sel_hi:[1,1,0] neg_lo:[0,0,1] neg_hi:[0,0,1]
	s_waitcnt lgkmcnt(12)
	v_pk_mul_f32 v[66:67], v[2:3], v[30:31] op_sel_hi:[0,1]
	v_mov_b32_e32 v69, v27
	v_pk_add_f32 v[26:27], v[24:25], v[68:69]
	v_pk_add_f32 v[24:25], v[24:25], v[68:69] neg_lo:[0,1] neg_hi:[0,1]
	v_pk_fma_f32 v[68:69], v[64:65], v[30:31], v[66:67] op_sel:[0,0,1] op_sel_hi:[1,1,0]
	v_pk_fma_f32 v[30:31], v[64:65], v[30:31], v[66:67] op_sel:[0,0,1] op_sel_hi:[1,1,0] neg_lo:[0,0,1] neg_hi:[0,0,1]
	s_waitcnt lgkmcnt(10)
	v_pk_mul_f32 v[66:67], v[2:3], v[34:35] op_sel_hi:[0,1]
	v_mov_b32_e32 v69, v31
	v_pk_add_f32 v[30:31], v[28:29], v[68:69]
	v_pk_add_f32 v[28:29], v[28:29], v[68:69] neg_lo:[0,1] neg_hi:[0,1]
	v_pk_fma_f32 v[68:69], v[64:65], v[34:35], v[66:67] op_sel:[0,0,1] op_sel_hi:[1,1,0]
	v_pk_fma_f32 v[34:35], v[64:65], v[34:35], v[66:67] op_sel:[0,0,1] op_sel_hi:[1,1,0] neg_lo:[0,0,1] neg_hi:[0,0,1]
	s_waitcnt lgkmcnt(8)
	v_pk_mul_f32 v[66:67], v[2:3], v[38:39] op_sel_hi:[0,1]
	v_mov_b32_e32 v69, v35
	v_pk_add_f32 v[34:35], v[32:33], v[68:69]
	v_pk_add_f32 v[32:33], v[32:33], v[68:69] neg_lo:[0,1] neg_hi:[0,1]
	v_pk_fma_f32 v[68:69], v[64:65], v[38:39], v[66:67] op_sel:[0,0,1] op_sel_hi:[1,1,0]
	v_pk_fma_f32 v[38:39], v[64:65], v[38:39], v[66:67] op_sel:[0,0,1] op_sel_hi:[1,1,0] neg_lo:[0,0,1] neg_hi:[0,0,1]
	s_waitcnt lgkmcnt(6)
	v_pk_mul_f32 v[66:67], v[2:3], v[42:43] op_sel_hi:[0,1]
	v_mov_b32_e32 v69, v39
	v_pk_add_f32 v[38:39], v[36:37], v[68:69]
	v_pk_add_f32 v[36:37], v[36:37], v[68:69] neg_lo:[0,1] neg_hi:[0,1]
	v_pk_fma_f32 v[68:69], v[64:65], v[42:43], v[66:67] op_sel:[0,0,1] op_sel_hi:[1,1,0]
	v_pk_fma_f32 v[42:43], v[64:65], v[42:43], v[66:67] op_sel:[0,0,1] op_sel_hi:[1,1,0] neg_lo:[0,0,1] neg_hi:[0,0,1]
	s_waitcnt lgkmcnt(4)
	v_pk_mul_f32 v[66:67], v[2:3], v[46:47] op_sel_hi:[0,1]
	v_mov_b32_e32 v69, v43
	v_pk_add_f32 v[42:43], v[40:41], v[68:69]
	v_pk_add_f32 v[40:41], v[40:41], v[68:69] neg_lo:[0,1] neg_hi:[0,1]
	v_pk_fma_f32 v[68:69], v[64:65], v[46:47], v[66:67] op_sel:[0,0,1] op_sel_hi:[1,1,0]
	v_pk_fma_f32 v[46:47], v[64:65], v[46:47], v[66:67] op_sel:[0,0,1] op_sel_hi:[1,1,0] neg_lo:[0,0,1] neg_hi:[0,0,1]
	s_waitcnt lgkmcnt(2)
	v_pk_mul_f32 v[66:67], v[2:3], v[50:51] op_sel_hi:[0,1]
	v_mov_b32_e32 v69, v47
	v_pk_add_f32 v[46:47], v[44:45], v[68:69]
	v_pk_add_f32 v[44:45], v[44:45], v[68:69] neg_lo:[0,1] neg_hi:[0,1]
	v_pk_fma_f32 v[68:69], v[64:65], v[50:51], v[66:67] op_sel:[0,0,1] op_sel_hi:[1,1,0]
	v_pk_fma_f32 v[50:51], v[64:65], v[50:51], v[66:67] op_sel:[0,0,1] op_sel_hi:[1,1,0] neg_lo:[0,0,1] neg_hi:[0,0,1]
	s_waitcnt lgkmcnt(0)
; __device__ __forceinline__ f32x2 cmul(f32x2 a, f32x2 b) { return (f32x2){a.x * b.x - a.y * b.y, a.x * b.y + a.y * b.x}; }
; __device__ __forceinline__ f32x2 cmulc(f32x2 a, f32x2 b) { return (f32x2){a.x * b.x + a.y * b.y, a.y * b.x - a.x * b.y}; }
; template <bool INV, int ST> __device__ __forceinline__ void fft_pass16(LAS f32x2* buf, int base, int bl) {
;     ...
;         for (int g = 0; g < 16; g += 2) { const f32x2 a = x[g], b = cmulc(x[g + 1], W8); x[g] = a + b; x[g + 1] = a - b; }
; #pragma unroll
;         for (int g = 0; g < 16; g += 4)
; #pragma unroll
;             for (int dd = 0; dd < 2; ++dd) { const int d = g + dd; const f32x2 w = dd ? (f32x2){W4.y, -W4.x} : W4; const f32x2 a = x[d], b = cmulc(x[d + 2], w); x[d] = a + b; x[d + 2] = a - b; }
; #pragma unroll
;         for (int g = 0; g < 16; g += 8)
; #pragma unroll
;             for (int dd = 0; dd < 4; ++dd) { const int d = g + dd; const f32x2 w = cmul(W2, (f32x2){C16[2 * dd], -S16[2 * dd]}); const f32x2 a = x[d], b = cmulc(x[d + 4], w); x[d] = a + b; x[d + 4] = a - b; }
	v_pk_mul_f32 v[66:67], v[2:3], v[54:55] op_sel_hi:[0,1]
	v_mov_b32_e32 v69, v51
	v_pk_add_f32 v[50:51], v[48:49], v[68:69]
	v_pk_add_f32 v[48:49], v[48:49], v[68:69] neg_lo:[0,1] neg_hi:[0,1]
	v_pk_fma_f32 v[68:69], v[64:65], v[54:55], v[66:67] op_sel:[0,0,1] op_sel_hi:[1,1,0]
	v_pk_fma_f32 v[54:55], v[64:65], v[54:55], v[66:67] op_sel:[0,0,1] op_sel_hi:[1,1,0] neg_lo:[0,0,1] neg_hi:[0,0,1]
	v_pk_mul_f32 v[64:65], v[58:59], v[30:31] op_sel:[1,0]
	v_mov_b32_e32 v69, v55
	v_pk_fma_f32 v[66:67], v[62:63], v[30:31], v[64:65] op_sel:[0,0,1] op_sel_hi:[1,1,0]
	v_pk_fma_f32 v[30:31], v[62:63], v[30:31], v[64:65] op_sel:[0,0,1] op_sel_hi:[0,1,0] neg_lo:[0,0,1] neg_hi:[0,0,1]
	v_mov_b32_e32 v67, v31
	v_pk_mul_f32 v[64:65], v[62:63], v[28:29] op_sel_hi:[0,1]
	v_pk_add_f32 v[30:31], v[26:27], v[66:67]
	v_pk_add_f32 v[26:27], v[26:27], v[66:67] neg_lo:[0,1] neg_hi:[0,1]
	v_pk_fma_f32 v[66:67], v[58:59], v[28:29], v[64:65] op_sel:[1,0,1] op_sel_hi:[1,1,0] neg_lo:[0,0,1] neg_hi:[0,0,1]
	v_pk_fma_f32 v[28:29], v[58:59], v[28:29], v[64:65] op_sel:[1,0,1] op_sel_hi:[1,1,0]
	v_pk_mul_f32 v[64:65], v[58:59], v[38:39] op_sel:[1,0]
	v_mov_b32_e32 v67, v29
	v_pk_add_f32 v[28:29], v[24:25], v[66:67]
	v_pk_add_f32 v[24:25], v[24:25], v[66:67] neg_lo:[0,1] neg_hi:[0,1]
	v_pk_fma_f32 v[66:67], v[62:63], v[38:39], v[64:65] op_sel:[0,0,1] op_sel_hi:[1,1,0]
	v_pk_fma_f32 v[38:39], v[62:63], v[38:39], v[64:65] op_sel:[0,0,1] op_sel_hi:[0,1,0] neg_lo:[0,0,1] neg_hi:[0,0,1]
	v_mov_b32_e32 v67, v39
	v_pk_mul_f32 v[64:65], v[62:63], v[36:37] op_sel_hi:[0,1]
	v_pk_add_f32 v[38:39], v[34:35], v[66:67]
	v_pk_add_f32 v[34:35], v[34:35], v[66:67] neg_lo:[0,1] neg_hi:[0,1]
	v_pk_fma_f32 v[66:67], v[58:59], v[36:37], v[64:65] op_sel:[1,0,1] op_sel_hi:[1,1,0] neg_lo:[0,0,1] neg_hi:[0,0,1]
	v_pk_fma_f32 v[36:37], v[58:59], v[36:37], v[64:65] op_sel:[1,0,1] op_sel_hi:[1,1,0]
	v_pk_mul_f32 v[64:65], v[58:59], v[46:47] op_sel:[1,0]
	v_mov_b32_e32 v67, v37
	v_pk_add_f32 v[36:37], v[32:33], v[66:67]
	v_pk_add_f32 v[32:33], v[32:33], v[66:67] neg_lo:[0,1] neg_hi:[0,1]
	v_pk_fma_f32 v[66:67], v[62:63], v[46:47], v[64:65] op_sel:[0,0,1] op_sel_hi:[1,1,0]
	v_pk_fma_f32 v[46:47], v[62:63], v[46:47], v[64:65] op_sel:[0,0,1] op_sel_hi:[0,1,0] neg_lo:[0,0,1] neg_hi:[0,0,1]
	v_mov_b32_e32 v67, v47
	v_pk_mul_f32 v[64:65], v[62:63], v[44:45] op_sel_hi:[0,1]
	v_pk_add_f32 v[54:55], v[52:53], v[68:69]
	v_pk_add_f32 v[46:47], v[42:43], v[66:67]
	v_pk_add_f32 v[42:43], v[42:43], v[66:67] neg_lo:[0,1] neg_hi:[0,1]
	v_pk_fma_f32 v[66:67], v[58:59], v[44:45], v[64:65] op_sel:[1,0,1] op_sel_hi:[1,1,0] neg_lo:[0,0,1] neg_hi:[0,0,1]
	v_pk_fma_f32 v[44:45], v[58:59], v[44:45], v[64:65] op_sel:[1,0,1] op_sel_hi:[1,1,0]
	v_pk_add_f32 v[52:53], v[52:53], v[68:69] neg_lo:[0,1] neg_hi:[0,1]
	v_mov_b32_e32 v67, v45
	v_pk_mul_f32 v[64:65], v[58:59], v[54:55] op_sel:[1,0]
	v_pk_add_f32 v[44:45], v[40:41], v[66:67]
	v_pk_add_f32 v[40:41], v[40:41], v[66:67] neg_lo:[0,1] neg_hi:[0,1]
	v_pk_fma_f32 v[66:67], v[62:63], v[54:55], v[64:65] op_sel:[0,0,1] op_sel_hi:[1,1,0]
	v_pk_fma_f32 v[54:55], v[62:63], v[54:55], v[64:65] op_sel:[0,0,1] op_sel_hi:[0,1,0] neg_lo:[0,0,1] neg_hi:[0,0,1]
	v_pk_mul_f32 v[62:63], v[62:63], v[52:53] op_sel_hi:[0,1]
	v_fmamk_f32 v56, v57, 0x80000000, v60
	v_pk_fma_f32 v[64:65], v[58:59], v[52:53], v[62:63] op_sel:[1,0,1] op_sel_hi:[1,1,0] neg_lo:[0,0,1] neg_hi:[0,0,1]
	v_pk_fma_f32 v[52:53], v[58:59], v[52:53], v[62:63] op_sel:[1,0,1] op_sel_hi:[1,1,0]
	v_fma_f32 v2, 0, v60, v57
	v_pk_mul_f32 v[58:59], v[56:57], v[38:39] op_sel_hi:[0,1]
	v_mov_b32_e32 v65, v53
	v_pk_fma_f32 v[62:63], v[2:3], v[38:39], v[58:59] op_sel:[0,0,1] op_sel_hi:[1,1,0]
	v_pk_fma_f32 v[38:39], v[2:3], v[38:39], v[58:59] op_sel:[0,0,1] op_sel_hi:[0,1,0] neg_lo:[0,0,1] neg_hi:[0,0,1]
	v_pk_mul_f32 v[58:59], v[60:61], s[10:11] op_sel_hi:[1,0]
	v_mov_b32_e32 v67, v55
	v_pk_add_f32 v[52:53], v[48:49], v[64:65]
	v_pk_add_f32 v[48:49], v[48:49], v[64:65] neg_lo:[0,1] neg_hi:[0,1]
	v_mov_b32_e32 v63, v39
	v_pk_add_f32 v[64:65], v[58:59], v[58:59] op_sel:[0,1] op_sel_hi:[0,1] neg_lo:[0,1] neg_hi:[0,1]
	v_pk_add_f32 v[54:55], v[50:51], v[66:67]
	v_pk_add_f32 v[50:51], v[50:51], v[66:67] neg_lo:[0,1] neg_hi:[0,1]
	v_pk_add_f32 v[38:39], v[30:31], v[62:63]
	v_pk_add_f32 v[30:31], v[30:31], v[62:63] neg_lo:[0,1] neg_hi:[0,1]
	v_pk_add_f32 v[62:63], v[58:59], v[58:59] op_sel:[1,0] op_sel_hi:[1,0]
	v_pk_mul_f32 v[66:67], v[64:65], v[36:37]
	v_fma_f32 v58, 0, v57, v60
	v_pk_fma_f32 v[68:69], v[62:63], v[36:37], v[66:67] op_sel:[0,0,1] op_sel_hi:[1,1,0]
	v_pk_fma_f32 v[36:37], v[62:63], v[36:37], v[66:67] op_sel:[0,0,1] op_sel_hi:[1,1,0] neg_lo:[0,0,1] neg_hi:[0,0,1]
	v_fma_f32 v66, v60, 0, -v57
	v_mov_b32_e32 v69, v37
	v_pk_add_f32 v[36:37], v[28:29], v[68:69]
	v_pk_add_f32 v[28:29], v[28:29], v[68:69] neg_lo:[0,1] neg_hi:[0,1]
	v_pk_mul_f32 v[68:69], v[66:67], v[34:35] op_sel_hi:[0,1]
	v_pk_fma_f32 v[70:71], v[58:59], v[34:35], v[68:69] op_sel:[0,0,1] op_sel_hi:[1,1,0]
	v_pk_fma_f32 v[34:35], v[58:59], v[34:35], v[68:69] op_sel:[0,0,1] op_sel_hi:[0,1,0] neg_lo:[0,0,1] neg_hi:[0,0,1]
	v_fma_f32 v60, v60, s11, -v59
	v_mov_b32_e32 v71, v35
	v_pk_mul_f32 v[68:69], v[60:61], v[32:33] op_sel_hi:[0,1]
	v_pk_mul_f32 v[56:57], v[56:57], v[54:55] op_sel_hi:[0,1]
	v_pk_add_f32 v[34:35], v[26:27], v[70:71]
	v_pk_add_f32 v[26:27], v[26:27], v[70:71] neg_lo:[0,1] neg_hi:[0,1]
	v_pk_fma_f32 v[70:71], v[64:65], v[32:33], v[68:69] op_sel:[0,0,1] op_sel_hi:[1,1,0]
	v_pk_fma_f32 v[32:33], v[64:65], v[32:33], v[68:69] op_sel:[0,0,1] op_sel_hi:[1,1,0] neg_lo:[0,0,1] neg_hi:[0,0,1]
	v_pk_fma_f32 v[68:69], v[2:3], v[54:55], v[56:57] op_sel:[0,0,1] op_sel_hi:[1,1,0]
; __device__ __forceinline__ f32x2 cmul(f32x2 a, f32x2 b) { return (f32x2){a.x * b.x - a.y * b.y, a.x * b.y + a.y * b.x}; }
; __device__ __forceinline__ f32x2 cmulc(f32x2 a, f32x2 b) { return (f32x2){a.x * b.x + a.y * b.y, a.y * b.x - a.x * b.y}; }
; template <bool INV, int ST> __device__ __forceinline__ void fft_pass16(LAS f32x2* buf, int base, int bl) {
;     ...
;             for (int dd = 0; dd < 4; ++dd) { const int d = g + dd; const f32x2 w = cmul(W2, (f32x2){C16[2 * dd], -S16[2 * dd]}); const f32x2 a = x[d], b = cmulc(x[d + 4], w); x[d] = a + b; x[d + 4] = a - b; }
; #pragma unroll
;         for (int d = 0; d < 8; ++d) { const f32x2 w = cmul(W1, (f32x2){C16[d], -S16[d]}); const f32x2 a = x[d], b = cmulc(x[d + 8], w); x[d] = a + b; x[d + 8] = a - b; }
;     }
; #pragma unroll
;     for (int d = 0; d < 16; ++d) pb[d * STEP] = x[d];
; __device__ __forceinline__ void hyena_phase(const Params& P, int l, LAS unsigned char* lds) {
;     ...
;                 const float skip = P.in[14][(size_t)(l * 2 + ord) * 1024 + c];
	v_pk_fma_f32 v[54:55], v[2:3], v[54:55], v[56:57] op_sel:[0,0,1] op_sel_hi:[0,1,0] neg_lo:[0,0,1] neg_hi:[0,0,1]
	v_mov_b32_e32 v69, v55
	v_pk_mul_f32 v[56:57], v[64:65], v[52:53]
	v_pk_add_f32 v[54:55], v[46:47], v[68:69]
	v_pk_add_f32 v[46:47], v[46:47], v[68:69] neg_lo:[0,1] neg_hi:[0,1]
	v_pk_fma_f32 v[68:69], v[62:63], v[52:53], v[56:57] op_sel:[0,0,1] op_sel_hi:[1,1,0]
	v_pk_fma_f32 v[52:53], v[62:63], v[52:53], v[56:57] op_sel:[0,0,1] op_sel_hi:[1,1,0] neg_lo:[0,0,1] neg_hi:[0,0,1]
	v_pk_mul_f32 v[56:57], v[66:67], v[50:51] op_sel_hi:[0,1]
	v_pk_fma_f32 v[62:63], v[58:59], v[50:51], v[56:57] op_sel:[0,0,1] op_sel_hi:[1,1,0]
	v_pk_fma_f32 v[50:51], v[58:59], v[50:51], v[56:57] op_sel:[0,0,1] op_sel_hi:[0,1,0] neg_lo:[0,0,1] neg_hi:[0,0,1]
	v_pk_mul_f32 v[56:57], v[60:61], v[48:49] op_sel_hi:[0,1]
	v_pk_fma_f32 v[58:59], v[64:65], v[48:49], v[56:57] op_sel:[0,0,1] op_sel_hi:[1,1,0]
	v_pk_fma_f32 v[48:49], v[64:65], v[48:49], v[56:57] op_sel:[0,0,1] op_sel_hi:[1,1,0] neg_lo:[0,0,1] neg_hi:[0,0,1]
	v_fma_f32 v56, v20, s22, -v21
	v_mov_b32_e32 v59, v49
	v_fmamk_f32 v2, v21, 0x80000000, v20
	v_pk_mul_f32 v[56:57], v[56:57], v[54:55] op_sel:[0,1] op_sel_hi:[0,0]
	v_pk_add_f32 v[48:49], v[40:41], v[58:59]
	v_pk_add_f32 v[40:41], v[40:41], v[58:59] neg_lo:[0,1] neg_hi:[0,1]
	v_pk_fma_f32 v[58:59], v[2:3], v[54:55], v[56:57]
	v_pk_fma_f32 v[54:55], v[2:3], v[54:55], v[56:57] op_sel_hi:[0,1,1] neg_lo:[0,0,1] neg_hi:[0,0,1]
	v_mov_b32_e32 v63, v51
	v_mov_b32_e32 v59, v55
	v_mov_b32_e32 v56, v21
	v_mov_b32_e32 v57, v20
	v_mov_b32_e32 v69, v53
	v_pk_add_f32 v[50:51], v[42:43], v[62:63]
	v_pk_add_f32 v[42:43], v[42:43], v[62:63] neg_lo:[0,1] neg_hi:[0,1]
	v_pk_add_f32 v[54:55], v[38:39], v[58:59]
	v_pk_add_f32 v[38:39], v[38:39], v[58:59] neg_lo:[0,1] neg_hi:[0,1]
	v_pk_mul_f32 v[58:59], v[56:57], s[8:9]
	v_pk_mul_f32 v[62:63], v[56:57], s[20:21]
	v_pk_mul_f32 v[56:57], v[56:57], s[96:97]
	v_pk_add_f32 v[52:53], v[44:45], v[68:69]
	v_pk_add_f32 v[44:45], v[44:45], v[68:69] neg_lo:[0,1] neg_hi:[0,1]
	v_pk_add_f32 v[68:69], v[56:57], v[56:57] op_sel:[0,1] op_sel_hi:[0,1] neg_lo:[0,1] neg_hi:[0,1]
	v_mov_b32_e32 v71, v33
	v_fma_f32 v2, v21, s2, -v63
	v_pk_add_f32 v[66:67], v[62:63], v[62:63] op_sel:[1,0] op_sel_hi:[1,0] neg_lo:[0,1] neg_hi:[0,1]
	v_pk_mul_f32 v[68:69], v[68:69], v[48:49] op_sel:[0,1] op_sel_hi:[1,0]
	v_fma_f32 v56, v21, s22, -v20
	v_pk_add_f32 v[32:33], v[24:25], v[70:71]
	v_pk_add_f32 v[24:25], v[24:25], v[70:71] neg_lo:[0,1] neg_hi:[0,1]
	v_pk_mul_f32 v[64:65], v[2:3], v[52:53] op_sel:[0,1] op_sel_hi:[0,0]
	v_pk_fma_f32 v[70:71], v[66:67], v[48:49], v[68:69]
	v_pk_fma_f32 v[48:49], v[66:67], v[48:49], v[68:69] neg_lo:[0,0,1] neg_hi:[0,0,1]
	v_fma_f32 v2, v20, 0, -v21
	v_pk_mul_f32 v[66:67], v[56:57], v[46:47] op_sel:[0,1] op_sel_hi:[0,0]
	v_pk_add_f32 v[60:61], v[58:59], v[58:59] op_sel:[0,1] op_sel_hi:[0,1] neg_lo:[0,1] neg_hi:[0,1]
	v_pk_fma_f32 v[68:69], v[2:3], v[46:47], v[66:67]
	v_pk_fma_f32 v[46:47], v[2:3], v[46:47], v[66:67] op_sel_hi:[0,1,1] neg_lo:[0,0,1] neg_hi:[0,0,1]
	v_pk_mul_f32 v[66:67], v[20:21], s[8:9]
	v_pk_mul_f32 v[60:61], v[60:61], v[50:51] op_sel:[0,1] op_sel_hi:[1,0]
	v_mov_b32_e32 v69, v47
	v_sub_f32_e32 v56, v59, v67
	v_pk_add_f32 v[46:47], v[30:31], v[68:69]
	v_pk_add_f32 v[30:31], v[30:31], v[68:69] neg_lo:[0,1] neg_hi:[0,1]
	v_fma_f32 v2, v20, s96, -v62
	v_pk_fma_f32 v[68:69], v[56:57], v[50:51], v[60:61] op_sel_hi:[0,1,1]
	v_pk_fma_f32 v[50:51], v[56:57], v[50:51], v[60:61] op_sel_hi:[0,1,1] neg_lo:[0,0,1] neg_hi:[0,0,1]
	v_sub_f32_e32 v56, v67, v59
	v_pk_mul_f32 v[20:21], v[20:21], s[2:3]
	v_pk_add_f32 v[60:61], v[66:67], v[66:67] op_sel:[0,1] op_sel_hi:[0,1] neg_lo:[0,1] neg_hi:[0,1]
	v_pk_mul_f32 v[58:59], v[56:57], v[42:43] op_sel:[0,1] op_sel_hi:[0,0]
	v_sub_f32_e32 v56, v57, v21
	v_pk_fma_f32 v[66:67], v[60:61], v[42:43], v[58:59]
	v_pk_fma_f32 v[42:43], v[60:61], v[42:43], v[58:59] neg_lo:[0,0,1] neg_hi:[0,0,1]
	v_pk_fma_f32 v[58:59], v[56:57], v[52:53], v[64:65] op_sel_hi:[0,1,1]
	v_pk_fma_f32 v[52:53], v[56:57], v[52:53], v[64:65] op_sel_hi:[0,1,1] neg_lo:[0,0,1] neg_hi:[0,0,1]
	v_sub_f32_e32 v56, v21, v57
	v_mov_b32_e32 v59, v53
	v_pk_mul_f32 v[56:57], v[56:57], v[44:45] op_sel:[0,1] op_sel_hi:[0,0]
	v_pk_add_f32 v[52:53], v[36:37], v[58:59]
	v_pk_add_f32 v[36:37], v[36:37], v[58:59] neg_lo:[0,1] neg_hi:[0,1]
	v_pk_fma_f32 v[58:59], v[2:3], v[44:45], v[56:57]
	v_pk_fma_f32 v[44:45], v[2:3], v[44:45], v[56:57] op_sel_hi:[0,1,1] neg_lo:[0,0,1] neg_hi:[0,0,1]
	v_pk_add_f32 v[56:57], v[62:63], v[62:63] op_sel:[0,1] op_sel_hi:[0,1] neg_lo:[0,1] neg_hi:[0,1]
	v_mov_b32_e32 v59, v45
	v_pk_add_f32 v[20:21], v[20:21], v[20:21] op_sel:[0,1] op_sel_hi:[0,1] neg_lo:[0,1] neg_hi:[0,1]
	v_pk_mul_f32 v[56:57], v[56:57], v[40:41] op_sel:[0,1] op_sel_hi:[1,0]
	v_pk_add_f32 v[44:45], v[28:29], v[58:59]
	v_pk_add_f32 v[28:29], v[28:29], v[58:59] neg_lo:[0,1] neg_hi:[0,1]
	v_pk_fma_f32 v[58:59], v[20:21], v[40:41], v[56:57]
	v_pk_fma_f32 v[20:21], v[20:21], v[40:41], v[56:57] neg_lo:[0,0,1] neg_hi:[0,0,1]
	s_add_u32 s6, s27, s6
	v_mov_b32_e32 v71, v49
	v_mov_b32_e32 v69, v51
	v_mov_b32_e32 v67, v43
	v_mov_b32_e32 v59, v21
	s_addc_u32 s7, s46, s7
	v_pk_add_f32 v[48:49], v[32:33], v[70:71]
	v_pk_add_f32 v[32:33], v[32:33], v[70:71] neg_lo:[0,1] neg_hi:[0,1]
	v_pk_add_f32 v[50:51], v[34:35], v[68:69]
	v_pk_add_f32 v[34:35], v[34:35], v[68:69] neg_lo:[0,1] neg_hi:[0,1]
	v_pk_add_f32 v[42:43], v[26:27], v[66:67]
	v_pk_add_f32 v[26:27], v[26:27], v[66:67] neg_lo:[0,1] neg_hi:[0,1]
	v_pk_add_f32 v[20:21], v[24:25], v[58:59]
	v_pk_add_f32 v[24:25], v[24:25], v[58:59] neg_lo:[0,1] neg_hi:[0,1]
	ds_write_b64 v23, v[54:55]
	ds_write_b64 v23, v[52:53] offset:4352
	ds_write_b64 v23, v[50:51] offset:8704
	ds_write_b64 v23, v[48:49] offset:13056
	ds_write_b64 v23, v[46:47] offset:17408
	ds_write_b64 v23, v[44:45] offset:21760
	ds_write_b64 v23, v[42:43] offset:26112
	ds_write_b64 v23, v[20:21] offset:30464
	ds_write_b64 v23, v[38:39] offset:34816
	ds_write_b64 v23, v[36:37] offset:39168
	ds_write_b64 v23, v[34:35] offset:43520
	ds_write_b64 v23, v[32:33] offset:47872
	ds_write_b64 v23, v[30:31] offset:52224
	ds_write_b64 v23, v[28:29] offset:56576
	ds_write_b64 v23, v[26:27] offset:60928
	ds_write_b64 v23, v[24:25] offset:65280
	s_waitcnt lgkmcnt(0)
	s_barrier
; __device__ __forceinline__ unsigned pk2(float lo, float hi) { unsigned r; asm("v_cvt_pk_bf16_f32 %0, %1, %2" : "=v"(r) : "v"(lo), "v"(hi)); return r; }
; __device__ __forceinline__ float bflo(unsigned u) { return __uint_as_float(u << 16); }
; __device__ __forceinline__ float bfhi(unsigned u) { return __uint_as_float(u & 0xffff0000u); }
; __device__ __forceinline__ void hyena_phase(const Params& P, int l, LAS unsigned char* lds) {
;     ...
;                 const float skip = P.in[14][(size_t)(l * 2 + ord) * 1024 + c];
; #pragma unroll
;                 for (int u = 0; u < 8; ++u) { const int t = tid + 512 * u; const f32x2 cv = bufA[PADI(tid) + 544 * u]; const unsigned gw_ = ZT[(size_t)((ord + 1) * 1024 + c) * 4096 + t]; const f32x2 gt = {bflo(gw_), bfhi(gw_)};
;                     if (ord == 0) { y1[u] = gt * (cv + skip * vv[u]); bufA[PADI(tid) + 544 * u] = y1[u]; bufA[PADI(tid) + 544 * u + 4352] = (f32x2){0.f, 0.f}; }
;                     else { const f32x2 yo = gt * (cv + skip * y1[u]); ((unsigned*)(ws + WS_ZY))[(size_t)c * 4096 + t] = pk2(yo.x, yo.y); } }
	global_load_dword v2, v3, s[6:7]
	s_lshl_b64 s[6:7], s[18:19], 14
	s_add_u32 s6, s28, s6
	s_addc_u32 s7, s29, s7
	v_lshlrev_b64 v[0:1], 2, v[0:1]
	v_lshl_add_u64 v[20:21], s[6:7], 0, v[0:1]
	s_mov_b64 s[6:7], 0x2000000
	v_lshl_add_u64 v[24:25], v[20:21], 0, s[6:7]
	s_mov_b32 s6, 0x2001000
	v_add_co_u32_e32 v26, vcc, s6, v20
	ds_read_b64 v[30:31], v22
	s_nop 0
	v_addc_co_u32_e32 v27, vcc, 0, v21, vcc
	v_lshl_add_u64 v[0:1], s[4:5], 0, v[0:1]
	s_movk_i32 s3, 0x2000
	s_mov_b32 s4, 0x2002000
	s_movk_i32 s94, 0x3000
	s_waitcnt vmcnt(0) lgkmcnt(0)
	v_mov_b32_e32 v23, v192
	v_pk_fma_f32 v[14:15], v[14:15], v[2:3], v[30:31] op_sel_hi:[1,0,1]
	s_waitcnt vmcnt(0)
	v_lshlrev_b32_e32 v28, 16, v23
	v_and_b32_e32 v29, 0xffff0000, v23
	v_pk_mul_f32 v[14:15], v[14:15], v[28:29]
	s_nop 0
	v_cvt_pk_bf16_f32 v14, v14, v15
	v_mov_b32_e32 v15, v193
	ds_read_b64 v[24:25], v22 offset:4352
	global_store_dword v[0:1], v14, off
	s_waitcnt lgkmcnt(0)
	v_pk_fma_f32 v[18:19], v[18:19], v[2:3], v[24:25] op_sel_hi:[1,0,1]
	ds_read_b64 v[24:25], v22 offset:13056
	s_waitcnt lgkmcnt(0)
	v_pk_fma_f32 v[12:13], v[12:13], v[2:3], v[24:25] op_sel_hi:[1,0,1]
	v_lshlrev_b32_e32 v14, 16, v15
	v_and_b32_e32 v15, 0xffff0000, v15
	v_pk_mul_f32 v[14:15], v[18:19], v[14:15]
	ds_read_b64 v[18:19], v22 offset:8704
	v_cvt_pk_bf16_f32 v14, v14, v15
	v_mov_b32_e32 v15, v194
	s_waitcnt lgkmcnt(0)
	v_pk_fma_f32 v[16:17], v[16:17], v[2:3], v[18:19] op_sel_hi:[1,0,1]
	v_mov_b32_e32 v19, v195
	s_nop 0
	global_store_dword v[0:1], v14, off offset:2048
	v_lshlrev_b32_e32 v14, 16, v15
	v_and_b32_e32 v15, 0xffff0000, v15
	v_pk_mul_f32 v[14:15], v[16:17], v[14:15]
	s_nop 0
	v_cvt_pk_bf16_f32 v18, v14, v15
	v_add_co_u32_e32 v14, vcc, s59, v0
	s_nop 1
	v_addc_co_u32_e32 v15, vcc, 0, v1, vcc
	v_add_co_u32_e32 v16, vcc, s3, v0
	s_nop 1
	v_addc_co_u32_e32 v17, vcc, 0, v1, vcc
	global_store_dword v[16:17], v18, off offset:-4096
	v_lshlrev_b32_e32 v18, 16, v19
	v_and_b32_e32 v19, 0xffff0000, v19
	v_pk_mul_f32 v[12:13], v[12:13], v[18:19]
	s_nop 0
	v_cvt_pk_bf16_f32 v12, v12, v13
	global_store_dword v[14:15], v12, off offset:2048
	v_add_co_u32_e32 v12, vcc, s4, v20
	s_mov_b32 s4, 0x2003000
	s_nop 0
	v_addc_co_u32_e32 v13, vcc, 0, v21, vcc
	v_add_co_u32_e32 v14, vcc, s4, v20
	s_nop 1
	v_addc_co_u32_e32 v15, vcc, 0, v21, vcc
	v_mov_b32_e32 v19, v202
	ds_read_b64 v[20:21], v22 offset:17408
	v_add_co_u32_e32 v0, vcc, s94, v0
	s_waitcnt lgkmcnt(0)
	v_pk_fma_f32 v[10:11], v[10:11], v[2:3], v[20:21] op_sel_hi:[1,0,1]
	v_addc_co_u32_e32 v1, vcc, 0, v1, vcc
	v_lshlrev_b32_e32 v18, 16, v19
	v_and_b32_e32 v19, 0xffff0000, v19
	v_pk_mul_f32 v[10:11], v[10:11], v[18:19]
	s_nop 0
	v_cvt_pk_bf16_f32 v10, v10, v11
	v_mov_b32_e32 v11, v203
	ds_read_b64 v[12:13], v22 offset:21760
	global_store_dword v[16:17], v10, off
	s_waitcnt lgkmcnt(0)
	v_pk_fma_f32 v[8:9], v[8:9], v[2:3], v[12:13] op_sel_hi:[1,0,1]
	v_lshlrev_b32_e32 v10, 16, v11
	v_and_b32_e32 v11, 0xffff0000, v11
	v_pk_mul_f32 v[8:9], v[8:9], v[10:11]
	ds_read_b64 v[10:11], v22 offset:26112
	v_cvt_pk_bf16_f32 v8, v8, v9
	v_mov_b32_e32 v9, v204
	s_waitcnt lgkmcnt(0)
	v_pk_fma_f32 v[6:7], v[6:7], v[2:3], v[10:11] op_sel_hi:[1,0,1]
	global_store_dword v[16:17], v8, off offset:2048
	v_lshlrev_b32_e32 v8, 16, v9
	v_and_b32_e32 v9, 0xffff0000, v9
	v_pk_mul_f32 v[6:7], v[6:7], v[8:9]
	ds_read_b64 v[8:9], v22 offset:30464
	v_cvt_pk_bf16_f32 v6, v6, v7
	v_mov_b32_e32 v7, v205
	s_waitcnt lgkmcnt(0)
	v_pk_fma_f32 v[4:5], v[4:5], v[2:3], v[8:9] op_sel_hi:[1,0,1]
	global_store_dword v[0:1], v6, off
	v_lshlrev_b32_e32 v6, 16, v7
	v_and_b32_e32 v7, 0xffff0000, v7
	v_pk_mul_f32 v[4:5], v[4:5], v[6:7]
	s_nop 0
	v_cvt_pk_bf16_f32 v2, v4, v5
	global_store_dword v[0:1], v2, off offset:2048
	s_barrier
	s_branch .LBB0_331
